# GEMM K-loops: LDS-DMA waits moved to the consumer (one vmcnt(10) per read-preceding load segment instead of two early vmcnt(6) drains), more DMAs in flight
# speedup vs baseline: 1.0087x; 1.0053x over previous
.Lpk_wait_ret:
	s_add_u32 s14, s12, 0x100
	s_addc_u32 s15, s13, 0
	s_add_i32 s34, 0, 0x10000
	v_add_u32_e32 v0, s34, v165
	ds_read_b128 v[90:93], v0
	ds_read_b128 v[94:97], v0 offset:1024
	ds_read_b128 v[98:101], v0 offset:2048
	ds_read_b128 v[102:105], v0 offset:3072
	s_cmp_eq_u32 s50, 40
	s_cselect_b32 s3, s1, s15
	s_cselect_b32 s2, s0, s14
	s_cselect_b32 s17, s11, s39
	s_cselect_b32 s16, s10, s38
	v_lshl_add_u64 v[162:163], s[12:13], 0, v[150:151]
	s_add_i32 m0, s51, 0xc000
	ds_read_b128 v[154:157], v167
	ds_read_b128 v[158:161], v167 offset:1024
	ds_read_b128 v[168:171], v167 offset:2048
	ds_read_b128 v[172:175], v167 offset:3072
	ds_read_b128 v[176:179], v167 offset:4096
	ds_read_b128 v[180:183], v167 offset:5120
	ds_read_b128 v[184:187], v167 offset:6144
	ds_read_b128 v[188:191], v167 offset:7168
	global_load_lds_dwordx4 v[162:163], off
	v_lshl_add_u64 v[162:163], s[12:13], 0, v[152:153]
	s_add_i32 m0, s51, 0xe000
	s_nop 0
	global_load_lds_dwordx4 v[162:163], off
	s_waitcnt vmcnt(10)
	s_waitcnt lgkmcnt(8)
	s_barrier
	s_waitcnt lgkmcnt(0)
	s_setprio 1
	s_waitcnt lgkmcnt(0)
	v_mfma_f32_16x16x32_bf16 v[142:145], v[90:93], v[154:157], v[142:145]
	v_mfma_f32_16x16x32_bf16 v[138:141], v[98:101], v[154:157], v[138:141]
	v_mfma_f32_16x16x32_bf16 v[126:129], v[90:93], v[168:171], v[126:129]
	v_mfma_f32_16x16x32_bf16 v[122:125], v[98:101], v[168:171], v[122:125]
	v_mfma_f32_16x16x32_bf16 v[110:113], v[90:93], v[176:179], v[110:113]
	v_mfma_f32_16x16x32_bf16 v[106:109], v[98:101], v[176:179], v[106:109]
	v_mfma_f32_16x16x32_bf16 v[78:81], v[90:93], v[184:187], v[78:81]
	v_mfma_f32_16x16x32_bf16 v[74:77], v[98:101], v[184:187], v[74:77]
	v_mfma_f32_16x16x32_bf16 v[142:145], v[94:97], v[158:161], v[142:145]
	v_mfma_f32_16x16x32_bf16 v[138:141], v[102:105], v[158:161], v[138:141]
	v_mfma_f32_16x16x32_bf16 v[126:129], v[94:97], v[172:175], v[126:129]
	v_mfma_f32_16x16x32_bf16 v[122:125], v[102:105], v[172:175], v[122:125]
	v_mfma_f32_16x16x32_bf16 v[110:113], v[94:97], v[180:183], v[110:113]
	v_mfma_f32_16x16x32_bf16 v[106:109], v[102:105], v[180:183], v[106:109]
	v_mfma_f32_16x16x32_bf16 v[78:81], v[94:97], v[188:191], v[78:81]
	v_mfma_f32_16x16x32_bf16 v[74:77], v[102:105], v[188:191], v[74:77]
	s_setprio 0
	s_barrier
	s_add_i32 s35, 0, 0x14000
	s_add_i32 s12, s34, s45
	v_add_u32_e32 v0, s35, v165
	v_lshl_add_u64 v[162:163], s[16:17], 0, v[148:149]
	s_mov_b32 m0, s12
	ds_read_b128 v[196:199], v0
	ds_read_b128 v[200:203], v0 offset:1024
	ds_read_b128 v[206:209], v0 offset:2048
	ds_read_b128 v[210:213], v0 offset:3072
	global_load_lds_dwordx4 v[162:163], off
	v_lshl_add_u64 v[192:193], s[16:17], 0, v[146:147]
	s_add_i32 m0, s12, 0x2000
	s_nop 0
	global_load_lds_dwordx4 v[192:193], off
	s_waitcnt vmcnt(10)
	s_barrier
	s_waitcnt lgkmcnt(0)
	s_setprio 1
	s_waitcnt lgkmcnt(0)
	v_mfma_f32_16x16x32_bf16 v[134:137], v[196:199], v[154:157], v[134:137]
	v_mfma_f32_16x16x32_bf16 v[130:133], v[206:209], v[154:157], v[130:133]
	v_mfma_f32_16x16x32_bf16 v[118:121], v[196:199], v[168:171], v[118:121]
	v_mfma_f32_16x16x32_bf16 v[114:117], v[206:209], v[168:171], v[114:117]
	v_mfma_f32_16x16x32_bf16 v[86:89], v[196:199], v[176:179], v[86:89]
	v_mfma_f32_16x16x32_bf16 v[82:85], v[206:209], v[176:179], v[82:85]
	v_mfma_f32_16x16x32_bf16 v[70:73], v[196:199], v[184:187], v[70:73]
	v_mfma_f32_16x16x32_bf16 v[66:69], v[206:209], v[184:187], v[66:69]
	v_mfma_f32_16x16x32_bf16 v[134:137], v[200:203], v[158:161], v[134:137]
	v_mfma_f32_16x16x32_bf16 v[130:133], v[210:213], v[158:161], v[130:133]
	v_mfma_f32_16x16x32_bf16 v[118:121], v[200:203], v[172:175], v[118:121]
	v_mfma_f32_16x16x32_bf16 v[114:117], v[210:213], v[172:175], v[114:117]
	v_mfma_f32_16x16x32_bf16 v[86:89], v[200:203], v[180:183], v[86:89]
	v_mfma_f32_16x16x32_bf16 v[82:85], v[210:213], v[180:183], v[82:85]
	v_mfma_f32_16x16x32_bf16 v[70:73], v[200:203], v[188:191], v[70:73]
	v_mfma_f32_16x16x32_bf16 v[66:69], v[210:213], v[188:191], v[66:69]
	s_setprio 0
	s_mov_b32 m0, s51
	v_lshl_add_u64 v[214:215], s[2:3], 0, v[148:149]
	s_barrier
	ds_read_b128 v[154:157], v167 offset:16384
	ds_read_b128 v[158:161], v167 offset:17408
	ds_read_b128 v[168:171], v167 offset:18432
	ds_read_b128 v[172:175], v167 offset:19456
	ds_read_b128 v[176:179], v167 offset:20480
	ds_read_b128 v[180:183], v167 offset:21504
	ds_read_b128 v[184:187], v167 offset:22528
	ds_read_b128 v[188:191], v167 offset:23552
	global_load_lds_dwordx4 v[214:215], off
	v_lshl_add_u64 v[216:217], s[2:3], 0, v[146:147]
	s_mov_b32 m0, s52
	s_nop 0
	global_load_lds_dwordx4 v[216:217], off
	s_barrier
	s_waitcnt lgkmcnt(0)
	s_setprio 1
	s_waitcnt lgkmcnt(0)
	v_mfma_f32_16x16x32_bf16 v[62:65], v[90:93], v[154:157], v[62:65]
	v_mfma_f32_16x16x32_bf16 v[58:61], v[98:101], v[154:157], v[58:61]
	v_mfma_f32_16x16x32_bf16 v[54:57], v[90:93], v[168:171], v[54:57]
	v_mfma_f32_16x16x32_bf16 v[50:53], v[98:101], v[168:171], v[50:53]
	v_mfma_f32_16x16x32_bf16 v[30:33], v[90:93], v[176:179], v[30:33]
	v_mfma_f32_16x16x32_bf16 v[26:29], v[98:101], v[176:179], v[26:29]
	v_mfma_f32_16x16x32_bf16 v[22:25], v[90:93], v[184:187], v[22:25]
	v_mfma_f32_16x16x32_bf16 v[18:21], v[98:101], v[184:187], v[18:21]
	v_mfma_f32_16x16x32_bf16 v[62:65], v[94:97], v[158:161], v[62:65]
	v_mfma_f32_16x16x32_bf16 v[58:61], v[102:105], v[158:161], v[58:61]
	v_mfma_f32_16x16x32_bf16 v[54:57], v[94:97], v[172:175], v[54:57]
	v_mfma_f32_16x16x32_bf16 v[50:53], v[102:105], v[172:175], v[50:53]
	v_mfma_f32_16x16x32_bf16 v[30:33], v[94:97], v[180:183], v[30:33]
	v_mfma_f32_16x16x32_bf16 v[26:29], v[102:105], v[180:183], v[26:29]
	v_mfma_f32_16x16x32_bf16 v[22:25], v[94:97], v[188:191], v[22:25]
	v_mfma_f32_16x16x32_bf16 v[18:21], v[102:105], v[188:191], v[18:21]
	s_setprio 0
	s_barrier
	s_add_u32 s12, s16, 0xb0000
	s_addc_u32 s13, s17, 0
	s_add_i32 s34, s35, s45
	v_lshl_add_u64 v[90:91], s[12:13], 0, v[148:149]
	s_mov_b32 m0, s34
	s_nop 0
	global_load_lds_dwordx4 v[90:91], off
	v_lshl_add_u64 v[90:91], s[12:13], 0, v[146:147]
	s_add_i32 m0, s34, 0x2000
	s_nop 0
	global_load_lds_dwordx4 v[90:91], off
	s_waitcnt vmcnt(10)
	s_barrier
	s_setprio 1
	v_mfma_f32_16x16x32_bf16 v[46:49], v[196:199], v[154:157], v[46:49]
	v_mfma_f32_16x16x32_bf16 v[42:45], v[206:209], v[154:157], v[42:45]
	v_mfma_f32_16x16x32_bf16 v[38:41], v[196:199], v[168:171], v[38:41]
	v_mfma_f32_16x16x32_bf16 v[34:37], v[206:209], v[168:171], v[34:37]
	v_mfma_f32_16x16x32_bf16 v[14:17], v[196:199], v[176:179], v[14:17]
	v_mfma_f32_16x16x32_bf16 v[10:13], v[206:209], v[176:179], v[10:13]
	v_mfma_f32_16x16x32_bf16 v[6:9], v[196:199], v[184:187], v[6:9]
	v_mfma_f32_16x16x32_bf16 v[2:5], v[206:209], v[184:187], v[2:5]
	v_mfma_f32_16x16x32_bf16 v[46:49], v[200:203], v[158:161], v[46:49]
	v_mfma_f32_16x16x32_bf16 v[42:45], v[210:213], v[158:161], v[42:45]
	v_mfma_f32_16x16x32_bf16 v[38:41], v[200:203], v[172:175], v[38:41]
	v_mfma_f32_16x16x32_bf16 v[34:37], v[210:213], v[172:175], v[34:37]
	v_mfma_f32_16x16x32_bf16 v[14:17], v[200:203], v[180:183], v[14:17]
	v_mfma_f32_16x16x32_bf16 v[10:13], v[210:213], v[180:183], v[10:13]
	v_mfma_f32_16x16x32_bf16 v[6:9], v[200:203], v[188:191], v[6:9]
	v_mfma_f32_16x16x32_bf16 v[2:5], v[210:213], v[188:191], v[2:5]
	s_setprio 0
	s_add_i32 s12, 0, 0x18000
	v_add_u32_e32 v0, s12, v165
	s_barrier
	ds_read_b128 v[90:93], v0
	ds_read_b128 v[94:97], v0 offset:1024
	ds_read_b128 v[98:101], v0 offset:2048
	ds_read_b128 v[102:105], v0 offset:3072
	s_add_u32 s2, s2, 0xb0000
	s_addc_u32 s3, s3, 0
	s_mov_b32 m0, s53
	v_lshl_add_u64 v[196:197], s[2:3], 0, v[148:149]
	ds_read_b128 v[154:157], v167 offset:32768
	ds_read_b128 v[158:161], v167 offset:33792
	ds_read_b128 v[168:171], v167 offset:34816
	ds_read_b128 v[172:175], v167 offset:35840
	ds_read_b128 v[176:179], v167 offset:36864
	ds_read_b128 v[180:183], v167 offset:37888
	ds_read_b128 v[184:187], v167 offset:38912
	ds_read_b128 v[188:191], v167 offset:39936
	global_load_lds_dwordx4 v[196:197], off
	v_lshl_add_u64 v[196:197], s[2:3], 0, v[146:147]
	s_mov_b32 m0, s59
	s_nop 0
	global_load_lds_dwordx4 v[196:197], off
	s_waitcnt vmcnt(10)
	s_waitcnt lgkmcnt(8)
	s_barrier
	s_waitcnt lgkmcnt(0)
	s_setprio 1
	s_waitcnt lgkmcnt(0)
	v_mfma_f32_16x16x32_bf16 v[142:145], v[90:93], v[154:157], v[142:145]
	v_mfma_f32_16x16x32_bf16 v[138:141], v[98:101], v[154:157], v[138:141]
	v_mfma_f32_16x16x32_bf16 v[126:129], v[90:93], v[168:171], v[126:129]
	v_mfma_f32_16x16x32_bf16 v[122:125], v[98:101], v[168:171], v[122:125]
	v_mfma_f32_16x16x32_bf16 v[110:113], v[90:93], v[176:179], v[110:113]
	v_mfma_f32_16x16x32_bf16 v[106:109], v[98:101], v[176:179], v[106:109]
	v_mfma_f32_16x16x32_bf16 v[78:81], v[90:93], v[184:187], v[78:81]
	v_mfma_f32_16x16x32_bf16 v[74:77], v[98:101], v[184:187], v[74:77]
	v_mfma_f32_16x16x32_bf16 v[142:145], v[94:97], v[158:161], v[142:145]
	v_mfma_f32_16x16x32_bf16 v[138:141], v[102:105], v[158:161], v[138:141]
	v_mfma_f32_16x16x32_bf16 v[126:129], v[94:97], v[172:175], v[126:129]
	v_mfma_f32_16x16x32_bf16 v[122:125], v[102:105], v[172:175], v[122:125]
	v_mfma_f32_16x16x32_bf16 v[110:113], v[94:97], v[180:183], v[110:113]
	v_mfma_f32_16x16x32_bf16 v[106:109], v[102:105], v[180:183], v[106:109]
	v_mfma_f32_16x16x32_bf16 v[78:81], v[94:97], v[188:191], v[78:81]
	v_mfma_f32_16x16x32_bf16 v[74:77], v[102:105], v[188:191], v[74:77]
	s_setprio 0
	s_barrier
	s_add_i32 s13, 0, 0x1c000
	s_add_i32 s2, s12, s45
	v_add_u32_e32 v0, s13, v165
	v_lshl_add_u64 v[162:163], v[162:163], 0, s[74:75]
	s_mov_b32 m0, s2
	ds_read_b128 v[196:199], v0
	ds_read_b128 v[200:203], v0 offset:1024
	ds_read_b128 v[206:209], v0 offset:2048
	ds_read_b128 v[210:213], v0 offset:3072
	global_load_lds_dwordx4 v[162:163], off
	v_lshl_add_u64 v[162:163], v[192:193], 0, s[74:75]
	s_add_i32 m0, s2, 0x2000
	s_nop 0
	global_load_lds_dwordx4 v[162:163], off
	s_waitcnt vmcnt(10)
	s_barrier
	s_waitcnt lgkmcnt(0)
	s_setprio 1
	s_waitcnt lgkmcnt(0)
	v_mfma_f32_16x16x32_bf16 v[134:137], v[196:199], v[154:157], v[134:137]
	v_mfma_f32_16x16x32_bf16 v[130:133], v[206:209], v[154:157], v[130:133]
	v_mfma_f32_16x16x32_bf16 v[118:121], v[196:199], v[168:171], v[118:121]
	v_mfma_f32_16x16x32_bf16 v[114:117], v[206:209], v[168:171], v[114:117]
	v_mfma_f32_16x16x32_bf16 v[86:89], v[196:199], v[176:179], v[86:89]
	v_mfma_f32_16x16x32_bf16 v[82:85], v[206:209], v[176:179], v[82:85]
	v_mfma_f32_16x16x32_bf16 v[70:73], v[196:199], v[184:187], v[70:73]
	v_mfma_f32_16x16x32_bf16 v[66:69], v[206:209], v[184:187], v[66:69]
	v_mfma_f32_16x16x32_bf16 v[134:137], v[200:203], v[158:161], v[134:137]
	v_mfma_f32_16x16x32_bf16 v[130:133], v[210:213], v[158:161], v[130:133]
	v_mfma_f32_16x16x32_bf16 v[118:121], v[200:203], v[172:175], v[118:121]
	v_mfma_f32_16x16x32_bf16 v[114:117], v[210:213], v[172:175], v[114:117]
	v_mfma_f32_16x16x32_bf16 v[86:89], v[200:203], v[180:183], v[86:89]
	v_mfma_f32_16x16x32_bf16 v[82:85], v[210:213], v[180:183], v[82:85]
	v_mfma_f32_16x16x32_bf16 v[70:73], v[200:203], v[188:191], v[70:73]
	v_mfma_f32_16x16x32_bf16 v[66:69], v[210:213], v[188:191], v[66:69]
	s_setprio 0
	s_mov_b32 m0, s67
	v_lshl_add_u64 v[162:163], v[214:215], 0, s[74:75]
	s_barrier
	ds_read_b128 v[154:157], v167 offset:49152
	ds_read_b128 v[158:161], v167 offset:50176
	ds_read_b128 v[168:171], v167 offset:51200
	ds_read_b128 v[172:175], v167 offset:52224
	ds_read_b128 v[176:179], v167 offset:53248
	ds_read_b128 v[180:183], v167 offset:54272
	ds_read_b128 v[184:187], v167 offset:55296
	ds_read_b128 v[188:191], v167 offset:56320
	global_load_lds_dwordx4 v[162:163], off
	v_lshl_add_u64 v[162:163], v[216:217], 0, s[74:75]
	s_mov_b32 m0, s72
	s_nop 0
	global_load_lds_dwordx4 v[162:163], off
	s_barrier
	s_waitcnt lgkmcnt(0)
	s_setprio 1
	s_waitcnt lgkmcnt(0)
	v_mfma_f32_16x16x32_bf16 v[62:65], v[90:93], v[154:157], v[62:65]
	v_mfma_f32_16x16x32_bf16 v[58:61], v[98:101], v[154:157], v[58:61]
	v_mfma_f32_16x16x32_bf16 v[54:57], v[90:93], v[168:171], v[54:57]
	v_mfma_f32_16x16x32_bf16 v[50:53], v[98:101], v[168:171], v[50:53]
	v_mfma_f32_16x16x32_bf16 v[30:33], v[90:93], v[176:179], v[30:33]
	v_mfma_f32_16x16x32_bf16 v[26:29], v[98:101], v[176:179], v[26:29]
	v_mfma_f32_16x16x32_bf16 v[22:25], v[90:93], v[184:187], v[22:25]
	v_mfma_f32_16x16x32_bf16 v[18:21], v[98:101], v[184:187], v[18:21]
	v_mfma_f32_16x16x32_bf16 v[62:65], v[94:97], v[158:161], v[62:65]
	v_mfma_f32_16x16x32_bf16 v[58:61], v[102:105], v[158:161], v[58:61]
	v_mfma_f32_16x16x32_bf16 v[54:57], v[94:97], v[172:175], v[54:57]
	v_mfma_f32_16x16x32_bf16 v[50:53], v[102:105], v[172:175], v[50:53]
	v_mfma_f32_16x16x32_bf16 v[30:33], v[94:97], v[180:183], v[30:33]
	v_mfma_f32_16x16x32_bf16 v[26:29], v[102:105], v[180:183], v[26:29]
	v_mfma_f32_16x16x32_bf16 v[22:25], v[94:97], v[188:191], v[22:25]
	v_mfma_f32_16x16x32_bf16 v[18:21], v[102:105], v[188:191], v[18:21]
	s_setprio 0
	s_barrier
	s_add_u32 s2, s16, 0xb0080
	s_addc_u32 s3, s17, 0
	s_add_i32 s12, s13, s45
	v_lshl_add_u64 v[90:91], s[2:3], 0, v[148:149]
	s_mov_b32 m0, s12
	s_nop 0
	global_load_lds_dwordx4 v[90:91], off
	v_lshl_add_u64 v[90:91], s[2:3], 0, v[146:147]
	s_add_i32 m0, s12, 0x2000
	s_nop 0
	global_load_lds_dwordx4 v[90:91], off
	s_waitcnt vmcnt(10)
	s_barrier
	s_setprio 1
	v_mfma_f32_16x16x32_bf16 v[46:49], v[196:199], v[154:157], v[46:49]
	v_mfma_f32_16x16x32_bf16 v[42:45], v[206:209], v[154:157], v[42:45]
	v_mfma_f32_16x16x32_bf16 v[38:41], v[196:199], v[168:171], v[38:41]
	v_mfma_f32_16x16x32_bf16 v[34:37], v[206:209], v[168:171], v[34:37]
	v_mfma_f32_16x16x32_bf16 v[14:17], v[196:199], v[176:179], v[14:17]
	v_mfma_f32_16x16x32_bf16 v[10:13], v[206:209], v[176:179], v[10:13]
	v_mfma_f32_16x16x32_bf16 v[6:9], v[196:199], v[184:187], v[6:9]
	v_mfma_f32_16x16x32_bf16 v[2:5], v[206:209], v[184:187], v[2:5]
	v_mfma_f32_16x16x32_bf16 v[46:49], v[200:203], v[158:161], v[46:49]
	v_mfma_f32_16x16x32_bf16 v[42:45], v[210:213], v[158:161], v[42:45]
	v_mfma_f32_16x16x32_bf16 v[38:41], v[200:203], v[172:175], v[38:41]
	v_mfma_f32_16x16x32_bf16 v[34:37], v[210:213], v[172:175], v[34:37]
	v_mfma_f32_16x16x32_bf16 v[14:17], v[200:203], v[180:183], v[14:17]
	v_mfma_f32_16x16x32_bf16 v[10:13], v[210:213], v[180:183], v[10:13]
	v_mfma_f32_16x16x32_bf16 v[6:9], v[200:203], v[188:191], v[6:9]
	v_mfma_f32_16x16x32_bf16 v[2:5], v[210:213], v[188:191], v[2:5]
	s_setprio 0
	s_add_i32 s50, s50, 2
	s_add_u32 s38, s38, 0x100
	s_addc_u32 s39, s39, 0
	s_cmp_gt_u32 s50, 41
	s_mov_b64 s[12:13], s[14:15]
	s_barrier
	s_cbranch_scc0 .LBB0_40
	v_lshl_add_u32 v156, s54, 8, v164
	v_add_u32_e32 v158, 0xffffe000, v156
	v_lshrrev_b32_e32 v0, 11, v158
	s_movk_i32 s2, 0x1800
	v_mad_u32_u24 v0, v0, s2, s2
	v_cmp_lt_i32_e32 vcc, s40, v156
	v_lshl_or_b32 v154, s49, 8, v166
	v_ashrrev_i32_e32 v155, 31, v154
	v_cndmask_b32_e32 v0, 0, v0, vcc
	v_lshl_add_u64 v[90:91], v[0:1], 2, s[8:9]
	v_lshl_add_u64 v[90:91], v[154:155], 2, v[90:91]
	global_load_dwordx4 v[102:105], v[90:91], off
	global_load_dwordx4 v[98:101], v[90:91], off offset:64
	global_load_dwordx4 v[94:97], v[90:91], off offset:512
	s_nop 0
	global_load_dwordx4 v[90:93], v[90:91], off offset:576
	s_and_saveexec_b64 s[2:3], vcc
	s_xor_b64 s[2:3], exec, s[2:3]
	s_cbranch_execz .LBB0_43
	v_mov_b32_e32 v159, v1
	v_readlane_b32 s12, v249, 10
	v_lshlrev_b64 v[158:159], 12, v[158:159]
	v_readlane_b32 s13, v249, 11
	v_mov_b32_e32 v157, v1
	v_lshlrev_b64 v[160:161], 12, v[156:157]
	v_lshl_add_u64 v[162:163], s[12:13], 0, v[158:159]

.LBB0_113:
	s_add_u32 s2, s14, 0xfffc0080
	s_addc_u32 s3, s15, -1
	s_add_i32 s34, 0, 0x10000
	v_add_u32_e32 v145, s34, v143
	ds_read_b128 v[146:149], v145
	ds_read_b128 v[150:153], v145 offset:1024
	ds_read_b128 v[154:157], v145 offset:2048
	ds_read_b128 v[158:161], v145 offset:3072
	s_cmp_eq_u32 s56, 12
	s_cselect_b32 s3, s9, s3
	s_cselect_b32 s2, s49, s2
	s_cselect_b32 s17, s7, s50
	s_cselect_b32 s16, s54, s55
	v_lshl_add_u64 v[196:197], s[14:15], 0, v[138:139]
	s_add_i32 m0, s39, 0xc000
	ds_read_b128 v[162:165], v144
	ds_read_b128 v[166:169], v144 offset:1024
	ds_read_b128 v[170:173], v144 offset:2048
	ds_read_b128 v[174:177], v144 offset:3072
	ds_read_b128 v[178:181], v144 offset:4096
	ds_read_b128 v[182:185], v144 offset:5120
	ds_read_b128 v[186:189], v144 offset:6144
	ds_read_b128 v[190:193], v144 offset:7168
	global_load_lds_dwordx4 v[196:197], off
	v_lshl_add_u64 v[196:197], s[14:15], 0, v[140:141]
	s_add_i32 m0, s39, 0xe000
	s_nop 0
	global_load_lds_dwordx4 v[196:197], off
	s_waitcnt vmcnt(10)
	s_waitcnt lgkmcnt(8)
	s_barrier
	s_waitcnt lgkmcnt(0)
	s_setprio 1
	s_waitcnt lgkmcnt(0)
	v_mfma_f32_16x16x32_bf16 v[126:129], v[146:149], v[162:165], v[126:129]
	v_mfma_f32_16x16x32_bf16 v[118:121], v[154:157], v[162:165], v[118:121]
	v_mfma_f32_16x16x32_bf16 v[110:113], v[146:149], v[170:173], v[110:113]
	v_mfma_f32_16x16x32_bf16 v[102:105], v[154:157], v[170:173], v[102:105]
	v_mfma_f32_16x16x32_bf16 v[94:97], v[146:149], v[178:181], v[94:97]
	v_mfma_f32_16x16x32_bf16 v[86:89], v[154:157], v[178:181], v[86:89]
	v_mfma_f32_16x16x32_bf16 v[78:81], v[146:149], v[186:189], v[78:81]
	v_mfma_f32_16x16x32_bf16 v[70:73], v[154:157], v[186:189], v[70:73]
	v_mfma_f32_16x16x32_bf16 v[126:129], v[150:153], v[166:169], v[126:129]
	v_mfma_f32_16x16x32_bf16 v[118:121], v[158:161], v[166:169], v[118:121]
	v_mfma_f32_16x16x32_bf16 v[110:113], v[150:153], v[174:177], v[110:113]
	v_mfma_f32_16x16x32_bf16 v[102:105], v[158:161], v[174:177], v[102:105]
	v_mfma_f32_16x16x32_bf16 v[94:97], v[150:153], v[182:185], v[94:97]
	v_mfma_f32_16x16x32_bf16 v[86:89], v[158:161], v[182:185], v[86:89]
	v_mfma_f32_16x16x32_bf16 v[78:81], v[150:153], v[190:193], v[78:81]
	v_mfma_f32_16x16x32_bf16 v[70:73], v[158:161], v[190:193], v[70:73]
	s_setprio 0
	s_barrier
	s_add_i32 s40, 0, 0x14000
	s_add_i32 s34, s34, s38
	v_add_u32_e32 v145, s40, v143
	v_lshl_add_u64 v[214:215], s[16:17], 0, v[134:135]
	s_mov_b32 m0, s34
	ds_read_b128 v[196:199], v145
	ds_read_b128 v[200:203], v145 offset:1024
	ds_read_b128 v[206:209], v145 offset:2048
	ds_read_b128 v[210:213], v145 offset:3072
	global_load_lds_dwordx4 v[214:215], off
	v_lshl_add_u64 v[216:217], s[16:17], 0, v[130:131]
	s_add_i32 m0, s34, 0x2000
	s_nop 0
	global_load_lds_dwordx4 v[216:217], off
	s_waitcnt vmcnt(10)
	s_barrier
	s_waitcnt lgkmcnt(0)
	s_setprio 1
	s_waitcnt lgkmcnt(0)
	v_mfma_f32_16x16x32_bf16 v[122:125], v[196:199], v[162:165], v[122:125]
	v_mfma_f32_16x16x32_bf16 v[114:117], v[206:209], v[162:165], v[114:117]
	v_mfma_f32_16x16x32_bf16 v[106:109], v[196:199], v[170:173], v[106:109]
	v_mfma_f32_16x16x32_bf16 v[98:101], v[206:209], v[170:173], v[98:101]
	v_mfma_f32_16x16x32_bf16 v[90:93], v[196:199], v[178:181], v[90:93]
	v_mfma_f32_16x16x32_bf16 v[82:85], v[206:209], v[178:181], v[82:85]
	v_mfma_f32_16x16x32_bf16 v[74:77], v[196:199], v[186:189], v[74:77]
	v_mfma_f32_16x16x32_bf16 v[66:69], v[206:209], v[186:189], v[66:69]
	v_mfma_f32_16x16x32_bf16 v[122:125], v[200:203], v[166:169], v[122:125]
	v_mfma_f32_16x16x32_bf16 v[114:117], v[210:213], v[166:169], v[114:117]
	v_mfma_f32_16x16x32_bf16 v[106:109], v[200:203], v[174:177], v[106:109]
	v_mfma_f32_16x16x32_bf16 v[98:101], v[210:213], v[174:177], v[98:101]
	v_mfma_f32_16x16x32_bf16 v[90:93], v[200:203], v[182:185], v[90:93]
	v_mfma_f32_16x16x32_bf16 v[82:85], v[210:213], v[182:185], v[82:85]
	v_mfma_f32_16x16x32_bf16 v[74:77], v[200:203], v[190:193], v[74:77]
	v_mfma_f32_16x16x32_bf16 v[66:69], v[210:213], v[190:193], v[66:69]
	s_setprio 0
	s_mov_b32 m0, s39
	v_lshl_add_u64 v[218:219], s[2:3], 0, v[136:137]
	s_barrier
	ds_read_b128 v[162:165], v144 offset:16384
	ds_read_b128 v[166:169], v144 offset:17408
	ds_read_b128 v[170:173], v144 offset:18432
	ds_read_b128 v[174:177], v144 offset:19456
	ds_read_b128 v[178:181], v144 offset:20480
	ds_read_b128 v[182:185], v144 offset:21504
	ds_read_b128 v[186:189], v144 offset:22528
	ds_read_b128 v[190:193], v144 offset:23552
	global_load_lds_dwordx4 v[218:219], off
	v_lshl_add_u64 v[220:221], s[2:3], 0, v[132:133]
	s_mov_b32 m0, s45
	s_nop 0
	global_load_lds_dwordx4 v[220:221], off
	s_barrier
	s_waitcnt lgkmcnt(0)
	s_setprio 1
	s_waitcnt lgkmcnt(0)
	v_mfma_f32_16x16x32_bf16 v[62:65], v[146:149], v[162:165], v[62:65]
	v_mfma_f32_16x16x32_bf16 v[54:57], v[154:157], v[162:165], v[54:57]
	v_mfma_f32_16x16x32_bf16 v[46:49], v[146:149], v[170:173], v[46:49]
	v_mfma_f32_16x16x32_bf16 v[38:41], v[154:157], v[170:173], v[38:41]
	v_mfma_f32_16x16x32_bf16 v[30:33], v[146:149], v[178:181], v[30:33]
	v_mfma_f32_16x16x32_bf16 v[22:25], v[154:157], v[178:181], v[22:25]
	v_mfma_f32_16x16x32_bf16 v[14:17], v[146:149], v[186:189], v[14:17]
	v_mfma_f32_16x16x32_bf16 v[6:9], v[154:157], v[186:189], v[6:9]
	v_mfma_f32_16x16x32_bf16 v[62:65], v[150:153], v[166:169], v[62:65]
	v_mfma_f32_16x16x32_bf16 v[54:57], v[158:161], v[166:169], v[54:57]
	v_mfma_f32_16x16x32_bf16 v[46:49], v[150:153], v[174:177], v[46:49]
	v_mfma_f32_16x16x32_bf16 v[38:41], v[158:161], v[174:177], v[38:41]
	v_mfma_f32_16x16x32_bf16 v[30:33], v[150:153], v[182:185], v[30:33]
	v_mfma_f32_16x16x32_bf16 v[22:25], v[158:161], v[182:185], v[22:25]
	v_mfma_f32_16x16x32_bf16 v[14:17], v[150:153], v[190:193], v[14:17]
	v_mfma_f32_16x16x32_bf16 v[6:9], v[158:161], v[190:193], v[6:9]
	s_setprio 0
	s_barrier
	s_add_u32 s34, s16, 0x40000
	s_addc_u32 s35, s17, 0
	s_add_i32 s40, s40, s38
	v_lshl_add_u64 v[146:147], s[34:35], 0, v[134:135]
	s_mov_b32 m0, s40
	s_nop 0
	global_load_lds_dwordx4 v[146:147], off
	v_lshl_add_u64 v[146:147], s[34:35], 0, v[130:131]
	s_add_i32 m0, s40, 0x2000
	s_nop 0
	global_load_lds_dwordx4 v[146:147], off
	s_waitcnt vmcnt(10)
	s_barrier
	s_setprio 1
	v_mfma_f32_16x16x32_bf16 v[58:61], v[196:199], v[162:165], v[58:61]
	v_mfma_f32_16x16x32_bf16 v[50:53], v[206:209], v[162:165], v[50:53]
	v_mfma_f32_16x16x32_bf16 v[42:45], v[196:199], v[170:173], v[42:45]
	v_mfma_f32_16x16x32_bf16 v[34:37], v[206:209], v[170:173], v[34:37]
	v_mfma_f32_16x16x32_bf16 v[26:29], v[196:199], v[178:181], v[26:29]
	v_mfma_f32_16x16x32_bf16 v[18:21], v[206:209], v[178:181], v[18:21]
	v_mfma_f32_16x16x32_bf16 v[10:13], v[196:199], v[186:189], v[10:13]
	v_mfma_f32_16x16x32_bf16 v[2:5], v[206:209], v[186:189], v[2:5]
	v_mfma_f32_16x16x32_bf16 v[58:61], v[200:203], v[166:169], v[58:61]
	v_mfma_f32_16x16x32_bf16 v[50:53], v[210:213], v[166:169], v[50:53]
	v_mfma_f32_16x16x32_bf16 v[42:45], v[200:203], v[174:177], v[42:45]
	v_mfma_f32_16x16x32_bf16 v[34:37], v[210:213], v[174:177], v[34:37]
	v_mfma_f32_16x16x32_bf16 v[26:29], v[200:203], v[182:185], v[26:29]
	v_mfma_f32_16x16x32_bf16 v[18:21], v[210:213], v[182:185], v[18:21]
	v_mfma_f32_16x16x32_bf16 v[10:13], v[200:203], v[190:193], v[10:13]
	v_mfma_f32_16x16x32_bf16 v[2:5], v[210:213], v[190:193], v[2:5]
	s_setprio 0
	s_add_i32 s34, 0, 0x18000
	v_add_u32_e32 v145, s34, v143
	s_barrier
	ds_read_b128 v[146:149], v145
	ds_read_b128 v[150:153], v145 offset:1024
	ds_read_b128 v[154:157], v145 offset:2048
	ds_read_b128 v[158:161], v145 offset:3072
	s_add_u32 s2, s2, 0x40000
	s_addc_u32 s3, s3, 0
	s_mov_b32 m0, s51
	v_lshl_add_u64 v[196:197], s[2:3], 0, v[136:137]
	ds_read_b128 v[162:165], v144 offset:32768
	ds_read_b128 v[166:169], v144 offset:33792
	ds_read_b128 v[170:173], v144 offset:34816
	ds_read_b128 v[174:177], v144 offset:35840
	ds_read_b128 v[178:181], v144 offset:36864
	ds_read_b128 v[182:185], v144 offset:37888
	ds_read_b128 v[186:189], v144 offset:38912
	ds_read_b128 v[190:193], v144 offset:39936
	global_load_lds_dwordx4 v[196:197], off
	v_lshl_add_u64 v[196:197], s[2:3], 0, v[132:133]
	s_mov_b32 m0, s52
	s_nop 0
	global_load_lds_dwordx4 v[196:197], off
	s_waitcnt vmcnt(10)
	s_waitcnt lgkmcnt(8)
	s_barrier
	s_waitcnt lgkmcnt(0)
	s_setprio 1
	s_waitcnt lgkmcnt(0)
	v_mfma_f32_16x16x32_bf16 v[126:129], v[146:149], v[162:165], v[126:129]
	v_mfma_f32_16x16x32_bf16 v[118:121], v[154:157], v[162:165], v[118:121]
	v_mfma_f32_16x16x32_bf16 v[110:113], v[146:149], v[170:173], v[110:113]
	v_mfma_f32_16x16x32_bf16 v[102:105], v[154:157], v[170:173], v[102:105]
	v_mfma_f32_16x16x32_bf16 v[94:97], v[146:149], v[178:181], v[94:97]
	v_mfma_f32_16x16x32_bf16 v[86:89], v[154:157], v[178:181], v[86:89]
	v_mfma_f32_16x16x32_bf16 v[78:81], v[146:149], v[186:189], v[78:81]
	v_mfma_f32_16x16x32_bf16 v[70:73], v[154:157], v[186:189], v[70:73]
	v_mfma_f32_16x16x32_bf16 v[126:129], v[150:153], v[166:169], v[126:129]
	v_mfma_f32_16x16x32_bf16 v[118:121], v[158:161], v[166:169], v[118:121]
	v_mfma_f32_16x16x32_bf16 v[110:113], v[150:153], v[174:177], v[110:113]
	v_mfma_f32_16x16x32_bf16 v[102:105], v[158:161], v[174:177], v[102:105]
	v_mfma_f32_16x16x32_bf16 v[94:97], v[150:153], v[182:185], v[94:97]
	v_mfma_f32_16x16x32_bf16 v[86:89], v[158:161], v[182:185], v[86:89]
	v_mfma_f32_16x16x32_bf16 v[78:81], v[150:153], v[190:193], v[78:81]
	v_mfma_f32_16x16x32_bf16 v[70:73], v[158:161], v[190:193], v[70:73]
	s_setprio 0
	s_barrier
	s_add_i32 s35, 0, 0x1c000
	s_add_i32 s2, s34, s38
	v_add_u32_e32 v145, s35, v143
	v_lshl_add_u64 v[214:215], v[214:215], 0, s[74:75]
	s_mov_b32 m0, s2
	ds_read_b128 v[196:199], v145
	ds_read_b128 v[200:203], v145 offset:1024
	ds_read_b128 v[206:209], v145 offset:2048
	ds_read_b128 v[210:213], v145 offset:3072
	global_load_lds_dwordx4 v[214:215], off
	v_lshl_add_u64 v[214:215], v[216:217], 0, s[74:75]
	s_add_i32 m0, s2, 0x2000
	s_nop 0
	global_load_lds_dwordx4 v[214:215], off
	s_waitcnt vmcnt(10)
	s_barrier
	s_waitcnt lgkmcnt(0)
	s_setprio 1
	s_waitcnt lgkmcnt(0)
	v_mfma_f32_16x16x32_bf16 v[122:125], v[196:199], v[162:165], v[122:125]
	v_mfma_f32_16x16x32_bf16 v[114:117], v[206:209], v[162:165], v[114:117]
	v_mfma_f32_16x16x32_bf16 v[106:109], v[196:199], v[170:173], v[106:109]
	v_mfma_f32_16x16x32_bf16 v[98:101], v[206:209], v[170:173], v[98:101]
	v_mfma_f32_16x16x32_bf16 v[90:93], v[196:199], v[178:181], v[90:93]
	v_mfma_f32_16x16x32_bf16 v[82:85], v[206:209], v[178:181], v[82:85]
	v_mfma_f32_16x16x32_bf16 v[74:77], v[196:199], v[186:189], v[74:77]
	v_mfma_f32_16x16x32_bf16 v[66:69], v[206:209], v[186:189], v[66:69]
	v_mfma_f32_16x16x32_bf16 v[122:125], v[200:203], v[166:169], v[122:125]
	v_mfma_f32_16x16x32_bf16 v[114:117], v[210:213], v[166:169], v[114:117]
	v_mfma_f32_16x16x32_bf16 v[106:109], v[200:203], v[174:177], v[106:109]
	v_mfma_f32_16x16x32_bf16 v[98:101], v[210:213], v[174:177], v[98:101]
	v_mfma_f32_16x16x32_bf16 v[90:93], v[200:203], v[182:185], v[90:93]
	v_mfma_f32_16x16x32_bf16 v[82:85], v[210:213], v[182:185], v[82:85]
	v_mfma_f32_16x16x32_bf16 v[74:77], v[200:203], v[190:193], v[74:77]
	v_mfma_f32_16x16x32_bf16 v[66:69], v[210:213], v[190:193], v[66:69]
	s_setprio 0
	s_mov_b32 m0, s53
	v_lshl_add_u64 v[214:215], v[218:219], 0, s[74:75]
	s_barrier
	ds_read_b128 v[162:165], v144 offset:49152
	ds_read_b128 v[166:169], v144 offset:50176
	ds_read_b128 v[170:173], v144 offset:51200
	ds_read_b128 v[174:177], v144 offset:52224
	ds_read_b128 v[178:181], v144 offset:53248
	ds_read_b128 v[182:185], v144 offset:54272
	ds_read_b128 v[186:189], v144 offset:55296
	ds_read_b128 v[190:193], v144 offset:56320
	global_load_lds_dwordx4 v[214:215], off
	v_lshl_add_u64 v[214:215], v[220:221], 0, s[74:75]
	s_mov_b32 m0, s59
	s_nop 0
	global_load_lds_dwordx4 v[214:215], off
	s_barrier
	s_waitcnt lgkmcnt(0)
	s_setprio 1
	s_waitcnt lgkmcnt(0)
	v_mfma_f32_16x16x32_bf16 v[62:65], v[146:149], v[162:165], v[62:65]
	v_mfma_f32_16x16x32_bf16 v[54:57], v[154:157], v[162:165], v[54:57]
	v_mfma_f32_16x16x32_bf16 v[46:49], v[146:149], v[170:173], v[46:49]
	v_mfma_f32_16x16x32_bf16 v[38:41], v[154:157], v[170:173], v[38:41]
	v_mfma_f32_16x16x32_bf16 v[30:33], v[146:149], v[178:181], v[30:33]
	v_mfma_f32_16x16x32_bf16 v[22:25], v[154:157], v[178:181], v[22:25]
	v_mfma_f32_16x16x32_bf16 v[14:17], v[146:149], v[186:189], v[14:17]
	v_mfma_f32_16x16x32_bf16 v[6:9], v[154:157], v[186:189], v[6:9]
	v_mfma_f32_16x16x32_bf16 v[62:65], v[150:153], v[166:169], v[62:65]
	v_mfma_f32_16x16x32_bf16 v[54:57], v[158:161], v[166:169], v[54:57]
	v_mfma_f32_16x16x32_bf16 v[46:49], v[150:153], v[174:177], v[46:49]
	v_mfma_f32_16x16x32_bf16 v[38:41], v[158:161], v[174:177], v[38:41]
	v_mfma_f32_16x16x32_bf16 v[30:33], v[150:153], v[182:185], v[30:33]
	v_mfma_f32_16x16x32_bf16 v[22:25], v[158:161], v[182:185], v[22:25]
	v_mfma_f32_16x16x32_bf16 v[14:17], v[150:153], v[190:193], v[14:17]
	v_mfma_f32_16x16x32_bf16 v[6:9], v[158:161], v[190:193], v[6:9]
	s_setprio 0
	s_barrier
	s_add_u32 s2, s16, 0x40080
	s_addc_u32 s3, s17, 0
	s_add_i32 s16, s35, s38
	v_lshl_add_u64 v[146:147], s[2:3], 0, v[134:135]
	s_mov_b32 m0, s16
	s_nop 0
	global_load_lds_dwordx4 v[146:147], off
	v_lshl_add_u64 v[146:147], s[2:3], 0, v[130:131]
	s_add_i32 m0, s16, 0x2000
	s_nop 0
	global_load_lds_dwordx4 v[146:147], off
	s_waitcnt vmcnt(10)
	s_barrier
	s_setprio 1
	v_mfma_f32_16x16x32_bf16 v[58:61], v[196:199], v[162:165], v[58:61]
	v_mfma_f32_16x16x32_bf16 v[50:53], v[206:209], v[162:165], v[50:53]
	v_mfma_f32_16x16x32_bf16 v[42:45], v[196:199], v[170:173], v[42:45]
	v_mfma_f32_16x16x32_bf16 v[34:37], v[206:209], v[170:173], v[34:37]
	v_mfma_f32_16x16x32_bf16 v[26:29], v[196:199], v[178:181], v[26:29]
	v_mfma_f32_16x16x32_bf16 v[18:21], v[206:209], v[178:181], v[18:21]
	v_mfma_f32_16x16x32_bf16 v[10:13], v[196:199], v[186:189], v[10:13]
	v_mfma_f32_16x16x32_bf16 v[2:5], v[206:209], v[186:189], v[2:5]
	v_mfma_f32_16x16x32_bf16 v[58:61], v[200:203], v[166:169], v[58:61]
	v_mfma_f32_16x16x32_bf16 v[50:53], v[210:213], v[166:169], v[50:53]
	v_mfma_f32_16x16x32_bf16 v[42:45], v[200:203], v[174:177], v[42:45]
	v_mfma_f32_16x16x32_bf16 v[34:37], v[210:213], v[174:177], v[34:37]
	v_mfma_f32_16x16x32_bf16 v[26:29], v[200:203], v[182:185], v[26:29]
	v_mfma_f32_16x16x32_bf16 v[18:21], v[210:213], v[182:185], v[18:21]
	v_mfma_f32_16x16x32_bf16 v[10:13], v[200:203], v[190:193], v[10:13]
	v_mfma_f32_16x16x32_bf16 v[2:5], v[210:213], v[190:193], v[2:5]
	s_setprio 0
	s_add_i32 s56, s56, 2
	s_add_u32 s14, s14, 0x100
	s_addc_u32 s15, s15, 0
	s_add_u32 s55, s55, 0x100
	s_addc_u32 s50, s50, 0
	s_cmp_gt_u32 s56, 13
	s_barrier
	s_cbranch_scc0 .LBB0_113
	v_mul_f32_e32 v146, 0xbfb8aa3b, v126
	v_mul_f32_e32 v147, 0xbfb8aa3b, v127
	v_exp_f32_e32 v146, v146
	v_exp_f32_e32 v147, v147
	v_readlane_b32 s2, v249, 15
	v_readlane_b32 s3, v249, 16
	v_add_f32_e32 v146, 1.0, v146
	v_add_f32_e32 v147, 1.0, v147
	v_rcp_f32_e32 v146, v146
	v_rcp_f32_e32 v147, v147
	v_lshl_add_u32 v145, s18, 8, v142
	s_movk_i32 s7, 0x1600
	s_and_b64 vcc, exec, s[36:37]
	v_pk_mul_f32 v[126:127], v[126:127], v[146:147]
	s_mov_b32 s18, s8
	v_pk_mul_f32 v[122:123], v[126:127], v[122:123]
	s_nop 0
	v_cvt_pk_bf16_f32 v122, v122, v123
	v_mul_f32_e32 v123, 0xbfb8aa3b, v128
	v_exp_f32_e32 v123, v123
	s_nop 0
	v_add_f32_e32 v123, 1.0, v123
	v_rcp_f32_e32 v126, v123
	v_mul_f32_e32 v123, 0xbfb8aa3b, v129
	v_exp_f32_e32 v123, v123
	s_nop 0
	v_add_f32_e32 v123, 1.0, v123
	v_rcp_f32_e32 v127, v123
	s_nop 0
	v_pk_mul_f32 v[126:127], v[128:129], v[126:127]
	s_nop 0
	v_pk_mul_f32 v[124:125], v[126:127], v[124:125]
	s_nop 0
	v_cvt_pk_bf16_f32 v123, v124, v125
	v_mul_f32_e32 v124, 0xbfb8aa3b, v118
	v_mul_f32_e32 v125, 0xbfb8aa3b, v119
	v_exp_f32_e32 v124, v124
	v_exp_f32_e32 v125, v125
	v_add_f32_e32 v124, 1.0, v124
	v_add_f32_e32 v125, 1.0, v125
	v_rcp_f32_e32 v124, v124
	v_rcp_f32_e32 v125, v125
	s_nop 0
	v_pk_mul_f32 v[118:119], v[118:119], v[124:125]
	s_nop 0
	v_pk_mul_f32 v[114:115], v[118:119], v[114:115]
	v_or_b32_e32 v118, 16, v145
	v_cvt_pk_bf16_f32 v124, v114, v115
	v_mul_f32_e32 v114, 0xbfb8aa3b, v120
	v_mul_f32_e32 v115, 0xbfb8aa3b, v121
	v_exp_f32_e32 v114, v114
	v_exp_f32_e32 v115, v115
	v_add_f32_e32 v114, 1.0, v114
	v_add_f32_e32 v115, 1.0, v115
	v_rcp_f32_e32 v114, v114
	v_rcp_f32_e32 v115, v115
	s_nop 0
	v_pk_mul_f32 v[114:115], v[120:121], v[114:115]
	s_nop 0
	v_pk_mul_f32 v[114:115], v[114:115], v[116:117]
	s_nop 0
	v_cvt_pk_bf16_f32 v125, v114, v115
	v_mov_b64_e32 v[114:115], s[2:3]
	v_mad_i64_i32 v[116:117], s[2:3], v145, s7, v[114:115]
	s_lshl_b32 s2, s1, 7
	s_ashr_i32 s3, s2, 31
	s_lshl_b64 s[14:15], s[2:3], 1
	v_lshl_add_u64 v[116:117], v[116:117], 0, s[14:15]
	s_mov_b32 s1, s4
	v_lshl_add_u64 v[116:117], v[116:117], 0, s[0:1]
	v_lshl_add_u64 v[116:117], v[116:117], 0, v[0:1]
	global_store_dwordx4 v[116:117], v[122:125], off
	v_mul_f32_e32 v116, 0xbfb8aa3b, v110
	v_mul_f32_e32 v117, 0xbfb8aa3b, v111
	v_exp_f32_e32 v116, v116
	v_exp_f32_e32 v117, v117
	v_add_f32_e32 v116, 1.0, v116
	v_add_f32_e32 v117, 1.0, v117
	v_rcp_f32_e32 v116, v116
	v_rcp_f32_e32 v117, v117
	s_nop 0
	v_pk_mul_f32 v[110:111], v[110:111], v[116:117]
	s_nop 0
	v_pk_mul_f32 v[106:107], v[110:111], v[106:107]
	s_nop 0
	v_cvt_pk_bf16_f32 v106, v106, v107
	v_mul_f32_e32 v107, 0xbfb8aa3b, v112
	v_exp_f32_e32 v107, v107
	s_nop 0
	v_add_f32_e32 v107, 1.0, v107
	v_rcp_f32_e32 v110, v107
	v_mul_f32_e32 v107, 0xbfb8aa3b, v113
	v_exp_f32_e32 v107, v107
	s_nop 0
	v_add_f32_e32 v107, 1.0, v107
	v_rcp_f32_e32 v111, v107
	s_nop 0
	v_pk_mul_f32 v[110:111], v[112:113], v[110:111]
	s_nop 0
	v_pk_mul_f32 v[108:109], v[110:111], v[108:109]
	s_nop 0
	v_cvt_pk_bf16_f32 v107, v108, v109
	v_mul_f32_e32 v108, 0xbfb8aa3b, v102
	v_mul_f32_e32 v109, 0xbfb8aa3b, v103
	v_exp_f32_e32 v108, v108
	v_exp_f32_e32 v109, v109
	v_add_f32_e32 v108, 1.0, v108
	v_add_f32_e32 v109, 1.0, v109
	v_rcp_f32_e32 v108, v108
	v_rcp_f32_e32 v109, v109
	s_nop 0
	v_pk_mul_f32 v[102:103], v[102:103], v[108:109]
	s_nop 0
	v_pk_mul_f32 v[98:99], v[102:103], v[98:99]
	s_nop 0
	v_cvt_pk_bf16_f32 v108, v98, v99
	v_mul_f32_e32 v98, 0xbfb8aa3b, v104
	v_mul_f32_e32 v99, 0xbfb8aa3b, v105
	v_exp_f32_e32 v98, v98
	v_exp_f32_e32 v99, v99
	v_add_f32_e32 v98, 1.0, v98
	v_add_f32_e32 v99, 1.0, v99
	v_rcp_f32_e32 v98, v98
	v_rcp_f32_e32 v99, v99
	s_nop 0
	v_pk_mul_f32 v[98:99], v[104:105], v[98:99]
	s_nop 0
	v_pk_mul_f32 v[98:99], v[98:99], v[100:101]
	v_or_b32_e32 v100, 32, v145
	v_cvt_pk_bf16_f32 v109, v98, v99
	v_mad_i64_i32 v[98:99], s[2:3], v118, s7, v[114:115]
	v_lshl_add_u64 v[98:99], v[98:99], 0, s[14:15]
	v_lshl_add_u64 v[98:99], v[98:99], 0, s[0:1]
	v_lshl_add_u64 v[98:99], v[98:99], 0, v[0:1]
	global_store_dwordx4 v[98:99], v[106:109], off
	v_mul_f32_e32 v98, 0xbfb8aa3b, v94
	v_mul_f32_e32 v99, 0xbfb8aa3b, v95
	v_exp_f32_e32 v98, v98
	v_exp_f32_e32 v99, v99
	v_add_f32_e32 v98, 1.0, v98
	v_add_f32_e32 v99, 1.0, v99
	v_rcp_f32_e32 v98, v98
	v_rcp_f32_e32 v99, v99
	s_nop 0
	v_pk_mul_f32 v[94:95], v[94:95], v[98:99]
	s_nop 0
	v_pk_mul_f32 v[90:91], v[94:95], v[90:91]
	s_nop 0
	v_cvt_pk_bf16_f32 v90, v90, v91
	v_mul_f32_e32 v91, 0xbfb8aa3b, v96
	v_exp_f32_e32 v91, v91
	s_nop 0
	v_add_f32_e32 v91, 1.0, v91
	v_rcp_f32_e32 v94, v91
	v_mul_f32_e32 v91, 0xbfb8aa3b, v97
	v_exp_f32_e32 v91, v91
	s_nop 0
	v_add_f32_e32 v91, 1.0, v91
	v_rcp_f32_e32 v95, v91
	s_nop 0
	v_pk_mul_f32 v[94:95], v[96:97], v[94:95]
	s_nop 0
	v_pk_mul_f32 v[92:93], v[94:95], v[92:93]
	s_nop 0
	v_cvt_pk_bf16_f32 v91, v92, v93
	v_mul_f32_e32 v92, 0xbfb8aa3b, v86
	v_mul_f32_e32 v93, 0xbfb8aa3b, v87
	v_exp_f32_e32 v92, v92
	v_exp_f32_e32 v93, v93
	v_add_f32_e32 v92, 1.0, v92
	v_add_f32_e32 v93, 1.0, v93
	v_rcp_f32_e32 v92, v92
	v_rcp_f32_e32 v93, v93
	s_nop 0
	v_pk_mul_f32 v[86:87], v[86:87], v[92:93]
	s_nop 0
	v_pk_mul_f32 v[82:83], v[86:87], v[82:83]
	s_nop 0
	v_cvt_pk_bf16_f32 v92, v82, v83
	v_mul_f32_e32 v82, 0xbfb8aa3b, v88
	v_mul_f32_e32 v83, 0xbfb8aa3b, v89
	v_exp_f32_e32 v82, v82
	v_exp_f32_e32 v83, v83
	v_add_f32_e32 v82, 1.0, v82
	v_add_f32_e32 v83, 1.0, v83
	v_rcp_f32_e32 v82, v82
	v_rcp_f32_e32 v83, v83
	s_nop 0
	v_pk_mul_f32 v[82:83], v[88:89], v[82:83]
	s_nop 0
	v_pk_mul_f32 v[82:83], v[82:83], v[84:85]
	v_or_b32_e32 v84, 48, v145
	v_cvt_pk_bf16_f32 v93, v82, v83
	v_mad_i64_i32 v[82:83], s[2:3], v100, s7, v[114:115]
	v_lshl_add_u64 v[82:83], v[82:83], 0, s[14:15]
	v_lshl_add_u64 v[82:83], v[82:83], 0, s[0:1]
	v_lshl_add_u64 v[82:83], v[82:83], 0, v[0:1]
	global_store_dwordx4 v[82:83], v[90:93], off
	v_mul_f32_e32 v82, 0xbfb8aa3b, v78
	v_mul_f32_e32 v83, 0xbfb8aa3b, v79
	v_exp_f32_e32 v82, v82
	v_exp_f32_e32 v83, v83
	v_add_f32_e32 v82, 1.0, v82
	v_add_f32_e32 v83, 1.0, v83
	v_rcp_f32_e32 v82, v82
	v_rcp_f32_e32 v83, v83
	s_nop 0
	v_pk_mul_f32 v[78:79], v[78:79], v[82:83]
	s_nop 0
	v_pk_mul_f32 v[74:75], v[78:79], v[74:75]
	s_nop 0
	v_cvt_pk_bf16_f32 v74, v74, v75
	v_mul_f32_e32 v75, 0xbfb8aa3b, v80
	v_exp_f32_e32 v75, v75
	s_nop 0
	v_add_f32_e32 v75, 1.0, v75
	v_rcp_f32_e32 v78, v75
	v_mul_f32_e32 v75, 0xbfb8aa3b, v81
	v_exp_f32_e32 v75, v75
	s_nop 0
	v_add_f32_e32 v75, 1.0, v75
	v_rcp_f32_e32 v79, v75
	s_nop 0
	v_pk_mul_f32 v[78:79], v[80:81], v[78:79]
	s_nop 0
	v_pk_mul_f32 v[76:77], v[78:79], v[76:77]
	s_nop 0
	v_cvt_pk_bf16_f32 v75, v76, v77
	v_mul_f32_e32 v76, 0xbfb8aa3b, v70
	v_mul_f32_e32 v77, 0xbfb8aa3b, v71
	v_exp_f32_e32 v76, v76
	v_exp_f32_e32 v77, v77
	v_add_f32_e32 v76, 1.0, v76
	v_add_f32_e32 v77, 1.0, v77
	v_rcp_f32_e32 v76, v76
	v_rcp_f32_e32 v77, v77
	s_nop 0
	v_pk_mul_f32 v[70:71], v[70:71], v[76:77]
	s_nop 0
	v_pk_mul_f32 v[66:67], v[70:71], v[66:67]
	s_nop 0
	v_cvt_pk_bf16_f32 v76, v66, v67
	v_mul_f32_e32 v66, 0xbfb8aa3b, v72
	v_mul_f32_e32 v67, 0xbfb8aa3b, v73
	v_exp_f32_e32 v66, v66
	v_exp_f32_e32 v67, v67
	v_add_f32_e32 v66, 1.0, v66
	v_add_f32_e32 v67, 1.0, v67
	v_rcp_f32_e32 v66, v66
	v_rcp_f32_e32 v67, v67
	s_nop 0
	v_pk_mul_f32 v[66:67], v[72:73], v[66:67]
	s_nop 0
	v_pk_mul_f32 v[66:67], v[66:67], v[68:69]
	v_add_u32_e32 v68, 0x80, v145
	v_cvt_pk_bf16_f32 v77, v66, v67
	v_mad_i64_i32 v[66:67], s[2:3], v84, s7, v[114:115]
	v_lshl_add_u64 v[66:67], v[66:67], 0, s[14:15]
	v_lshl_add_u64 v[66:67], v[66:67], 0, s[0:1]
	v_lshl_add_u64 v[66:67], v[66:67], 0, v[0:1]
	global_store_dwordx4 v[66:67], v[74:77], off
	v_mul_f32_e32 v66, 0xbfb8aa3b, v62
	v_mul_f32_e32 v67, 0xbfb8aa3b, v63
	v_exp_f32_e32 v66, v66
	v_exp_f32_e32 v67, v67
	v_add_f32_e32 v66, 1.0, v66
	v_add_f32_e32 v67, 1.0, v67
	v_rcp_f32_e32 v66, v66
	v_rcp_f32_e32 v67, v67
	s_nop 0
	v_pk_mul_f32 v[62:63], v[62:63], v[66:67]
	s_nop 0
	v_pk_mul_f32 v[58:59], v[62:63], v[58:59]
	s_nop 0
	v_cvt_pk_bf16_f32 v58, v58, v59
	v_mul_f32_e32 v59, 0xbfb8aa3b, v64
	v_exp_f32_e32 v59, v59
	s_nop 0
	v_add_f32_e32 v59, 1.0, v59
	v_rcp_f32_e32 v62, v59
	v_mul_f32_e32 v59, 0xbfb8aa3b, v65
	v_exp_f32_e32 v59, v59
	s_nop 0
	v_add_f32_e32 v59, 1.0, v59
	v_rcp_f32_e32 v63, v59
	s_nop 0
	v_pk_mul_f32 v[62:63], v[64:65], v[62:63]
	s_nop 0
	v_pk_mul_f32 v[60:61], v[62:63], v[60:61]
	s_nop 0
	v_cvt_pk_bf16_f32 v59, v60, v61
	v_mul_f32_e32 v60, 0xbfb8aa3b, v54
	v_mul_f32_e32 v61, 0xbfb8aa3b, v55
	v_exp_f32_e32 v60, v60
	v_exp_f32_e32 v61, v61
	v_add_f32_e32 v60, 1.0, v60
	v_add_f32_e32 v61, 1.0, v61
	v_rcp_f32_e32 v60, v60
	v_rcp_f32_e32 v61, v61
	s_nop 0
	v_pk_mul_f32 v[54:55], v[54:55], v[60:61]
	s_nop 0
	v_pk_mul_f32 v[50:51], v[54:55], v[50:51]
	s_nop 0
	v_cvt_pk_bf16_f32 v60, v50, v51
	v_mul_f32_e32 v50, 0xbfb8aa3b, v56
	v_mul_f32_e32 v51, 0xbfb8aa3b, v57
	v_exp_f32_e32 v50, v50
	v_exp_f32_e32 v51, v51
	v_add_f32_e32 v50, 1.0, v50
	v_add_f32_e32 v51, 1.0, v51
	v_rcp_f32_e32 v50, v50
	v_rcp_f32_e32 v51, v51
	s_nop 0
	v_pk_mul_f32 v[50:51], v[56:57], v[50:51]
	s_nop 0
	v_pk_mul_f32 v[50:51], v[50:51], v[52:53]
	v_add_u32_e32 v52, 0x90, v145
	v_cvt_pk_bf16_f32 v61, v50, v51
	v_mad_i64_i32 v[50:51], s[2:3], v68, s7, v[114:115]
	v_lshl_add_u64 v[50:51], v[50:51], 0, s[14:15]
	v_lshl_add_u64 v[50:51], v[50:51], 0, s[0:1]
	v_lshl_add_u64 v[50:51], v[50:51], 0, v[0:1]
	global_store_dwordx4 v[50:51], v[58:61], off
	v_mul_f32_e32 v50, 0xbfb8aa3b, v46
	v_mul_f32_e32 v51, 0xbfb8aa3b, v47
	v_exp_f32_e32 v50, v50
	v_exp_f32_e32 v51, v51
	v_add_f32_e32 v50, 1.0, v50
	v_add_f32_e32 v51, 1.0, v51
	v_rcp_f32_e32 v50, v50
	v_rcp_f32_e32 v51, v51
	s_nop 0
	v_pk_mul_f32 v[46:47], v[46:47], v[50:51]
	s_nop 0
	v_pk_mul_f32 v[42:43], v[46:47], v[42:43]
	s_nop 0
	v_cvt_pk_bf16_f32 v42, v42, v43
	v_mul_f32_e32 v43, 0xbfb8aa3b, v48
	v_exp_f32_e32 v43, v43
	s_nop 0
	v_add_f32_e32 v43, 1.0, v43
	v_rcp_f32_e32 v46, v43
	v_mul_f32_e32 v43, 0xbfb8aa3b, v49
	v_exp_f32_e32 v43, v43
	s_nop 0
	v_add_f32_e32 v43, 1.0, v43
	v_rcp_f32_e32 v47, v43
	s_nop 0
	v_pk_mul_f32 v[46:47], v[48:49], v[46:47]
	s_nop 0
	v_pk_mul_f32 v[44:45], v[46:47], v[44:45]
	s_nop 0
	v_cvt_pk_bf16_f32 v43, v44, v45
	v_mul_f32_e32 v44, 0xbfb8aa3b, v38
	v_mul_f32_e32 v45, 0xbfb8aa3b, v39
	v_exp_f32_e32 v44, v44
	v_exp_f32_e32 v45, v45
	v_add_f32_e32 v44, 1.0, v44
	v_add_f32_e32 v45, 1.0, v45
	v_rcp_f32_e32 v44, v44
	v_rcp_f32_e32 v45, v45
	s_nop 0
	v_pk_mul_f32 v[38:39], v[38:39], v[44:45]
	s_nop 0
	v_pk_mul_f32 v[34:35], v[38:39], v[34:35]
	s_nop 0
	v_cvt_pk_bf16_f32 v44, v34, v35
	v_mul_f32_e32 v34, 0xbfb8aa3b, v40
	v_mul_f32_e32 v35, 0xbfb8aa3b, v41
	v_exp_f32_e32 v34, v34
	v_exp_f32_e32 v35, v35
	v_add_f32_e32 v34, 1.0, v34
	v_add_f32_e32 v35, 1.0, v35
	v_rcp_f32_e32 v34, v34
	v_rcp_f32_e32 v35, v35
	s_nop 0
	v_pk_mul_f32 v[34:35], v[40:41], v[34:35]
	s_nop 0
	v_pk_mul_f32 v[34:35], v[34:35], v[36:37]
	v_add_u32_e32 v36, 0xa0, v145
	v_cvt_pk_bf16_f32 v45, v34, v35
	v_mad_i64_i32 v[34:35], s[2:3], v52, s7, v[114:115]
	v_lshl_add_u64 v[34:35], v[34:35], 0, s[14:15]
	v_lshl_add_u64 v[34:35], v[34:35], 0, s[0:1]
	v_lshl_add_u64 v[34:35], v[34:35], 0, v[0:1]
	global_store_dwordx4 v[34:35], v[42:45], off
	v_mul_f32_e32 v34, 0xbfb8aa3b, v30
	v_mul_f32_e32 v35, 0xbfb8aa3b, v31
	v_exp_f32_e32 v34, v34
	v_exp_f32_e32 v35, v35
	v_add_f32_e32 v34, 1.0, v34
	v_add_f32_e32 v35, 1.0, v35
	v_rcp_f32_e32 v34, v34
	v_rcp_f32_e32 v35, v35
	s_nop 0
	v_pk_mul_f32 v[30:31], v[30:31], v[34:35]
	s_nop 0
	v_pk_mul_f32 v[26:27], v[30:31], v[26:27]
	s_nop 0
	v_cvt_pk_bf16_f32 v26, v26, v27
	v_mul_f32_e32 v27, 0xbfb8aa3b, v32
	v_exp_f32_e32 v27, v27
	s_nop 0
	v_add_f32_e32 v27, 1.0, v27
	v_rcp_f32_e32 v30, v27
	v_mul_f32_e32 v27, 0xbfb8aa3b, v33
	v_exp_f32_e32 v27, v27
	s_nop 0
	v_add_f32_e32 v27, 1.0, v27
	v_rcp_f32_e32 v31, v27
	s_nop 0
	v_pk_mul_f32 v[30:31], v[32:33], v[30:31]
	s_nop 0
	v_pk_mul_f32 v[28:29], v[30:31], v[28:29]
	s_nop 0
	v_cvt_pk_bf16_f32 v27, v28, v29
	v_mul_f32_e32 v28, 0xbfb8aa3b, v22
	v_mul_f32_e32 v29, 0xbfb8aa3b, v23
	v_exp_f32_e32 v28, v28
	v_exp_f32_e32 v29, v29
	v_add_f32_e32 v28, 1.0, v28
	v_add_f32_e32 v29, 1.0, v29
	v_rcp_f32_e32 v28, v28
	v_rcp_f32_e32 v29, v29
	s_nop 0
	v_pk_mul_f32 v[22:23], v[22:23], v[28:29]
	s_nop 0
	v_pk_mul_f32 v[18:19], v[22:23], v[18:19]
	s_nop 0
	v_cvt_pk_bf16_f32 v28, v18, v19
	v_mul_f32_e32 v18, 0xbfb8aa3b, v24
	v_mul_f32_e32 v19, 0xbfb8aa3b, v25
	v_exp_f32_e32 v18, v18
	v_exp_f32_e32 v19, v19
	v_add_f32_e32 v18, 1.0, v18
	v_add_f32_e32 v19, 1.0, v19
	v_rcp_f32_e32 v18, v18
	v_rcp_f32_e32 v19, v19
	s_nop 0
	v_pk_mul_f32 v[18:19], v[24:25], v[18:19]
	s_nop 0
	v_pk_mul_f32 v[18:19], v[18:19], v[20:21]
	v_add_u32_e32 v20, 0xb0, v145
	v_cvt_pk_bf16_f32 v29, v18, v19
	v_mad_i64_i32 v[18:19], s[2:3], v36, s7, v[114:115]
	v_lshl_add_u64 v[18:19], v[18:19], 0, s[14:15]
	v_lshl_add_u64 v[18:19], v[18:19], 0, s[0:1]
	v_lshl_add_u64 v[18:19], v[18:19], 0, v[0:1]
	global_store_dwordx4 v[18:19], v[26:29], off
	v_mul_f32_e32 v18, 0xbfb8aa3b, v14
	v_mul_f32_e32 v19, 0xbfb8aa3b, v15
	v_exp_f32_e32 v18, v18
	v_exp_f32_e32 v19, v19
	v_add_f32_e32 v18, 1.0, v18
	v_add_f32_e32 v19, 1.0, v19
	v_rcp_f32_e32 v18, v18
	v_rcp_f32_e32 v19, v19
	s_nop 0
	v_pk_mul_f32 v[14:15], v[14:15], v[18:19]
	s_nop 0
	v_pk_mul_f32 v[10:11], v[14:15], v[10:11]
	s_nop 0
	v_cvt_pk_bf16_f32 v10, v10, v11
	v_mul_f32_e32 v11, 0xbfb8aa3b, v16
	v_exp_f32_e32 v11, v11
	s_nop 0
	v_add_f32_e32 v11, 1.0, v11
	v_rcp_f32_e32 v14, v11
	v_mul_f32_e32 v11, 0xbfb8aa3b, v17
	v_exp_f32_e32 v11, v11
	s_nop 0
	v_add_f32_e32 v11, 1.0, v11
	v_rcp_f32_e32 v15, v11
	s_nop 0
	v_pk_mul_f32 v[14:15], v[16:17], v[14:15]
	s_nop 0
	v_pk_mul_f32 v[12:13], v[14:15], v[12:13]
	s_nop 0
	v_cvt_pk_bf16_f32 v11, v12, v13
	v_mul_f32_e32 v12, 0xbfb8aa3b, v6
	v_mul_f32_e32 v13, 0xbfb8aa3b, v7
	v_exp_f32_e32 v12, v12
	v_exp_f32_e32 v13, v13
	v_add_f32_e32 v12, 1.0, v12
	v_add_f32_e32 v13, 1.0, v13
	v_rcp_f32_e32 v12, v12
	v_rcp_f32_e32 v13, v13
	s_nop 0
	v_pk_mul_f32 v[6:7], v[6:7], v[12:13]
	s_nop 0
	v_pk_mul_f32 v[2:3], v[6:7], v[2:3]
	s_nop 0
	v_cvt_pk_bf16_f32 v12, v2, v3
	v_mul_f32_e32 v2, 0xbfb8aa3b, v8
	v_mul_f32_e32 v3, 0xbfb8aa3b, v9
	v_exp_f32_e32 v2, v2
	v_exp_f32_e32 v3, v3
	v_add_f32_e32 v2, 1.0, v2
	v_add_f32_e32 v3, 1.0, v3
	v_rcp_f32_e32 v2, v2
	v_rcp_f32_e32 v3, v3
	s_nop 0
	v_pk_mul_f32 v[2:3], v[8:9], v[2:3]
	s_nop 0
	v_pk_mul_f32 v[2:3], v[2:3], v[4:5]
	s_nop 0
	v_cvt_pk_bf16_f32 v13, v2, v3
	v_mad_i64_i32 v[2:3], s[2:3], v20, s7, v[114:115]
	v_lshl_add_u64 v[2:3], v[2:3], 0, s[14:15]
	v_lshl_add_u64 v[2:3], v[2:3], 0, s[0:1]
	v_lshl_add_u64 v[2:3], v[2:3], 0, v[0:1]
	s_mov_b32 s1, s6
	s_mov_b64 s[2:3], s[12:13]
	s_mov_b64 s[14:15], s[10:11]
	global_store_dwordx4 v[2:3], v[10:13], off
	s_cbranch_vccz .LBB0_110
	s_waitcnt vmcnt(0)
	s_cmpk_gt_u32 s5, 0xff
	v_readlane_b32 s50, v255, 53
	v_readlane_b32 s51, v255, 54
	s_cbranch_scc1 .LBB0_117
	s_barrier

.LBB0_136:
	s_add_u32 s2, s18, 0xfffc0080
	s_addc_u32 s3, s19, -1
	s_add_i32 s34, 0, 0x10000
	v_add_u32_e32 v0, s34, v165
	ds_read_b128 v[90:93], v0
	ds_read_b128 v[94:97], v0 offset:1024
	ds_read_b128 v[98:101], v0 offset:2048
	ds_read_b128 v[102:105], v0 offset:3072
	s_cmp_eq_u32 s58, 12
	s_cselect_b32 s3, s13, s3
	s_cselect_b32 s2, s55, s2
	s_cselect_b32 s39, s11, s50
	s_cselect_b32 s38, s56, s57
	v_lshl_add_u64 v[162:163], s[18:19], 0, v[150:151]
	s_add_i32 m0, s45, 0xc000
	ds_read_b128 v[154:157], v167
	ds_read_b128 v[158:161], v167 offset:1024
	ds_read_b128 v[168:171], v167 offset:2048
	ds_read_b128 v[172:175], v167 offset:3072
	ds_read_b128 v[176:179], v167 offset:4096
	ds_read_b128 v[180:183], v167 offset:5120
	ds_read_b128 v[184:187], v167 offset:6144
	ds_read_b128 v[188:191], v167 offset:7168
	global_load_lds_dwordx4 v[162:163], off
	v_lshl_add_u64 v[162:163], s[18:19], 0, v[152:153]
	s_add_i32 m0, s45, 0xe000
	s_nop 0
	global_load_lds_dwordx4 v[162:163], off
	s_waitcnt vmcnt(10)
	s_waitcnt lgkmcnt(8)
	s_barrier
	s_waitcnt lgkmcnt(0)
	s_setprio 1
	s_waitcnt lgkmcnt(0)
	v_mfma_f32_16x16x32_bf16 v[142:145], v[90:93], v[154:157], v[142:145]
	v_mfma_f32_16x16x32_bf16 v[138:141], v[98:101], v[154:157], v[138:141]
	v_mfma_f32_16x16x32_bf16 v[126:129], v[90:93], v[168:171], v[126:129]
	v_mfma_f32_16x16x32_bf16 v[122:125], v[98:101], v[168:171], v[122:125]
	v_mfma_f32_16x16x32_bf16 v[110:113], v[90:93], v[176:179], v[110:113]
	v_mfma_f32_16x16x32_bf16 v[106:109], v[98:101], v[176:179], v[106:109]
	v_mfma_f32_16x16x32_bf16 v[78:81], v[90:93], v[184:187], v[78:81]
	v_mfma_f32_16x16x32_bf16 v[74:77], v[98:101], v[184:187], v[74:77]
	v_mfma_f32_16x16x32_bf16 v[142:145], v[94:97], v[158:161], v[142:145]
	v_mfma_f32_16x16x32_bf16 v[138:141], v[102:105], v[158:161], v[138:141]
	v_mfma_f32_16x16x32_bf16 v[126:129], v[94:97], v[172:175], v[126:129]
	v_mfma_f32_16x16x32_bf16 v[122:125], v[102:105], v[172:175], v[122:125]
	v_mfma_f32_16x16x32_bf16 v[110:113], v[94:97], v[180:183], v[110:113]
	v_mfma_f32_16x16x32_bf16 v[106:109], v[102:105], v[180:183], v[106:109]
	v_mfma_f32_16x16x32_bf16 v[78:81], v[94:97], v[188:191], v[78:81]
	v_mfma_f32_16x16x32_bf16 v[74:77], v[102:105], v[188:191], v[74:77]
	s_setprio 0
	s_barrier
	s_add_i32 s40, 0, 0x14000
	s_add_i32 s34, s34, s44
	v_add_u32_e32 v0, s40, v165
	v_lshl_add_u64 v[162:163], s[38:39], 0, v[148:149]
	s_mov_b32 m0, s34
	ds_read_b128 v[196:199], v0
	ds_read_b128 v[200:203], v0 offset:1024
	ds_read_b128 v[206:209], v0 offset:2048
	ds_read_b128 v[210:213], v0 offset:3072
	global_load_lds_dwordx4 v[162:163], off
	v_lshl_add_u64 v[192:193], s[38:39], 0, v[146:147]
	s_add_i32 m0, s34, 0x2000
	s_nop 0
	global_load_lds_dwordx4 v[192:193], off
	s_waitcnt vmcnt(10)
	s_barrier
	s_waitcnt lgkmcnt(0)
	s_setprio 1
	s_waitcnt lgkmcnt(0)
	v_mfma_f32_16x16x32_bf16 v[134:137], v[196:199], v[154:157], v[134:137]
	v_mfma_f32_16x16x32_bf16 v[130:133], v[206:209], v[154:157], v[130:133]
	v_mfma_f32_16x16x32_bf16 v[118:121], v[196:199], v[168:171], v[118:121]
	v_mfma_f32_16x16x32_bf16 v[114:117], v[206:209], v[168:171], v[114:117]
	v_mfma_f32_16x16x32_bf16 v[86:89], v[196:199], v[176:179], v[86:89]
	v_mfma_f32_16x16x32_bf16 v[82:85], v[206:209], v[176:179], v[82:85]
	v_mfma_f32_16x16x32_bf16 v[70:73], v[196:199], v[184:187], v[70:73]
	v_mfma_f32_16x16x32_bf16 v[66:69], v[206:209], v[184:187], v[66:69]
	v_mfma_f32_16x16x32_bf16 v[134:137], v[200:203], v[158:161], v[134:137]
	v_mfma_f32_16x16x32_bf16 v[130:133], v[210:213], v[158:161], v[130:133]
	v_mfma_f32_16x16x32_bf16 v[118:121], v[200:203], v[172:175], v[118:121]
	v_mfma_f32_16x16x32_bf16 v[114:117], v[210:213], v[172:175], v[114:117]
	v_mfma_f32_16x16x32_bf16 v[86:89], v[200:203], v[180:183], v[86:89]
	v_mfma_f32_16x16x32_bf16 v[82:85], v[210:213], v[180:183], v[82:85]
	v_mfma_f32_16x16x32_bf16 v[70:73], v[200:203], v[188:191], v[70:73]
	v_mfma_f32_16x16x32_bf16 v[66:69], v[210:213], v[188:191], v[66:69]
	s_setprio 0
	s_mov_b32 m0, s45
	v_lshl_add_u64 v[214:215], s[2:3], 0, v[148:149]
	s_barrier
	ds_read_b128 v[154:157], v167 offset:16384
	ds_read_b128 v[158:161], v167 offset:17408
	ds_read_b128 v[168:171], v167 offset:18432
	ds_read_b128 v[172:175], v167 offset:19456
	ds_read_b128 v[176:179], v167 offset:20480
	ds_read_b128 v[180:183], v167 offset:21504
	ds_read_b128 v[184:187], v167 offset:22528
	ds_read_b128 v[188:191], v167 offset:23552
	global_load_lds_dwordx4 v[214:215], off
	v_lshl_add_u64 v[216:217], s[2:3], 0, v[146:147]
	s_mov_b32 m0, s51
	s_nop 0
	global_load_lds_dwordx4 v[216:217], off
	s_barrier
	s_waitcnt lgkmcnt(0)
	s_setprio 1
	s_waitcnt lgkmcnt(0)
	v_mfma_f32_16x16x32_bf16 v[62:65], v[90:93], v[154:157], v[62:65]
	v_mfma_f32_16x16x32_bf16 v[58:61], v[98:101], v[154:157], v[58:61]
	v_mfma_f32_16x16x32_bf16 v[54:57], v[90:93], v[168:171], v[54:57]
	v_mfma_f32_16x16x32_bf16 v[50:53], v[98:101], v[168:171], v[50:53]
	v_mfma_f32_16x16x32_bf16 v[30:33], v[90:93], v[176:179], v[30:33]
	v_mfma_f32_16x16x32_bf16 v[26:29], v[98:101], v[176:179], v[26:29]
	v_mfma_f32_16x16x32_bf16 v[22:25], v[90:93], v[184:187], v[22:25]
	v_mfma_f32_16x16x32_bf16 v[18:21], v[98:101], v[184:187], v[18:21]
	v_mfma_f32_16x16x32_bf16 v[62:65], v[94:97], v[158:161], v[62:65]
	v_mfma_f32_16x16x32_bf16 v[58:61], v[102:105], v[158:161], v[58:61]
	v_mfma_f32_16x16x32_bf16 v[54:57], v[94:97], v[172:175], v[54:57]
	v_mfma_f32_16x16x32_bf16 v[50:53], v[102:105], v[172:175], v[50:53]
	v_mfma_f32_16x16x32_bf16 v[30:33], v[94:97], v[180:183], v[30:33]
	v_mfma_f32_16x16x32_bf16 v[26:29], v[102:105], v[180:183], v[26:29]
	v_mfma_f32_16x16x32_bf16 v[22:25], v[94:97], v[188:191], v[22:25]
	v_mfma_f32_16x16x32_bf16 v[18:21], v[102:105], v[188:191], v[18:21]
	s_setprio 0
	s_barrier
	s_add_u32 s34, s38, 0x40000
	s_addc_u32 s35, s39, 0
	s_add_i32 s40, s40, s44
	v_lshl_add_u64 v[90:91], s[34:35], 0, v[148:149]
	s_mov_b32 m0, s40
	s_nop 0
	global_load_lds_dwordx4 v[90:91], off
	v_lshl_add_u64 v[90:91], s[34:35], 0, v[146:147]
	s_add_i32 m0, s40, 0x2000
	s_nop 0
	global_load_lds_dwordx4 v[90:91], off
	s_waitcnt vmcnt(10)
	s_barrier
	s_setprio 1
	v_mfma_f32_16x16x32_bf16 v[46:49], v[196:199], v[154:157], v[46:49]
	v_mfma_f32_16x16x32_bf16 v[42:45], v[206:209], v[154:157], v[42:45]
	v_mfma_f32_16x16x32_bf16 v[38:41], v[196:199], v[168:171], v[38:41]
	v_mfma_f32_16x16x32_bf16 v[34:37], v[206:209], v[168:171], v[34:37]
	v_mfma_f32_16x16x32_bf16 v[14:17], v[196:199], v[176:179], v[14:17]
	v_mfma_f32_16x16x32_bf16 v[10:13], v[206:209], v[176:179], v[10:13]
	v_mfma_f32_16x16x32_bf16 v[6:9], v[196:199], v[184:187], v[6:9]
	v_mfma_f32_16x16x32_bf16 v[2:5], v[206:209], v[184:187], v[2:5]
	v_mfma_f32_16x16x32_bf16 v[46:49], v[200:203], v[158:161], v[46:49]
	v_mfma_f32_16x16x32_bf16 v[42:45], v[210:213], v[158:161], v[42:45]
	v_mfma_f32_16x16x32_bf16 v[38:41], v[200:203], v[172:175], v[38:41]
	v_mfma_f32_16x16x32_bf16 v[34:37], v[210:213], v[172:175], v[34:37]
	v_mfma_f32_16x16x32_bf16 v[14:17], v[200:203], v[180:183], v[14:17]
	v_mfma_f32_16x16x32_bf16 v[10:13], v[210:213], v[180:183], v[10:13]
	v_mfma_f32_16x16x32_bf16 v[6:9], v[200:203], v[188:191], v[6:9]
	v_mfma_f32_16x16x32_bf16 v[2:5], v[210:213], v[188:191], v[2:5]
	s_setprio 0
	s_add_i32 s34, 0, 0x18000
	v_add_u32_e32 v0, s34, v165
	s_barrier
	ds_read_b128 v[90:93], v0
	ds_read_b128 v[94:97], v0 offset:1024
	ds_read_b128 v[98:101], v0 offset:2048
	ds_read_b128 v[102:105], v0 offset:3072
	s_add_u32 s2, s2, 0x40000
	s_addc_u32 s3, s3, 0
	s_mov_b32 m0, s52
	v_lshl_add_u64 v[196:197], s[2:3], 0, v[148:149]
	ds_read_b128 v[154:157], v167 offset:32768
	ds_read_b128 v[158:161], v167 offset:33792
	ds_read_b128 v[168:171], v167 offset:34816
	ds_read_b128 v[172:175], v167 offset:35840
	ds_read_b128 v[176:179], v167 offset:36864
	ds_read_b128 v[180:183], v167 offset:37888
	ds_read_b128 v[184:187], v167 offset:38912
	ds_read_b128 v[188:191], v167 offset:39936
	global_load_lds_dwordx4 v[196:197], off
	v_lshl_add_u64 v[196:197], s[2:3], 0, v[146:147]
	s_mov_b32 m0, s53
	s_nop 0
	global_load_lds_dwordx4 v[196:197], off
	s_waitcnt vmcnt(10)
	s_waitcnt lgkmcnt(8)
	s_barrier
	s_waitcnt lgkmcnt(0)
	s_setprio 1
	s_waitcnt lgkmcnt(0)
	v_mfma_f32_16x16x32_bf16 v[142:145], v[90:93], v[154:157], v[142:145]
	v_mfma_f32_16x16x32_bf16 v[138:141], v[98:101], v[154:157], v[138:141]
	v_mfma_f32_16x16x32_bf16 v[126:129], v[90:93], v[168:171], v[126:129]
	v_mfma_f32_16x16x32_bf16 v[122:125], v[98:101], v[168:171], v[122:125]
	v_mfma_f32_16x16x32_bf16 v[110:113], v[90:93], v[176:179], v[110:113]
	v_mfma_f32_16x16x32_bf16 v[106:109], v[98:101], v[176:179], v[106:109]
	v_mfma_f32_16x16x32_bf16 v[78:81], v[90:93], v[184:187], v[78:81]
	v_mfma_f32_16x16x32_bf16 v[74:77], v[98:101], v[184:187], v[74:77]
	v_mfma_f32_16x16x32_bf16 v[142:145], v[94:97], v[158:161], v[142:145]
	v_mfma_f32_16x16x32_bf16 v[138:141], v[102:105], v[158:161], v[138:141]
	v_mfma_f32_16x16x32_bf16 v[126:129], v[94:97], v[172:175], v[126:129]
	v_mfma_f32_16x16x32_bf16 v[122:125], v[102:105], v[172:175], v[122:125]
	v_mfma_f32_16x16x32_bf16 v[110:113], v[94:97], v[180:183], v[110:113]
	v_mfma_f32_16x16x32_bf16 v[106:109], v[102:105], v[180:183], v[106:109]
	v_mfma_f32_16x16x32_bf16 v[78:81], v[94:97], v[188:191], v[78:81]
	v_mfma_f32_16x16x32_bf16 v[74:77], v[102:105], v[188:191], v[74:77]
	s_setprio 0
	s_barrier
	s_add_i32 s35, 0, 0x1c000
	s_add_i32 s2, s34, s44
	v_add_u32_e32 v0, s35, v165
	v_lshl_add_u64 v[162:163], v[162:163], 0, s[74:75]
	s_mov_b32 m0, s2
	ds_read_b128 v[196:199], v0
	ds_read_b128 v[200:203], v0 offset:1024
	ds_read_b128 v[206:209], v0 offset:2048
	ds_read_b128 v[210:213], v0 offset:3072
	global_load_lds_dwordx4 v[162:163], off
	v_lshl_add_u64 v[162:163], v[192:193], 0, s[74:75]
	s_add_i32 m0, s2, 0x2000
	s_nop 0
	global_load_lds_dwordx4 v[162:163], off
	s_waitcnt vmcnt(10)
	s_barrier
	s_waitcnt lgkmcnt(0)
	s_setprio 1
	s_waitcnt lgkmcnt(0)
	v_mfma_f32_16x16x32_bf16 v[134:137], v[196:199], v[154:157], v[134:137]
	v_mfma_f32_16x16x32_bf16 v[130:133], v[206:209], v[154:157], v[130:133]
	v_mfma_f32_16x16x32_bf16 v[118:121], v[196:199], v[168:171], v[118:121]
	v_mfma_f32_16x16x32_bf16 v[114:117], v[206:209], v[168:171], v[114:117]
	v_mfma_f32_16x16x32_bf16 v[86:89], v[196:199], v[176:179], v[86:89]
	v_mfma_f32_16x16x32_bf16 v[82:85], v[206:209], v[176:179], v[82:85]
	v_mfma_f32_16x16x32_bf16 v[70:73], v[196:199], v[184:187], v[70:73]
	v_mfma_f32_16x16x32_bf16 v[66:69], v[206:209], v[184:187], v[66:69]
	v_mfma_f32_16x16x32_bf16 v[134:137], v[200:203], v[158:161], v[134:137]
	v_mfma_f32_16x16x32_bf16 v[130:133], v[210:213], v[158:161], v[130:133]
	v_mfma_f32_16x16x32_bf16 v[118:121], v[200:203], v[172:175], v[118:121]
	v_mfma_f32_16x16x32_bf16 v[114:117], v[210:213], v[172:175], v[114:117]
	v_mfma_f32_16x16x32_bf16 v[86:89], v[200:203], v[180:183], v[86:89]
	v_mfma_f32_16x16x32_bf16 v[82:85], v[210:213], v[180:183], v[82:85]
	v_mfma_f32_16x16x32_bf16 v[70:73], v[200:203], v[188:191], v[70:73]
	v_mfma_f32_16x16x32_bf16 v[66:69], v[210:213], v[188:191], v[66:69]
	s_setprio 0
	s_mov_b32 m0, s59
	v_lshl_add_u64 v[162:163], v[214:215], 0, s[74:75]
	s_barrier
	ds_read_b128 v[154:157], v167 offset:49152
	ds_read_b128 v[158:161], v167 offset:50176
	ds_read_b128 v[168:171], v167 offset:51200
	ds_read_b128 v[172:175], v167 offset:52224
	ds_read_b128 v[176:179], v167 offset:53248
	ds_read_b128 v[180:183], v167 offset:54272
	ds_read_b128 v[184:187], v167 offset:55296
	ds_read_b128 v[188:191], v167 offset:56320
	global_load_lds_dwordx4 v[162:163], off
	v_lshl_add_u64 v[162:163], v[216:217], 0, s[74:75]
	s_mov_b32 m0, s67
	s_nop 0
	global_load_lds_dwordx4 v[162:163], off
	s_barrier
	s_waitcnt lgkmcnt(0)
	s_setprio 1
	s_waitcnt lgkmcnt(0)
	v_mfma_f32_16x16x32_bf16 v[62:65], v[90:93], v[154:157], v[62:65]
	v_mfma_f32_16x16x32_bf16 v[58:61], v[98:101], v[154:157], v[58:61]
	v_mfma_f32_16x16x32_bf16 v[54:57], v[90:93], v[168:171], v[54:57]
	v_mfma_f32_16x16x32_bf16 v[50:53], v[98:101], v[168:171], v[50:53]
	v_mfma_f32_16x16x32_bf16 v[30:33], v[90:93], v[176:179], v[30:33]
	v_mfma_f32_16x16x32_bf16 v[26:29], v[98:101], v[176:179], v[26:29]
	v_mfma_f32_16x16x32_bf16 v[22:25], v[90:93], v[184:187], v[22:25]
	v_mfma_f32_16x16x32_bf16 v[18:21], v[98:101], v[184:187], v[18:21]
	v_mfma_f32_16x16x32_bf16 v[62:65], v[94:97], v[158:161], v[62:65]
	v_mfma_f32_16x16x32_bf16 v[58:61], v[102:105], v[158:161], v[58:61]
	v_mfma_f32_16x16x32_bf16 v[54:57], v[94:97], v[172:175], v[54:57]
	v_mfma_f32_16x16x32_bf16 v[50:53], v[102:105], v[172:175], v[50:53]
	v_mfma_f32_16x16x32_bf16 v[30:33], v[94:97], v[180:183], v[30:33]
	v_mfma_f32_16x16x32_bf16 v[26:29], v[102:105], v[180:183], v[26:29]
	v_mfma_f32_16x16x32_bf16 v[22:25], v[94:97], v[188:191], v[22:25]
	v_mfma_f32_16x16x32_bf16 v[18:21], v[102:105], v[188:191], v[18:21]
	s_setprio 0
	s_barrier
	s_add_u32 s2, s38, 0x40080
	s_addc_u32 s3, s39, 0
	s_add_i32 s34, s35, s44
	v_lshl_add_u64 v[90:91], s[2:3], 0, v[148:149]
	s_mov_b32 m0, s34
	s_nop 0
	global_load_lds_dwordx4 v[90:91], off
	v_lshl_add_u64 v[90:91], s[2:3], 0, v[146:147]
	s_add_i32 m0, s34, 0x2000
	s_nop 0
	global_load_lds_dwordx4 v[90:91], off
	s_waitcnt vmcnt(10)
	s_barrier
	s_setprio 1
	v_mfma_f32_16x16x32_bf16 v[46:49], v[196:199], v[154:157], v[46:49]
	v_mfma_f32_16x16x32_bf16 v[42:45], v[206:209], v[154:157], v[42:45]
	v_mfma_f32_16x16x32_bf16 v[38:41], v[196:199], v[168:171], v[38:41]
	v_mfma_f32_16x16x32_bf16 v[34:37], v[206:209], v[168:171], v[34:37]
	v_mfma_f32_16x16x32_bf16 v[14:17], v[196:199], v[176:179], v[14:17]
	v_mfma_f32_16x16x32_bf16 v[10:13], v[206:209], v[176:179], v[10:13]
	v_mfma_f32_16x16x32_bf16 v[6:9], v[196:199], v[184:187], v[6:9]
	v_mfma_f32_16x16x32_bf16 v[2:5], v[206:209], v[184:187], v[2:5]
	v_mfma_f32_16x16x32_bf16 v[46:49], v[200:203], v[158:161], v[46:49]
	v_mfma_f32_16x16x32_bf16 v[42:45], v[210:213], v[158:161], v[42:45]
	v_mfma_f32_16x16x32_bf16 v[38:41], v[200:203], v[172:175], v[38:41]
	v_mfma_f32_16x16x32_bf16 v[34:37], v[210:213], v[172:175], v[34:37]
	v_mfma_f32_16x16x32_bf16 v[14:17], v[200:203], v[180:183], v[14:17]
	v_mfma_f32_16x16x32_bf16 v[10:13], v[210:213], v[180:183], v[10:13]
	v_mfma_f32_16x16x32_bf16 v[6:9], v[200:203], v[188:191], v[6:9]
	v_mfma_f32_16x16x32_bf16 v[2:5], v[210:213], v[188:191], v[2:5]
	s_setprio 0
	s_add_i32 s58, s58, 2
	s_add_u32 s18, s18, 0x100
	s_addc_u32 s19, s19, 0
	s_add_u32 s57, s57, 0x100
	s_addc_u32 s50, s50, 0
	s_cmp_gt_u32 s58, 13
	s_barrier
	s_cbranch_scc0 .LBB0_136
	v_lshl_add_u32 v156, s54, 8, v164
	v_add_u32_e32 v158, 0xffffe000, v156
	v_lshrrev_b32_e32 v0, 11, v158
	s_movk_i32 s2, 0x1800
	v_mad_u32_u24 v0, v0, s2, s2
	s_movk_i32 s2, 0x1fff
	v_cmp_lt_i32_e32 vcc, s2, v156
	v_lshl_or_b32 v154, s49, 8, v166
	v_ashrrev_i32_e32 v155, 31, v154
	v_cndmask_b32_e32 v0, 0, v0, vcc
	v_lshl_add_u64 v[90:91], v[0:1], 2, s[0:1]
	v_lshl_add_u64 v[90:91], v[154:155], 2, v[90:91]
	global_load_dwordx4 v[102:105], v[90:91], off
	global_load_dwordx4 v[98:101], v[90:91], off offset:64
	global_load_dwordx4 v[94:97], v[90:91], off offset:512
	s_nop 0
	global_load_dwordx4 v[90:93], v[90:91], off offset:576
	s_and_saveexec_b64 s[2:3], vcc
	s_xor_b64 s[2:3], exec, s[2:3]
	v_mov_b32_e32 v159, v1
	v_lshlrev_b64 v[158:159], 12, v[158:159]
	v_mov_b32_e32 v157, v1
	v_lshl_add_u64 v[162:163], s[8:9], 0, v[158:159]
	v_lshlrev_b64 v[160:161], 12, v[156:157]
	s_or_saveexec_b64 s[2:3], s[2:3]
	v_ashrrev_i32_e32 v157, 31, v156
	v_readlane_b32 s57, v255, 48
	s_mov_b32 s35, 0x3fb8aa3b
	s_mov_b32 s34, 0xc2ce8ed0
	s_xor_b64 exec, exec, s[2:3]
	s_cbranch_execz .LBB0_132
	v_lshlrev_b64 v[160:161], 12, v[156:157]
	v_lshl_add_u64 v[162:163], s[6:7], 0, v[160:161]
	s_branch .LBB0_132

.LBB0_197:
	s_add_u32 s2, s0, 0xfffe0080
	s_addc_u32 s3, s1, -1
	s_add_i32 s34, 0, 0x10000
	v_add_u32_e32 v94, s34, v241
	ds_read_b128 v[66:69], v94
	ds_read_b128 v[78:81], v94 offset:1024
	ds_read_b128 v[82:85], v94 offset:2048
	ds_read_b128 v[94:97], v94 offset:3072
	s_cmp_eq_u32 s38, 4
	s_cselect_b32 s3, s13, s3
	s_cselect_b32 s2, s12, s2
	s_cselect_b32 s17, s7, s18
	s_cselect_b32 s16, s9, s11
	v_lshl_add_u64 v[178:179], s[0:1], 0, v[216:217]
	s_add_i32 m0, s67, 0xc000
	ds_read_b128 v[106:109], v243
	ds_read_b128 v[114:117], v243 offset:1024
	ds_read_b128 v[126:129], v243 offset:2048
	ds_read_b128 v[134:137], v243 offset:3072
	ds_read_b128 v[162:165], v243 offset:4096
	ds_read_b128 v[166:169], v243 offset:5120
	ds_read_b128 v[170:173], v243 offset:6144
	ds_read_b128 v[174:177], v243 offset:7168
	global_load_lds_dwordx4 v[178:179], off
	v_lshl_add_u64 v[178:179], s[0:1], 0, v[218:219]
	s_add_i32 m0, s67, 0xe000
	s_nop 0
	global_load_lds_dwordx4 v[178:179], off
	s_waitcnt vmcnt(10)
	s_waitcnt lgkmcnt(8)
	s_barrier
	s_waitcnt lgkmcnt(0)
	s_setprio 1
	s_waitcnt lgkmcnt(0)
	v_mfma_f32_16x16x32_bf16 v[158:161], v[66:69], v[106:109], v[158:161]
	v_mfma_f32_16x16x32_bf16 v[154:157], v[82:85], v[106:109], v[154:157]
	v_mfma_f32_16x16x32_bf16 v[142:145], v[66:69], v[126:129], v[142:145]
	v_mfma_f32_16x16x32_bf16 v[138:141], v[82:85], v[126:129], v[138:141]
	v_mfma_f32_16x16x32_bf16 v[118:121], v[66:69], v[162:165], v[118:121]
	v_mfma_f32_16x16x32_bf16 v[110:113], v[82:85], v[162:165], v[110:113]
	v_mfma_f32_16x16x32_bf16 v[90:93], v[66:69], v[170:173], v[90:93]
	v_mfma_f32_16x16x32_bf16 v[86:89], v[82:85], v[170:173], v[86:89]
	v_mfma_f32_16x16x32_bf16 v[158:161], v[78:81], v[114:117], v[158:161]
	v_mfma_f32_16x16x32_bf16 v[154:157], v[94:97], v[114:117], v[154:157]
	v_mfma_f32_16x16x32_bf16 v[142:145], v[78:81], v[134:137], v[142:145]
	v_mfma_f32_16x16x32_bf16 v[138:141], v[94:97], v[134:137], v[138:141]
	v_mfma_f32_16x16x32_bf16 v[118:121], v[78:81], v[166:169], v[118:121]
	v_mfma_f32_16x16x32_bf16 v[110:113], v[94:97], v[166:169], v[110:113]
	v_mfma_f32_16x16x32_bf16 v[90:93], v[78:81], v[174:177], v[90:93]
	v_mfma_f32_16x16x32_bf16 v[86:89], v[94:97], v[174:177], v[86:89]
	s_setprio 0
	s_barrier
	s_add_i32 s39, 0, 0x14000
	s_add_i32 s34, s34, s53
	v_add_u32_e32 v190, s39, v241
	v_lshl_add_u64 v[200:201], s[16:17], 0, v[0:1]
	s_mov_b32 m0, s34
	ds_read_b128 v[178:181], v190
	ds_read_b128 v[182:185], v190 offset:1024
	ds_read_b128 v[186:189], v190 offset:2048
	ds_read_b128 v[190:193], v190 offset:3072
	global_load_lds_dwordx4 v[200:201], off
	v_lshl_add_u64 v[202:203], s[16:17], 0, v[206:207]
	s_add_i32 m0, s34, 0x2000
	s_nop 0
	global_load_lds_dwordx4 v[202:203], off
	s_waitcnt vmcnt(10)
	s_barrier
	s_waitcnt lgkmcnt(0)
	s_setprio 1
	s_waitcnt lgkmcnt(0)
	v_mfma_f32_16x16x32_bf16 v[150:153], v[178:181], v[106:109], v[150:153]
	v_mfma_f32_16x16x32_bf16 v[106:109], v[186:189], v[106:109], v[146:149]
	v_mfma_f32_16x16x32_bf16 v[122:125], v[186:189], v[126:129], v[122:125]
	v_mfma_f32_16x16x32_bf16 v[102:105], v[178:181], v[162:165], v[102:105]
	v_mfma_f32_16x16x32_bf16 v[98:101], v[186:189], v[162:165], v[98:101]
	v_mfma_f32_16x16x32_bf16 v[74:77], v[178:181], v[170:173], v[74:77]
	v_mfma_f32_16x16x32_bf16 v[70:73], v[186:189], v[170:173], v[70:73]
	v_mfma_f32_16x16x32_bf16 v[150:153], v[182:185], v[114:117], v[150:153]
	v_mfma_f32_16x16x32_bf16 v[106:109], v[190:193], v[114:117], v[106:109]
	v_mfma_f32_16x16x32_bf16 v[114:117], v[178:181], v[126:129], v[130:133]
	v_mfma_f32_16x16x32_bf16 v[122:125], v[190:193], v[134:137], v[122:125]
	v_mfma_f32_16x16x32_bf16 v[102:105], v[182:185], v[166:169], v[102:105]
	v_mfma_f32_16x16x32_bf16 v[98:101], v[190:193], v[166:169], v[98:101]
	v_mfma_f32_16x16x32_bf16 v[74:77], v[182:185], v[174:177], v[74:77]
	v_mfma_f32_16x16x32_bf16 v[70:73], v[190:193], v[174:177], v[70:73]
	v_mfma_f32_16x16x32_bf16 v[114:117], v[182:185], v[134:137], v[114:117]
	s_setprio 0
	s_mov_b32 m0, s67
	v_lshl_add_u64 v[220:221], s[2:3], 0, v[210:211]
	s_barrier
	ds_read_b128 v[126:129], v243 offset:16384
	ds_read_b128 v[130:133], v243 offset:17408
	ds_read_b128 v[134:137], v243 offset:18432
	ds_read_b128 v[146:149], v243 offset:19456
	ds_read_b128 v[162:165], v243 offset:20480
	ds_read_b128 v[166:169], v243 offset:21504
	ds_read_b128 v[170:173], v243 offset:22528
	ds_read_b128 v[174:177], v243 offset:23552
	global_load_lds_dwordx4 v[220:221], off
	v_lshl_add_u64 v[222:223], s[2:3], 0, v[208:209]
	s_mov_b32 m0, s72
	s_nop 0
	global_load_lds_dwordx4 v[222:223], off
	s_barrier
	s_waitcnt lgkmcnt(0)
	s_setprio 1
	s_waitcnt lgkmcnt(0)
	v_mfma_f32_16x16x32_bf16 v[62:65], v[66:69], v[126:129], v[62:65]
	v_mfma_f32_16x16x32_bf16 v[58:61], v[82:85], v[126:129], v[58:61]
	v_mfma_f32_16x16x32_bf16 v[46:49], v[66:69], v[134:137], v[46:49]
	v_mfma_f32_16x16x32_bf16 v[42:45], v[82:85], v[134:137], v[42:45]
	v_mfma_f32_16x16x32_bf16 v[30:33], v[66:69], v[162:165], v[30:33]
	v_mfma_f32_16x16x32_bf16 v[26:29], v[82:85], v[162:165], v[26:29]
	v_mfma_f32_16x16x32_bf16 v[14:17], v[66:69], v[170:173], v[14:17]
	v_mfma_f32_16x16x32_bf16 v[10:13], v[82:85], v[170:173], v[10:13]
	v_mfma_f32_16x16x32_bf16 v[62:65], v[78:81], v[130:133], v[62:65]
	v_mfma_f32_16x16x32_bf16 v[58:61], v[94:97], v[130:133], v[58:61]
	v_mfma_f32_16x16x32_bf16 v[46:49], v[78:81], v[146:149], v[46:49]
	v_mfma_f32_16x16x32_bf16 v[42:45], v[94:97], v[146:149], v[42:45]
	v_mfma_f32_16x16x32_bf16 v[30:33], v[78:81], v[166:169], v[30:33]
	v_mfma_f32_16x16x32_bf16 v[26:29], v[94:97], v[166:169], v[26:29]
	v_mfma_f32_16x16x32_bf16 v[14:17], v[78:81], v[174:177], v[14:17]
	v_mfma_f32_16x16x32_bf16 v[10:13], v[94:97], v[174:177], v[10:13]
	s_setprio 0
	s_barrier
	s_add_u32 s34, s16, 0x20000
	s_addc_u32 s35, s17, 0
	s_add_i32 s39, s39, s53
	v_lshl_add_u64 v[66:67], s[34:35], 0, v[0:1]
	s_mov_b32 m0, s39
	s_nop 0
	global_load_lds_dwordx4 v[66:67], off
	v_lshl_add_u64 v[66:67], s[34:35], 0, v[206:207]
	s_add_i32 m0, s39, 0x2000
	s_nop 0
	global_load_lds_dwordx4 v[66:67], off
	s_waitcnt vmcnt(10)
	s_barrier
	s_setprio 1
	v_mfma_f32_16x16x32_bf16 v[54:57], v[178:181], v[126:129], v[54:57]
	v_mfma_f32_16x16x32_bf16 v[50:53], v[186:189], v[126:129], v[50:53]
	v_mfma_f32_16x16x32_bf16 v[38:41], v[178:181], v[134:137], v[38:41]
	v_mfma_f32_16x16x32_bf16 v[34:37], v[186:189], v[134:137], v[34:37]
	v_mfma_f32_16x16x32_bf16 v[22:25], v[178:181], v[162:165], v[22:25]
	v_mfma_f32_16x16x32_bf16 v[18:21], v[186:189], v[162:165], v[18:21]
	v_mfma_f32_16x16x32_bf16 v[6:9], v[178:181], v[170:173], v[6:9]
	v_mfma_f32_16x16x32_bf16 v[2:5], v[186:189], v[170:173], v[2:5]
	v_mfma_f32_16x16x32_bf16 v[54:57], v[182:185], v[130:133], v[54:57]
	v_mfma_f32_16x16x32_bf16 v[50:53], v[190:193], v[130:133], v[50:53]
	v_mfma_f32_16x16x32_bf16 v[38:41], v[182:185], v[146:149], v[38:41]
	v_mfma_f32_16x16x32_bf16 v[34:37], v[190:193], v[146:149], v[34:37]
	v_mfma_f32_16x16x32_bf16 v[22:25], v[182:185], v[166:169], v[22:25]
	v_mfma_f32_16x16x32_bf16 v[18:21], v[190:193], v[166:169], v[18:21]
	v_mfma_f32_16x16x32_bf16 v[6:9], v[182:185], v[174:177], v[6:9]
	v_mfma_f32_16x16x32_bf16 v[2:5], v[190:193], v[174:177], v[2:5]
	s_setprio 0
	s_add_i32 s34, 0, 0x18000
	v_add_u32_e32 v94, s34, v241
	s_barrier
	ds_read_b128 v[66:69], v94
	ds_read_b128 v[78:81], v94 offset:1024
	ds_read_b128 v[82:85], v94 offset:2048
	ds_read_b128 v[94:97], v94 offset:3072
	s_add_u32 s2, s2, 0x20000
	s_addc_u32 s3, s3, 0
	s_mov_b32 m0, s73
	v_lshl_add_u64 v[146:147], s[2:3], 0, v[210:211]
	ds_read_b128 v[126:129], v243 offset:32768
	ds_read_b128 v[130:133], v243 offset:33792
	ds_read_b128 v[134:137], v243 offset:34816
	ds_read_b128 v[162:165], v243 offset:35840
	ds_read_b128 v[166:169], v243 offset:36864
	ds_read_b128 v[170:173], v243 offset:37888
	ds_read_b128 v[174:177], v243 offset:38912
	ds_read_b128 v[178:181], v243 offset:39936
	global_load_lds_dwordx4 v[146:147], off
	v_lshl_add_u64 v[146:147], s[2:3], 0, v[208:209]
	s_mov_b32 m0, s52
	s_nop 0
	global_load_lds_dwordx4 v[146:147], off
	s_waitcnt vmcnt(10)
	s_waitcnt lgkmcnt(8)
	s_barrier
	s_waitcnt lgkmcnt(0)
	s_setprio 1
	s_waitcnt lgkmcnt(0)
	v_mfma_f32_16x16x32_bf16 v[146:149], v[66:69], v[126:129], v[158:161]
	v_mfma_f32_16x16x32_bf16 v[158:161], v[78:81], v[130:133], v[146:149]
	v_mfma_f32_16x16x32_bf16 v[146:149], v[82:85], v[126:129], v[154:157]
	v_mfma_f32_16x16x32_bf16 v[142:145], v[66:69], v[134:137], v[142:145]
	v_mfma_f32_16x16x32_bf16 v[138:141], v[82:85], v[134:137], v[138:141]
	v_mfma_f32_16x16x32_bf16 v[118:121], v[66:69], v[166:169], v[118:121]
	v_mfma_f32_16x16x32_bf16 v[110:113], v[82:85], v[166:169], v[110:113]
	v_mfma_f32_16x16x32_bf16 v[90:93], v[66:69], v[174:177], v[90:93]
	v_mfma_f32_16x16x32_bf16 v[86:89], v[82:85], v[174:177], v[86:89]
	v_mfma_f32_16x16x32_bf16 v[154:157], v[94:97], v[130:133], v[146:149]
	v_mfma_f32_16x16x32_bf16 v[142:145], v[78:81], v[162:165], v[142:145]
	v_mfma_f32_16x16x32_bf16 v[138:141], v[94:97], v[162:165], v[138:141]
	v_mfma_f32_16x16x32_bf16 v[118:121], v[78:81], v[170:173], v[118:121]
	v_mfma_f32_16x16x32_bf16 v[110:113], v[94:97], v[170:173], v[110:113]
	v_mfma_f32_16x16x32_bf16 v[90:93], v[78:81], v[178:181], v[90:93]
	v_mfma_f32_16x16x32_bf16 v[86:89], v[94:97], v[178:181], v[86:89]
	s_setprio 0
	s_barrier
	s_add_i32 s35, 0, 0x1c000
	v_add_u32_e32 v146, s35, v241
	s_add_i32 s2, s34, s53
	ds_read_b128 v[182:185], v146
	ds_read_b128 v[186:189], v146 offset:1024
	ds_read_b128 v[190:193], v146 offset:2048
	ds_read_b128 v[196:199], v146 offset:3072
	v_lshl_add_u64 v[146:147], v[200:201], 0, s[74:75]
	s_mov_b32 m0, s2
	s_nop 0
	global_load_lds_dwordx4 v[146:147], off
	v_lshl_add_u64 v[146:147], v[202:203], 0, s[74:75]
	s_add_i32 m0, s2, 0x2000
	s_nop 0
	global_load_lds_dwordx4 v[146:147], off
	s_waitcnt vmcnt(10)
	s_barrier
	s_waitcnt lgkmcnt(0)
	s_setprio 1
	s_waitcnt lgkmcnt(0)
	v_mfma_f32_16x16x32_bf16 v[146:149], v[182:185], v[126:129], v[150:153]
	v_mfma_f32_16x16x32_bf16 v[106:109], v[190:193], v[126:129], v[106:109]
	v_mfma_f32_16x16x32_bf16 v[150:153], v[186:189], v[130:133], v[146:149]
	v_mfma_f32_16x16x32_bf16 v[146:149], v[196:199], v[130:133], v[106:109]
	v_mfma_f32_16x16x32_bf16 v[106:109], v[182:185], v[134:137], v[114:117]
	v_mfma_f32_16x16x32_bf16 v[130:133], v[186:189], v[162:165], v[106:109]
	v_mfma_f32_16x16x32_bf16 v[106:109], v[190:193], v[134:137], v[122:125]
	v_mfma_f32_16x16x32_bf16 v[102:105], v[182:185], v[166:169], v[102:105]
	v_mfma_f32_16x16x32_bf16 v[98:101], v[190:193], v[166:169], v[98:101]
	v_mfma_f32_16x16x32_bf16 v[74:77], v[182:185], v[174:177], v[74:77]
	v_mfma_f32_16x16x32_bf16 v[70:73], v[190:193], v[174:177], v[70:73]
	v_mfma_f32_16x16x32_bf16 v[122:125], v[196:199], v[162:165], v[106:109]
	v_mfma_f32_16x16x32_bf16 v[102:105], v[186:189], v[170:173], v[102:105]
	v_mfma_f32_16x16x32_bf16 v[98:101], v[196:199], v[170:173], v[98:101]
	v_mfma_f32_16x16x32_bf16 v[74:77], v[186:189], v[178:181], v[74:77]
	v_mfma_f32_16x16x32_bf16 v[70:73], v[196:199], v[178:181], v[70:73]
	s_setprio 0
	s_mov_b32 m0, s5
	v_lshl_add_u64 v[178:179], v[220:221], 0, s[74:75]
	s_barrier
	ds_read_b128 v[106:109], v243 offset:49152
	ds_read_b128 v[114:117], v243 offset:50176
	ds_read_b128 v[126:129], v243 offset:51200
	ds_read_b128 v[134:137], v243 offset:52224
	ds_read_b128 v[162:165], v243 offset:53248
	ds_read_b128 v[166:169], v243 offset:54272
	ds_read_b128 v[170:173], v243 offset:55296
	ds_read_b128 v[174:177], v243 offset:56320
	global_load_lds_dwordx4 v[178:179], off
	v_lshl_add_u64 v[178:179], v[222:223], 0, s[74:75]
	s_mov_b32 m0, s51
	s_nop 0
	global_load_lds_dwordx4 v[178:179], off
	s_barrier
	s_waitcnt lgkmcnt(0)
	s_setprio 1
	s_waitcnt lgkmcnt(0)
	v_mfma_f32_16x16x32_bf16 v[62:65], v[66:69], v[106:109], v[62:65]
	v_mfma_f32_16x16x32_bf16 v[58:61], v[82:85], v[106:109], v[58:61]
	v_mfma_f32_16x16x32_bf16 v[46:49], v[66:69], v[126:129], v[46:49]
	v_mfma_f32_16x16x32_bf16 v[42:45], v[82:85], v[126:129], v[42:45]
	v_mfma_f32_16x16x32_bf16 v[30:33], v[66:69], v[162:165], v[30:33]
	v_mfma_f32_16x16x32_bf16 v[26:29], v[82:85], v[162:165], v[26:29]
	v_mfma_f32_16x16x32_bf16 v[14:17], v[66:69], v[170:173], v[14:17]
	v_mfma_f32_16x16x32_bf16 v[10:13], v[82:85], v[170:173], v[10:13]
	v_mfma_f32_16x16x32_bf16 v[62:65], v[78:81], v[114:117], v[62:65]
	v_mfma_f32_16x16x32_bf16 v[58:61], v[94:97], v[114:117], v[58:61]
	v_mfma_f32_16x16x32_bf16 v[46:49], v[78:81], v[134:137], v[46:49]
	v_mfma_f32_16x16x32_bf16 v[42:45], v[94:97], v[134:137], v[42:45]
	v_mfma_f32_16x16x32_bf16 v[30:33], v[78:81], v[166:169], v[30:33]
	v_mfma_f32_16x16x32_bf16 v[26:29], v[94:97], v[166:169], v[26:29]
	v_mfma_f32_16x16x32_bf16 v[14:17], v[78:81], v[174:177], v[14:17]
	v_mfma_f32_16x16x32_bf16 v[10:13], v[94:97], v[174:177], v[10:13]
	s_setprio 0
	s_barrier
	s_add_u32 s2, s16, 0x20080
	s_addc_u32 s3, s17, 0
	s_add_i32 s16, s35, s53
	v_lshl_add_u64 v[66:67], s[2:3], 0, v[0:1]
	s_mov_b32 m0, s16
	s_nop 0
	global_load_lds_dwordx4 v[66:67], off
	v_lshl_add_u64 v[66:67], s[2:3], 0, v[206:207]
	s_add_i32 m0, s16, 0x2000
	s_nop 0
	global_load_lds_dwordx4 v[66:67], off
	s_waitcnt vmcnt(10)
	s_barrier
	s_setprio 1
	v_mfma_f32_16x16x32_bf16 v[54:57], v[182:185], v[106:109], v[54:57]
	v_mfma_f32_16x16x32_bf16 v[50:53], v[190:193], v[106:109], v[50:53]
	v_mfma_f32_16x16x32_bf16 v[38:41], v[182:185], v[126:129], v[38:41]
	v_mfma_f32_16x16x32_bf16 v[34:37], v[190:193], v[126:129], v[34:37]
	v_mfma_f32_16x16x32_bf16 v[22:25], v[182:185], v[162:165], v[22:25]
	v_mfma_f32_16x16x32_bf16 v[18:21], v[190:193], v[162:165], v[18:21]
	v_mfma_f32_16x16x32_bf16 v[6:9], v[182:185], v[170:173], v[6:9]
	v_mfma_f32_16x16x32_bf16 v[2:5], v[190:193], v[170:173], v[2:5]
	v_mfma_f32_16x16x32_bf16 v[54:57], v[186:189], v[114:117], v[54:57]
	v_mfma_f32_16x16x32_bf16 v[50:53], v[196:199], v[114:117], v[50:53]
	v_mfma_f32_16x16x32_bf16 v[38:41], v[186:189], v[134:137], v[38:41]
	v_mfma_f32_16x16x32_bf16 v[34:37], v[196:199], v[134:137], v[34:37]
	v_mfma_f32_16x16x32_bf16 v[22:25], v[186:189], v[166:169], v[22:25]
	v_mfma_f32_16x16x32_bf16 v[18:21], v[196:199], v[166:169], v[18:21]
	v_mfma_f32_16x16x32_bf16 v[6:9], v[186:189], v[174:177], v[6:9]
	v_mfma_f32_16x16x32_bf16 v[2:5], v[196:199], v[174:177], v[2:5]
	s_setprio 0
	s_add_i32 s38, s38, 2
	s_add_u32 s0, s0, 0x100
	s_addc_u32 s1, s1, 0
	s_add_u32 s11, s11, 0x100
	s_addc_u32 s18, s18, 0
	s_cmp_gt_u32 s38, 5
	s_barrier
	s_cbranch_scc0 .LBB0_197
	s_lshl_b32 s2, s19, 8
	s_cmp_gt_i32 s44, 0
	s_cselect_b64 s[0:1], -1, 0
	s_lshl_b32 s3, s44, 6
	s_lshl_b32 s7, s45, 4
	s_add_i32 s3, s7, s3
	s_add_i32 s18, s3, s2
	s_lshl_b32 s3, s19, 6
	s_ashr_i32 s19, s18, 31
	s_lshl_b64 s[34:35], s[18:19], 13
	v_lshl_add_u64 v[66:67], v[214:215], 0, s[34:35]
	global_load_dwordx4 v[190:193], v[66:67], off
	s_add_i32 s16, s3, s7
	s_cmp_lt_i32 s44, 1
	s_cbranch_scc1 .LBB0_200
	s_ashr_i32 s17, s16, 31
	s_lshl_b64 s[34:35], s[16:17], 13
	v_lshl_add_u64 v[66:67], v[212:213], 0, s[34:35]
	global_load_dwordx4 v[134:137], v[66:67], off

.LBB0_402:
	s_add_u32 s2, s12, 0xfffe0080
	s_addc_u32 s3, s13, -1
	s_add_i32 s34, 0, 0x10000
	v_add_u32_e32 v134, s34, v185
	ds_read_b128 v[106:109], v134
	ds_read_b128 v[110:113], v134 offset:1024
	ds_read_b128 v[126:129], v134 offset:2048
	ds_read_b128 v[134:137], v134 offset:3072
	s_cmp_eq_u32 s54, 4
	s_cselect_b32 s3, s7, s3
	s_cselect_b32 s2, s51, s2
	s_cselect_b32 s15, s1, s50
	s_cselect_b32 s14, s52, s53
	v_lshl_add_u64 v[192:193], s[12:13], 0, v[168:169]
	s_add_i32 m0, s18, 0xc000
	ds_read_b128 v[138:141], v187
	ds_read_b128 v[146:149], v187 offset:1024
	ds_read_b128 v[154:157], v187 offset:2048
	ds_read_b128 v[158:161], v187 offset:3072
	ds_read_b128 v[172:175], v187 offset:4096
	ds_read_b128 v[176:179], v187 offset:5120
	ds_read_b128 v[180:183], v187 offset:6144
	ds_read_b128 v[188:191], v187 offset:7168
	global_load_lds_dwordx4 v[192:193], off
	v_lshl_add_u64 v[192:193], s[12:13], 0, v[170:171]
	s_add_i32 m0, s18, 0xe000
	s_nop 0
	global_load_lds_dwordx4 v[192:193], off
	s_waitcnt vmcnt(10)
	s_waitcnt lgkmcnt(8)
	s_barrier
	s_waitcnt lgkmcnt(0)
	s_setprio 1
	s_waitcnt lgkmcnt(0)
	v_mfma_f32_16x16x32_bf16 v[150:153], v[106:109], v[138:141], v[150:153]
	v_mfma_f32_16x16x32_bf16 v[142:145], v[126:129], v[138:141], v[142:145]
	v_mfma_f32_16x16x32_bf16 v[118:121], v[106:109], v[154:157], v[118:121]
	v_mfma_f32_16x16x32_bf16 v[114:117], v[126:129], v[154:157], v[114:117]
	v_mfma_f32_16x16x32_bf16 v[94:97], v[106:109], v[172:175], v[94:97]
	v_mfma_f32_16x16x32_bf16 v[90:93], v[126:129], v[172:175], v[90:93]
	v_mfma_f32_16x16x32_bf16 v[78:81], v[106:109], v[180:183], v[78:81]
	v_mfma_f32_16x16x32_bf16 v[74:77], v[126:129], v[180:183], v[74:77]
	v_mfma_f32_16x16x32_bf16 v[150:153], v[110:113], v[146:149], v[150:153]
	v_mfma_f32_16x16x32_bf16 v[142:145], v[134:137], v[146:149], v[142:145]
	v_mfma_f32_16x16x32_bf16 v[118:121], v[110:113], v[158:161], v[118:121]
	v_mfma_f32_16x16x32_bf16 v[114:117], v[134:137], v[158:161], v[114:117]
	v_mfma_f32_16x16x32_bf16 v[94:97], v[110:113], v[176:179], v[94:97]
	v_mfma_f32_16x16x32_bf16 v[90:93], v[134:137], v[176:179], v[90:93]
	v_mfma_f32_16x16x32_bf16 v[78:81], v[110:113], v[188:191], v[78:81]
	v_mfma_f32_16x16x32_bf16 v[74:77], v[134:137], v[188:191], v[74:77]
	s_setprio 0
	s_barrier
	s_add_i32 s40, 0, 0x14000
	v_add_u32_e32 v192, s40, v185
	s_add_i32 s34, s34, s17
	ds_read_b128 v[196:199], v192
	ds_read_b128 v[200:203], v192 offset:1024
	ds_read_b128 v[206:209], v192 offset:2048
	ds_read_b128 v[210:213], v192 offset:3072
	v_lshl_add_u64 v[192:193], s[14:15], 0, v[0:1]
	s_mov_b32 m0, s34
	v_lshl_add_u64 v[214:215], s[14:15], 0, v[162:163]
	global_load_lds_dwordx4 v[192:193], off
	s_add_i32 m0, s34, 0x2000
	s_nop 0
	global_load_lds_dwordx4 v[214:215], off
	s_waitcnt vmcnt(10)
	s_barrier
	s_waitcnt lgkmcnt(0)
	s_setprio 1
	s_waitcnt lgkmcnt(0)
	v_mfma_f32_16x16x32_bf16 v[130:133], v[196:199], v[138:141], v[130:133]
	v_mfma_f32_16x16x32_bf16 v[122:125], v[206:209], v[138:141], v[122:125]
	v_mfma_f32_16x16x32_bf16 v[102:105], v[196:199], v[154:157], v[102:105]
	v_mfma_f32_16x16x32_bf16 v[98:101], v[206:209], v[154:157], v[98:101]
	v_mfma_f32_16x16x32_bf16 v[86:89], v[196:199], v[172:175], v[86:89]
	v_mfma_f32_16x16x32_bf16 v[82:85], v[206:209], v[172:175], v[82:85]
	v_mfma_f32_16x16x32_bf16 v[70:73], v[196:199], v[180:183], v[70:73]
	v_mfma_f32_16x16x32_bf16 v[66:69], v[206:209], v[180:183], v[66:69]
	v_mfma_f32_16x16x32_bf16 v[130:133], v[200:203], v[146:149], v[130:133]
	v_mfma_f32_16x16x32_bf16 v[122:125], v[210:213], v[146:149], v[122:125]
	v_mfma_f32_16x16x32_bf16 v[102:105], v[200:203], v[158:161], v[102:105]
	v_mfma_f32_16x16x32_bf16 v[98:101], v[210:213], v[158:161], v[98:101]
	v_mfma_f32_16x16x32_bf16 v[86:89], v[200:203], v[176:179], v[86:89]
	v_mfma_f32_16x16x32_bf16 v[82:85], v[210:213], v[176:179], v[82:85]
	v_mfma_f32_16x16x32_bf16 v[70:73], v[200:203], v[188:191], v[70:73]
	v_mfma_f32_16x16x32_bf16 v[66:69], v[210:213], v[188:191], v[66:69]
	s_setprio 0
	s_mov_b32 m0, s18
	v_lshl_add_u64 v[216:217], s[2:3], 0, v[166:167]
	s_barrier
	ds_read_b128 v[138:141], v187 offset:16384
	ds_read_b128 v[146:149], v187 offset:17408
	ds_read_b128 v[154:157], v187 offset:18432
	ds_read_b128 v[158:161], v187 offset:19456
	ds_read_b128 v[172:175], v187 offset:20480
	ds_read_b128 v[176:179], v187 offset:21504
	ds_read_b128 v[180:183], v187 offset:22528
	ds_read_b128 v[188:191], v187 offset:23552
	global_load_lds_dwordx4 v[216:217], off
	v_lshl_add_u64 v[218:219], s[2:3], 0, v[164:165]
	s_mov_b32 m0, s19
	s_nop 0
	global_load_lds_dwordx4 v[218:219], off
	s_barrier
	s_waitcnt lgkmcnt(0)
	s_setprio 1
	s_waitcnt lgkmcnt(0)
	v_mfma_f32_16x16x32_bf16 v[62:65], v[106:109], v[138:141], v[62:65]
	v_mfma_f32_16x16x32_bf16 v[58:61], v[126:129], v[138:141], v[58:61]
	v_mfma_f32_16x16x32_bf16 v[46:49], v[106:109], v[154:157], v[46:49]
	v_mfma_f32_16x16x32_bf16 v[42:45], v[126:129], v[154:157], v[42:45]
	v_mfma_f32_16x16x32_bf16 v[30:33], v[106:109], v[172:175], v[30:33]
	v_mfma_f32_16x16x32_bf16 v[26:29], v[126:129], v[172:175], v[26:29]
	v_mfma_f32_16x16x32_bf16 v[14:17], v[106:109], v[180:183], v[14:17]
	v_mfma_f32_16x16x32_bf16 v[10:13], v[126:129], v[180:183], v[10:13]
	v_mfma_f32_16x16x32_bf16 v[62:65], v[110:113], v[146:149], v[62:65]
	v_mfma_f32_16x16x32_bf16 v[58:61], v[134:137], v[146:149], v[58:61]
	v_mfma_f32_16x16x32_bf16 v[46:49], v[110:113], v[158:161], v[46:49]
	v_mfma_f32_16x16x32_bf16 v[42:45], v[134:137], v[158:161], v[42:45]
	v_mfma_f32_16x16x32_bf16 v[30:33], v[110:113], v[176:179], v[30:33]
	v_mfma_f32_16x16x32_bf16 v[26:29], v[134:137], v[176:179], v[26:29]
	v_mfma_f32_16x16x32_bf16 v[14:17], v[110:113], v[188:191], v[14:17]
	v_mfma_f32_16x16x32_bf16 v[10:13], v[134:137], v[188:191], v[10:13]
	s_setprio 0
	s_barrier
	s_add_u32 s34, s14, 0x20000
	s_addc_u32 s35, s15, 0
	s_add_i32 s40, s40, s17
	v_lshl_add_u64 v[106:107], s[34:35], 0, v[0:1]
	s_mov_b32 m0, s40
	s_nop 0
	global_load_lds_dwordx4 v[106:107], off
	v_lshl_add_u64 v[106:107], s[34:35], 0, v[162:163]
	s_add_i32 m0, s40, 0x2000
	s_nop 0
	global_load_lds_dwordx4 v[106:107], off
	s_waitcnt vmcnt(10)
	s_barrier
	s_setprio 1
	v_mfma_f32_16x16x32_bf16 v[54:57], v[196:199], v[138:141], v[54:57]
	v_mfma_f32_16x16x32_bf16 v[50:53], v[206:209], v[138:141], v[50:53]
	v_mfma_f32_16x16x32_bf16 v[38:41], v[196:199], v[154:157], v[38:41]
	v_mfma_f32_16x16x32_bf16 v[34:37], v[206:209], v[154:157], v[34:37]
	v_mfma_f32_16x16x32_bf16 v[22:25], v[196:199], v[172:175], v[22:25]
	v_mfma_f32_16x16x32_bf16 v[18:21], v[206:209], v[172:175], v[18:21]
	v_mfma_f32_16x16x32_bf16 v[6:9], v[196:199], v[180:183], v[6:9]
	v_mfma_f32_16x16x32_bf16 v[2:5], v[206:209], v[180:183], v[2:5]
	v_mfma_f32_16x16x32_bf16 v[54:57], v[200:203], v[146:149], v[54:57]
	v_mfma_f32_16x16x32_bf16 v[50:53], v[210:213], v[146:149], v[50:53]
	v_mfma_f32_16x16x32_bf16 v[38:41], v[200:203], v[158:161], v[38:41]
	v_mfma_f32_16x16x32_bf16 v[34:37], v[210:213], v[158:161], v[34:37]
	v_mfma_f32_16x16x32_bf16 v[22:25], v[200:203], v[176:179], v[22:25]
	v_mfma_f32_16x16x32_bf16 v[18:21], v[210:213], v[176:179], v[18:21]
	v_mfma_f32_16x16x32_bf16 v[6:9], v[200:203], v[188:191], v[6:9]
	v_mfma_f32_16x16x32_bf16 v[2:5], v[210:213], v[188:191], v[2:5]
	s_setprio 0
	s_add_i32 s34, 0, 0x18000
	v_add_u32_e32 v134, s34, v185
	s_barrier
	ds_read_b128 v[106:109], v134
	ds_read_b128 v[110:113], v134 offset:1024
	ds_read_b128 v[126:129], v134 offset:2048
	ds_read_b128 v[134:137], v134 offset:3072
	s_add_u32 s2, s2, 0x20000
	s_addc_u32 s3, s3, 0
	s_mov_b32 m0, s38
	v_lshl_add_u64 v[196:197], s[2:3], 0, v[166:167]
	ds_read_b128 v[138:141], v187 offset:32768
	ds_read_b128 v[146:149], v187 offset:33792
	ds_read_b128 v[154:157], v187 offset:34816
	ds_read_b128 v[158:161], v187 offset:35840
	ds_read_b128 v[172:175], v187 offset:36864
	ds_read_b128 v[176:179], v187 offset:37888
	ds_read_b128 v[180:183], v187 offset:38912
	ds_read_b128 v[188:191], v187 offset:39936
	global_load_lds_dwordx4 v[196:197], off
	v_lshl_add_u64 v[196:197], s[2:3], 0, v[164:165]
	s_mov_b32 m0, s39
	s_nop 0
	global_load_lds_dwordx4 v[196:197], off
	s_waitcnt vmcnt(10)
	s_waitcnt lgkmcnt(8)
	s_barrier
	s_waitcnt lgkmcnt(0)
	s_setprio 1
	s_waitcnt lgkmcnt(0)
	v_mfma_f32_16x16x32_bf16 v[150:153], v[106:109], v[138:141], v[150:153]
	v_mfma_f32_16x16x32_bf16 v[142:145], v[126:129], v[138:141], v[142:145]
	v_mfma_f32_16x16x32_bf16 v[118:121], v[106:109], v[154:157], v[118:121]
	v_mfma_f32_16x16x32_bf16 v[114:117], v[126:129], v[154:157], v[114:117]
	v_mfma_f32_16x16x32_bf16 v[94:97], v[106:109], v[172:175], v[94:97]
	v_mfma_f32_16x16x32_bf16 v[90:93], v[126:129], v[172:175], v[90:93]
	v_mfma_f32_16x16x32_bf16 v[78:81], v[106:109], v[180:183], v[78:81]
	v_mfma_f32_16x16x32_bf16 v[74:77], v[126:129], v[180:183], v[74:77]
	v_mfma_f32_16x16x32_bf16 v[150:153], v[110:113], v[146:149], v[150:153]
	v_mfma_f32_16x16x32_bf16 v[142:145], v[134:137], v[146:149], v[142:145]
	v_mfma_f32_16x16x32_bf16 v[118:121], v[110:113], v[158:161], v[118:121]
	v_mfma_f32_16x16x32_bf16 v[114:117], v[134:137], v[158:161], v[114:117]
	v_mfma_f32_16x16x32_bf16 v[94:97], v[110:113], v[176:179], v[94:97]
	v_mfma_f32_16x16x32_bf16 v[90:93], v[134:137], v[176:179], v[90:93]
	v_mfma_f32_16x16x32_bf16 v[78:81], v[110:113], v[188:191], v[78:81]
	v_mfma_f32_16x16x32_bf16 v[74:77], v[134:137], v[188:191], v[74:77]
	s_setprio 0
	s_barrier
	s_add_i32 s35, 0, 0x1c000
	s_add_i32 s2, s34, s17
	v_add_u32_e32 v195, s35, v185
	v_lshl_add_u64 v[192:193], v[192:193], 0, s[74:75]
	s_mov_b32 m0, s2
	ds_read_b128 v[196:199], v195
	ds_read_b128 v[200:203], v195 offset:1024
	ds_read_b128 v[206:209], v195 offset:2048
	ds_read_b128 v[210:213], v195 offset:3072
	global_load_lds_dwordx4 v[192:193], off
	v_lshl_add_u64 v[192:193], v[214:215], 0, s[74:75]
	s_add_i32 m0, s2, 0x2000
	s_nop 0
	global_load_lds_dwordx4 v[192:193], off
	s_waitcnt vmcnt(10)
	s_barrier
	s_waitcnt lgkmcnt(0)
	s_setprio 1
	s_waitcnt lgkmcnt(0)
	v_mfma_f32_16x16x32_bf16 v[130:133], v[196:199], v[138:141], v[130:133]
	v_mfma_f32_16x16x32_bf16 v[122:125], v[206:209], v[138:141], v[122:125]
	v_mfma_f32_16x16x32_bf16 v[102:105], v[196:199], v[154:157], v[102:105]
	v_mfma_f32_16x16x32_bf16 v[98:101], v[206:209], v[154:157], v[98:101]
	v_mfma_f32_16x16x32_bf16 v[86:89], v[196:199], v[172:175], v[86:89]
	v_mfma_f32_16x16x32_bf16 v[82:85], v[206:209], v[172:175], v[82:85]
	v_mfma_f32_16x16x32_bf16 v[70:73], v[196:199], v[180:183], v[70:73]
	v_mfma_f32_16x16x32_bf16 v[66:69], v[206:209], v[180:183], v[66:69]
	v_mfma_f32_16x16x32_bf16 v[130:133], v[200:203], v[146:149], v[130:133]
	v_mfma_f32_16x16x32_bf16 v[122:125], v[210:213], v[146:149], v[122:125]
	v_mfma_f32_16x16x32_bf16 v[102:105], v[200:203], v[158:161], v[102:105]
	v_mfma_f32_16x16x32_bf16 v[98:101], v[210:213], v[158:161], v[98:101]
	v_mfma_f32_16x16x32_bf16 v[86:89], v[200:203], v[176:179], v[86:89]
	v_mfma_f32_16x16x32_bf16 v[82:85], v[210:213], v[176:179], v[82:85]
	v_mfma_f32_16x16x32_bf16 v[70:73], v[200:203], v[188:191], v[70:73]
	v_mfma_f32_16x16x32_bf16 v[66:69], v[210:213], v[188:191], v[66:69]
	s_setprio 0
	s_mov_b32 m0, s44
	v_lshl_add_u64 v[192:193], v[216:217], 0, s[74:75]
	s_barrier
	ds_read_b128 v[138:141], v187 offset:49152
	ds_read_b128 v[146:149], v187 offset:50176
	ds_read_b128 v[154:157], v187 offset:51200
	ds_read_b128 v[158:161], v187 offset:52224
	ds_read_b128 v[172:175], v187 offset:53248
	ds_read_b128 v[176:179], v187 offset:54272
	ds_read_b128 v[180:183], v187 offset:55296
	ds_read_b128 v[188:191], v187 offset:56320
	global_load_lds_dwordx4 v[192:193], off
	v_lshl_add_u64 v[192:193], v[218:219], 0, s[74:75]
	s_mov_b32 m0, s45
	s_nop 0
	global_load_lds_dwordx4 v[192:193], off
	s_barrier
	s_waitcnt lgkmcnt(0)
	s_setprio 1
	s_waitcnt lgkmcnt(0)
	v_mfma_f32_16x16x32_bf16 v[62:65], v[106:109], v[138:141], v[62:65]
	v_mfma_f32_16x16x32_bf16 v[58:61], v[126:129], v[138:141], v[58:61]
	v_mfma_f32_16x16x32_bf16 v[46:49], v[106:109], v[154:157], v[46:49]
	v_mfma_f32_16x16x32_bf16 v[42:45], v[126:129], v[154:157], v[42:45]
	v_mfma_f32_16x16x32_bf16 v[30:33], v[106:109], v[172:175], v[30:33]
	v_mfma_f32_16x16x32_bf16 v[26:29], v[126:129], v[172:175], v[26:29]
	v_mfma_f32_16x16x32_bf16 v[14:17], v[106:109], v[180:183], v[14:17]
	v_mfma_f32_16x16x32_bf16 v[10:13], v[126:129], v[180:183], v[10:13]
	v_mfma_f32_16x16x32_bf16 v[62:65], v[110:113], v[146:149], v[62:65]
	v_mfma_f32_16x16x32_bf16 v[58:61], v[134:137], v[146:149], v[58:61]
	v_mfma_f32_16x16x32_bf16 v[46:49], v[110:113], v[158:161], v[46:49]
	v_mfma_f32_16x16x32_bf16 v[42:45], v[134:137], v[158:161], v[42:45]
	v_mfma_f32_16x16x32_bf16 v[30:33], v[110:113], v[176:179], v[30:33]
	v_mfma_f32_16x16x32_bf16 v[26:29], v[134:137], v[176:179], v[26:29]
	v_mfma_f32_16x16x32_bf16 v[14:17], v[110:113], v[188:191], v[14:17]
	v_mfma_f32_16x16x32_bf16 v[10:13], v[134:137], v[188:191], v[10:13]
	s_setprio 0
	s_barrier
	s_add_u32 s2, s14, 0x20080
	s_addc_u32 s3, s15, 0
	s_add_i32 s14, s35, s17
	v_lshl_add_u64 v[106:107], s[2:3], 0, v[0:1]
	s_mov_b32 m0, s14
	s_nop 0
	global_load_lds_dwordx4 v[106:107], off
	v_lshl_add_u64 v[106:107], s[2:3], 0, v[162:163]
	s_add_i32 m0, s14, 0x2000
	s_nop 0
	global_load_lds_dwordx4 v[106:107], off
	s_waitcnt vmcnt(10)
	s_barrier
	s_setprio 1
	v_mfma_f32_16x16x32_bf16 v[54:57], v[196:199], v[138:141], v[54:57]
	v_mfma_f32_16x16x32_bf16 v[50:53], v[206:209], v[138:141], v[50:53]
	v_mfma_f32_16x16x32_bf16 v[38:41], v[196:199], v[154:157], v[38:41]
	v_mfma_f32_16x16x32_bf16 v[34:37], v[206:209], v[154:157], v[34:37]
	v_mfma_f32_16x16x32_bf16 v[22:25], v[196:199], v[172:175], v[22:25]
	v_mfma_f32_16x16x32_bf16 v[18:21], v[206:209], v[172:175], v[18:21]
	v_mfma_f32_16x16x32_bf16 v[6:9], v[196:199], v[180:183], v[6:9]
	v_mfma_f32_16x16x32_bf16 v[2:5], v[206:209], v[180:183], v[2:5]
	v_mfma_f32_16x16x32_bf16 v[54:57], v[200:203], v[146:149], v[54:57]
	v_mfma_f32_16x16x32_bf16 v[50:53], v[210:213], v[146:149], v[50:53]
	v_mfma_f32_16x16x32_bf16 v[38:41], v[200:203], v[158:161], v[38:41]
	v_mfma_f32_16x16x32_bf16 v[34:37], v[210:213], v[158:161], v[34:37]
	v_mfma_f32_16x16x32_bf16 v[22:25], v[200:203], v[176:179], v[22:25]
	v_mfma_f32_16x16x32_bf16 v[18:21], v[210:213], v[176:179], v[18:21]
	v_mfma_f32_16x16x32_bf16 v[6:9], v[200:203], v[188:191], v[6:9]
	v_mfma_f32_16x16x32_bf16 v[2:5], v[210:213], v[188:191], v[2:5]
	s_setprio 0
	s_add_i32 s54, s54, 2
	s_add_u32 s12, s12, 0x100
	s_addc_u32 s13, s13, 0
	s_add_u32 s53, s53, 0x100
	s_addc_u32 s50, s50, 0
	s_cmp_gt_u32 s54, 5
	s_barrier
	s_cbranch_scc0 .LBB0_402
	v_lshl_or_b32 v108, s5, 8, v186
	v_lshl_add_u32 v106, s49, 8, v184
	v_ashrrev_i32_e32 v109, 31, v108
	v_readlane_b32 s2, v250, 57
	v_lshlrev_b64 v[172:173], 1, v[108:109]
	v_readlane_b32 s3, v250, 58
	v_ashrrev_i32_e32 v107, 31, v106
	v_lshlrev_b64 v[176:177], 10, v[106:107]
	v_lshl_add_u64 v[174:175], s[2:3], 0, v[172:173]
	v_lshl_add_u64 v[108:109], v[174:175], 0, v[176:177]
	global_load_dwordx4 v[158:161], v[108:109], off
	global_load_dwordx4 v[154:157], v[108:109], off offset:256
	v_or_b32_e32 v108, 16, v106
	v_ashrrev_i32_e32 v109, 31, v108
	v_lshlrev_b64 v[182:183], 10, v[108:109]
	v_lshl_add_u64 v[108:109], v[174:175], 0, v[182:183]
	global_load_dwordx4 v[146:149], v[108:109], off
	global_load_dwordx4 v[138:141], v[108:109], off offset:256
	v_mul_f32_e32 v150, 0xbfb8aa3b, v150
	v_mul_f32_e32 v151, 0xbfb8aa3b, v151
	v_exp_f32_e32 v150, v150
	v_exp_f32_e32 v151, v151
	v_mul_f32_e32 v142, 0xbfb8aa3b, v142
	v_mul_f32_e32 v143, 0xbfb8aa3b, v143
	v_add_f32_e32 v150, 1.0, v150
	v_add_f32_e32 v151, 1.0, v151
	v_rcp_f32_e32 v150, v150
	v_rcp_f32_e32 v151, v151
	v_exp_f32_e32 v142, v142
	v_exp_f32_e32 v143, v143
	v_mul_f32_e32 v130, 0xbfb8aa3b, v130
	v_mul_f32_e32 v131, 0xbfb8aa3b, v131
	v_add_f32_e32 v142, 1.0, v142
	v_add_f32_e32 v143, 1.0, v143
	v_rcp_f32_e32 v142, v142
	v_rcp_f32_e32 v143, v143
	v_exp_f32_e32 v130, v130
	v_exp_f32_e32 v131, v131
	v_mul_f32_e32 v122, 0xbfb8aa3b, v122
	v_mul_f32_e32 v123, 0xbfb8aa3b, v123
	v_add_f32_e32 v130, 1.0, v130
	v_add_f32_e32 v131, 1.0, v131
	v_rcp_f32_e32 v130, v130
	v_rcp_f32_e32 v131, v131
	v_exp_f32_e32 v122, v122
	v_exp_f32_e32 v123, v123
	v_or_b32_e32 v108, 32, v106
	v_ashrrev_i32_e32 v109, 31, v108
	v_lshlrev_b64 v[180:181], 10, v[108:109]
	v_lshl_add_u64 v[108:109], v[174:175], 0, v[180:181]
	v_add_f32_e32 v122, 1.0, v122
	v_add_f32_e32 v123, 1.0, v123
	global_load_dwordx4 v[134:137], v[108:109], off
	global_load_dwordx4 v[126:129], v[108:109], off offset:256
	v_rcp_f32_e32 v122, v122
	v_rcp_f32_e32 v123, v123
	v_mul_f32_e32 v118, 0xbfb8aa3b, v118
	v_mul_f32_e32 v119, 0xbfb8aa3b, v119
	v_exp_f32_e32 v118, v118
	v_exp_f32_e32 v119, v119
	v_mul_f32_e32 v114, 0xbfb8aa3b, v114
	v_mul_f32_e32 v115, 0xbfb8aa3b, v115
	v_add_f32_e32 v118, 1.0, v118
	v_add_f32_e32 v119, 1.0, v119
	v_rcp_f32_e32 v118, v118
	v_rcp_f32_e32 v119, v119
	v_exp_f32_e32 v114, v114
	v_exp_f32_e32 v115, v115
	v_mul_f32_e32 v102, 0xbfb8aa3b, v102
	v_mul_f32_e32 v103, 0xbfb8aa3b, v103
	v_add_f32_e32 v114, 1.0, v114
	v_add_f32_e32 v115, 1.0, v115
	v_rcp_f32_e32 v114, v114
	v_rcp_f32_e32 v115, v115
	v_exp_f32_e32 v102, v102
	v_exp_f32_e32 v103, v103
	v_mul_f32_e32 v98, 0xbfb8aa3b, v98
	v_mul_f32_e32 v99, 0xbfb8aa3b, v99
	v_add_f32_e32 v102, 1.0, v102
	v_add_f32_e32 v103, 1.0, v103
	v_rcp_f32_e32 v102, v102
	v_rcp_f32_e32 v103, v103
	v_exp_f32_e32 v98, v98
	v_exp_f32_e32 v99, v99
	v_or_b32_e32 v106, 48, v106
	v_ashrrev_i32_e32 v107, 31, v106
	v_lshlrev_b64 v[178:179], 10, v[106:107]
	v_lshl_add_u64 v[106:107], v[174:175], 0, v[178:179]
	v_add_f32_e32 v98, 1.0, v98
	v_add_f32_e32 v99, 1.0, v99
	global_load_dwordx4 v[110:113], v[106:107], off
	s_nop 0
	global_load_dwordx4 v[106:109], v[106:107], off offset:256
	v_rcp_f32_e32 v98, v98
	s_waitcnt vmcnt(0)
	v_lshlrev_b32_e32 v188, 16, v158
	v_and_b32_e32 v189, 0xffff0000, v158
	v_pk_mul_f32 v[150:151], v[150:151], v[188:189]
	v_lshlrev_b32_e32 v158, 16, v159
	v_cvt_pk_bf16_f32 v150, v150, v151
	v_mul_f32_e32 v151, 0xbfb8aa3b, v152
	v_exp_f32_e32 v151, v151
	v_and_b32_e32 v159, 0xffff0000, v159
	v_rcp_f32_e32 v99, v99
	v_mul_f32_e32 v94, 0xbfb8aa3b, v94
	v_add_f32_e32 v151, 1.0, v151
	v_rcp_f32_e32 v152, v151
	v_mul_f32_e32 v151, 0xbfb8aa3b, v153
	v_exp_f32_e32 v151, v151
	v_mul_f32_e32 v95, 0xbfb8aa3b, v95
	v_exp_f32_e32 v94, v94
	v_exp_f32_e32 v95, v95
	v_add_f32_e32 v151, 1.0, v151
	v_rcp_f32_e32 v153, v151
	v_add_f32_e32 v94, 1.0, v94
	v_add_f32_e32 v95, 1.0, v95
	v_rcp_f32_e32 v94, v94
	v_pk_mul_f32 v[152:153], v[152:153], v[158:159]
	v_rcp_f32_e32 v95, v95
	v_cvt_pk_bf16_f32 v151, v152, v153
	v_lshlrev_b32_e32 v152, 16, v160
	v_and_b32_e32 v153, 0xffff0000, v160
	v_pk_mul_f32 v[142:143], v[142:143], v[152:153]
	v_mul_f32_e32 v90, 0xbfb8aa3b, v90
	v_cvt_pk_bf16_f32 v152, v142, v143
	v_mul_f32_e32 v142, 0xbfb8aa3b, v144
	v_mul_f32_e32 v143, 0xbfb8aa3b, v145
	v_exp_f32_e32 v142, v142
	v_exp_f32_e32 v143, v143
	v_lshlrev_b32_e32 v144, 16, v161
	v_and_b32_e32 v145, 0xffff0000, v161
	v_add_f32_e32 v142, 1.0, v142
	v_add_f32_e32 v143, 1.0, v143
	v_rcp_f32_e32 v142, v142
	v_rcp_f32_e32 v143, v143
	v_mul_f32_e32 v91, 0xbfb8aa3b, v91
	v_exp_f32_e32 v90, v90
	v_exp_f32_e32 v91, v91
	v_pk_mul_f32 v[142:143], v[142:143], v[144:145]
	v_lshlrev_b32_e32 v144, 16, v154
	v_and_b32_e32 v145, 0xffff0000, v154
	v_pk_mul_f32 v[130:131], v[130:131], v[144:145]
	v_lshlrev_b32_e32 v144, 16, v155
	v_cvt_pk_bf16_f32 v130, v130, v131
	v_mul_f32_e32 v131, 0xbfb8aa3b, v132
	v_exp_f32_e32 v131, v131
	v_and_b32_e32 v145, 0xffff0000, v155
	v_add_f32_e32 v90, 1.0, v90
	v_add_f32_e32 v91, 1.0, v91
	v_add_f32_e32 v131, 1.0, v131
	v_rcp_f32_e32 v132, v131
	v_mul_f32_e32 v131, 0xbfb8aa3b, v133
	v_exp_f32_e32 v131, v131
	v_rcp_f32_e32 v90, v90
	v_rcp_f32_e32 v91, v91
	v_mul_f32_e32 v86, 0xbfb8aa3b, v86
	v_add_f32_e32 v131, 1.0, v131
	v_rcp_f32_e32 v133, v131
	v_mul_f32_e32 v87, 0xbfb8aa3b, v87
	v_exp_f32_e32 v86, v86
	v_exp_f32_e32 v87, v87
	v_pk_mul_f32 v[132:133], v[132:133], v[144:145]
	v_mul_f32_e32 v82, 0xbfb8aa3b, v82
	v_cvt_pk_bf16_f32 v131, v132, v133
	v_lshlrev_b32_e32 v132, 16, v156
	v_and_b32_e32 v133, 0xffff0000, v156
	v_pk_mul_f32 v[122:123], v[122:123], v[132:133]
	v_add_f32_e32 v86, 1.0, v86
	v_cvt_pk_bf16_f32 v132, v122, v123
	v_mul_f32_e32 v122, 0xbfb8aa3b, v124
	v_mul_f32_e32 v123, 0xbfb8aa3b, v125
	v_exp_f32_e32 v122, v122
	v_exp_f32_e32 v123, v123
	v_lshlrev_b32_e32 v124, 16, v157
	v_and_b32_e32 v125, 0xffff0000, v157
	v_add_f32_e32 v122, 1.0, v122
	v_add_f32_e32 v123, 1.0, v123
	v_rcp_f32_e32 v122, v122
	v_rcp_f32_e32 v123, v123
	v_add_f32_e32 v87, 1.0, v87
	v_rcp_f32_e32 v86, v86
	v_rcp_f32_e32 v87, v87
	v_pk_mul_f32 v[122:123], v[122:123], v[124:125]
	v_mul_f32_e32 v83, 0xbfb8aa3b, v83
	v_cvt_pk_bf16_f32 v133, v122, v123
	v_lshlrev_b32_e32 v122, 16, v146
	v_and_b32_e32 v123, 0xffff0000, v146
	v_pk_mul_f32 v[118:119], v[118:119], v[122:123]
	v_lshlrev_b32_e32 v122, 16, v147
	v_cvt_pk_bf16_f32 v118, v118, v119
	v_mul_f32_e32 v119, 0xbfb8aa3b, v120
	v_exp_f32_e32 v119, v119
	v_and_b32_e32 v123, 0xffff0000, v147
	v_exp_f32_e32 v82, v82
	v_exp_f32_e32 v83, v83
	v_add_f32_e32 v119, 1.0, v119
	v_rcp_f32_e32 v120, v119
	v_mul_f32_e32 v119, 0xbfb8aa3b, v121
	v_exp_f32_e32 v119, v119
	v_add_f32_e32 v82, 1.0, v82
	v_add_f32_e32 v83, 1.0, v83
	v_rcp_f32_e32 v82, v82
	v_add_f32_e32 v119, 1.0, v119
	v_rcp_f32_e32 v121, v119
	v_rcp_f32_e32 v83, v83
	v_mul_f32_e32 v78, 0xbfb8aa3b, v78
	v_mul_f32_e32 v79, 0xbfb8aa3b, v79
	v_pk_mul_f32 v[120:121], v[120:121], v[122:123]
	v_exp_f32_e32 v78, v78
	v_cvt_pk_bf16_f32 v119, v120, v121
	v_lshlrev_b32_e32 v120, 16, v148
	v_and_b32_e32 v121, 0xffff0000, v148
	v_pk_mul_f32 v[114:115], v[114:115], v[120:121]
	v_exp_f32_e32 v79, v79
	v_cvt_pk_bf16_f32 v120, v114, v115
	v_mul_f32_e32 v114, 0xbfb8aa3b, v116
	v_mul_f32_e32 v115, 0xbfb8aa3b, v117
	v_exp_f32_e32 v114, v114
	v_exp_f32_e32 v115, v115
	v_lshlrev_b32_e32 v116, 16, v149
	v_and_b32_e32 v117, 0xffff0000, v149
	v_add_f32_e32 v114, 1.0, v114
	v_add_f32_e32 v115, 1.0, v115
	v_rcp_f32_e32 v114, v114
	v_rcp_f32_e32 v115, v115
	v_add_f32_e32 v78, 1.0, v78
	v_add_f32_e32 v79, 1.0, v79
	v_rcp_f32_e32 v78, v78
	v_pk_mul_f32 v[114:115], v[114:115], v[116:117]
	v_lshlrev_b32_e32 v116, 16, v138
	v_and_b32_e32 v117, 0xffff0000, v138
	v_pk_mul_f32 v[102:103], v[102:103], v[116:117]
	v_lshlrev_b32_e32 v116, 16, v139
	v_cvt_pk_bf16_f32 v102, v102, v103
	v_mul_f32_e32 v103, 0xbfb8aa3b, v104
	v_exp_f32_e32 v103, v103
	v_and_b32_e32 v117, 0xffff0000, v139
	v_rcp_f32_e32 v79, v79
	v_mul_f32_e32 v74, 0xbfb8aa3b, v74
	v_add_f32_e32 v103, 1.0, v103
	v_rcp_f32_e32 v104, v103
	v_mul_f32_e32 v103, 0xbfb8aa3b, v105
	v_exp_f32_e32 v103, v103
	v_mul_f32_e32 v75, 0xbfb8aa3b, v75
	v_exp_f32_e32 v74, v74
	v_exp_f32_e32 v75, v75
	v_add_f32_e32 v103, 1.0, v103
	v_rcp_f32_e32 v105, v103
	v_add_f32_e32 v74, 1.0, v74
	v_add_f32_e32 v75, 1.0, v75
	v_rcp_f32_e32 v74, v74
	v_pk_mul_f32 v[104:105], v[104:105], v[116:117]
	v_rcp_f32_e32 v75, v75
	v_cvt_pk_bf16_f32 v103, v104, v105
	v_lshlrev_b32_e32 v104, 16, v140
	v_and_b32_e32 v105, 0xffff0000, v140
	v_pk_mul_f32 v[98:99], v[98:99], v[104:105]
	v_mul_f32_e32 v70, 0xbfb8aa3b, v70
	v_cvt_pk_bf16_f32 v104, v98, v99
	v_mul_f32_e32 v98, 0xbfb8aa3b, v100
	v_mul_f32_e32 v99, 0xbfb8aa3b, v101
	v_exp_f32_e32 v98, v98
	v_exp_f32_e32 v99, v99
	v_lshlrev_b32_e32 v100, 16, v141
	v_and_b32_e32 v101, 0xffff0000, v141
	v_add_f32_e32 v98, 1.0, v98
	v_add_f32_e32 v99, 1.0, v99
	v_rcp_f32_e32 v98, v98
	v_rcp_f32_e32 v99, v99
	v_mul_f32_e32 v71, 0xbfb8aa3b, v71
	v_exp_f32_e32 v70, v70
	v_exp_f32_e32 v71, v71
	v_pk_mul_f32 v[98:99], v[98:99], v[100:101]
	v_mul_f32_e32 v66, 0xbfb8aa3b, v66
	v_cvt_pk_bf16_f32 v105, v98, v99
	v_lshlrev_b32_e32 v98, 16, v134
	v_and_b32_e32 v99, 0xffff0000, v134
	v_pk_mul_f32 v[94:95], v[94:95], v[98:99]
	v_lshlrev_b32_e32 v98, 16, v135
	v_cvt_pk_bf16_f32 v94, v94, v95
	v_mul_f32_e32 v95, 0xbfb8aa3b, v96
	v_exp_f32_e32 v95, v95
	v_and_b32_e32 v99, 0xffff0000, v135
	v_add_f32_e32 v70, 1.0, v70
	v_add_f32_e32 v71, 1.0, v71
	v_add_f32_e32 v95, 1.0, v95
	v_rcp_f32_e32 v96, v95
	v_mul_f32_e32 v95, 0xbfb8aa3b, v97
	v_exp_f32_e32 v95, v95
	v_rcp_f32_e32 v70, v70
	v_rcp_f32_e32 v71, v71
	v_mul_f32_e32 v67, 0xbfb8aa3b, v67
	v_add_f32_e32 v95, 1.0, v95
	v_rcp_f32_e32 v97, v95
	v_exp_f32_e32 v66, v66
	v_exp_f32_e32 v67, v67
	v_readlane_b32 s2, v253, 6
	v_pk_mul_f32 v[96:97], v[96:97], v[98:99]
	v_add_f32_e32 v66, 1.0, v66
	v_cvt_pk_bf16_f32 v95, v96, v97
	v_lshlrev_b32_e32 v96, 16, v136
	v_and_b32_e32 v97, 0xffff0000, v136
	v_pk_mul_f32 v[90:91], v[90:91], v[96:97]
	v_add_f32_e32 v67, 1.0, v67
	v_cvt_pk_bf16_f32 v96, v90, v91
	v_mul_f32_e32 v90, 0xbfb8aa3b, v92
	v_mul_f32_e32 v91, 0xbfb8aa3b, v93
	v_exp_f32_e32 v90, v90
	v_exp_f32_e32 v91, v91
	v_lshlrev_b32_e32 v92, 16, v137
	v_and_b32_e32 v93, 0xffff0000, v137
	v_add_f32_e32 v90, 1.0, v90
	v_add_f32_e32 v91, 1.0, v91
	v_rcp_f32_e32 v90, v90
	v_rcp_f32_e32 v91, v91
	v_rcp_f32_e32 v66, v66
	v_rcp_f32_e32 v67, v67
	v_readlane_b32 s3, v253, 7
	v_pk_mul_f32 v[90:91], v[90:91], v[92:93]
	v_lshlrev_b32_e32 v92, 16, v126
	v_and_b32_e32 v93, 0xffff0000, v126
	v_pk_mul_f32 v[86:87], v[86:87], v[92:93]
	v_lshlrev_b32_e32 v92, 16, v127
	v_cvt_pk_bf16_f32 v86, v86, v87
	v_mul_f32_e32 v87, 0xbfb8aa3b, v88
	v_exp_f32_e32 v87, v87
	v_and_b32_e32 v93, 0xffff0000, v127
	v_cvt_pk_bf16_f32 v121, v114, v115
	v_lshl_add_u64 v[114:115], s[2:3], 0, v[182:183]
	v_add_f32_e32 v87, 1.0, v87
	v_rcp_f32_e32 v88, v87
	v_mul_f32_e32 v87, 0xbfb8aa3b, v89
	v_exp_f32_e32 v87, v87
	v_cvt_pk_bf16_f32 v153, v142, v143
	v_lshl_add_u64 v[142:143], s[2:3], 0, v[176:177]
	v_lshl_add_u64 v[114:115], v[114:115], 0, v[172:173]
	v_add_f32_e32 v87, 1.0, v87
	v_rcp_f32_e32 v89, v87
	v_cvt_pk_bf16_f32 v97, v90, v91
	v_lshl_add_u64 v[90:91], s[2:3], 0, v[180:181]
	s_mov_b64 s[12:13], 0x20000
	v_pk_mul_f32 v[88:89], v[88:89], v[92:93]
	v_lshl_add_u64 v[142:143], v[142:143], 0, v[172:173]
	v_cvt_pk_bf16_f32 v87, v88, v89
	v_lshlrev_b32_e32 v88, 16, v128
	v_and_b32_e32 v89, 0xffff0000, v128
	v_pk_mul_f32 v[82:83], v[82:83], v[88:89]
	global_store_dwordx4 v[114:115], v[102:105], off offset:256
	v_cvt_pk_bf16_f32 v88, v82, v83
	v_mul_f32_e32 v82, 0xbfb8aa3b, v84
	v_mul_f32_e32 v83, 0xbfb8aa3b, v85
	v_exp_f32_e32 v82, v82
	v_exp_f32_e32 v83, v83
	v_lshlrev_b32_e32 v84, 16, v129
	v_and_b32_e32 v85, 0xffff0000, v129
	v_add_f32_e32 v82, 1.0, v82
	v_add_f32_e32 v83, 1.0, v83
	v_rcp_f32_e32 v82, v82
	v_rcp_f32_e32 v83, v83
	v_lshl_add_u64 v[90:91], v[90:91], 0, v[172:173]
	v_lshl_add_u64 v[104:105], v[176:177], 0, s[12:13]
	global_store_dwordx4 v[142:143], v[150:153], off
	v_pk_mul_f32 v[82:83], v[82:83], v[84:85]
	global_store_dwordx4 v[142:143], v[130:133], off offset:256
	v_cvt_pk_bf16_f32 v89, v82, v83
	v_lshlrev_b32_e32 v82, 16, v110
	v_and_b32_e32 v83, 0xffff0000, v110
	v_pk_mul_f32 v[78:79], v[78:79], v[82:83]
	v_lshlrev_b32_e32 v82, 16, v111
	v_cvt_pk_bf16_f32 v78, v78, v79
	v_mul_f32_e32 v79, 0xbfb8aa3b, v80
	v_exp_f32_e32 v79, v79
	v_and_b32_e32 v83, 0xffff0000, v111
	global_store_dwordx4 v[114:115], v[118:121], off
	global_store_dwordx4 v[90:91], v[94:97], off
	v_add_f32_e32 v79, 1.0, v79
	v_rcp_f32_e32 v80, v79
	v_mul_f32_e32 v79, 0xbfb8aa3b, v81
	v_exp_f32_e32 v79, v79
	global_store_dwordx4 v[90:91], v[86:89], off offset:256
	s_mov_b64 s[12:13], 0x24000
	v_lshl_add_u64 v[102:103], v[176:177], 0, s[12:13]
	v_add_f32_e32 v79, 1.0, v79
	v_rcp_f32_e32 v81, v79
	v_mul_f32_e32 v62, 0xbfb8aa3b, v62
	v_mul_f32_e32 v63, 0xbfb8aa3b, v63
	v_exp_f32_e32 v62, v62
	v_pk_mul_f32 v[80:81], v[80:81], v[82:83]
	v_exp_f32_e32 v63, v63
	v_cvt_pk_bf16_f32 v79, v80, v81
	v_lshlrev_b32_e32 v80, 16, v112
	v_and_b32_e32 v81, 0xffff0000, v112
	v_pk_mul_f32 v[74:75], v[74:75], v[80:81]
	v_add_f32_e32 v62, 1.0, v62
	v_cvt_pk_bf16_f32 v80, v74, v75
	v_mul_f32_e32 v74, 0xbfb8aa3b, v76
	v_mul_f32_e32 v75, 0xbfb8aa3b, v77
	v_exp_f32_e32 v74, v74
	v_exp_f32_e32 v75, v75
	v_lshlrev_b32_e32 v76, 16, v113
	v_and_b32_e32 v77, 0xffff0000, v113
	v_add_f32_e32 v74, 1.0, v74
	v_add_f32_e32 v75, 1.0, v75
	v_rcp_f32_e32 v74, v74
	v_rcp_f32_e32 v75, v75
	v_add_f32_e32 v63, 1.0, v63
	v_rcp_f32_e32 v62, v62
	v_rcp_f32_e32 v63, v63
	v_pk_mul_f32 v[74:75], v[74:75], v[76:77]
	v_lshlrev_b32_e32 v76, 16, v106
	v_and_b32_e32 v77, 0xffff0000, v106
	v_pk_mul_f32 v[70:71], v[70:71], v[76:77]
	v_lshlrev_b32_e32 v76, 16, v107
	v_cvt_pk_bf16_f32 v70, v70, v71
	v_mul_f32_e32 v71, 0xbfb8aa3b, v72
	v_exp_f32_e32 v71, v71
	v_and_b32_e32 v77, 0xffff0000, v107
	v_cvt_pk_bf16_f32 v81, v74, v75
	v_lshl_add_u64 v[74:75], s[2:3], 0, v[178:179]
	v_add_f32_e32 v71, 1.0, v71
	v_rcp_f32_e32 v72, v71
	v_mul_f32_e32 v71, 0xbfb8aa3b, v73
	v_exp_f32_e32 v71, v71
	v_lshl_add_u64 v[74:75], v[74:75], 0, v[172:173]
	global_store_dwordx4 v[74:75], v[78:81], off
	v_mul_f32_e32 v58, 0xbfb8aa3b, v58
	v_add_f32_e32 v71, 1.0, v71
	v_rcp_f32_e32 v73, v71
	v_mul_f32_e32 v59, 0xbfb8aa3b, v59
	v_exp_f32_e32 v58, v58
	v_exp_f32_e32 v59, v59
	v_pk_mul_f32 v[72:73], v[72:73], v[76:77]
	v_mul_f32_e32 v54, 0xbfb8aa3b, v54
	v_cvt_pk_bf16_f32 v71, v72, v73
	v_lshlrev_b32_e32 v72, 16, v108
	v_and_b32_e32 v73, 0xffff0000, v108
	v_pk_mul_f32 v[66:67], v[66:67], v[72:73]
	v_add_f32_e32 v58, 1.0, v58
	v_cvt_pk_bf16_f32 v72, v66, v67
	v_mul_f32_e32 v66, 0xbfb8aa3b, v68
	v_mul_f32_e32 v67, 0xbfb8aa3b, v69
	v_exp_f32_e32 v66, v66
	v_exp_f32_e32 v67, v67
	v_lshlrev_b32_e32 v68, 16, v109
	v_and_b32_e32 v69, 0xffff0000, v109
	v_add_f32_e32 v66, 1.0, v66
	v_add_f32_e32 v67, 1.0, v67
	v_rcp_f32_e32 v66, v66
	v_rcp_f32_e32 v67, v67
	v_add_f32_e32 v59, 1.0, v59
	v_rcp_f32_e32 v58, v58
	v_rcp_f32_e32 v59, v59
	v_pk_mul_f32 v[66:67], v[66:67], v[68:69]
	v_mul_f32_e32 v55, 0xbfb8aa3b, v55
	v_cvt_pk_bf16_f32 v73, v66, v67
	global_store_dwordx4 v[74:75], v[70:73], off offset:256
	v_lshl_add_u64 v[66:67], v[174:175], 0, v[104:105]
	global_load_dwordx4 v[90:93], v[66:67], off
	global_load_dwordx4 v[94:97], v[66:67], off offset:256
	v_lshl_add_u64 v[66:67], v[174:175], 0, v[102:103]
	global_load_dwordx4 v[86:89], v[66:67], off
	global_load_dwordx4 v[82:85], v[66:67], off offset:256
	v_exp_f32_e32 v54, v54
	v_exp_f32_e32 v55, v55
	v_mul_f32_e32 v50, 0xbfb8aa3b, v50
	v_mul_f32_e32 v51, 0xbfb8aa3b, v51
	v_add_f32_e32 v54, 1.0, v54
	v_add_f32_e32 v55, 1.0, v55
	v_rcp_f32_e32 v54, v54
	v_rcp_f32_e32 v55, v55
	v_exp_f32_e32 v50, v50
	v_exp_f32_e32 v51, v51
	s_mov_b64 s[12:13], 0x28000
	v_lshl_add_u64 v[100:101], v[176:177], 0, s[12:13]
	v_lshl_add_u64 v[66:67], v[174:175], 0, v[100:101]
	v_add_f32_e32 v50, 1.0, v50
	v_add_f32_e32 v51, 1.0, v51
	global_load_dwordx4 v[78:81], v[66:67], off
	global_load_dwordx4 v[74:77], v[66:67], off offset:256
	v_rcp_f32_e32 v50, v50
	v_rcp_f32_e32 v51, v51
	v_mul_f32_e32 v46, 0xbfb8aa3b, v46
	v_mul_f32_e32 v47, 0xbfb8aa3b, v47
	v_exp_f32_e32 v46, v46
	v_exp_f32_e32 v47, v47
	v_mul_f32_e32 v42, 0xbfb8aa3b, v42
	v_mul_f32_e32 v43, 0xbfb8aa3b, v43
	v_add_f32_e32 v46, 1.0, v46
	v_add_f32_e32 v47, 1.0, v47
	v_rcp_f32_e32 v46, v46
	v_rcp_f32_e32 v47, v47
	v_exp_f32_e32 v42, v42
	v_exp_f32_e32 v43, v43
	v_mul_f32_e32 v38, 0xbfb8aa3b, v38
	v_mul_f32_e32 v39, 0xbfb8aa3b, v39
	v_add_f32_e32 v42, 1.0, v42
	v_add_f32_e32 v43, 1.0, v43
	v_rcp_f32_e32 v42, v42
	v_rcp_f32_e32 v43, v43
	v_exp_f32_e32 v38, v38
	v_exp_f32_e32 v39, v39
	v_mul_f32_e32 v34, 0xbfb8aa3b, v34
	v_mul_f32_e32 v35, 0xbfb8aa3b, v35
	v_add_f32_e32 v38, 1.0, v38
	v_add_f32_e32 v39, 1.0, v39
	v_rcp_f32_e32 v38, v38
	v_rcp_f32_e32 v39, v39
	v_exp_f32_e32 v34, v34
	v_exp_f32_e32 v35, v35
	s_mov_b64 s[12:13], 0x2c000
	v_lshl_add_u64 v[98:99], v[176:177], 0, s[12:13]
	v_lshl_add_u64 v[66:67], v[174:175], 0, v[98:99]
	v_add_f32_e32 v34, 1.0, v34
	v_add_f32_e32 v35, 1.0, v35
	global_load_dwordx4 v[70:73], v[66:67], off
	s_nop 0
	global_load_dwordx4 v[66:69], v[66:67], off offset:256
	v_rcp_f32_e32 v34, v34
	v_rcp_f32_e32 v35, v35
	v_mul_f32_e32 v30, 0xbfb8aa3b, v30
	v_mul_f32_e32 v31, 0xbfb8aa3b, v31
	v_exp_f32_e32 v30, v30
	v_exp_f32_e32 v31, v31
	v_mul_f32_e32 v26, 0xbfb8aa3b, v26
	v_mul_f32_e32 v27, 0xbfb8aa3b, v27
	v_add_f32_e32 v30, 1.0, v30
	v_add_f32_e32 v31, 1.0, v31
	v_rcp_f32_e32 v30, v30
	v_rcp_f32_e32 v31, v31
	v_exp_f32_e32 v26, v26
	v_exp_f32_e32 v27, v27
	v_mul_f32_e32 v22, 0xbfb8aa3b, v22
	v_mul_f32_e32 v23, 0xbfb8aa3b, v23
	v_add_f32_e32 v26, 1.0, v26
	v_add_f32_e32 v27, 1.0, v27
	v_rcp_f32_e32 v26, v26
	v_rcp_f32_e32 v27, v27
	v_exp_f32_e32 v22, v22
	v_exp_f32_e32 v23, v23
	v_mul_f32_e32 v18, 0xbfb8aa3b, v18
	v_mul_f32_e32 v19, 0xbfb8aa3b, v19
	s_waitcnt vmcnt(0)
	v_lshlrev_b32_e32 v106, 16, v90
	v_and_b32_e32 v107, 0xffff0000, v90
	v_pk_mul_f32 v[62:63], v[62:63], v[106:107]
	v_lshlrev_b32_e32 v90, 16, v91
	v_cvt_pk_bf16_f32 v62, v62, v63
	v_mul_f32_e32 v63, 0xbfb8aa3b, v64
	v_exp_f32_e32 v63, v63
	v_and_b32_e32 v91, 0xffff0000, v91
	v_add_f32_e32 v22, 1.0, v22
	v_add_f32_e32 v23, 1.0, v23
	v_add_f32_e32 v63, 1.0, v63
	v_rcp_f32_e32 v64, v63
	v_mul_f32_e32 v63, 0xbfb8aa3b, v65
	v_exp_f32_e32 v63, v63
	v_rcp_f32_e32 v22, v22
	v_rcp_f32_e32 v23, v23
	v_exp_f32_e32 v18, v18
	v_add_f32_e32 v63, 1.0, v63
	v_rcp_f32_e32 v65, v63
	v_exp_f32_e32 v19, v19
	v_add_f32_e32 v18, 1.0, v18
	v_rcp_f32_e32 v18, v18
	v_pk_mul_f32 v[64:65], v[64:65], v[90:91]
	v_add_f32_e32 v19, 1.0, v19
	v_cvt_pk_bf16_f32 v63, v64, v65
	v_lshlrev_b32_e32 v64, 16, v92
	v_and_b32_e32 v65, 0xffff0000, v92
	v_pk_mul_f32 v[58:59], v[58:59], v[64:65]
	v_rcp_f32_e32 v19, v19
	v_cvt_pk_bf16_f32 v64, v58, v59
	v_mul_f32_e32 v58, 0xbfb8aa3b, v60
	v_mul_f32_e32 v59, 0xbfb8aa3b, v61
	v_exp_f32_e32 v58, v58
	v_exp_f32_e32 v59, v59
	v_lshlrev_b32_e32 v60, 16, v93
	v_and_b32_e32 v61, 0xffff0000, v93
	v_add_f32_e32 v58, 1.0, v58
	v_add_f32_e32 v59, 1.0, v59
	v_rcp_f32_e32 v58, v58
	v_rcp_f32_e32 v59, v59
	v_mul_f32_e32 v14, 0xbfb8aa3b, v14
	v_mul_f32_e32 v15, 0xbfb8aa3b, v15
	v_exp_f32_e32 v14, v14
	v_pk_mul_f32 v[58:59], v[58:59], v[60:61]
	v_lshlrev_b32_e32 v60, 16, v94
	v_and_b32_e32 v61, 0xffff0000, v94
	v_pk_mul_f32 v[54:55], v[54:55], v[60:61]
	v_lshlrev_b32_e32 v60, 16, v95
	v_cvt_pk_bf16_f32 v54, v54, v55
	v_mul_f32_e32 v55, 0xbfb8aa3b, v56
	v_exp_f32_e32 v55, v55
	v_and_b32_e32 v61, 0xffff0000, v95
	v_exp_f32_e32 v15, v15
	v_add_f32_e32 v14, 1.0, v14
	v_add_f32_e32 v55, 1.0, v55
	v_rcp_f32_e32 v56, v55
	v_mul_f32_e32 v55, 0xbfb8aa3b, v57
	v_exp_f32_e32 v55, v55
	v_add_f32_e32 v15, 1.0, v15
	v_rcp_f32_e32 v14, v14
	v_rcp_f32_e32 v15, v15
	v_add_f32_e32 v55, 1.0, v55
	v_rcp_f32_e32 v57, v55
	v_mul_f32_e32 v10, 0xbfb8aa3b, v10
	v_mul_f32_e32 v11, 0xbfb8aa3b, v11
	v_exp_f32_e32 v10, v10
	v_pk_mul_f32 v[56:57], v[56:57], v[60:61]
	v_exp_f32_e32 v11, v11
	v_cvt_pk_bf16_f32 v55, v56, v57
	v_lshlrev_b32_e32 v56, 16, v96
	v_and_b32_e32 v57, 0xffff0000, v96
	v_pk_mul_f32 v[50:51], v[50:51], v[56:57]
	v_add_f32_e32 v10, 1.0, v10
	v_cvt_pk_bf16_f32 v56, v50, v51
	v_mul_f32_e32 v50, 0xbfb8aa3b, v52
	v_mul_f32_e32 v51, 0xbfb8aa3b, v53
	v_exp_f32_e32 v50, v50
	v_exp_f32_e32 v51, v51
	v_lshlrev_b32_e32 v52, 16, v97
	v_and_b32_e32 v53, 0xffff0000, v97
	v_add_f32_e32 v50, 1.0, v50
	v_add_f32_e32 v51, 1.0, v51
	v_rcp_f32_e32 v50, v50
	v_rcp_f32_e32 v51, v51
	v_add_f32_e32 v11, 1.0, v11
	v_rcp_f32_e32 v10, v10
	v_rcp_f32_e32 v11, v11
	v_pk_mul_f32 v[50:51], v[50:51], v[52:53]
	v_mul_f32_e32 v6, 0xbfb8aa3b, v6
	v_cvt_pk_bf16_f32 v57, v50, v51
	v_lshlrev_b32_e32 v50, 16, v86
	v_and_b32_e32 v51, 0xffff0000, v86
	v_pk_mul_f32 v[46:47], v[46:47], v[50:51]
	v_lshlrev_b32_e32 v50, 16, v87
	v_cvt_pk_bf16_f32 v46, v46, v47
	v_mul_f32_e32 v47, 0xbfb8aa3b, v48
	v_exp_f32_e32 v47, v47
	v_and_b32_e32 v51, 0xffff0000, v87
	v_mul_f32_e32 v7, 0xbfb8aa3b, v7
	v_exp_f32_e32 v6, v6
	v_add_f32_e32 v47, 1.0, v47
	v_rcp_f32_e32 v48, v47
	v_mul_f32_e32 v47, 0xbfb8aa3b, v49
	v_exp_f32_e32 v47, v47
	v_exp_f32_e32 v7, v7
	v_add_f32_e32 v6, 1.0, v6
	v_rcp_f32_e32 v6, v6
	v_add_f32_e32 v47, 1.0, v47
	v_rcp_f32_e32 v49, v47
	v_add_f32_e32 v7, 1.0, v7
	v_rcp_f32_e32 v7, v7
	v_mul_f32_e32 v2, 0xbfb8aa3b, v2
	v_pk_mul_f32 v[48:49], v[48:49], v[50:51]
	v_mul_f32_e32 v3, 0xbfb8aa3b, v3
	v_cvt_pk_bf16_f32 v47, v48, v49
	v_lshlrev_b32_e32 v48, 16, v88
	v_and_b32_e32 v49, 0xffff0000, v88
	v_pk_mul_f32 v[42:43], v[42:43], v[48:49]
	v_exp_f32_e32 v2, v2
	v_cvt_pk_bf16_f32 v48, v42, v43
	v_mul_f32_e32 v42, 0xbfb8aa3b, v44
	v_mul_f32_e32 v43, 0xbfb8aa3b, v45
	v_exp_f32_e32 v42, v42
	v_exp_f32_e32 v43, v43
	v_lshlrev_b32_e32 v44, 16, v89
	v_and_b32_e32 v45, 0xffff0000, v89
	v_add_f32_e32 v42, 1.0, v42
	v_add_f32_e32 v43, 1.0, v43
	v_rcp_f32_e32 v42, v42
	v_rcp_f32_e32 v43, v43
	v_exp_f32_e32 v3, v3
	v_add_f32_e32 v2, 1.0, v2
	v_rcp_f32_e32 v2, v2
	v_pk_mul_f32 v[42:43], v[42:43], v[44:45]
	v_lshlrev_b32_e32 v44, 16, v82
	v_and_b32_e32 v45, 0xffff0000, v82
	v_pk_mul_f32 v[38:39], v[38:39], v[44:45]
	v_lshlrev_b32_e32 v44, 16, v83
	v_cvt_pk_bf16_f32 v38, v38, v39
	v_mul_f32_e32 v39, 0xbfb8aa3b, v40
	v_exp_f32_e32 v39, v39
	v_and_b32_e32 v45, 0xffff0000, v83
	v_add_f32_e32 v3, 1.0, v3
	v_rcp_f32_e32 v3, v3
	v_add_f32_e32 v39, 1.0, v39
	v_rcp_f32_e32 v40, v39
	v_mul_f32_e32 v39, 0xbfb8aa3b, v41
	v_exp_f32_e32 v39, v39
	v_cvt_pk_bf16_f32 v65, v58, v59
	v_lshl_add_u64 v[58:59], s[2:3], 0, v[104:105]
	v_cvt_pk_bf16_f32 v49, v42, v43
	v_add_f32_e32 v39, 1.0, v39
	v_rcp_f32_e32 v41, v39
	v_lshl_add_u64 v[42:43], s[2:3], 0, v[102:103]
	v_lshl_add_u64 v[58:59], v[58:59], 0, v[172:173]
	v_lshl_add_u64 v[42:43], v[42:43], 0, v[172:173]
	v_pk_mul_f32 v[40:41], v[40:41], v[44:45]
	s_and_b64 vcc, exec, s[36:37]
	v_cvt_pk_bf16_f32 v39, v40, v41
	v_lshlrev_b32_e32 v40, 16, v84
	v_and_b32_e32 v41, 0xffff0000, v84
	v_pk_mul_f32 v[34:35], v[34:35], v[40:41]
	s_mov_b32 s5, s0
	v_cvt_pk_bf16_f32 v40, v34, v35
	v_mul_f32_e32 v34, 0xbfb8aa3b, v36
	v_mul_f32_e32 v35, 0xbfb8aa3b, v37
	v_exp_f32_e32 v34, v34
	v_exp_f32_e32 v35, v35
	v_lshlrev_b32_e32 v36, 16, v85
	v_and_b32_e32 v37, 0xffff0000, v85
	v_add_f32_e32 v34, 1.0, v34
	v_add_f32_e32 v35, 1.0, v35
	v_rcp_f32_e32 v34, v34
	v_rcp_f32_e32 v35, v35
	s_mov_b32 s49, s6
	s_mov_b64 s[12:13], s[8:9]
	global_store_dwordx4 v[58:59], v[62:65], off
	v_pk_mul_f32 v[34:35], v[34:35], v[36:37]
	global_store_dwordx4 v[58:59], v[54:57], off offset:256
	v_cvt_pk_bf16_f32 v41, v34, v35
	v_lshlrev_b32_e32 v34, 16, v78
	v_and_b32_e32 v35, 0xffff0000, v78
	v_pk_mul_f32 v[30:31], v[30:31], v[34:35]
	v_lshlrev_b32_e32 v34, 16, v79
	v_cvt_pk_bf16_f32 v30, v30, v31
	v_mul_f32_e32 v31, 0xbfb8aa3b, v32
	v_exp_f32_e32 v31, v31
	v_and_b32_e32 v35, 0xffff0000, v79
	global_store_dwordx4 v[42:43], v[46:49], off
	global_store_dwordx4 v[42:43], v[38:41], off offset:256
	v_add_f32_e32 v31, 1.0, v31
	v_rcp_f32_e32 v32, v31
	v_mul_f32_e32 v31, 0xbfb8aa3b, v33
	v_exp_f32_e32 v31, v31
	s_nop 0
	v_add_f32_e32 v31, 1.0, v31
	v_rcp_f32_e32 v33, v31
	s_nop 0
	v_pk_mul_f32 v[32:33], v[32:33], v[34:35]
	s_nop 0
	v_cvt_pk_bf16_f32 v31, v32, v33
	v_lshlrev_b32_e32 v32, 16, v80
	v_and_b32_e32 v33, 0xffff0000, v80
	v_pk_mul_f32 v[26:27], v[26:27], v[32:33]
	s_nop 0
	v_cvt_pk_bf16_f32 v32, v26, v27
	v_mul_f32_e32 v26, 0xbfb8aa3b, v28
	v_mul_f32_e32 v27, 0xbfb8aa3b, v29
	v_exp_f32_e32 v26, v26
	v_exp_f32_e32 v27, v27
	v_lshlrev_b32_e32 v28, 16, v81
	v_and_b32_e32 v29, 0xffff0000, v81
	v_add_f32_e32 v26, 1.0, v26
	v_add_f32_e32 v27, 1.0, v27
	v_rcp_f32_e32 v26, v26
	v_rcp_f32_e32 v27, v27
	s_nop 0
	v_pk_mul_f32 v[26:27], v[26:27], v[28:29]
	v_lshlrev_b32_e32 v28, 16, v74
	v_and_b32_e32 v29, 0xffff0000, v74
	v_pk_mul_f32 v[22:23], v[22:23], v[28:29]
	v_lshlrev_b32_e32 v28, 16, v75
	v_cvt_pk_bf16_f32 v22, v22, v23
	v_mul_f32_e32 v23, 0xbfb8aa3b, v24
	v_exp_f32_e32 v23, v23
	v_and_b32_e32 v29, 0xffff0000, v75
	v_cvt_pk_bf16_f32 v33, v26, v27
	v_lshl_add_u64 v[26:27], s[2:3], 0, v[100:101]
	v_add_f32_e32 v23, 1.0, v23
	v_rcp_f32_e32 v24, v23
	v_mul_f32_e32 v23, 0xbfb8aa3b, v25
	v_exp_f32_e32 v23, v23
	v_lshl_add_u64 v[26:27], v[26:27], 0, v[172:173]
	global_store_dwordx4 v[26:27], v[30:33], off
	v_add_f32_e32 v23, 1.0, v23
	v_rcp_f32_e32 v25, v23
	s_nop 0
	v_pk_mul_f32 v[24:25], v[24:25], v[28:29]
	s_nop 0
	v_cvt_pk_bf16_f32 v23, v24, v25
	v_lshlrev_b32_e32 v24, 16, v76
	v_and_b32_e32 v25, 0xffff0000, v76
	v_pk_mul_f32 v[18:19], v[18:19], v[24:25]
	s_nop 0
	v_cvt_pk_bf16_f32 v24, v18, v19
	v_mul_f32_e32 v18, 0xbfb8aa3b, v20
	v_mul_f32_e32 v19, 0xbfb8aa3b, v21
	v_exp_f32_e32 v18, v18
	v_exp_f32_e32 v19, v19
	v_lshlrev_b32_e32 v20, 16, v77
	v_and_b32_e32 v21, 0xffff0000, v77
	v_add_f32_e32 v18, 1.0, v18
	v_add_f32_e32 v19, 1.0, v19
	v_rcp_f32_e32 v18, v18
	v_rcp_f32_e32 v19, v19
	s_nop 0
	v_pk_mul_f32 v[18:19], v[18:19], v[20:21]
	s_nop 0
	v_cvt_pk_bf16_f32 v25, v18, v19
	v_lshlrev_b32_e32 v18, 16, v70
	v_and_b32_e32 v19, 0xffff0000, v70
	v_pk_mul_f32 v[14:15], v[14:15], v[18:19]
	v_lshlrev_b32_e32 v18, 16, v71
	v_cvt_pk_bf16_f32 v14, v14, v15
	v_mul_f32_e32 v15, 0xbfb8aa3b, v16
	v_exp_f32_e32 v15, v15
	v_and_b32_e32 v19, 0xffff0000, v71
	global_store_dwordx4 v[26:27], v[22:25], off offset:256
	v_add_f32_e32 v15, 1.0, v15
	v_rcp_f32_e32 v16, v15
	v_mul_f32_e32 v15, 0xbfb8aa3b, v17
	v_exp_f32_e32 v15, v15
	s_nop 0
	v_add_f32_e32 v15, 1.0, v15
	v_rcp_f32_e32 v17, v15
	s_nop 0
	v_pk_mul_f32 v[16:17], v[16:17], v[18:19]
	s_nop 0
	v_cvt_pk_bf16_f32 v15, v16, v17
	v_lshlrev_b32_e32 v16, 16, v72
	v_and_b32_e32 v17, 0xffff0000, v72
	v_pk_mul_f32 v[10:11], v[10:11], v[16:17]
	s_nop 0
	v_cvt_pk_bf16_f32 v16, v10, v11
	v_mul_f32_e32 v10, 0xbfb8aa3b, v12
	v_mul_f32_e32 v11, 0xbfb8aa3b, v13
	v_exp_f32_e32 v10, v10
	v_exp_f32_e32 v11, v11
	v_lshlrev_b32_e32 v12, 16, v73
	v_and_b32_e32 v13, 0xffff0000, v73
	v_add_f32_e32 v10, 1.0, v10
	v_add_f32_e32 v11, 1.0, v11
	v_rcp_f32_e32 v10, v10
	v_rcp_f32_e32 v11, v11
	s_nop 0
	v_pk_mul_f32 v[10:11], v[10:11], v[12:13]
	v_lshlrev_b32_e32 v12, 16, v66
	v_and_b32_e32 v13, 0xffff0000, v66
	v_pk_mul_f32 v[6:7], v[6:7], v[12:13]
	v_lshlrev_b32_e32 v12, 16, v67
	v_cvt_pk_bf16_f32 v6, v6, v7
	v_mul_f32_e32 v7, 0xbfb8aa3b, v8
	v_exp_f32_e32 v7, v7
	v_and_b32_e32 v13, 0xffff0000, v67
	v_cvt_pk_bf16_f32 v17, v10, v11
	v_lshl_add_u64 v[10:11], s[2:3], 0, v[98:99]
	v_add_f32_e32 v7, 1.0, v7
	v_rcp_f32_e32 v8, v7
	v_mul_f32_e32 v7, 0xbfb8aa3b, v9
	v_exp_f32_e32 v7, v7
	v_lshl_add_u64 v[10:11], v[10:11], 0, v[172:173]
	s_mov_b64 s[2:3], s[10:11]
	global_store_dwordx4 v[10:11], v[14:17], off
	v_add_f32_e32 v7, 1.0, v7
	v_rcp_f32_e32 v9, v7
	s_nop 0
	v_pk_mul_f32 v[8:9], v[8:9], v[12:13]
	s_nop 0
	v_cvt_pk_bf16_f32 v7, v8, v9
	v_lshlrev_b32_e32 v8, 16, v68
	v_and_b32_e32 v9, 0xffff0000, v68
	v_pk_mul_f32 v[2:3], v[2:3], v[8:9]
	s_nop 0
	v_cvt_pk_bf16_f32 v8, v2, v3
	v_mul_f32_e32 v2, 0xbfb8aa3b, v4
	v_mul_f32_e32 v3, 0xbfb8aa3b, v5
	v_exp_f32_e32 v2, v2
	v_exp_f32_e32 v3, v3
	v_lshlrev_b32_e32 v4, 16, v69
	v_and_b32_e32 v5, 0xffff0000, v69
	v_add_f32_e32 v2, 1.0, v2
	v_add_f32_e32 v3, 1.0, v3
	v_rcp_f32_e32 v2, v2
	v_rcp_f32_e32 v3, v3
	s_nop 0
	v_pk_mul_f32 v[2:3], v[2:3], v[4:5]
	s_nop 0
	v_cvt_pk_bf16_f32 v9, v2, v3
	global_store_dwordx4 v[10:11], v[6:9], off offset:256
	s_cbranch_vccz .LBB0_399
	s_waitcnt vmcnt(0)
	s_cmpk_gt_u32 s16, 0xff
	v_readlane_b32 s50, v255, 53
	v_readlane_b32 s51, v255, 54
	s_cbranch_scc1 .LBB0_406
	s_barrier

.LBB0_442:
	s_add_u32 s2, s36, 0xfff00080
	s_addc_u32 s3, s37, -1
	s_add_i32 s34, 0, 0x10000
	v_add_u32_e32 v156, s34, v141
	ds_read_b128 v[144:147], v156
	ds_read_b128 v[148:151], v156 offset:1024
	ds_read_b128 v[152:155], v156 offset:2048
	ds_read_b128 v[156:159], v156 offset:3072
	s_cmp_eq_u32 s60, 28
	s_cselect_b32 s3, s11, s3
	s_cselect_b32 s2, vcc_lo, s2
	s_cselect_b32 s39, s7, s50
	s_cselect_b32 s38, s9, vcc_hi
	v_lshl_add_u64 v[192:193], s[36:37], 0, v[136:137]
	s_add_i32 m0, s59, 0xc000
	ds_read_b128 v[160:163], v143
	ds_read_b128 v[164:167], v143 offset:1024
	ds_read_b128 v[168:171], v143 offset:2048
	ds_read_b128 v[172:175], v143 offset:3072
	ds_read_b128 v[176:179], v143 offset:4096
	ds_read_b128 v[180:183], v143 offset:5120
	ds_read_b128 v[184:187], v143 offset:6144
	ds_read_b128 v[188:191], v143 offset:7168
	global_load_lds_dwordx4 v[192:193], off
	v_lshl_add_u64 v[192:193], s[36:37], 0, v[138:139]
	s_add_i32 m0, s59, 0xe000
	s_nop 0
	global_load_lds_dwordx4 v[192:193], off
	s_waitcnt vmcnt(10)
	s_waitcnt lgkmcnt(8)
	s_barrier
	s_waitcnt lgkmcnt(0)
	s_setprio 1
	s_waitcnt lgkmcnt(0)
	v_mfma_f32_16x16x32_bf16 v[126:129], v[144:147], v[160:163], v[126:129]
	v_mfma_f32_16x16x32_bf16 v[122:125], v[152:155], v[160:163], v[122:125]
	v_mfma_f32_16x16x32_bf16 v[118:121], v[144:147], v[168:171], v[118:121]
	v_mfma_f32_16x16x32_bf16 v[114:117], v[152:155], v[168:171], v[114:117]
	v_mfma_f32_16x16x32_bf16 v[102:105], v[144:147], v[176:179], v[102:105]
	v_mfma_f32_16x16x32_bf16 v[98:101], v[152:155], v[176:179], v[98:101]
	v_mfma_f32_16x16x32_bf16 v[86:89], v[144:147], v[184:187], v[86:89]
	v_mfma_f32_16x16x32_bf16 v[82:85], v[152:155], v[184:187], v[82:85]
	v_mfma_f32_16x16x32_bf16 v[126:129], v[148:151], v[164:167], v[126:129]
	v_mfma_f32_16x16x32_bf16 v[122:125], v[156:159], v[164:167], v[122:125]
	v_mfma_f32_16x16x32_bf16 v[118:121], v[148:151], v[172:175], v[118:121]
	v_mfma_f32_16x16x32_bf16 v[114:117], v[156:159], v[172:175], v[114:117]
	v_mfma_f32_16x16x32_bf16 v[102:105], v[148:151], v[180:183], v[102:105]
	v_mfma_f32_16x16x32_bf16 v[98:101], v[156:159], v[180:183], v[98:101]
	v_mfma_f32_16x16x32_bf16 v[86:89], v[148:151], v[188:191], v[86:89]
	v_mfma_f32_16x16x32_bf16 v[82:85], v[156:159], v[188:191], v[82:85]
	s_setprio 0
	s_barrier
	s_add_i32 s40, 0, 0x14000
	v_add_u32_e32 v192, s40, v141
	s_add_i32 s34, s34, s53
	ds_read_b128 v[200:203], v192
	ds_read_b128 v[206:209], v192 offset:1024
	ds_read_b128 v[210:213], v192 offset:2048
	ds_read_b128 v[214:217], v192 offset:3072
	v_lshl_add_u64 v[192:193], s[38:39], 0, v[0:1]
	s_mov_b32 m0, s34
	v_lshl_add_u64 v[196:197], s[38:39], 0, v[130:131]
	global_load_lds_dwordx4 v[192:193], off
	s_add_i32 m0, s34, 0x2000
	s_nop 0
	global_load_lds_dwordx4 v[196:197], off
	s_waitcnt vmcnt(10)
	s_barrier
	s_waitcnt lgkmcnt(0)
	s_setprio 1
	s_waitcnt lgkmcnt(0)
	v_mfma_f32_16x16x32_bf16 v[110:113], v[200:203], v[160:163], v[110:113]
	v_mfma_f32_16x16x32_bf16 v[106:109], v[210:213], v[160:163], v[106:109]
	v_mfma_f32_16x16x32_bf16 v[94:97], v[200:203], v[168:171], v[94:97]
	v_mfma_f32_16x16x32_bf16 v[90:93], v[210:213], v[168:171], v[90:93]
	v_mfma_f32_16x16x32_bf16 v[78:81], v[200:203], v[176:179], v[78:81]
	v_mfma_f32_16x16x32_bf16 v[74:77], v[210:213], v[176:179], v[74:77]
	v_mfma_f32_16x16x32_bf16 v[70:73], v[200:203], v[184:187], v[70:73]
	v_mfma_f32_16x16x32_bf16 v[66:69], v[210:213], v[184:187], v[66:69]
	v_mfma_f32_16x16x32_bf16 v[110:113], v[206:209], v[164:167], v[110:113]
	v_mfma_f32_16x16x32_bf16 v[106:109], v[214:217], v[164:167], v[106:109]
	v_mfma_f32_16x16x32_bf16 v[94:97], v[206:209], v[172:175], v[94:97]
	v_mfma_f32_16x16x32_bf16 v[90:93], v[214:217], v[172:175], v[90:93]
	v_mfma_f32_16x16x32_bf16 v[78:81], v[206:209], v[180:183], v[78:81]
	v_mfma_f32_16x16x32_bf16 v[74:77], v[214:217], v[180:183], v[74:77]
	v_mfma_f32_16x16x32_bf16 v[70:73], v[206:209], v[188:191], v[70:73]
	v_mfma_f32_16x16x32_bf16 v[66:69], v[214:217], v[188:191], v[66:69]
	s_setprio 0
	s_mov_b32 m0, s59
	v_lshl_add_u64 v[198:199], s[2:3], 0, v[134:135]
	s_barrier
	ds_read_b128 v[160:163], v143 offset:16384
	ds_read_b128 v[164:167], v143 offset:17408
	ds_read_b128 v[168:171], v143 offset:18432
	ds_read_b128 v[172:175], v143 offset:19456
	ds_read_b128 v[176:179], v143 offset:20480
	ds_read_b128 v[180:183], v143 offset:21504
	ds_read_b128 v[184:187], v143 offset:22528
	ds_read_b128 v[188:191], v143 offset:23552
	global_load_lds_dwordx4 v[198:199], off
	v_lshl_add_u64 v[218:219], s[2:3], 0, v[132:133]
	s_mov_b32 m0, s67
	s_nop 0
	global_load_lds_dwordx4 v[218:219], off
	s_barrier
	s_waitcnt lgkmcnt(0)
	s_setprio 1
	s_waitcnt lgkmcnt(0)
	v_mfma_f32_16x16x32_bf16 v[62:65], v[144:147], v[160:163], v[62:65]
	v_mfma_f32_16x16x32_bf16 v[58:61], v[152:155], v[160:163], v[58:61]
	v_mfma_f32_16x16x32_bf16 v[54:57], v[144:147], v[168:171], v[54:57]
	v_mfma_f32_16x16x32_bf16 v[50:53], v[152:155], v[168:171], v[50:53]
	v_mfma_f32_16x16x32_bf16 v[38:41], v[144:147], v[176:179], v[38:41]
	v_mfma_f32_16x16x32_bf16 v[34:37], v[152:155], v[176:179], v[34:37]
	v_mfma_f32_16x16x32_bf16 v[22:25], v[144:147], v[184:187], v[22:25]
	v_mfma_f32_16x16x32_bf16 v[18:21], v[152:155], v[184:187], v[18:21]
	v_mfma_f32_16x16x32_bf16 v[62:65], v[148:151], v[164:167], v[62:65]
	v_mfma_f32_16x16x32_bf16 v[58:61], v[156:159], v[164:167], v[58:61]
	v_mfma_f32_16x16x32_bf16 v[54:57], v[148:151], v[172:175], v[54:57]
	v_mfma_f32_16x16x32_bf16 v[50:53], v[156:159], v[172:175], v[50:53]
	v_mfma_f32_16x16x32_bf16 v[38:41], v[148:151], v[180:183], v[38:41]
	v_mfma_f32_16x16x32_bf16 v[34:37], v[156:159], v[180:183], v[34:37]
	v_mfma_f32_16x16x32_bf16 v[22:25], v[148:151], v[188:191], v[22:25]
	v_mfma_f32_16x16x32_bf16 v[18:21], v[156:159], v[188:191], v[18:21]
	s_setprio 0
	s_barrier
	s_add_u32 s34, s38, 0x200000
	s_addc_u32 s35, s39, 0
	s_add_i32 s40, s40, s53
	v_lshl_add_u64 v[144:145], s[34:35], 0, v[0:1]
	s_mov_b32 m0, s40
	s_nop 0
	global_load_lds_dwordx4 v[144:145], off
	v_lshl_add_u64 v[144:145], s[34:35], 0, v[130:131]
	s_add_i32 m0, s40, 0x2000
	s_nop 0
	global_load_lds_dwordx4 v[144:145], off
	s_waitcnt vmcnt(10)
	s_barrier
	s_setprio 1
	v_mfma_f32_16x16x32_bf16 v[46:49], v[200:203], v[160:163], v[46:49]
	v_mfma_f32_16x16x32_bf16 v[42:45], v[210:213], v[160:163], v[42:45]
	v_mfma_f32_16x16x32_bf16 v[30:33], v[200:203], v[168:171], v[30:33]
	v_mfma_f32_16x16x32_bf16 v[26:29], v[210:213], v[168:171], v[26:29]
	v_mfma_f32_16x16x32_bf16 v[14:17], v[200:203], v[176:179], v[14:17]
	v_mfma_f32_16x16x32_bf16 v[10:13], v[210:213], v[176:179], v[10:13]
	v_mfma_f32_16x16x32_bf16 v[6:9], v[200:203], v[184:187], v[6:9]
	v_mfma_f32_16x16x32_bf16 v[2:5], v[210:213], v[184:187], v[2:5]
	v_mfma_f32_16x16x32_bf16 v[46:49], v[206:209], v[164:167], v[46:49]
	v_mfma_f32_16x16x32_bf16 v[42:45], v[214:217], v[164:167], v[42:45]
	v_mfma_f32_16x16x32_bf16 v[30:33], v[206:209], v[172:175], v[30:33]
	v_mfma_f32_16x16x32_bf16 v[26:29], v[214:217], v[172:175], v[26:29]
	v_mfma_f32_16x16x32_bf16 v[14:17], v[206:209], v[180:183], v[14:17]
	v_mfma_f32_16x16x32_bf16 v[10:13], v[214:217], v[180:183], v[10:13]
	v_mfma_f32_16x16x32_bf16 v[6:9], v[206:209], v[188:191], v[6:9]
	v_mfma_f32_16x16x32_bf16 v[2:5], v[214:217], v[188:191], v[2:5]
	s_setprio 0
	s_add_i32 s34, 0, 0x18000
	v_add_u32_e32 v156, s34, v141
	s_barrier
	ds_read_b128 v[144:147], v156
	ds_read_b128 v[148:151], v156 offset:1024
	ds_read_b128 v[152:155], v156 offset:2048
	ds_read_b128 v[156:159], v156 offset:3072
	s_add_u32 s2, s2, 0x100000
	s_addc_u32 s3, s3, 0
	s_mov_b32 m0, s72
	v_lshl_add_u64 v[200:201], s[2:3], 0, v[134:135]
	ds_read_b128 v[160:163], v143 offset:32768
	ds_read_b128 v[164:167], v143 offset:33792
	ds_read_b128 v[168:171], v143 offset:34816
	ds_read_b128 v[172:175], v143 offset:35840
	ds_read_b128 v[176:179], v143 offset:36864
	ds_read_b128 v[180:183], v143 offset:37888
	ds_read_b128 v[184:187], v143 offset:38912
	ds_read_b128 v[188:191], v143 offset:39936
	global_load_lds_dwordx4 v[200:201], off
	v_lshl_add_u64 v[200:201], s[2:3], 0, v[132:133]
	s_mov_b32 m0, s73
	s_nop 0
	global_load_lds_dwordx4 v[200:201], off
	s_waitcnt vmcnt(10)
	s_waitcnt lgkmcnt(8)
	s_barrier
	s_waitcnt lgkmcnt(0)
	s_setprio 1
	s_waitcnt lgkmcnt(0)
	v_mfma_f32_16x16x32_bf16 v[126:129], v[144:147], v[160:163], v[126:129]
	v_mfma_f32_16x16x32_bf16 v[122:125], v[152:155], v[160:163], v[122:125]
	v_mfma_f32_16x16x32_bf16 v[118:121], v[144:147], v[168:171], v[118:121]
	v_mfma_f32_16x16x32_bf16 v[114:117], v[152:155], v[168:171], v[114:117]
	v_mfma_f32_16x16x32_bf16 v[102:105], v[144:147], v[176:179], v[102:105]
	v_mfma_f32_16x16x32_bf16 v[98:101], v[152:155], v[176:179], v[98:101]
	v_mfma_f32_16x16x32_bf16 v[86:89], v[144:147], v[184:187], v[86:89]
	v_mfma_f32_16x16x32_bf16 v[82:85], v[152:155], v[184:187], v[82:85]
	v_mfma_f32_16x16x32_bf16 v[126:129], v[148:151], v[164:167], v[126:129]
	v_mfma_f32_16x16x32_bf16 v[122:125], v[156:159], v[164:167], v[122:125]
	v_mfma_f32_16x16x32_bf16 v[118:121], v[148:151], v[172:175], v[118:121]
	v_mfma_f32_16x16x32_bf16 v[114:117], v[156:159], v[172:175], v[114:117]
	v_mfma_f32_16x16x32_bf16 v[102:105], v[148:151], v[180:183], v[102:105]
	v_mfma_f32_16x16x32_bf16 v[98:101], v[156:159], v[180:183], v[98:101]
	v_mfma_f32_16x16x32_bf16 v[86:89], v[148:151], v[188:191], v[86:89]
	v_mfma_f32_16x16x32_bf16 v[82:85], v[156:159], v[188:191], v[82:85]
	s_setprio 0
	s_barrier
	s_add_i32 s35, 0, 0x1c000
	s_add_i32 s2, s34, s53
	v_add_u32_e32 v195, s35, v141
	v_lshl_add_u64 v[192:193], v[192:193], 0, s[74:75]
	s_mov_b32 m0, s2
	ds_read_b128 v[200:203], v195
	ds_read_b128 v[206:209], v195 offset:1024
	ds_read_b128 v[210:213], v195 offset:2048
	ds_read_b128 v[214:217], v195 offset:3072
	global_load_lds_dwordx4 v[192:193], off
	v_lshl_add_u64 v[192:193], v[196:197], 0, s[74:75]
	s_add_i32 m0, s2, 0x2000
	s_nop 0
	global_load_lds_dwordx4 v[192:193], off
	s_waitcnt vmcnt(10)
	s_barrier
	s_waitcnt lgkmcnt(0)
	s_setprio 1
	s_waitcnt lgkmcnt(0)
	v_mfma_f32_16x16x32_bf16 v[110:113], v[200:203], v[160:163], v[110:113]
	v_mfma_f32_16x16x32_bf16 v[106:109], v[210:213], v[160:163], v[106:109]
	v_mfma_f32_16x16x32_bf16 v[94:97], v[200:203], v[168:171], v[94:97]
	v_mfma_f32_16x16x32_bf16 v[90:93], v[210:213], v[168:171], v[90:93]
	v_mfma_f32_16x16x32_bf16 v[78:81], v[200:203], v[176:179], v[78:81]
	v_mfma_f32_16x16x32_bf16 v[74:77], v[210:213], v[176:179], v[74:77]
	v_mfma_f32_16x16x32_bf16 v[70:73], v[200:203], v[184:187], v[70:73]
	v_mfma_f32_16x16x32_bf16 v[66:69], v[210:213], v[184:187], v[66:69]
	v_mfma_f32_16x16x32_bf16 v[110:113], v[206:209], v[164:167], v[110:113]
	v_mfma_f32_16x16x32_bf16 v[106:109], v[214:217], v[164:167], v[106:109]
	v_mfma_f32_16x16x32_bf16 v[94:97], v[206:209], v[172:175], v[94:97]
	v_mfma_f32_16x16x32_bf16 v[90:93], v[214:217], v[172:175], v[90:93]
	v_mfma_f32_16x16x32_bf16 v[78:81], v[206:209], v[180:183], v[78:81]
	v_mfma_f32_16x16x32_bf16 v[74:77], v[214:217], v[180:183], v[74:77]
	v_mfma_f32_16x16x32_bf16 v[70:73], v[206:209], v[188:191], v[70:73]
	v_mfma_f32_16x16x32_bf16 v[66:69], v[214:217], v[188:191], v[66:69]
	s_setprio 0
	s_mov_b32 m0, s56
	v_lshl_add_u64 v[192:193], v[198:199], 0, s[74:75]
	s_barrier
	ds_read_b128 v[160:163], v143 offset:49152
	ds_read_b128 v[164:167], v143 offset:50176
	ds_read_b128 v[168:171], v143 offset:51200
	ds_read_b128 v[172:175], v143 offset:52224
	ds_read_b128 v[176:179], v143 offset:53248
	ds_read_b128 v[180:183], v143 offset:54272
	ds_read_b128 v[184:187], v143 offset:55296
	ds_read_b128 v[188:191], v143 offset:56320
	global_load_lds_dwordx4 v[192:193], off
	v_lshl_add_u64 v[192:193], v[218:219], 0, s[74:75]
	s_mov_b32 m0, s57
	s_nop 0
	global_load_lds_dwordx4 v[192:193], off
	s_barrier
	s_waitcnt lgkmcnt(0)
	s_setprio 1
	s_waitcnt lgkmcnt(0)
	v_mfma_f32_16x16x32_bf16 v[62:65], v[144:147], v[160:163], v[62:65]
	v_mfma_f32_16x16x32_bf16 v[58:61], v[152:155], v[160:163], v[58:61]
	v_mfma_f32_16x16x32_bf16 v[54:57], v[144:147], v[168:171], v[54:57]
	v_mfma_f32_16x16x32_bf16 v[50:53], v[152:155], v[168:171], v[50:53]
	v_mfma_f32_16x16x32_bf16 v[38:41], v[144:147], v[176:179], v[38:41]
	v_mfma_f32_16x16x32_bf16 v[34:37], v[152:155], v[176:179], v[34:37]
	v_mfma_f32_16x16x32_bf16 v[22:25], v[144:147], v[184:187], v[22:25]
	v_mfma_f32_16x16x32_bf16 v[18:21], v[152:155], v[184:187], v[18:21]
	v_mfma_f32_16x16x32_bf16 v[62:65], v[148:151], v[164:167], v[62:65]
	v_mfma_f32_16x16x32_bf16 v[58:61], v[156:159], v[164:167], v[58:61]
	v_mfma_f32_16x16x32_bf16 v[54:57], v[148:151], v[172:175], v[54:57]
	v_mfma_f32_16x16x32_bf16 v[50:53], v[156:159], v[172:175], v[50:53]
	v_mfma_f32_16x16x32_bf16 v[38:41], v[148:151], v[180:183], v[38:41]
	v_mfma_f32_16x16x32_bf16 v[34:37], v[156:159], v[180:183], v[34:37]
	v_mfma_f32_16x16x32_bf16 v[22:25], v[148:151], v[188:191], v[22:25]
	v_mfma_f32_16x16x32_bf16 v[18:21], v[156:159], v[188:191], v[18:21]
	s_setprio 0
	s_barrier
	s_add_u32 s2, s38, 0x200080
	s_addc_u32 s3, s39, 0
	s_add_i32 s34, s35, s53
	v_lshl_add_u64 v[144:145], s[2:3], 0, v[0:1]
	s_mov_b32 m0, s34
	s_nop 0
	global_load_lds_dwordx4 v[144:145], off
	v_lshl_add_u64 v[144:145], s[2:3], 0, v[130:131]
	s_add_i32 m0, s34, 0x2000
	s_nop 0
	global_load_lds_dwordx4 v[144:145], off
	s_waitcnt vmcnt(10)
	s_barrier
	s_setprio 1
	v_mfma_f32_16x16x32_bf16 v[46:49], v[200:203], v[160:163], v[46:49]
	v_mfma_f32_16x16x32_bf16 v[42:45], v[210:213], v[160:163], v[42:45]
	v_mfma_f32_16x16x32_bf16 v[30:33], v[200:203], v[168:171], v[30:33]
	v_mfma_f32_16x16x32_bf16 v[26:29], v[210:213], v[168:171], v[26:29]
	v_mfma_f32_16x16x32_bf16 v[14:17], v[200:203], v[176:179], v[14:17]
	v_mfma_f32_16x16x32_bf16 v[10:13], v[210:213], v[176:179], v[10:13]
	v_mfma_f32_16x16x32_bf16 v[6:9], v[200:203], v[184:187], v[6:9]
	v_mfma_f32_16x16x32_bf16 v[2:5], v[210:213], v[184:187], v[2:5]
	v_mfma_f32_16x16x32_bf16 v[46:49], v[206:209], v[164:167], v[46:49]
	v_mfma_f32_16x16x32_bf16 v[42:45], v[214:217], v[164:167], v[42:45]
	v_mfma_f32_16x16x32_bf16 v[30:33], v[206:209], v[172:175], v[30:33]
	v_mfma_f32_16x16x32_bf16 v[26:29], v[214:217], v[172:175], v[26:29]
	v_mfma_f32_16x16x32_bf16 v[14:17], v[206:209], v[180:183], v[14:17]
	v_mfma_f32_16x16x32_bf16 v[10:13], v[214:217], v[180:183], v[10:13]
	v_mfma_f32_16x16x32_bf16 v[6:9], v[206:209], v[188:191], v[6:9]
	v_mfma_f32_16x16x32_bf16 v[2:5], v[214:217], v[188:191], v[2:5]
	s_setprio 0
	s_add_i32 s60, s60, 2
	s_add_u32 s36, s36, 0x100
	s_addc_u32 s37, s37, 0
	s_add_u32 vcc_hi, vcc_hi, 0x100
	s_addc_u32 s50, s50, 0
	s_cmp_gt_u32 s60, 29
	s_barrier
	s_cbranch_scc0 .LBB0_442
	v_lshl_or_b32 v146, s19, 8, v142
	s_ashr_i32 s19, s18, 31
	v_lshl_add_u32 v144, s58, 8, v140
	s_lshl_b64 s[2:3], s[18:19], 21
	v_ashrrev_i32_e32 v145, 31, v144
	s_add_u32 s2, s49, s2
	v_cvt_pk_bf16_f32 v110, v110, v111
	v_cvt_pk_bf16_f32 v111, v112, v113
	v_cvt_pk_bf16_f32 v112, v106, v107
	v_or_b32_e32 v106, 16, v144
	v_cvt_pk_bf16_f32 v94, v94, v95
	v_cvt_pk_bf16_f32 v95, v96, v97
	v_cvt_pk_bf16_f32 v96, v90, v91
	v_or_b32_e32 v90, 32, v144
	v_cvt_pk_bf16_f32 v78, v78, v79
	v_cvt_pk_bf16_f32 v79, v80, v81
	v_cvt_pk_bf16_f32 v80, v74, v75
	v_or_b32_e32 v74, 48, v144
	s_addc_u32 s3, s55, s3
	v_lshlrev_b64 v[148:149], 10, v[144:145]
	v_ashrrev_i32_e32 v147, 31, v146
	v_ashrrev_i32_e32 v107, 31, v106
	v_ashrrev_i32_e32 v91, 31, v90
	v_ashrrev_i32_e32 v75, 31, v74
	v_lshl_add_u64 v[148:149], s[2:3], 0, v[148:149]
	v_lshlrev_b64 v[146:147], 1, v[146:147]
	v_lshlrev_b64 v[106:107], 10, v[106:107]
	v_lshlrev_b64 v[90:91], 10, v[90:91]
	v_lshlrev_b64 v[74:75], 10, v[74:75]
	v_lshl_add_u64 v[148:149], v[148:149], 0, v[146:147]
	v_lshl_add_u64 v[106:107], s[2:3], 0, v[106:107]
	v_lshl_add_u64 v[90:91], s[2:3], 0, v[90:91]
	v_lshl_add_u64 v[74:75], s[2:3], 0, v[74:75]
	s_mov_b64 s[2:3], 0x20000
	v_cvt_pk_bf16_f32 v70, v70, v71
	v_cvt_pk_bf16_f32 v71, v72, v73
	v_cvt_pk_bf16_f32 v72, v66, v67
	v_lshl_add_u64 v[66:67], v[148:149], 0, s[2:3]
	s_mov_b32 s2, 0x20000
	v_cvt_pk_bf16_f32 v62, v62, v63
	v_cvt_pk_bf16_f32 v63, v64, v65
	v_cvt_pk_bf16_f32 v64, v58, v59
	v_add_co_u32_e32 v58, vcc, s2, v148
	v_cvt_pk_bf16_f32 v46, v46, v47
	s_nop 0
	v_addc_co_u32_e32 v59, vcc, 0, v149, vcc
	v_cvt_pk_bf16_f32 v47, v48, v49
	v_cvt_pk_bf16_f32 v48, v42, v43
	v_cvt_pk_bf16_f32 v49, v44, v45
	s_mov_b64 s[2:3], 0x24000
	global_store_dwordx4 v[66:67], v[46:49], off offset:256
	v_cvt_pk_bf16_f32 v30, v30, v31
	v_cvt_pk_bf16_f32 v31, v32, v33
	v_lshl_add_u64 v[46:47], v[148:149], 0, s[2:3]
	v_add_co_u32_e32 v48, vcc, s63, v148
	v_cvt_pk_bf16_f32 v32, v26, v27
	v_cvt_pk_bf16_f32 v33, v28, v29
	s_mov_b64 s[2:3], 0x28000
	v_addc_co_u32_e32 v49, vcc, 0, v149, vcc
	global_store_dwordx4 v[46:47], v[30:33], off offset:256
	v_cvt_pk_bf16_f32 v14, v14, v15
	v_cvt_pk_bf16_f32 v15, v16, v17
	v_lshl_add_u64 v[30:31], v[148:149], 0, s[2:3]
	s_mov_b32 s2, 0x28000
	v_add_co_u32_e32 v32, vcc, s2, v148
	v_cvt_pk_bf16_f32 v16, v10, v11
	v_cvt_pk_bf16_f32 v17, v12, v13
	s_mov_b64 s[2:3], 0x2c000
	v_cvt_pk_bf16_f32 v113, v108, v109
	v_addc_co_u32_e32 v33, vcc, 0, v149, vcc
	global_store_dwordx4 v[30:31], v[14:17], off offset:256
	global_store_dwordx4 v[148:149], v[110:113], off offset:256
	v_cvt_pk_bf16_f32 v97, v92, v93
	v_lshl_add_u64 v[14:15], v[148:149], 0, s[2:3]
	s_mov_b32 s2, 0x2c000
	v_lshl_add_u64 v[110:111], v[106:107], 0, v[146:147]
	v_add_co_u32_e32 v16, vcc, s2, v148
	global_store_dwordx4 v[110:111], v[94:97], off offset:256
	v_cvt_pk_bf16_f32 v81, v76, v77
	v_addc_co_u32_e32 v17, vcc, 0, v149, vcc
	v_lshl_add_u64 v[94:95], v[90:91], 0, v[146:147]
	v_cvt_pk_bf16_f32 v126, v126, v127
	v_cvt_pk_bf16_f32 v127, v128, v129
	v_cvt_pk_bf16_f32 v128, v122, v123
	v_cvt_pk_bf16_f32 v129, v124, v125
	v_cvt_pk_bf16_f32 v106, v118, v119
	v_cvt_pk_bf16_f32 v107, v120, v121
	v_cvt_pk_bf16_f32 v108, v114, v115
	v_cvt_pk_bf16_f32 v109, v116, v117
	v_cvt_pk_bf16_f32 v90, v102, v103
	v_cvt_pk_bf16_f32 v91, v104, v105
	v_cvt_pk_bf16_f32 v92, v98, v99
	v_cvt_pk_bf16_f32 v93, v100, v101
	global_store_dwordx4 v[94:95], v[78:81], off offset:256
	v_cvt_pk_bf16_f32 v76, v82, v83
	v_cvt_pk_bf16_f32 v77, v84, v85
	v_lshl_add_u64 v[78:79], v[74:75], 0, v[146:147]
	v_cvt_pk_bf16_f32 v74, v86, v87
	v_cvt_pk_bf16_f32 v75, v88, v89
	v_cvt_pk_bf16_f32 v73, v68, v69
	v_cvt_pk_bf16_f32 v65, v60, v61
	v_cvt_pk_bf16_f32 v42, v54, v55
	v_cvt_pk_bf16_f32 v43, v56, v57
	v_cvt_pk_bf16_f32 v44, v50, v51
	v_cvt_pk_bf16_f32 v45, v52, v53
	v_cvt_pk_bf16_f32 v26, v38, v39
	v_cvt_pk_bf16_f32 v27, v40, v41
	v_cvt_pk_bf16_f32 v28, v34, v35
	v_cvt_pk_bf16_f32 v29, v36, v37
	v_cvt_pk_bf16_f32 v10, v22, v23
	v_cvt_pk_bf16_f32 v11, v24, v25
	v_cvt_pk_bf16_f32 v12, v18, v19
	v_cvt_pk_bf16_f32 v13, v20, v21
	v_cvt_pk_bf16_f32 v6, v6, v7
	v_cvt_pk_bf16_f32 v7, v8, v9
	v_cvt_pk_bf16_f32 v8, v2, v3
	v_cvt_pk_bf16_f32 v9, v4, v5
	s_and_b64 vcc, exec, s[12:13]
	s_mov_b32 s34, 0xc2ce8ed0
	global_store_dwordx4 v[148:149], v[126:129], off
	global_store_dwordx4 v[110:111], v[106:109], off
	global_store_dwordx4 v[94:95], v[90:93], off
	global_store_dwordx4 v[78:79], v[74:77], off
	global_store_dwordx4 v[78:79], v[70:73], off offset:256
	global_store_dwordx4 v[58:59], v[62:65], off
	global_store_dwordx4 v[48:49], v[42:45], off
	global_store_dwordx4 v[32:33], v[26:29], off
	global_store_dwordx4 v[16:17], v[10:13], off
	global_store_dwordx4 v[14:15], v[6:9], off offset:256
	s_cbranch_vccnz .LBB0_445
	s_mov_b32 s18, s6
	s_mov_b32 s19, s8
	s_mov_b32 s58, s10
	s_mov_b64 s[38:39], s[16:17]
	s_mov_b64 s[36:37], s[14:15]
	s_branch .LBB0_439

.LBB0_459:
	s_add_u32 s12, s10, 0x100
	s_addc_u32 s13, s11, 0
	s_add_i32 s34, 0, 0x10000
	v_add_u32_e32 v156, s34, v141
	ds_read_b128 v[144:147], v156
	ds_read_b128 v[148:151], v156 offset:1024
	ds_read_b128 v[152:155], v156 offset:2048
	ds_read_b128 v[156:159], v156 offset:3072
	s_cmp_eq_u32 s38, 2
	s_cselect_b32 s3, s7, s13
	s_cselect_b32 s2, s6, s12
	s_cselect_b32 s15, s9, s37
	s_cselect_b32 s14, s8, s36
	v_lshl_add_u64 v[192:193], s[10:11], 0, v[136:137]
	s_add_i32 m0, s17, 0xc000
	ds_read_b128 v[160:163], v143
	ds_read_b128 v[164:167], v143 offset:1024
	ds_read_b128 v[168:171], v143 offset:2048
	ds_read_b128 v[172:175], v143 offset:3072
	ds_read_b128 v[176:179], v143 offset:4096
	ds_read_b128 v[180:183], v143 offset:5120
	ds_read_b128 v[184:187], v143 offset:6144
	ds_read_b128 v[188:191], v143 offset:7168
	global_load_lds_dwordx4 v[192:193], off
	v_lshl_add_u64 v[192:193], s[10:11], 0, v[138:139]
	s_add_i32 m0, s17, 0xe000
	s_nop 0
	global_load_lds_dwordx4 v[192:193], off
	s_waitcnt vmcnt(10)
	s_waitcnt lgkmcnt(8)
	s_barrier
	s_waitcnt lgkmcnt(0)
	s_setprio 1
	s_waitcnt lgkmcnt(0)
	v_mfma_f32_16x16x32_bf16 v[126:129], v[144:147], v[160:163], v[126:129]
	v_mfma_f32_16x16x32_bf16 v[122:125], v[152:155], v[160:163], v[122:125]
	v_mfma_f32_16x16x32_bf16 v[118:121], v[144:147], v[168:171], v[118:121]
	v_mfma_f32_16x16x32_bf16 v[114:117], v[152:155], v[168:171], v[114:117]
	v_mfma_f32_16x16x32_bf16 v[102:105], v[144:147], v[176:179], v[102:105]
	v_mfma_f32_16x16x32_bf16 v[98:101], v[152:155], v[176:179], v[98:101]
	v_mfma_f32_16x16x32_bf16 v[86:89], v[144:147], v[184:187], v[86:89]
	v_mfma_f32_16x16x32_bf16 v[82:85], v[152:155], v[184:187], v[82:85]
	v_mfma_f32_16x16x32_bf16 v[126:129], v[148:151], v[164:167], v[126:129]
	v_mfma_f32_16x16x32_bf16 v[122:125], v[156:159], v[164:167], v[122:125]
	v_mfma_f32_16x16x32_bf16 v[118:121], v[148:151], v[172:175], v[118:121]
	v_mfma_f32_16x16x32_bf16 v[114:117], v[156:159], v[172:175], v[114:117]
	v_mfma_f32_16x16x32_bf16 v[102:105], v[148:151], v[180:183], v[102:105]
	v_mfma_f32_16x16x32_bf16 v[98:101], v[156:159], v[180:183], v[98:101]
	v_mfma_f32_16x16x32_bf16 v[86:89], v[148:151], v[188:191], v[86:89]
	v_mfma_f32_16x16x32_bf16 v[82:85], v[156:159], v[188:191], v[82:85]
	s_setprio 0
	s_barrier
	s_add_i32 s35, 0, 0x14000
	v_add_u32_e32 v192, s35, v141
	s_add_i32 s10, s34, s16
	ds_read_b128 v[200:203], v192
	ds_read_b128 v[206:209], v192 offset:1024
	ds_read_b128 v[210:213], v192 offset:2048
	ds_read_b128 v[214:217], v192 offset:3072
	v_lshl_add_u64 v[192:193], s[14:15], 0, v[0:1]
	s_mov_b32 m0, s10
	v_lshl_add_u64 v[196:197], s[14:15], 0, v[130:131]
	global_load_lds_dwordx4 v[192:193], off
	s_add_i32 m0, s10, 0x2000
	s_nop 0
	global_load_lds_dwordx4 v[196:197], off
	s_waitcnt vmcnt(10)
	s_barrier
	s_waitcnt lgkmcnt(0)
	s_setprio 1
	s_waitcnt lgkmcnt(0)
	v_mfma_f32_16x16x32_bf16 v[110:113], v[200:203], v[160:163], v[110:113]
	v_mfma_f32_16x16x32_bf16 v[106:109], v[210:213], v[160:163], v[106:109]
	v_mfma_f32_16x16x32_bf16 v[94:97], v[200:203], v[168:171], v[94:97]
	v_mfma_f32_16x16x32_bf16 v[90:93], v[210:213], v[168:171], v[90:93]
	v_mfma_f32_16x16x32_bf16 v[78:81], v[200:203], v[176:179], v[78:81]
	v_mfma_f32_16x16x32_bf16 v[74:77], v[210:213], v[176:179], v[74:77]
	v_mfma_f32_16x16x32_bf16 v[70:73], v[200:203], v[184:187], v[70:73]
	v_mfma_f32_16x16x32_bf16 v[66:69], v[210:213], v[184:187], v[66:69]
	v_mfma_f32_16x16x32_bf16 v[110:113], v[206:209], v[164:167], v[110:113]
	v_mfma_f32_16x16x32_bf16 v[106:109], v[214:217], v[164:167], v[106:109]
	v_mfma_f32_16x16x32_bf16 v[94:97], v[206:209], v[172:175], v[94:97]
	v_mfma_f32_16x16x32_bf16 v[90:93], v[214:217], v[172:175], v[90:93]
	v_mfma_f32_16x16x32_bf16 v[78:81], v[206:209], v[180:183], v[78:81]
	v_mfma_f32_16x16x32_bf16 v[74:77], v[214:217], v[180:183], v[74:77]
	v_mfma_f32_16x16x32_bf16 v[70:73], v[206:209], v[188:191], v[70:73]
	v_mfma_f32_16x16x32_bf16 v[66:69], v[214:217], v[188:191], v[66:69]
	s_setprio 0
	s_mov_b32 m0, s17
	v_lshl_add_u64 v[198:199], s[2:3], 0, v[134:135]
	s_barrier
	ds_read_b128 v[160:163], v143 offset:16384
	ds_read_b128 v[164:167], v143 offset:17408
	ds_read_b128 v[168:171], v143 offset:18432
	ds_read_b128 v[172:175], v143 offset:19456
	ds_read_b128 v[176:179], v143 offset:20480
	ds_read_b128 v[180:183], v143 offset:21504
	ds_read_b128 v[184:187], v143 offset:22528
	ds_read_b128 v[188:191], v143 offset:23552
	global_load_lds_dwordx4 v[198:199], off
	v_lshl_add_u64 v[218:219], s[2:3], 0, v[132:133]
	s_mov_b32 m0, s18
	s_nop 0
	global_load_lds_dwordx4 v[218:219], off
	s_barrier
	s_waitcnt lgkmcnt(0)
	s_setprio 1
	s_waitcnt lgkmcnt(0)
	v_mfma_f32_16x16x32_bf16 v[62:65], v[144:147], v[160:163], v[62:65]
	v_mfma_f32_16x16x32_bf16 v[58:61], v[152:155], v[160:163], v[58:61]
	v_mfma_f32_16x16x32_bf16 v[54:57], v[144:147], v[168:171], v[54:57]
	v_mfma_f32_16x16x32_bf16 v[50:53], v[152:155], v[168:171], v[50:53]
	v_mfma_f32_16x16x32_bf16 v[38:41], v[144:147], v[176:179], v[38:41]
	v_mfma_f32_16x16x32_bf16 v[34:37], v[152:155], v[176:179], v[34:37]
	v_mfma_f32_16x16x32_bf16 v[22:25], v[144:147], v[184:187], v[22:25]
	v_mfma_f32_16x16x32_bf16 v[18:21], v[152:155], v[184:187], v[18:21]
	v_mfma_f32_16x16x32_bf16 v[62:65], v[148:151], v[164:167], v[62:65]
	v_mfma_f32_16x16x32_bf16 v[58:61], v[156:159], v[164:167], v[58:61]
	v_mfma_f32_16x16x32_bf16 v[54:57], v[148:151], v[172:175], v[54:57]
	v_mfma_f32_16x16x32_bf16 v[50:53], v[156:159], v[172:175], v[50:53]
	v_mfma_f32_16x16x32_bf16 v[38:41], v[148:151], v[180:183], v[38:41]
	v_mfma_f32_16x16x32_bf16 v[34:37], v[156:159], v[180:183], v[34:37]
	v_mfma_f32_16x16x32_bf16 v[22:25], v[148:151], v[188:191], v[22:25]
	v_mfma_f32_16x16x32_bf16 v[18:21], v[156:159], v[188:191], v[18:21]
	s_setprio 0
	s_barrier
	s_add_u32 s10, s14, 0x18000
	s_addc_u32 s11, s15, 0
	s_add_i32 s34, s35, s16
	v_lshl_add_u64 v[144:145], s[10:11], 0, v[0:1]
	s_mov_b32 m0, s34
	s_nop 0
	global_load_lds_dwordx4 v[144:145], off
	v_lshl_add_u64 v[144:145], s[10:11], 0, v[130:131]
	s_add_i32 m0, s34, 0x2000
	s_nop 0
	global_load_lds_dwordx4 v[144:145], off
	s_waitcnt vmcnt(10)
	s_barrier
	s_setprio 1
	v_mfma_f32_16x16x32_bf16 v[46:49], v[200:203], v[160:163], v[46:49]
	v_mfma_f32_16x16x32_bf16 v[42:45], v[210:213], v[160:163], v[42:45]
	v_mfma_f32_16x16x32_bf16 v[30:33], v[200:203], v[168:171], v[30:33]
	v_mfma_f32_16x16x32_bf16 v[26:29], v[210:213], v[168:171], v[26:29]
	v_mfma_f32_16x16x32_bf16 v[14:17], v[200:203], v[176:179], v[14:17]
	v_mfma_f32_16x16x32_bf16 v[10:13], v[210:213], v[176:179], v[10:13]
	v_mfma_f32_16x16x32_bf16 v[6:9], v[200:203], v[184:187], v[6:9]
	v_mfma_f32_16x16x32_bf16 v[2:5], v[210:213], v[184:187], v[2:5]
	v_mfma_f32_16x16x32_bf16 v[46:49], v[206:209], v[164:167], v[46:49]
	v_mfma_f32_16x16x32_bf16 v[42:45], v[214:217], v[164:167], v[42:45]
	v_mfma_f32_16x16x32_bf16 v[30:33], v[206:209], v[172:175], v[30:33]
	v_mfma_f32_16x16x32_bf16 v[26:29], v[214:217], v[172:175], v[26:29]
	v_mfma_f32_16x16x32_bf16 v[14:17], v[206:209], v[180:183], v[14:17]
	v_mfma_f32_16x16x32_bf16 v[10:13], v[214:217], v[180:183], v[10:13]
	v_mfma_f32_16x16x32_bf16 v[6:9], v[206:209], v[188:191], v[6:9]
	v_mfma_f32_16x16x32_bf16 v[2:5], v[214:217], v[188:191], v[2:5]
	s_setprio 0
	s_add_i32 s10, 0, 0x18000
	v_add_u32_e32 v156, s10, v141
	s_barrier
	ds_read_b128 v[144:147], v156
	ds_read_b128 v[148:151], v156 offset:1024
	ds_read_b128 v[152:155], v156 offset:2048
	ds_read_b128 v[156:159], v156 offset:3072
	s_add_u32 s2, s2, 0x18000
	s_addc_u32 s3, s3, 0
	s_mov_b32 m0, s19
	v_lshl_add_u64 v[200:201], s[2:3], 0, v[134:135]
	ds_read_b128 v[160:163], v143 offset:32768
	ds_read_b128 v[164:167], v143 offset:33792
	ds_read_b128 v[168:171], v143 offset:34816
	ds_read_b128 v[172:175], v143 offset:35840
	ds_read_b128 v[176:179], v143 offset:36864
	ds_read_b128 v[180:183], v143 offset:37888
	ds_read_b128 v[184:187], v143 offset:38912
	ds_read_b128 v[188:191], v143 offset:39936
	global_load_lds_dwordx4 v[200:201], off
	v_lshl_add_u64 v[200:201], s[2:3], 0, v[132:133]
	s_mov_b32 m0, s44
	s_nop 0
	global_load_lds_dwordx4 v[200:201], off
	s_waitcnt vmcnt(10)
	s_waitcnt lgkmcnt(8)
	s_barrier
	s_waitcnt lgkmcnt(0)
	s_setprio 1
	s_waitcnt lgkmcnt(0)
	v_mfma_f32_16x16x32_bf16 v[126:129], v[144:147], v[160:163], v[126:129]
	v_mfma_f32_16x16x32_bf16 v[122:125], v[152:155], v[160:163], v[122:125]
	v_mfma_f32_16x16x32_bf16 v[118:121], v[144:147], v[168:171], v[118:121]
	v_mfma_f32_16x16x32_bf16 v[114:117], v[152:155], v[168:171], v[114:117]
	v_mfma_f32_16x16x32_bf16 v[102:105], v[144:147], v[176:179], v[102:105]
	v_mfma_f32_16x16x32_bf16 v[98:101], v[152:155], v[176:179], v[98:101]
	v_mfma_f32_16x16x32_bf16 v[86:89], v[144:147], v[184:187], v[86:89]
	v_mfma_f32_16x16x32_bf16 v[82:85], v[152:155], v[184:187], v[82:85]
	v_mfma_f32_16x16x32_bf16 v[126:129], v[148:151], v[164:167], v[126:129]
	v_mfma_f32_16x16x32_bf16 v[122:125], v[156:159], v[164:167], v[122:125]
	v_mfma_f32_16x16x32_bf16 v[118:121], v[148:151], v[172:175], v[118:121]
	v_mfma_f32_16x16x32_bf16 v[114:117], v[156:159], v[172:175], v[114:117]
	v_mfma_f32_16x16x32_bf16 v[102:105], v[148:151], v[180:183], v[102:105]
	v_mfma_f32_16x16x32_bf16 v[98:101], v[156:159], v[180:183], v[98:101]
	v_mfma_f32_16x16x32_bf16 v[86:89], v[148:151], v[188:191], v[86:89]
	v_mfma_f32_16x16x32_bf16 v[82:85], v[156:159], v[188:191], v[82:85]
	s_setprio 0
	s_barrier
	s_add_i32 s11, 0, 0x1c000
	s_add_i32 s2, s10, s16
	v_add_u32_e32 v195, s11, v141
	v_lshl_add_u64 v[192:193], v[192:193], 0, s[74:75]
	s_mov_b32 m0, s2
	ds_read_b128 v[200:203], v195
	ds_read_b128 v[206:209], v195 offset:1024
	ds_read_b128 v[210:213], v195 offset:2048
	ds_read_b128 v[214:217], v195 offset:3072
	global_load_lds_dwordx4 v[192:193], off
	v_lshl_add_u64 v[192:193], v[196:197], 0, s[74:75]
	s_add_i32 m0, s2, 0x2000
	s_nop 0
	global_load_lds_dwordx4 v[192:193], off
	s_waitcnt vmcnt(10)
	s_barrier
	s_waitcnt lgkmcnt(0)
	s_setprio 1
	s_waitcnt lgkmcnt(0)
	v_mfma_f32_16x16x32_bf16 v[110:113], v[200:203], v[160:163], v[110:113]
	v_mfma_f32_16x16x32_bf16 v[106:109], v[210:213], v[160:163], v[106:109]
	v_mfma_f32_16x16x32_bf16 v[94:97], v[200:203], v[168:171], v[94:97]
	v_mfma_f32_16x16x32_bf16 v[90:93], v[210:213], v[168:171], v[90:93]
	v_mfma_f32_16x16x32_bf16 v[78:81], v[200:203], v[176:179], v[78:81]
	v_mfma_f32_16x16x32_bf16 v[74:77], v[210:213], v[176:179], v[74:77]
	v_mfma_f32_16x16x32_bf16 v[70:73], v[200:203], v[184:187], v[70:73]
	v_mfma_f32_16x16x32_bf16 v[66:69], v[210:213], v[184:187], v[66:69]
	v_mfma_f32_16x16x32_bf16 v[110:113], v[206:209], v[164:167], v[110:113]
	v_mfma_f32_16x16x32_bf16 v[106:109], v[214:217], v[164:167], v[106:109]
	v_mfma_f32_16x16x32_bf16 v[94:97], v[206:209], v[172:175], v[94:97]
	v_mfma_f32_16x16x32_bf16 v[90:93], v[214:217], v[172:175], v[90:93]
	v_mfma_f32_16x16x32_bf16 v[78:81], v[206:209], v[180:183], v[78:81]
	v_mfma_f32_16x16x32_bf16 v[74:77], v[214:217], v[180:183], v[74:77]
	v_mfma_f32_16x16x32_bf16 v[70:73], v[206:209], v[188:191], v[70:73]
	v_mfma_f32_16x16x32_bf16 v[66:69], v[214:217], v[188:191], v[66:69]
	s_setprio 0
	s_mov_b32 m0, s45
	v_lshl_add_u64 v[192:193], v[198:199], 0, s[74:75]
	s_barrier
	ds_read_b128 v[160:163], v143 offset:49152
	ds_read_b128 v[164:167], v143 offset:50176
	ds_read_b128 v[168:171], v143 offset:51200
	ds_read_b128 v[172:175], v143 offset:52224
	ds_read_b128 v[176:179], v143 offset:53248
	ds_read_b128 v[180:183], v143 offset:54272
	ds_read_b128 v[184:187], v143 offset:55296
	ds_read_b128 v[188:191], v143 offset:56320
	global_load_lds_dwordx4 v[192:193], off
	v_lshl_add_u64 v[192:193], v[218:219], 0, s[74:75]
	s_mov_b32 m0, s49
	s_nop 0
	global_load_lds_dwordx4 v[192:193], off
	s_barrier
	s_waitcnt lgkmcnt(0)
	s_setprio 1
	s_waitcnt lgkmcnt(0)
	v_mfma_f32_16x16x32_bf16 v[62:65], v[144:147], v[160:163], v[62:65]
	v_mfma_f32_16x16x32_bf16 v[58:61], v[152:155], v[160:163], v[58:61]
	v_mfma_f32_16x16x32_bf16 v[54:57], v[144:147], v[168:171], v[54:57]
	v_mfma_f32_16x16x32_bf16 v[50:53], v[152:155], v[168:171], v[50:53]
	v_mfma_f32_16x16x32_bf16 v[38:41], v[144:147], v[176:179], v[38:41]
	v_mfma_f32_16x16x32_bf16 v[34:37], v[152:155], v[176:179], v[34:37]
	v_mfma_f32_16x16x32_bf16 v[22:25], v[144:147], v[184:187], v[22:25]
	v_mfma_f32_16x16x32_bf16 v[18:21], v[152:155], v[184:187], v[18:21]
	v_mfma_f32_16x16x32_bf16 v[62:65], v[148:151], v[164:167], v[62:65]
	v_mfma_f32_16x16x32_bf16 v[58:61], v[156:159], v[164:167], v[58:61]
	v_mfma_f32_16x16x32_bf16 v[54:57], v[148:151], v[172:175], v[54:57]
	v_mfma_f32_16x16x32_bf16 v[50:53], v[156:159], v[172:175], v[50:53]
	v_mfma_f32_16x16x32_bf16 v[38:41], v[148:151], v[180:183], v[38:41]
	v_mfma_f32_16x16x32_bf16 v[34:37], v[156:159], v[180:183], v[34:37]
	v_mfma_f32_16x16x32_bf16 v[22:25], v[148:151], v[188:191], v[22:25]
	v_mfma_f32_16x16x32_bf16 v[18:21], v[156:159], v[188:191], v[18:21]
	s_setprio 0
	s_barrier
	s_add_u32 s2, s14, 0x18080
	s_addc_u32 s3, s15, 0
	s_add_i32 s10, s11, s16
	v_lshl_add_u64 v[144:145], s[2:3], 0, v[0:1]
	s_mov_b32 m0, s10
	s_nop 0
	global_load_lds_dwordx4 v[144:145], off
	v_lshl_add_u64 v[144:145], s[2:3], 0, v[130:131]
	s_add_i32 m0, s10, 0x2000
	s_nop 0
	global_load_lds_dwordx4 v[144:145], off
	s_waitcnt vmcnt(10)
	s_barrier
	s_setprio 1
	v_mfma_f32_16x16x32_bf16 v[46:49], v[200:203], v[160:163], v[46:49]
	v_mfma_f32_16x16x32_bf16 v[42:45], v[210:213], v[160:163], v[42:45]
	v_mfma_f32_16x16x32_bf16 v[30:33], v[200:203], v[168:171], v[30:33]
	v_mfma_f32_16x16x32_bf16 v[26:29], v[210:213], v[168:171], v[26:29]
	v_mfma_f32_16x16x32_bf16 v[14:17], v[200:203], v[176:179], v[14:17]
	v_mfma_f32_16x16x32_bf16 v[10:13], v[210:213], v[176:179], v[10:13]
	v_mfma_f32_16x16x32_bf16 v[6:9], v[200:203], v[184:187], v[6:9]
	v_mfma_f32_16x16x32_bf16 v[2:5], v[210:213], v[184:187], v[2:5]
	v_mfma_f32_16x16x32_bf16 v[46:49], v[206:209], v[164:167], v[46:49]
	v_mfma_f32_16x16x32_bf16 v[42:45], v[214:217], v[164:167], v[42:45]
	v_mfma_f32_16x16x32_bf16 v[30:33], v[206:209], v[172:175], v[30:33]
	v_mfma_f32_16x16x32_bf16 v[26:29], v[214:217], v[172:175], v[26:29]
	v_mfma_f32_16x16x32_bf16 v[14:17], v[206:209], v[180:183], v[14:17]
	v_mfma_f32_16x16x32_bf16 v[10:13], v[214:217], v[180:183], v[10:13]
	v_mfma_f32_16x16x32_bf16 v[6:9], v[206:209], v[188:191], v[6:9]
	v_mfma_f32_16x16x32_bf16 v[2:5], v[214:217], v[188:191], v[2:5]
	s_setprio 0
	s_add_i32 s38, s38, 2
	s_add_u32 s36, s36, 0x100
	s_addc_u32 s37, s37, 0
	s_cmp_gt_u32 s38, 3
	s_mov_b64 s[10:11], s[12:13]
	s_barrier
	s_cbranch_scc0 .LBB0_459
	v_readlane_b32 s2, v250, 0
	v_lshl_add_u32 v150, s55, 8, v140
	v_lshl_or_b32 v144, s54, 8, v142
	v_readlane_b32 s3, v250, 1
	v_ashrrev_i32_e32 v145, 31, v144
	v_cvt_pk_bf16_f32 v70, v70, v71
	v_mov_b64_e32 v[146:147], s[2:3]
	v_cvt_pk_bf16_f32 v71, v72, v73
	v_cvt_pk_bf16_f32 v72, v66, v67
	v_add_u32_e32 v66, 0x80, v150
	v_mad_i64_i32 v[148:149], s[2:3], v150, s48, v[146:147]
	v_lshlrev_b64 v[144:145], 1, v[144:145]
	v_cvt_pk_bf16_f32 v110, v110, v111
	v_cvt_pk_bf16_f32 v111, v112, v113
	v_cvt_pk_bf16_f32 v112, v106, v107
	v_or_b32_e32 v106, 16, v150
	v_mad_i64_i32 v[66:67], s[2:3], v66, s48, v[146:147]
	v_cvt_pk_bf16_f32 v46, v46, v47
	v_cvt_pk_bf16_f32 v47, v48, v49
	v_cvt_pk_bf16_f32 v48, v42, v43
	v_add_u32_e32 v42, 0x90, v150
	v_lshl_add_u64 v[148:149], v[148:149], 0, v[144:145]
	v_cvt_pk_bf16_f32 v113, v108, v109
	v_mad_i64_i32 v[106:107], s[2:3], v106, s48, v[146:147]
	v_cvt_pk_bf16_f32 v94, v94, v95
	v_cvt_pk_bf16_f32 v95, v96, v97
	v_cvt_pk_bf16_f32 v96, v90, v91
	v_or_b32_e32 v90, 32, v150
	v_lshl_add_u64 v[66:67], v[66:67], 0, v[144:145]
	v_cvt_pk_bf16_f32 v49, v44, v45
	v_mad_i64_i32 v[42:43], s[2:3], v42, s48, v[146:147]
	v_cvt_pk_bf16_f32 v30, v30, v31
	v_cvt_pk_bf16_f32 v31, v32, v33
	v_cvt_pk_bf16_f32 v32, v26, v27
	v_add_u32_e32 v26, 0xa0, v150
	global_store_dwordx4 v[148:149], v[110:113], off offset:256
	v_cvt_pk_bf16_f32 v97, v92, v93
	v_mad_i64_i32 v[90:91], s[2:3], v90, s48, v[146:147]
	v_lshl_add_u64 v[110:111], v[106:107], 0, v[144:145]
	v_cvt_pk_bf16_f32 v78, v78, v79
	v_cvt_pk_bf16_f32 v79, v80, v81
	v_cvt_pk_bf16_f32 v80, v74, v75
	v_or_b32_e32 v74, 48, v150
	global_store_dwordx4 v[66:67], v[46:49], off offset:256
	v_cvt_pk_bf16_f32 v33, v28, v29
	v_mad_i64_i32 v[26:27], s[2:3], v26, s48, v[146:147]
	v_lshl_add_u64 v[46:47], v[42:43], 0, v[144:145]
	v_cvt_pk_bf16_f32 v14, v14, v15
	v_cvt_pk_bf16_f32 v15, v16, v17
	v_cvt_pk_bf16_f32 v16, v10, v11
	v_add_u32_e32 v10, 0xb0, v150
	global_store_dwordx4 v[110:111], v[94:97], off offset:256
	v_cvt_pk_bf16_f32 v81, v76, v77
	v_mad_i64_i32 v[74:75], s[2:3], v74, s48, v[146:147]
	v_lshl_add_u64 v[94:95], v[90:91], 0, v[144:145]
	global_store_dwordx4 v[46:47], v[30:33], off offset:256
	v_cvt_pk_bf16_f32 v17, v12, v13
	v_mad_i64_i32 v[10:11], s[2:3], v10, s48, v[146:147]
	v_lshl_add_u64 v[30:31], v[26:27], 0, v[144:145]
	v_cvt_pk_bf16_f32 v126, v126, v127
	v_cvt_pk_bf16_f32 v127, v128, v129
	v_cvt_pk_bf16_f32 v128, v122, v123
	v_cvt_pk_bf16_f32 v129, v124, v125
	v_cvt_pk_bf16_f32 v106, v118, v119
	v_cvt_pk_bf16_f32 v107, v120, v121
	v_cvt_pk_bf16_f32 v108, v114, v115
	v_cvt_pk_bf16_f32 v109, v116, v117
	v_cvt_pk_bf16_f32 v90, v102, v103
	v_cvt_pk_bf16_f32 v91, v104, v105
	v_cvt_pk_bf16_f32 v92, v98, v99
	v_cvt_pk_bf16_f32 v93, v100, v101
	global_store_dwordx4 v[94:95], v[78:81], off offset:256
	v_cvt_pk_bf16_f32 v76, v82, v83
	v_cvt_pk_bf16_f32 v77, v84, v85
	v_lshl_add_u64 v[78:79], v[74:75], 0, v[144:145]
	v_cvt_pk_bf16_f32 v74, v86, v87
	v_cvt_pk_bf16_f32 v75, v88, v89
	v_cvt_pk_bf16_f32 v73, v68, v69
	v_cvt_pk_bf16_f32 v62, v62, v63
	v_cvt_pk_bf16_f32 v63, v64, v65
	v_cvt_pk_bf16_f32 v64, v58, v59
	v_cvt_pk_bf16_f32 v65, v60, v61
	v_cvt_pk_bf16_f32 v42, v54, v55
	v_cvt_pk_bf16_f32 v43, v56, v57
	v_cvt_pk_bf16_f32 v44, v50, v51
	v_cvt_pk_bf16_f32 v45, v52, v53
	v_cvt_pk_bf16_f32 v26, v38, v39
	v_cvt_pk_bf16_f32 v27, v40, v41
	v_cvt_pk_bf16_f32 v28, v34, v35
	v_cvt_pk_bf16_f32 v29, v36, v37
	global_store_dwordx4 v[30:31], v[14:17], off offset:256
	v_cvt_pk_bf16_f32 v12, v18, v19
	v_cvt_pk_bf16_f32 v13, v20, v21
	v_lshl_add_u64 v[14:15], v[10:11], 0, v[144:145]
	v_cvt_pk_bf16_f32 v10, v22, v23
	v_cvt_pk_bf16_f32 v11, v24, v25
	v_cvt_pk_bf16_f32 v6, v6, v7
	v_cvt_pk_bf16_f32 v7, v8, v9
	v_cvt_pk_bf16_f32 v8, v2, v3
	v_cvt_pk_bf16_f32 v9, v4, v5
	s_and_b64 vcc, exec, s[0:1]
	s_mov_b32 s54, s52
	s_mov_b32 s55, s53
	s_mov_b64 s[2:3], s[8:9]
	s_mov_b64 s[10:11], s[6:7]
	s_mov_b32 s35, 0x3fb8aa3b
	s_mov_b32 s34, 0xc2ce8ed0
	global_store_dwordx4 v[148:149], v[126:129], off
	global_store_dwordx4 v[110:111], v[106:109], off
	global_store_dwordx4 v[94:95], v[90:93], off
	global_store_dwordx4 v[78:79], v[74:77], off
	global_store_dwordx4 v[78:79], v[70:73], off offset:256
	global_store_dwordx4 v[66:67], v[62:65], off
	global_store_dwordx4 v[46:47], v[42:45], off
	global_store_dwordx4 v[30:31], v[26:29], off
	global_store_dwordx4 v[14:15], v[10:13], off
	global_store_dwordx4 v[14:15], v[6:9], off offset:256
	s_cbranch_vccz .LBB0_452
	s_waitcnt vmcnt(0)
	s_cmpk_gt_u32 s5, 0xff
	s_cbranch_scc1 .LBB0_463
	s_barrier

.LBB0_471:
	s_add_u32 s38, s16, s2
	s_addc_u32 s39, s17, 0
	s_add_u32 s3, s38, 0x100
	s_addc_u32 s40, s39, 0
	s_and_b64 s[34:35], s[36:37], exec
	s_cselect_b32 vcc_hi, s9, s40
	s_cselect_b32 vcc_lo, s58, s3
	s_add_u32 s2, s14, s2
	s_addc_u32 s3, s15, 0
	s_add_u32 s34, s2, 0x100
	s_addc_u32 s35, s3, 0
	s_add_i32 s71, 0, 0x10000
	s_and_b64 s[2:3], s[36:37], exec
	s_cselect_b32 s73, s7, s35
	s_cselect_b32 s72, s5, s34
	s_add_u32 s2, s38, 0x10080
	s_addc_u32 s3, s39, 0
	s_add_i32 s41, s71, s51
	s_add_i32 m0, s42, 0xc000
	s_add_i32 s49, s42, 0xe000
	s_add_i32 s65, 0, 0x14000
	s_add_i32 s35, s41, 0x2000
	s_add_u32 s44, s72, 0x10000
	v_add_u32_e32 v152, s71, v137
	s_addc_u32 s45, s73, 0
	s_add_i32 s64, s65, s51
	ds_read_b128 v[140:143], v152
	ds_read_b128 v[144:147], v152 offset:1024
	ds_read_b128 v[148:151], v152 offset:2048
	ds_read_b128 v[152:155], v152 offset:3072
	s_add_i32 s40, s64, 0x2000
	s_add_i32 s97, 0, 0x18000
	s_add_u32 s38, vcc_lo, 0x10000
	s_addc_u32 s39, vcc_hi, 0
	s_add_i32 s50, s97, s51
	s_add_i32 s60, 0, 0x1c000
	s_add_i32 s96, s50, 0x2000
	s_add_u32 s36, s72, 0x10080
	s_addc_u32 s37, s73, 0
	s_add_i32 s71, s60, s51
	s_add_i32 s34, s71, 0x2000
	v_lshl_add_u64 v[188:189], s[2:3], 0, v[134:135]
	ds_read_b128 v[156:159], v139
	ds_read_b128 v[160:163], v139 offset:1024
	ds_read_b128 v[164:167], v139 offset:2048
	ds_read_b128 v[168:171], v139 offset:3072
	ds_read_b128 v[172:175], v139 offset:4096
	ds_read_b128 v[176:179], v139 offset:5120
	ds_read_b128 v[180:183], v139 offset:6144
	ds_read_b128 v[184:187], v139 offset:7168
	global_load_lds_dwordx4 v[188:189], off
	v_lshl_add_u64 v[188:189], s[2:3], 0, v[132:133]
	s_mov_b32 m0, s49
	s_nop 0
	global_load_lds_dwordx4 v[188:189], off
	s_waitcnt vmcnt(10)
	s_waitcnt lgkmcnt(8)
	s_barrier
	s_waitcnt lgkmcnt(0)
	s_setprio 1
	s_waitcnt lgkmcnt(0)
	v_mfma_f32_16x16x32_bf16 v[126:129], v[140:143], v[156:159], v[126:129]
	v_mfma_f32_16x16x32_bf16 v[122:125], v[148:151], v[156:159], v[122:125]
	v_mfma_f32_16x16x32_bf16 v[118:121], v[140:143], v[164:167], v[118:121]
	v_mfma_f32_16x16x32_bf16 v[114:117], v[148:151], v[164:167], v[114:117]
	v_mfma_f32_16x16x32_bf16 v[102:105], v[140:143], v[172:175], v[102:105]
	v_mfma_f32_16x16x32_bf16 v[98:101], v[148:151], v[172:175], v[98:101]
	v_mfma_f32_16x16x32_bf16 v[86:89], v[140:143], v[180:183], v[86:89]
	v_mfma_f32_16x16x32_bf16 v[82:85], v[148:151], v[180:183], v[82:85]
	v_mfma_f32_16x16x32_bf16 v[126:129], v[144:147], v[160:163], v[126:129]
	v_mfma_f32_16x16x32_bf16 v[122:125], v[152:155], v[160:163], v[122:125]
	v_mfma_f32_16x16x32_bf16 v[118:121], v[144:147], v[168:171], v[118:121]
	v_mfma_f32_16x16x32_bf16 v[114:117], v[152:155], v[168:171], v[114:117]
	v_mfma_f32_16x16x32_bf16 v[102:105], v[144:147], v[176:179], v[102:105]
	v_mfma_f32_16x16x32_bf16 v[98:101], v[152:155], v[176:179], v[98:101]
	v_mfma_f32_16x16x32_bf16 v[86:89], v[144:147], v[184:187], v[86:89]
	v_mfma_f32_16x16x32_bf16 v[82:85], v[152:155], v[184:187], v[82:85]
	s_setprio 0
	s_barrier
	v_add_u32_e32 v192, s65, v137
	s_mov_b32 m0, s41
	ds_read_b128 v[188:191], v192
	ds_read_b128 v[200:203], v192 offset:1024
	ds_read_b128 v[206:209], v192 offset:2048
	ds_read_b128 v[210:213], v192 offset:3072
	v_lshl_add_u64 v[192:193], s[72:73], 0, v[0:1]
	global_load_lds_dwordx4 v[192:193], off
	v_lshl_add_u64 v[196:197], s[72:73], 0, v[130:131]
	s_mov_b32 m0, s35
	s_nop 0
	global_load_lds_dwordx4 v[196:197], off
	s_waitcnt vmcnt(10)
	s_barrier
	s_waitcnt lgkmcnt(0)
	s_setprio 1
	s_waitcnt lgkmcnt(0)
	v_mfma_f32_16x16x32_bf16 v[110:113], v[188:191], v[156:159], v[110:113]
	v_mfma_f32_16x16x32_bf16 v[106:109], v[206:209], v[156:159], v[106:109]
	v_mfma_f32_16x16x32_bf16 v[94:97], v[188:191], v[164:167], v[94:97]
	v_mfma_f32_16x16x32_bf16 v[90:93], v[206:209], v[164:167], v[90:93]
	v_mfma_f32_16x16x32_bf16 v[78:81], v[188:191], v[172:175], v[78:81]
	v_mfma_f32_16x16x32_bf16 v[74:77], v[206:209], v[172:175], v[74:77]
	v_mfma_f32_16x16x32_bf16 v[70:73], v[188:191], v[180:183], v[70:73]
	v_mfma_f32_16x16x32_bf16 v[66:69], v[206:209], v[180:183], v[66:69]
	v_mfma_f32_16x16x32_bf16 v[110:113], v[200:203], v[160:163], v[110:113]
	v_mfma_f32_16x16x32_bf16 v[106:109], v[210:213], v[160:163], v[106:109]
	v_mfma_f32_16x16x32_bf16 v[94:97], v[200:203], v[168:171], v[94:97]
	v_mfma_f32_16x16x32_bf16 v[90:93], v[210:213], v[168:171], v[90:93]
	v_mfma_f32_16x16x32_bf16 v[78:81], v[200:203], v[176:179], v[78:81]
	v_mfma_f32_16x16x32_bf16 v[74:77], v[210:213], v[176:179], v[74:77]
	v_mfma_f32_16x16x32_bf16 v[70:73], v[200:203], v[184:187], v[70:73]
	v_mfma_f32_16x16x32_bf16 v[66:69], v[210:213], v[184:187], v[66:69]
	s_setprio 0
	s_mov_b32 m0, s42
	v_lshl_add_u64 v[198:199], vcc, 0, v[134:135]
	s_barrier
	ds_read_b128 v[156:159], v139 offset:16384
	ds_read_b128 v[160:163], v139 offset:17408
	ds_read_b128 v[164:167], v139 offset:18432
	ds_read_b128 v[168:171], v139 offset:19456
	ds_read_b128 v[172:175], v139 offset:20480
	ds_read_b128 v[176:179], v139 offset:21504
	ds_read_b128 v[180:183], v139 offset:22528
	ds_read_b128 v[184:187], v139 offset:23552
	global_load_lds_dwordx4 v[198:199], off
	v_lshl_add_u64 v[214:215], vcc, 0, v[132:133]
	s_mov_b32 m0, s52
	s_nop 0
	global_load_lds_dwordx4 v[214:215], off
	s_barrier
	s_waitcnt lgkmcnt(0)
	s_setprio 1
	s_waitcnt lgkmcnt(0)
	v_mfma_f32_16x16x32_bf16 v[62:65], v[140:143], v[156:159], v[62:65]
	v_mfma_f32_16x16x32_bf16 v[58:61], v[148:151], v[156:159], v[58:61]
	v_mfma_f32_16x16x32_bf16 v[54:57], v[140:143], v[164:167], v[54:57]
	v_mfma_f32_16x16x32_bf16 v[50:53], v[148:151], v[164:167], v[50:53]
	v_mfma_f32_16x16x32_bf16 v[38:41], v[140:143], v[172:175], v[38:41]
	v_mfma_f32_16x16x32_bf16 v[34:37], v[148:151], v[172:175], v[34:37]
	v_mfma_f32_16x16x32_bf16 v[22:25], v[140:143], v[180:183], v[22:25]
	v_mfma_f32_16x16x32_bf16 v[18:21], v[148:151], v[180:183], v[18:21]
	v_mfma_f32_16x16x32_bf16 v[62:65], v[144:147], v[160:163], v[62:65]
	v_mfma_f32_16x16x32_bf16 v[58:61], v[152:155], v[160:163], v[58:61]
	v_mfma_f32_16x16x32_bf16 v[54:57], v[144:147], v[168:171], v[54:57]
	v_mfma_f32_16x16x32_bf16 v[50:53], v[152:155], v[168:171], v[50:53]
	v_mfma_f32_16x16x32_bf16 v[38:41], v[144:147], v[176:179], v[38:41]
	v_mfma_f32_16x16x32_bf16 v[34:37], v[152:155], v[176:179], v[34:37]
	v_mfma_f32_16x16x32_bf16 v[22:25], v[144:147], v[184:187], v[22:25]
	v_mfma_f32_16x16x32_bf16 v[18:21], v[152:155], v[184:187], v[18:21]
	s_setprio 0
	s_barrier
	s_mov_b32 m0, s64
	v_lshl_add_u64 v[140:141], s[44:45], 0, v[0:1]
	global_load_lds_dwordx4 v[140:141], off
	v_lshl_add_u64 v[140:141], s[44:45], 0, v[130:131]
	s_mov_b32 m0, s40
	s_nop 0
	global_load_lds_dwordx4 v[140:141], off
	s_waitcnt vmcnt(10)
	s_barrier
	s_setprio 1
	v_mfma_f32_16x16x32_bf16 v[46:49], v[188:191], v[156:159], v[46:49]
	v_mfma_f32_16x16x32_bf16 v[42:45], v[206:209], v[156:159], v[42:45]
	v_mfma_f32_16x16x32_bf16 v[30:33], v[188:191], v[164:167], v[30:33]
	v_mfma_f32_16x16x32_bf16 v[26:29], v[206:209], v[164:167], v[26:29]
	v_mfma_f32_16x16x32_bf16 v[14:17], v[188:191], v[172:175], v[14:17]
	v_mfma_f32_16x16x32_bf16 v[10:13], v[206:209], v[172:175], v[10:13]
	v_mfma_f32_16x16x32_bf16 v[6:9], v[188:191], v[180:183], v[6:9]
	v_mfma_f32_16x16x32_bf16 v[2:5], v[206:209], v[180:183], v[2:5]
	v_mfma_f32_16x16x32_bf16 v[46:49], v[200:203], v[160:163], v[46:49]
	v_mfma_f32_16x16x32_bf16 v[42:45], v[210:213], v[160:163], v[42:45]
	v_mfma_f32_16x16x32_bf16 v[30:33], v[200:203], v[168:171], v[30:33]
	v_mfma_f32_16x16x32_bf16 v[26:29], v[210:213], v[168:171], v[26:29]
	v_mfma_f32_16x16x32_bf16 v[14:17], v[200:203], v[176:179], v[14:17]
	v_mfma_f32_16x16x32_bf16 v[10:13], v[210:213], v[176:179], v[10:13]
	v_mfma_f32_16x16x32_bf16 v[6:9], v[200:203], v[184:187], v[6:9]
	v_mfma_f32_16x16x32_bf16 v[2:5], v[210:213], v[184:187], v[2:5]
	s_setprio 0
	v_add_u32_e32 v152, s97, v137
	s_barrier
	ds_read_b128 v[140:143], v152
	ds_read_b128 v[144:147], v152 offset:1024
	ds_read_b128 v[148:151], v152 offset:2048
	ds_read_b128 v[152:155], v152 offset:3072
	s_mov_b32 m0, s53
	v_lshl_add_u64 v[188:189], s[38:39], 0, v[134:135]
	ds_read_b128 v[156:159], v139 offset:32768
	ds_read_b128 v[160:163], v139 offset:33792
	ds_read_b128 v[164:167], v139 offset:34816
	ds_read_b128 v[168:171], v139 offset:35840
	ds_read_b128 v[172:175], v139 offset:36864
	ds_read_b128 v[176:179], v139 offset:37888
	ds_read_b128 v[180:183], v139 offset:38912
	ds_read_b128 v[184:187], v139 offset:39936
	global_load_lds_dwordx4 v[188:189], off
	v_lshl_add_u64 v[188:189], s[38:39], 0, v[132:133]
	s_mov_b32 m0, s54
	s_nop 0
	global_load_lds_dwordx4 v[188:189], off
	s_waitcnt vmcnt(10)
	s_waitcnt lgkmcnt(8)
	s_barrier
	s_waitcnt lgkmcnt(0)
	s_setprio 1
	s_waitcnt lgkmcnt(0)
	v_mfma_f32_16x16x32_bf16 v[126:129], v[140:143], v[156:159], v[126:129]
	v_mfma_f32_16x16x32_bf16 v[122:125], v[148:151], v[156:159], v[122:125]
	v_mfma_f32_16x16x32_bf16 v[118:121], v[140:143], v[164:167], v[118:121]
	v_mfma_f32_16x16x32_bf16 v[114:117], v[148:151], v[164:167], v[114:117]
	v_mfma_f32_16x16x32_bf16 v[102:105], v[140:143], v[172:175], v[102:105]
	v_mfma_f32_16x16x32_bf16 v[98:101], v[148:151], v[172:175], v[98:101]
	v_mfma_f32_16x16x32_bf16 v[86:89], v[140:143], v[180:183], v[86:89]
	v_mfma_f32_16x16x32_bf16 v[82:85], v[148:151], v[180:183], v[82:85]
	v_mfma_f32_16x16x32_bf16 v[126:129], v[144:147], v[160:163], v[126:129]
	v_mfma_f32_16x16x32_bf16 v[122:125], v[152:155], v[160:163], v[122:125]
	v_mfma_f32_16x16x32_bf16 v[118:121], v[144:147], v[168:171], v[118:121]
	v_mfma_f32_16x16x32_bf16 v[114:117], v[152:155], v[168:171], v[114:117]
	v_mfma_f32_16x16x32_bf16 v[102:105], v[144:147], v[176:179], v[102:105]
	v_mfma_f32_16x16x32_bf16 v[98:101], v[152:155], v[176:179], v[98:101]
	v_mfma_f32_16x16x32_bf16 v[86:89], v[144:147], v[184:187], v[86:89]
	v_mfma_f32_16x16x32_bf16 v[82:85], v[152:155], v[184:187], v[82:85]
	s_setprio 0
	s_barrier
	s_mov_b32 m0, s50
	v_add_u32_e32 v195, s60, v137
	v_lshl_add_u64 v[192:193], v[192:193], 0, s[74:75]
	ds_read_b128 v[188:191], v195
	ds_read_b128 v[200:203], v195 offset:1024
	ds_read_b128 v[206:209], v195 offset:2048
	ds_read_b128 v[210:213], v195 offset:3072
	global_load_lds_dwordx4 v[192:193], off
	v_lshl_add_u64 v[192:193], v[196:197], 0, s[74:75]
	s_mov_b32 m0, s96
	s_nop 0
	global_load_lds_dwordx4 v[192:193], off
	s_waitcnt vmcnt(10)
	s_barrier
	s_waitcnt lgkmcnt(0)
	s_setprio 1
	s_waitcnt lgkmcnt(0)
	v_mfma_f32_16x16x32_bf16 v[110:113], v[188:191], v[156:159], v[110:113]
	v_mfma_f32_16x16x32_bf16 v[106:109], v[206:209], v[156:159], v[106:109]
	v_mfma_f32_16x16x32_bf16 v[94:97], v[188:191], v[164:167], v[94:97]
	v_mfma_f32_16x16x32_bf16 v[90:93], v[206:209], v[164:167], v[90:93]
	v_mfma_f32_16x16x32_bf16 v[78:81], v[188:191], v[172:175], v[78:81]
	v_mfma_f32_16x16x32_bf16 v[74:77], v[206:209], v[172:175], v[74:77]
	v_mfma_f32_16x16x32_bf16 v[70:73], v[188:191], v[180:183], v[70:73]
	v_mfma_f32_16x16x32_bf16 v[66:69], v[206:209], v[180:183], v[66:69]
	v_mfma_f32_16x16x32_bf16 v[110:113], v[200:203], v[160:163], v[110:113]
	v_mfma_f32_16x16x32_bf16 v[106:109], v[210:213], v[160:163], v[106:109]
	v_mfma_f32_16x16x32_bf16 v[94:97], v[200:203], v[168:171], v[94:97]
	v_mfma_f32_16x16x32_bf16 v[90:93], v[210:213], v[168:171], v[90:93]
	v_mfma_f32_16x16x32_bf16 v[78:81], v[200:203], v[176:179], v[78:81]
	v_mfma_f32_16x16x32_bf16 v[74:77], v[210:213], v[176:179], v[74:77]
	v_mfma_f32_16x16x32_bf16 v[70:73], v[200:203], v[184:187], v[70:73]
	v_mfma_f32_16x16x32_bf16 v[66:69], v[210:213], v[184:187], v[66:69]
	s_setprio 0
	s_mov_b32 m0, s55
	v_lshl_add_u64 v[192:193], v[198:199], 0, s[74:75]
	s_barrier
	ds_read_b128 v[156:159], v139 offset:49152
	ds_read_b128 v[160:163], v139 offset:50176
	ds_read_b128 v[164:167], v139 offset:51200
	ds_read_b128 v[168:171], v139 offset:52224
	ds_read_b128 v[172:175], v139 offset:53248
	ds_read_b128 v[176:179], v139 offset:54272
	ds_read_b128 v[180:183], v139 offset:55296
	ds_read_b128 v[184:187], v139 offset:56320
	global_load_lds_dwordx4 v[192:193], off
	v_lshl_add_u64 v[192:193], v[214:215], 0, s[74:75]
	s_mov_b32 m0, s56
	s_nop 0
	global_load_lds_dwordx4 v[192:193], off
	s_barrier
	s_waitcnt lgkmcnt(0)
	s_setprio 1
	s_waitcnt lgkmcnt(0)
	v_mfma_f32_16x16x32_bf16 v[62:65], v[140:143], v[156:159], v[62:65]
	v_mfma_f32_16x16x32_bf16 v[58:61], v[148:151], v[156:159], v[58:61]
	v_mfma_f32_16x16x32_bf16 v[54:57], v[140:143], v[164:167], v[54:57]
	v_mfma_f32_16x16x32_bf16 v[50:53], v[148:151], v[164:167], v[50:53]
	v_mfma_f32_16x16x32_bf16 v[38:41], v[140:143], v[172:175], v[38:41]
	v_mfma_f32_16x16x32_bf16 v[34:37], v[148:151], v[172:175], v[34:37]
	v_mfma_f32_16x16x32_bf16 v[22:25], v[140:143], v[180:183], v[22:25]
	v_mfma_f32_16x16x32_bf16 v[18:21], v[148:151], v[180:183], v[18:21]
	v_mfma_f32_16x16x32_bf16 v[62:65], v[144:147], v[160:163], v[62:65]
	v_mfma_f32_16x16x32_bf16 v[58:61], v[152:155], v[160:163], v[58:61]
	v_mfma_f32_16x16x32_bf16 v[54:57], v[144:147], v[168:171], v[54:57]
	v_mfma_f32_16x16x32_bf16 v[50:53], v[152:155], v[168:171], v[50:53]
	v_mfma_f32_16x16x32_bf16 v[38:41], v[144:147], v[176:179], v[38:41]
	v_mfma_f32_16x16x32_bf16 v[34:37], v[152:155], v[176:179], v[34:37]
	v_mfma_f32_16x16x32_bf16 v[22:25], v[144:147], v[184:187], v[22:25]
	v_mfma_f32_16x16x32_bf16 v[18:21], v[152:155], v[184:187], v[18:21]
	s_setprio 0
	s_barrier
	s_mov_b32 m0, s71
	v_lshl_add_u64 v[140:141], s[36:37], 0, v[0:1]
	global_load_lds_dwordx4 v[140:141], off
	v_lshl_add_u64 v[140:141], s[36:37], 0, v[130:131]
	s_mov_b32 m0, s34
	s_nop 0
	global_load_lds_dwordx4 v[140:141], off
	s_waitcnt vmcnt(10)
	s_barrier
	s_setprio 1
	v_mfma_f32_16x16x32_bf16 v[46:49], v[188:191], v[156:159], v[46:49]
	v_mfma_f32_16x16x32_bf16 v[42:45], v[206:209], v[156:159], v[42:45]
	v_mfma_f32_16x16x32_bf16 v[30:33], v[188:191], v[164:167], v[30:33]
	v_mfma_f32_16x16x32_bf16 v[26:29], v[206:209], v[164:167], v[26:29]
	v_mfma_f32_16x16x32_bf16 v[14:17], v[188:191], v[172:175], v[14:17]
	v_mfma_f32_16x16x32_bf16 v[10:13], v[206:209], v[172:175], v[10:13]
	v_mfma_f32_16x16x32_bf16 v[6:9], v[188:191], v[180:183], v[6:9]
	v_mfma_f32_16x16x32_bf16 v[2:5], v[206:209], v[180:183], v[2:5]
	v_mfma_f32_16x16x32_bf16 v[46:49], v[200:203], v[160:163], v[46:49]
	v_mfma_f32_16x16x32_bf16 v[42:45], v[210:213], v[160:163], v[42:45]
	v_mfma_f32_16x16x32_bf16 v[30:33], v[200:203], v[168:171], v[30:33]
	v_mfma_f32_16x16x32_bf16 v[26:29], v[210:213], v[168:171], v[26:29]
	v_mfma_f32_16x16x32_bf16 v[14:17], v[200:203], v[176:179], v[14:17]
	v_mfma_f32_16x16x32_bf16 v[10:13], v[210:213], v[176:179], v[10:13]
	v_mfma_f32_16x16x32_bf16 v[6:9], v[200:203], v[184:187], v[6:9]
	v_mfma_f32_16x16x32_bf16 v[2:5], v[210:213], v[184:187], v[2:5]
	s_setprio 0
	s_movk_i32 s2, 0x100
	s_andn2_b64 vcc, exec, s[18:19]
	s_mov_b64 s[36:37], -1
	s_mov_b64 s[18:19], 0
	s_barrier
	s_cbranch_vccz .LBB0_471
	v_lshl_add_u32 v140, s67, 8, v136
	v_lshl_or_b32 v142, s59, 8, v138
	v_ashrrev_i32_e32 v141, 31, v140
	v_readlane_b32 s2, v250, 24
	v_cvt_pk_bf16_f32 v110, v110, v111
	v_cvt_pk_bf16_f32 v111, v112, v113
	v_cvt_pk_bf16_f32 v112, v106, v107
	v_or_b32_e32 v106, 16, v140
	v_cvt_pk_bf16_f32 v94, v94, v95
	v_cvt_pk_bf16_f32 v95, v96, v97
	v_cvt_pk_bf16_f32 v96, v90, v91
	v_or_b32_e32 v90, 32, v140
	v_cvt_pk_bf16_f32 v78, v78, v79
	v_cvt_pk_bf16_f32 v79, v80, v81
	v_cvt_pk_bf16_f32 v80, v74, v75
	v_or_b32_e32 v74, 48, v140
	v_lshlrev_b64 v[144:145], 10, v[140:141]
	v_readlane_b32 s3, v250, 25
	v_ashrrev_i32_e32 v143, 31, v142
	v_ashrrev_i32_e32 v107, 31, v106
	v_ashrrev_i32_e32 v91, 31, v90
	v_ashrrev_i32_e32 v75, 31, v74
	v_lshl_add_u64 v[144:145], s[2:3], 0, v[144:145]
	v_lshlrev_b64 v[142:143], 1, v[142:143]
	v_lshlrev_b64 v[106:107], 10, v[106:107]
	v_lshlrev_b64 v[90:91], 10, v[90:91]
	v_lshlrev_b64 v[74:75], 10, v[74:75]
	v_lshl_add_u64 v[144:145], v[144:145], 0, v[142:143]
	v_lshl_add_u64 v[106:107], s[2:3], 0, v[106:107]
	v_lshl_add_u64 v[90:91], s[2:3], 0, v[90:91]
	v_lshl_add_u64 v[74:75], s[2:3], 0, v[74:75]
	s_mov_b64 s[2:3], 0x20000
	v_cvt_pk_bf16_f32 v70, v70, v71
	v_cvt_pk_bf16_f32 v71, v72, v73
	v_cvt_pk_bf16_f32 v72, v66, v67
	v_lshl_add_u64 v[66:67], v[144:145], 0, s[2:3]
	s_mov_b32 s2, 0x20000
	v_cvt_pk_bf16_f32 v62, v62, v63
	v_cvt_pk_bf16_f32 v63, v64, v65
	v_cvt_pk_bf16_f32 v64, v58, v59
	v_add_co_u32_e32 v58, vcc, s2, v144
	v_cvt_pk_bf16_f32 v46, v46, v47
	s_nop 0
	v_addc_co_u32_e32 v59, vcc, 0, v145, vcc
	v_cvt_pk_bf16_f32 v47, v48, v49
	v_cvt_pk_bf16_f32 v48, v42, v43
	v_cvt_pk_bf16_f32 v49, v44, v45
	s_mov_b64 s[2:3], 0x24000
	global_store_dwordx4 v[66:67], v[46:49], off offset:256
	v_cvt_pk_bf16_f32 v30, v30, v31
	v_cvt_pk_bf16_f32 v31, v32, v33
	v_lshl_add_u64 v[46:47], v[144:145], 0, s[2:3]
	v_add_co_u32_e32 v48, vcc, s63, v144
	v_cvt_pk_bf16_f32 v32, v26, v27
	v_cvt_pk_bf16_f32 v33, v28, v29
	s_mov_b64 s[2:3], 0x28000
	v_addc_co_u32_e32 v49, vcc, 0, v145, vcc
	global_store_dwordx4 v[46:47], v[30:33], off offset:256
	v_cvt_pk_bf16_f32 v14, v14, v15
	v_cvt_pk_bf16_f32 v15, v16, v17
	v_lshl_add_u64 v[30:31], v[144:145], 0, s[2:3]
	s_mov_b32 s2, 0x28000
	v_add_co_u32_e32 v32, vcc, s2, v144
	v_cvt_pk_bf16_f32 v16, v10, v11
	v_cvt_pk_bf16_f32 v17, v12, v13
	s_mov_b64 s[2:3], 0x2c000
	v_cvt_pk_bf16_f32 v113, v108, v109
	v_addc_co_u32_e32 v33, vcc, 0, v145, vcc
	global_store_dwordx4 v[30:31], v[14:17], off offset:256
	global_store_dwordx4 v[144:145], v[110:113], off offset:256
	v_cvt_pk_bf16_f32 v97, v92, v93
	v_lshl_add_u64 v[14:15], v[144:145], 0, s[2:3]
	s_mov_b32 s2, 0x2c000
	v_lshl_add_u64 v[110:111], v[106:107], 0, v[142:143]
	v_add_co_u32_e32 v16, vcc, s2, v144
	global_store_dwordx4 v[110:111], v[94:97], off offset:256
	v_cvt_pk_bf16_f32 v81, v76, v77
	v_addc_co_u32_e32 v17, vcc, 0, v145, vcc
	v_lshl_add_u64 v[94:95], v[90:91], 0, v[142:143]
	v_cvt_pk_bf16_f32 v126, v126, v127
	v_cvt_pk_bf16_f32 v127, v128, v129
	v_cvt_pk_bf16_f32 v128, v122, v123
	v_cvt_pk_bf16_f32 v129, v124, v125
	v_cvt_pk_bf16_f32 v106, v118, v119
	v_cvt_pk_bf16_f32 v107, v120, v121
	v_cvt_pk_bf16_f32 v108, v114, v115
	v_cvt_pk_bf16_f32 v109, v116, v117
	v_cvt_pk_bf16_f32 v90, v102, v103
	v_cvt_pk_bf16_f32 v91, v104, v105
	v_cvt_pk_bf16_f32 v92, v98, v99
	v_cvt_pk_bf16_f32 v93, v100, v101
	global_store_dwordx4 v[94:95], v[78:81], off offset:256
	v_cvt_pk_bf16_f32 v76, v82, v83
	v_cvt_pk_bf16_f32 v77, v84, v85
	v_lshl_add_u64 v[78:79], v[74:75], 0, v[142:143]
	v_cvt_pk_bf16_f32 v74, v86, v87
	v_cvt_pk_bf16_f32 v75, v88, v89
	v_cvt_pk_bf16_f32 v73, v68, v69
	v_cvt_pk_bf16_f32 v65, v60, v61
	v_cvt_pk_bf16_f32 v42, v54, v55
	v_cvt_pk_bf16_f32 v43, v56, v57
	v_cvt_pk_bf16_f32 v44, v50, v51
	v_cvt_pk_bf16_f32 v45, v52, v53
	v_cvt_pk_bf16_f32 v26, v38, v39
	v_cvt_pk_bf16_f32 v27, v40, v41
	v_cvt_pk_bf16_f32 v28, v34, v35
	v_cvt_pk_bf16_f32 v29, v36, v37
	v_cvt_pk_bf16_f32 v10, v22, v23
	v_cvt_pk_bf16_f32 v11, v24, v25
	v_cvt_pk_bf16_f32 v12, v18, v19
	v_cvt_pk_bf16_f32 v13, v20, v21
	v_cvt_pk_bf16_f32 v6, v6, v7
	v_cvt_pk_bf16_f32 v7, v8, v9
	v_cvt_pk_bf16_f32 v8, v2, v3
	v_cvt_pk_bf16_f32 v9, v4, v5
	s_and_b64 vcc, exec, s[0:1]
	s_mov_b32 s59, s6
	s_mov_b32 s67, s8
	s_mov_b64 s[14:15], s[12:13]
	s_mov_b64 s[16:17], s[10:11]
	global_store_dwordx4 v[144:145], v[126:129], off
	global_store_dwordx4 v[110:111], v[106:109], off
	global_store_dwordx4 v[94:95], v[90:93], off
	global_store_dwordx4 v[78:79], v[74:77], off
	global_store_dwordx4 v[78:79], v[70:73], off offset:256
	global_store_dwordx4 v[58:59], v[62:65], off
	global_store_dwordx4 v[48:49], v[42:45], off
	global_store_dwordx4 v[32:33], v[26:29], off
	global_store_dwordx4 v[16:17], v[10:13], off
	global_store_dwordx4 v[14:15], v[6:9], off offset:256
	s_cbranch_vccz .LBB0_468
	s_waitcnt vmcnt(0)
	s_cmpk_gt_u32 s22, 0xff
	v_readlane_b32 s57, v255, 48
	s_cbranch_scc1 .LBB0_475
	s_barrier

.LBB0_483:
	s_add_u32 s38, s16, s2
	s_addc_u32 s39, s17, 0
	s_add_u32 s3, s38, 0x100
	s_addc_u32 s40, s39, 0
	s_and_b64 s[34:35], s[36:37], exec
	s_cselect_b32 vcc_hi, s9, s40
	s_cselect_b32 vcc_lo, s58, s3
	s_add_u32 s2, s14, s2
	s_addc_u32 s3, s15, 0
	s_add_u32 s34, s2, 0x100
	s_addc_u32 s35, s3, 0
	s_add_i32 s42, 0, 0x10000
	s_and_b64 s[2:3], s[36:37], exec
	s_cselect_b32 s73, s7, s35
	s_cselect_b32 s72, s5, s34
	s_add_u32 s2, s38, 0x10080
	s_addc_u32 s3, s39, 0
	s_add_i32 s41, s42, s51
	s_add_i32 m0, s49, 0xc000
	s_add_i32 s43, s49, 0xe000
	s_add_i32 s40, 0, 0x14000
	s_add_i32 s35, s41, 0x2000
	s_add_u32 s44, s72, 0x10000
	v_add_u32_e32 v152, s42, v137
	s_addc_u32 s45, s73, 0
	s_add_i32 s65, s40, s51
	ds_read_b128 v[140:143], v152
	ds_read_b128 v[144:147], v152 offset:1024
	ds_read_b128 v[148:151], v152 offset:2048
	ds_read_b128 v[152:155], v152 offset:3072
	s_add_i32 s64, s65, 0x2000
	s_add_i32 s97, 0, 0x18000
	s_add_u32 s38, vcc_lo, 0x10000
	s_addc_u32 s39, vcc_hi, 0
	s_add_i32 s96, s97, s51
	s_add_i32 s60, 0, 0x1c000
	s_add_i32 s50, s96, 0x2000
	s_add_u32 s36, s72, 0x10080
	s_addc_u32 s37, s73, 0
	s_add_i32 s34, s60, s51
	s_add_i32 s71, s34, 0x2000
	v_lshl_add_u64 v[188:189], s[2:3], 0, v[134:135]
	ds_read_b128 v[156:159], v139
	ds_read_b128 v[160:163], v139 offset:1024
	ds_read_b128 v[164:167], v139 offset:2048
	ds_read_b128 v[168:171], v139 offset:3072
	ds_read_b128 v[172:175], v139 offset:4096
	ds_read_b128 v[176:179], v139 offset:5120
	ds_read_b128 v[180:183], v139 offset:6144
	ds_read_b128 v[184:187], v139 offset:7168
	global_load_lds_dwordx4 v[188:189], off
	v_lshl_add_u64 v[188:189], s[2:3], 0, v[132:133]
	s_mov_b32 m0, s43
	s_nop 0
	global_load_lds_dwordx4 v[188:189], off
	s_waitcnt vmcnt(10)
	s_waitcnt lgkmcnt(8)
	s_barrier
	s_waitcnt lgkmcnt(0)
	s_setprio 1
	s_waitcnt lgkmcnt(0)
	v_mfma_f32_16x16x32_bf16 v[126:129], v[140:143], v[156:159], v[126:129]
	v_mfma_f32_16x16x32_bf16 v[122:125], v[148:151], v[156:159], v[122:125]
	v_mfma_f32_16x16x32_bf16 v[118:121], v[140:143], v[164:167], v[118:121]
	v_mfma_f32_16x16x32_bf16 v[114:117], v[148:151], v[164:167], v[114:117]
	v_mfma_f32_16x16x32_bf16 v[102:105], v[140:143], v[172:175], v[102:105]
	v_mfma_f32_16x16x32_bf16 v[98:101], v[148:151], v[172:175], v[98:101]
	v_mfma_f32_16x16x32_bf16 v[86:89], v[140:143], v[180:183], v[86:89]
	v_mfma_f32_16x16x32_bf16 v[82:85], v[148:151], v[180:183], v[82:85]
	v_mfma_f32_16x16x32_bf16 v[126:129], v[144:147], v[160:163], v[126:129]
	v_mfma_f32_16x16x32_bf16 v[122:125], v[152:155], v[160:163], v[122:125]
	v_mfma_f32_16x16x32_bf16 v[118:121], v[144:147], v[168:171], v[118:121]
	v_mfma_f32_16x16x32_bf16 v[114:117], v[152:155], v[168:171], v[114:117]
	v_mfma_f32_16x16x32_bf16 v[102:105], v[144:147], v[176:179], v[102:105]
	v_mfma_f32_16x16x32_bf16 v[98:101], v[152:155], v[176:179], v[98:101]
	v_mfma_f32_16x16x32_bf16 v[86:89], v[144:147], v[184:187], v[86:89]
	v_mfma_f32_16x16x32_bf16 v[82:85], v[152:155], v[184:187], v[82:85]
	s_setprio 0
	s_barrier
	v_add_u32_e32 v192, s40, v137
	s_mov_b32 m0, s41
	ds_read_b128 v[188:191], v192
	ds_read_b128 v[200:203], v192 offset:1024
	ds_read_b128 v[206:209], v192 offset:2048
	ds_read_b128 v[210:213], v192 offset:3072
	v_lshl_add_u64 v[192:193], s[72:73], 0, v[0:1]
	global_load_lds_dwordx4 v[192:193], off
	v_lshl_add_u64 v[196:197], s[72:73], 0, v[130:131]
	s_mov_b32 m0, s35
	s_nop 0
	global_load_lds_dwordx4 v[196:197], off
	s_waitcnt vmcnt(10)
	s_barrier
	s_waitcnt lgkmcnt(0)
	s_setprio 1
	s_waitcnt lgkmcnt(0)
	v_mfma_f32_16x16x32_bf16 v[110:113], v[188:191], v[156:159], v[110:113]
	v_mfma_f32_16x16x32_bf16 v[106:109], v[206:209], v[156:159], v[106:109]
	v_mfma_f32_16x16x32_bf16 v[94:97], v[188:191], v[164:167], v[94:97]
	v_mfma_f32_16x16x32_bf16 v[90:93], v[206:209], v[164:167], v[90:93]
	v_mfma_f32_16x16x32_bf16 v[78:81], v[188:191], v[172:175], v[78:81]
	v_mfma_f32_16x16x32_bf16 v[74:77], v[206:209], v[172:175], v[74:77]
	v_mfma_f32_16x16x32_bf16 v[70:73], v[188:191], v[180:183], v[70:73]
	v_mfma_f32_16x16x32_bf16 v[66:69], v[206:209], v[180:183], v[66:69]
	v_mfma_f32_16x16x32_bf16 v[110:113], v[200:203], v[160:163], v[110:113]
	v_mfma_f32_16x16x32_bf16 v[106:109], v[210:213], v[160:163], v[106:109]
	v_mfma_f32_16x16x32_bf16 v[94:97], v[200:203], v[168:171], v[94:97]
	v_mfma_f32_16x16x32_bf16 v[90:93], v[210:213], v[168:171], v[90:93]
	v_mfma_f32_16x16x32_bf16 v[78:81], v[200:203], v[176:179], v[78:81]
	v_mfma_f32_16x16x32_bf16 v[74:77], v[210:213], v[176:179], v[74:77]
	v_mfma_f32_16x16x32_bf16 v[70:73], v[200:203], v[184:187], v[70:73]
	v_mfma_f32_16x16x32_bf16 v[66:69], v[210:213], v[184:187], v[66:69]
	s_setprio 0
	s_mov_b32 m0, s49
	v_lshl_add_u64 v[198:199], vcc, 0, v[134:135]
	s_barrier
	ds_read_b128 v[156:159], v139 offset:16384
	ds_read_b128 v[160:163], v139 offset:17408
	ds_read_b128 v[164:167], v139 offset:18432
	ds_read_b128 v[168:171], v139 offset:19456
	ds_read_b128 v[172:175], v139 offset:20480
	ds_read_b128 v[176:179], v139 offset:21504
	ds_read_b128 v[180:183], v139 offset:22528
	ds_read_b128 v[184:187], v139 offset:23552
	global_load_lds_dwordx4 v[198:199], off
	v_lshl_add_u64 v[214:215], vcc, 0, v[132:133]
	s_mov_b32 m0, s52
	s_nop 0
	global_load_lds_dwordx4 v[214:215], off
	s_barrier
	s_waitcnt lgkmcnt(0)
	s_setprio 1
	s_waitcnt lgkmcnt(0)
	v_mfma_f32_16x16x32_bf16 v[62:65], v[140:143], v[156:159], v[62:65]
	v_mfma_f32_16x16x32_bf16 v[58:61], v[148:151], v[156:159], v[58:61]
	v_mfma_f32_16x16x32_bf16 v[54:57], v[140:143], v[164:167], v[54:57]
	v_mfma_f32_16x16x32_bf16 v[50:53], v[148:151], v[164:167], v[50:53]
	v_mfma_f32_16x16x32_bf16 v[38:41], v[140:143], v[172:175], v[38:41]
	v_mfma_f32_16x16x32_bf16 v[34:37], v[148:151], v[172:175], v[34:37]
	v_mfma_f32_16x16x32_bf16 v[22:25], v[140:143], v[180:183], v[22:25]
	v_mfma_f32_16x16x32_bf16 v[18:21], v[148:151], v[180:183], v[18:21]
	v_mfma_f32_16x16x32_bf16 v[62:65], v[144:147], v[160:163], v[62:65]
	v_mfma_f32_16x16x32_bf16 v[58:61], v[152:155], v[160:163], v[58:61]
	v_mfma_f32_16x16x32_bf16 v[54:57], v[144:147], v[168:171], v[54:57]
	v_mfma_f32_16x16x32_bf16 v[50:53], v[152:155], v[168:171], v[50:53]
	v_mfma_f32_16x16x32_bf16 v[38:41], v[144:147], v[176:179], v[38:41]
	v_mfma_f32_16x16x32_bf16 v[34:37], v[152:155], v[176:179], v[34:37]
	v_mfma_f32_16x16x32_bf16 v[22:25], v[144:147], v[184:187], v[22:25]
	v_mfma_f32_16x16x32_bf16 v[18:21], v[152:155], v[184:187], v[18:21]
	s_setprio 0
	s_barrier
	s_mov_b32 m0, s65
	v_lshl_add_u64 v[140:141], s[44:45], 0, v[0:1]
	global_load_lds_dwordx4 v[140:141], off
	v_lshl_add_u64 v[140:141], s[44:45], 0, v[130:131]
	s_mov_b32 m0, s64
	s_nop 0
	global_load_lds_dwordx4 v[140:141], off
	s_waitcnt vmcnt(10)
	s_barrier
	s_setprio 1
	v_mfma_f32_16x16x32_bf16 v[46:49], v[188:191], v[156:159], v[46:49]
	v_mfma_f32_16x16x32_bf16 v[42:45], v[206:209], v[156:159], v[42:45]
	v_mfma_f32_16x16x32_bf16 v[30:33], v[188:191], v[164:167], v[30:33]
	v_mfma_f32_16x16x32_bf16 v[26:29], v[206:209], v[164:167], v[26:29]
	v_mfma_f32_16x16x32_bf16 v[14:17], v[188:191], v[172:175], v[14:17]
	v_mfma_f32_16x16x32_bf16 v[10:13], v[206:209], v[172:175], v[10:13]
	v_mfma_f32_16x16x32_bf16 v[6:9], v[188:191], v[180:183], v[6:9]
	v_mfma_f32_16x16x32_bf16 v[2:5], v[206:209], v[180:183], v[2:5]
	v_mfma_f32_16x16x32_bf16 v[46:49], v[200:203], v[160:163], v[46:49]
	v_mfma_f32_16x16x32_bf16 v[42:45], v[210:213], v[160:163], v[42:45]
	v_mfma_f32_16x16x32_bf16 v[30:33], v[200:203], v[168:171], v[30:33]
	v_mfma_f32_16x16x32_bf16 v[26:29], v[210:213], v[168:171], v[26:29]
	v_mfma_f32_16x16x32_bf16 v[14:17], v[200:203], v[176:179], v[14:17]
	v_mfma_f32_16x16x32_bf16 v[10:13], v[210:213], v[176:179], v[10:13]
	v_mfma_f32_16x16x32_bf16 v[6:9], v[200:203], v[184:187], v[6:9]
	v_mfma_f32_16x16x32_bf16 v[2:5], v[210:213], v[184:187], v[2:5]
	s_setprio 0
	v_add_u32_e32 v152, s97, v137
	s_barrier
	ds_read_b128 v[140:143], v152
	ds_read_b128 v[144:147], v152 offset:1024
	ds_read_b128 v[148:151], v152 offset:2048
	ds_read_b128 v[152:155], v152 offset:3072
	s_mov_b32 m0, s53
	v_lshl_add_u64 v[188:189], s[38:39], 0, v[134:135]
	ds_read_b128 v[156:159], v139 offset:32768
	ds_read_b128 v[160:163], v139 offset:33792
	ds_read_b128 v[164:167], v139 offset:34816
	ds_read_b128 v[168:171], v139 offset:35840
	ds_read_b128 v[172:175], v139 offset:36864
	ds_read_b128 v[176:179], v139 offset:37888
	ds_read_b128 v[180:183], v139 offset:38912
	ds_read_b128 v[184:187], v139 offset:39936
	global_load_lds_dwordx4 v[188:189], off
	v_lshl_add_u64 v[188:189], s[38:39], 0, v[132:133]
	s_mov_b32 m0, s54
	s_nop 0
	global_load_lds_dwordx4 v[188:189], off
	s_waitcnt vmcnt(10)
	s_waitcnt lgkmcnt(8)
	s_barrier
	s_waitcnt lgkmcnt(0)
	s_setprio 1
	s_waitcnt lgkmcnt(0)
	v_mfma_f32_16x16x32_bf16 v[126:129], v[140:143], v[156:159], v[126:129]
	v_mfma_f32_16x16x32_bf16 v[122:125], v[148:151], v[156:159], v[122:125]
	v_mfma_f32_16x16x32_bf16 v[118:121], v[140:143], v[164:167], v[118:121]
	v_mfma_f32_16x16x32_bf16 v[114:117], v[148:151], v[164:167], v[114:117]
	v_mfma_f32_16x16x32_bf16 v[102:105], v[140:143], v[172:175], v[102:105]
	v_mfma_f32_16x16x32_bf16 v[98:101], v[148:151], v[172:175], v[98:101]
	v_mfma_f32_16x16x32_bf16 v[86:89], v[140:143], v[180:183], v[86:89]
	v_mfma_f32_16x16x32_bf16 v[82:85], v[148:151], v[180:183], v[82:85]
	v_mfma_f32_16x16x32_bf16 v[126:129], v[144:147], v[160:163], v[126:129]
	v_mfma_f32_16x16x32_bf16 v[122:125], v[152:155], v[160:163], v[122:125]
	v_mfma_f32_16x16x32_bf16 v[118:121], v[144:147], v[168:171], v[118:121]
	v_mfma_f32_16x16x32_bf16 v[114:117], v[152:155], v[168:171], v[114:117]
	v_mfma_f32_16x16x32_bf16 v[102:105], v[144:147], v[176:179], v[102:105]
	v_mfma_f32_16x16x32_bf16 v[98:101], v[152:155], v[176:179], v[98:101]
	v_mfma_f32_16x16x32_bf16 v[86:89], v[144:147], v[184:187], v[86:89]
	v_mfma_f32_16x16x32_bf16 v[82:85], v[152:155], v[184:187], v[82:85]
	s_setprio 0
	s_barrier
	s_mov_b32 m0, s96
	v_add_u32_e32 v195, s60, v137
	v_lshl_add_u64 v[192:193], v[192:193], 0, s[74:75]
	ds_read_b128 v[188:191], v195
	ds_read_b128 v[200:203], v195 offset:1024
	ds_read_b128 v[206:209], v195 offset:2048
	ds_read_b128 v[210:213], v195 offset:3072
	global_load_lds_dwordx4 v[192:193], off
	v_lshl_add_u64 v[192:193], v[196:197], 0, s[74:75]
	s_mov_b32 m0, s50
	s_nop 0
	global_load_lds_dwordx4 v[192:193], off
	s_waitcnt vmcnt(10)
	s_barrier
	s_waitcnt lgkmcnt(0)
	s_setprio 1
	s_waitcnt lgkmcnt(0)
	v_mfma_f32_16x16x32_bf16 v[110:113], v[188:191], v[156:159], v[110:113]
	v_mfma_f32_16x16x32_bf16 v[106:109], v[206:209], v[156:159], v[106:109]
	v_mfma_f32_16x16x32_bf16 v[94:97], v[188:191], v[164:167], v[94:97]
	v_mfma_f32_16x16x32_bf16 v[90:93], v[206:209], v[164:167], v[90:93]
	v_mfma_f32_16x16x32_bf16 v[78:81], v[188:191], v[172:175], v[78:81]
	v_mfma_f32_16x16x32_bf16 v[74:77], v[206:209], v[172:175], v[74:77]
	v_mfma_f32_16x16x32_bf16 v[70:73], v[188:191], v[180:183], v[70:73]
	v_mfma_f32_16x16x32_bf16 v[66:69], v[206:209], v[180:183], v[66:69]
	v_mfma_f32_16x16x32_bf16 v[110:113], v[200:203], v[160:163], v[110:113]
	v_mfma_f32_16x16x32_bf16 v[106:109], v[210:213], v[160:163], v[106:109]
	v_mfma_f32_16x16x32_bf16 v[94:97], v[200:203], v[168:171], v[94:97]
	v_mfma_f32_16x16x32_bf16 v[90:93], v[210:213], v[168:171], v[90:93]
	v_mfma_f32_16x16x32_bf16 v[78:81], v[200:203], v[176:179], v[78:81]
	v_mfma_f32_16x16x32_bf16 v[74:77], v[210:213], v[176:179], v[74:77]
	v_mfma_f32_16x16x32_bf16 v[70:73], v[200:203], v[184:187], v[70:73]
	v_mfma_f32_16x16x32_bf16 v[66:69], v[210:213], v[184:187], v[66:69]
	s_setprio 0
	s_mov_b32 m0, s55
	v_lshl_add_u64 v[192:193], v[198:199], 0, s[74:75]
	s_barrier
	ds_read_b128 v[156:159], v139 offset:49152
	ds_read_b128 v[160:163], v139 offset:50176
	ds_read_b128 v[164:167], v139 offset:51200
	ds_read_b128 v[168:171], v139 offset:52224
	ds_read_b128 v[172:175], v139 offset:53248
	ds_read_b128 v[176:179], v139 offset:54272
	ds_read_b128 v[180:183], v139 offset:55296
	ds_read_b128 v[184:187], v139 offset:56320
	global_load_lds_dwordx4 v[192:193], off
	v_lshl_add_u64 v[192:193], v[214:215], 0, s[74:75]
	s_mov_b32 m0, s56
	s_nop 0
	global_load_lds_dwordx4 v[192:193], off
	s_barrier
	s_waitcnt lgkmcnt(0)
	s_setprio 1
	s_waitcnt lgkmcnt(0)
	v_mfma_f32_16x16x32_bf16 v[62:65], v[140:143], v[156:159], v[62:65]
	v_mfma_f32_16x16x32_bf16 v[58:61], v[148:151], v[156:159], v[58:61]
	v_mfma_f32_16x16x32_bf16 v[54:57], v[140:143], v[164:167], v[54:57]
	v_mfma_f32_16x16x32_bf16 v[50:53], v[148:151], v[164:167], v[50:53]
	v_mfma_f32_16x16x32_bf16 v[38:41], v[140:143], v[172:175], v[38:41]
	v_mfma_f32_16x16x32_bf16 v[34:37], v[148:151], v[172:175], v[34:37]
	v_mfma_f32_16x16x32_bf16 v[22:25], v[140:143], v[180:183], v[22:25]
	v_mfma_f32_16x16x32_bf16 v[18:21], v[148:151], v[180:183], v[18:21]
	v_mfma_f32_16x16x32_bf16 v[62:65], v[144:147], v[160:163], v[62:65]
	v_mfma_f32_16x16x32_bf16 v[58:61], v[152:155], v[160:163], v[58:61]
	v_mfma_f32_16x16x32_bf16 v[54:57], v[144:147], v[168:171], v[54:57]
	v_mfma_f32_16x16x32_bf16 v[50:53], v[152:155], v[168:171], v[50:53]
	v_mfma_f32_16x16x32_bf16 v[38:41], v[144:147], v[176:179], v[38:41]
	v_mfma_f32_16x16x32_bf16 v[34:37], v[152:155], v[176:179], v[34:37]
	v_mfma_f32_16x16x32_bf16 v[22:25], v[144:147], v[184:187], v[22:25]
	v_mfma_f32_16x16x32_bf16 v[18:21], v[152:155], v[184:187], v[18:21]
	s_setprio 0
	s_barrier
	s_mov_b32 m0, s34
	v_lshl_add_u64 v[140:141], s[36:37], 0, v[0:1]
	global_load_lds_dwordx4 v[140:141], off
	v_lshl_add_u64 v[140:141], s[36:37], 0, v[130:131]
	s_mov_b32 m0, s71
	s_nop 0
	global_load_lds_dwordx4 v[140:141], off
	s_waitcnt vmcnt(10)
	s_barrier
	s_setprio 1
	v_mfma_f32_16x16x32_bf16 v[46:49], v[188:191], v[156:159], v[46:49]
	v_mfma_f32_16x16x32_bf16 v[42:45], v[206:209], v[156:159], v[42:45]
	v_mfma_f32_16x16x32_bf16 v[30:33], v[188:191], v[164:167], v[30:33]
	v_mfma_f32_16x16x32_bf16 v[26:29], v[206:209], v[164:167], v[26:29]
	v_mfma_f32_16x16x32_bf16 v[14:17], v[188:191], v[172:175], v[14:17]
	v_mfma_f32_16x16x32_bf16 v[10:13], v[206:209], v[172:175], v[10:13]
	v_mfma_f32_16x16x32_bf16 v[6:9], v[188:191], v[180:183], v[6:9]
	v_mfma_f32_16x16x32_bf16 v[2:5], v[206:209], v[180:183], v[2:5]
	v_mfma_f32_16x16x32_bf16 v[46:49], v[200:203], v[160:163], v[46:49]
	v_mfma_f32_16x16x32_bf16 v[42:45], v[210:213], v[160:163], v[42:45]
	v_mfma_f32_16x16x32_bf16 v[30:33], v[200:203], v[168:171], v[30:33]
	v_mfma_f32_16x16x32_bf16 v[26:29], v[210:213], v[168:171], v[26:29]
	v_mfma_f32_16x16x32_bf16 v[14:17], v[200:203], v[176:179], v[14:17]
	v_mfma_f32_16x16x32_bf16 v[10:13], v[210:213], v[176:179], v[10:13]
	v_mfma_f32_16x16x32_bf16 v[6:9], v[200:203], v[184:187], v[6:9]
	v_mfma_f32_16x16x32_bf16 v[2:5], v[210:213], v[184:187], v[2:5]
	s_setprio 0
	s_movk_i32 s2, 0x100
	s_andn2_b64 vcc, exec, s[18:19]
	s_mov_b64 s[36:37], -1
	s_mov_b64 s[18:19], 0
	s_barrier
	s_cbranch_vccz .LBB0_483
	v_readlane_b32 s2, v250, 6
	v_lshl_add_u32 v146, s67, 8, v136
	v_lshl_or_b32 v140, s59, 8, v138
	v_readlane_b32 s3, v250, 7
	s_movk_i32 s5, 0x6800
	v_ashrrev_i32_e32 v141, 31, v140
	v_mov_b64_e32 v[142:143], s[2:3]
	v_cvt_pk_bf16_f32 v70, v70, v71
	v_cvt_pk_bf16_f32 v71, v72, v73
	v_cvt_pk_bf16_f32 v72, v66, v67
	v_add_u32_e32 v66, 0x80, v146
	v_mad_i64_i32 v[144:145], s[2:3], v146, s5, v[142:143]
	v_lshlrev_b64 v[140:141], 1, v[140:141]
	v_cvt_pk_bf16_f32 v110, v110, v111
	v_cvt_pk_bf16_f32 v111, v112, v113
	v_cvt_pk_bf16_f32 v112, v106, v107
	v_or_b32_e32 v106, 16, v146
	v_mad_i64_i32 v[66:67], s[2:3], v66, s5, v[142:143]
	v_cvt_pk_bf16_f32 v46, v46, v47
	v_cvt_pk_bf16_f32 v47, v48, v49
	v_cvt_pk_bf16_f32 v48, v42, v43
	v_add_u32_e32 v42, 0x90, v146
	v_lshl_add_u64 v[144:145], v[144:145], 0, v[140:141]
	v_cvt_pk_bf16_f32 v113, v108, v109
	v_mad_i64_i32 v[106:107], s[2:3], v106, s5, v[142:143]
	v_cvt_pk_bf16_f32 v94, v94, v95
	v_cvt_pk_bf16_f32 v95, v96, v97
	v_cvt_pk_bf16_f32 v96, v90, v91
	v_or_b32_e32 v90, 32, v146
	v_lshl_add_u64 v[66:67], v[66:67], 0, v[140:141]
	v_cvt_pk_bf16_f32 v49, v44, v45
	v_mad_i64_i32 v[42:43], s[2:3], v42, s5, v[142:143]
	v_cvt_pk_bf16_f32 v30, v30, v31
	v_cvt_pk_bf16_f32 v31, v32, v33
	v_cvt_pk_bf16_f32 v32, v26, v27
	v_add_u32_e32 v26, 0xa0, v146
	global_store_dwordx4 v[144:145], v[110:113], off offset:256
	v_cvt_pk_bf16_f32 v97, v92, v93
	v_mad_i64_i32 v[90:91], s[2:3], v90, s5, v[142:143]
	v_lshl_add_u64 v[110:111], v[106:107], 0, v[140:141]
	v_cvt_pk_bf16_f32 v78, v78, v79
	v_cvt_pk_bf16_f32 v79, v80, v81
	v_cvt_pk_bf16_f32 v80, v74, v75
	v_or_b32_e32 v74, 48, v146
	global_store_dwordx4 v[66:67], v[46:49], off offset:256
	v_cvt_pk_bf16_f32 v33, v28, v29
	v_mad_i64_i32 v[26:27], s[2:3], v26, s5, v[142:143]
	v_lshl_add_u64 v[46:47], v[42:43], 0, v[140:141]
	v_cvt_pk_bf16_f32 v14, v14, v15
	v_cvt_pk_bf16_f32 v15, v16, v17
	v_cvt_pk_bf16_f32 v16, v10, v11
	v_add_u32_e32 v10, 0xb0, v146
	global_store_dwordx4 v[110:111], v[94:97], off offset:256
	v_cvt_pk_bf16_f32 v81, v76, v77
	v_mad_i64_i32 v[74:75], s[2:3], v74, s5, v[142:143]
	v_lshl_add_u64 v[94:95], v[90:91], 0, v[140:141]
	global_store_dwordx4 v[46:47], v[30:33], off offset:256
	v_cvt_pk_bf16_f32 v17, v12, v13
	v_mad_i64_i32 v[10:11], s[2:3], v10, s5, v[142:143]
	v_lshl_add_u64 v[30:31], v[26:27], 0, v[140:141]
	v_cvt_pk_bf16_f32 v126, v126, v127
	v_cvt_pk_bf16_f32 v127, v128, v129
	v_cvt_pk_bf16_f32 v128, v122, v123
	v_cvt_pk_bf16_f32 v129, v124, v125
	v_cvt_pk_bf16_f32 v106, v118, v119
	v_cvt_pk_bf16_f32 v107, v120, v121
	v_cvt_pk_bf16_f32 v108, v114, v115
	v_cvt_pk_bf16_f32 v109, v116, v117
	v_cvt_pk_bf16_f32 v90, v102, v103
	v_cvt_pk_bf16_f32 v91, v104, v105
	v_cvt_pk_bf16_f32 v92, v98, v99
	v_cvt_pk_bf16_f32 v93, v100, v101
	global_store_dwordx4 v[94:95], v[78:81], off offset:256
	v_cvt_pk_bf16_f32 v76, v82, v83
	v_cvt_pk_bf16_f32 v77, v84, v85
	v_lshl_add_u64 v[78:79], v[74:75], 0, v[140:141]
	v_cvt_pk_bf16_f32 v74, v86, v87
	v_cvt_pk_bf16_f32 v75, v88, v89
	v_cvt_pk_bf16_f32 v73, v68, v69
	v_cvt_pk_bf16_f32 v62, v62, v63
	v_cvt_pk_bf16_f32 v63, v64, v65
	v_cvt_pk_bf16_f32 v64, v58, v59
	v_cvt_pk_bf16_f32 v65, v60, v61
	v_cvt_pk_bf16_f32 v42, v54, v55
	v_cvt_pk_bf16_f32 v43, v56, v57
	v_cvt_pk_bf16_f32 v44, v50, v51
	v_cvt_pk_bf16_f32 v45, v52, v53
	v_cvt_pk_bf16_f32 v26, v38, v39
	v_cvt_pk_bf16_f32 v27, v40, v41
	v_cvt_pk_bf16_f32 v28, v34, v35
	v_cvt_pk_bf16_f32 v29, v36, v37
	global_store_dwordx4 v[30:31], v[14:17], off offset:256
	v_cvt_pk_bf16_f32 v12, v18, v19
	v_cvt_pk_bf16_f32 v13, v20, v21
	v_lshl_add_u64 v[14:15], v[10:11], 0, v[140:141]
	v_cvt_pk_bf16_f32 v10, v22, v23
	v_cvt_pk_bf16_f32 v11, v24, v25
	v_cvt_pk_bf16_f32 v6, v6, v7
	v_cvt_pk_bf16_f32 v7, v8, v9
	v_cvt_pk_bf16_f32 v8, v2, v3
	v_cvt_pk_bf16_f32 v9, v4, v5
	s_and_b64 vcc, exec, s[0:1]
	s_mov_b32 s59, s6
	s_mov_b32 s67, s8
	s_mov_b64 s[14:15], s[12:13]
	s_mov_b64 s[16:17], s[10:11]
	global_store_dwordx4 v[144:145], v[126:129], off
	global_store_dwordx4 v[110:111], v[106:109], off
	global_store_dwordx4 v[94:95], v[90:93], off
	global_store_dwordx4 v[78:79], v[74:77], off
	global_store_dwordx4 v[78:79], v[70:73], off offset:256
	global_store_dwordx4 v[66:67], v[62:65], off
	global_store_dwordx4 v[46:47], v[42:45], off
	global_store_dwordx4 v[30:31], v[26:29], off
	global_store_dwordx4 v[14:15], v[10:13], off
	global_store_dwordx4 v[14:15], v[6:9], off offset:256
	s_cbranch_vccz .LBB0_480
	s_waitcnt vmcnt(0)
	s_cmpk_gt_u32 s22, 0xff
	v_readlane_b32 s57, v255, 48
	s_cbranch_scc1 .LBB0_487
	s_barrier

.LBB0_495:
	s_add_u32 s16, s14, 0x100
	s_addc_u32 s17, s15, 0
	s_add_u32 s2, s50, s14
	s_addc_u32 s3, s52, s15
	s_cmp_eq_u32 s53, 4
	s_cselect_b32 s35, 0, s16
	s_cselect_b32 s34, 0, s17
	s_cselect_b32 s18, s7, s2
	s_cselect_b32 s19, s1, s3
	s_add_u32 s2, s46, s35
	s_addc_u32 s3, s47, s34
	s_add_i32 s34, 0, 0x10000
	v_add_u32_e32 v159, s34, v156
	ds_read_b128 v[160:163], v159
	ds_read_b128 v[164:167], v159 offset:1024
	ds_read_b128 v[168:171], v159 offset:2048
	ds_read_b128 v[172:175], v159 offset:3072
	v_lshl_add_u64 v[192:193], v[152:153], 0, s[14:15]
	s_add_i32 m0, s37, 0xc000
	ds_read_b128 v[176:179], v158
	ds_read_b128 v[180:183], v158 offset:1024
	ds_read_b128 v[184:187], v158 offset:2048
	ds_read_b128 v[188:191], v158 offset:3072
	ds_read_b128 v[200:203], v158 offset:4096
	ds_read_b128 v[206:209], v158 offset:5120
	ds_read_b128 v[210:213], v158 offset:6144
	ds_read_b128 v[214:217], v158 offset:7168
	global_load_lds_dwordx4 v[192:193], off
	v_lshl_add_u64 v[192:193], v[154:155], 0, s[14:15]
	s_add_i32 m0, s37, 0xe000
	s_nop 0
	global_load_lds_dwordx4 v[192:193], off
	s_waitcnt vmcnt(10)
	s_waitcnt lgkmcnt(8)
	s_barrier
	s_waitcnt lgkmcnt(0)
	s_setprio 1
	s_waitcnt lgkmcnt(0)
	v_mfma_f32_16x16x32_bf16 v[126:129], v[160:163], v[176:179], v[126:129]
	v_mfma_f32_16x16x32_bf16 v[122:125], v[168:171], v[176:179], v[122:125]
	v_mfma_f32_16x16x32_bf16 v[118:121], v[160:163], v[184:187], v[118:121]
	v_mfma_f32_16x16x32_bf16 v[114:117], v[168:171], v[184:187], v[114:117]
	v_mfma_f32_16x16x32_bf16 v[102:105], v[160:163], v[200:203], v[102:105]
	v_mfma_f32_16x16x32_bf16 v[98:101], v[168:171], v[200:203], v[98:101]
	v_mfma_f32_16x16x32_bf16 v[86:89], v[160:163], v[210:213], v[86:89]
	v_mfma_f32_16x16x32_bf16 v[82:85], v[168:171], v[210:213], v[82:85]
	v_mfma_f32_16x16x32_bf16 v[126:129], v[164:167], v[180:183], v[126:129]
	v_mfma_f32_16x16x32_bf16 v[122:125], v[172:175], v[180:183], v[122:125]
	v_mfma_f32_16x16x32_bf16 v[118:121], v[164:167], v[188:191], v[118:121]
	v_mfma_f32_16x16x32_bf16 v[114:117], v[172:175], v[188:191], v[114:117]
	v_mfma_f32_16x16x32_bf16 v[102:105], v[164:167], v[206:209], v[102:105]
	v_mfma_f32_16x16x32_bf16 v[98:101], v[172:175], v[206:209], v[98:101]
	v_mfma_f32_16x16x32_bf16 v[86:89], v[164:167], v[214:217], v[86:89]
	v_mfma_f32_16x16x32_bf16 v[82:85], v[172:175], v[214:217], v[82:85]
	s_setprio 0
	s_barrier
	s_add_i32 s35, 0, 0x14000
	s_add_i32 s14, s34, s36
	v_add_u32_e32 v159, s35, v156
	v_lshl_add_u64 v[192:193], s[18:19], 0, v[0:1]
	s_mov_b32 m0, s14
	ds_read_b128 v[218:221], v159
	ds_read_b128 v[228:231], v159 offset:1024
	ds_read_b128 v[196:199], v159 offset:2048
	ds_read_b128 v[222:225], v159 offset:3072
	global_load_lds_dwordx4 v[192:193], off
	v_lshl_add_u64 v[242:243], s[18:19], 0, v[130:131]
	s_add_i32 m0, s14, 0x2000
	s_nop 0
	global_load_lds_dwordx4 v[242:243], off
	s_waitcnt vmcnt(10)
	s_barrier
	s_waitcnt lgkmcnt(0)
	s_setprio 1
	s_waitcnt lgkmcnt(0)
	v_mfma_f32_16x16x32_bf16 v[110:113], v[218:221], v[176:179], v[110:113]
	v_mfma_f32_16x16x32_bf16 v[106:109], v[196:199], v[176:179], v[106:109]
	v_mfma_f32_16x16x32_bf16 v[94:97], v[218:221], v[184:187], v[94:97]
	v_mfma_f32_16x16x32_bf16 v[90:93], v[196:199], v[184:187], v[90:93]
	v_mfma_f32_16x16x32_bf16 v[78:81], v[218:221], v[200:203], v[78:81]
	v_mfma_f32_16x16x32_bf16 v[74:77], v[196:199], v[200:203], v[74:77]
	v_mfma_f32_16x16x32_bf16 v[70:73], v[218:221], v[210:213], v[70:73]
	v_mfma_f32_16x16x32_bf16 v[66:69], v[196:199], v[210:213], v[66:69]
	v_mfma_f32_16x16x32_bf16 v[110:113], v[228:231], v[180:183], v[110:113]
	v_mfma_f32_16x16x32_bf16 v[106:109], v[222:225], v[180:183], v[106:109]
	v_mfma_f32_16x16x32_bf16 v[94:97], v[228:231], v[188:191], v[94:97]
	v_mfma_f32_16x16x32_bf16 v[90:93], v[222:225], v[188:191], v[90:93]
	v_mfma_f32_16x16x32_bf16 v[78:81], v[228:231], v[206:209], v[78:81]
	v_mfma_f32_16x16x32_bf16 v[74:77], v[222:225], v[206:209], v[74:77]
	v_mfma_f32_16x16x32_bf16 v[70:73], v[228:231], v[214:217], v[70:73]
	v_mfma_f32_16x16x32_bf16 v[66:69], v[222:225], v[214:217], v[66:69]
	s_setprio 0
	s_mov_b32 m0, s37
	v_lshl_add_u64 v[234:235], s[2:3], 0, v[134:135]
	s_barrier
	ds_read_b128 v[176:179], v158 offset:16384
	ds_read_b128 v[180:183], v158 offset:17408
	ds_read_b128 v[184:187], v158 offset:18432
	ds_read_b128 v[188:191], v158 offset:19456
	ds_read_b128 v[200:203], v158 offset:20480
	ds_read_b128 v[206:209], v158 offset:21504
	ds_read_b128 v[210:213], v158 offset:22528
	ds_read_b128 v[214:217], v158 offset:23552
	global_load_lds_dwordx4 v[234:235], off
	v_lshl_add_u64 v[236:237], s[2:3], 0, v[132:133]
	s_mov_b32 m0, s38
	s_nop 0
	global_load_lds_dwordx4 v[236:237], off
	s_barrier
	s_waitcnt lgkmcnt(0)
	s_setprio 1
	s_waitcnt lgkmcnt(0)
	v_mfma_f32_16x16x32_bf16 v[62:65], v[160:163], v[176:179], v[62:65]
	v_mfma_f32_16x16x32_bf16 v[58:61], v[168:171], v[176:179], v[58:61]
	v_mfma_f32_16x16x32_bf16 v[54:57], v[160:163], v[184:187], v[54:57]
	v_mfma_f32_16x16x32_bf16 v[50:53], v[168:171], v[184:187], v[50:53]
	v_mfma_f32_16x16x32_bf16 v[38:41], v[160:163], v[200:203], v[38:41]
	v_mfma_f32_16x16x32_bf16 v[34:37], v[168:171], v[200:203], v[34:37]
	v_mfma_f32_16x16x32_bf16 v[22:25], v[160:163], v[210:213], v[22:25]
	v_mfma_f32_16x16x32_bf16 v[18:21], v[168:171], v[210:213], v[18:21]
	v_mfma_f32_16x16x32_bf16 v[62:65], v[164:167], v[180:183], v[62:65]
	v_mfma_f32_16x16x32_bf16 v[58:61], v[172:175], v[180:183], v[58:61]
	v_mfma_f32_16x16x32_bf16 v[54:57], v[164:167], v[188:191], v[54:57]
	v_mfma_f32_16x16x32_bf16 v[50:53], v[172:175], v[188:191], v[50:53]
	v_mfma_f32_16x16x32_bf16 v[38:41], v[164:167], v[206:209], v[38:41]
	v_mfma_f32_16x16x32_bf16 v[34:37], v[172:175], v[206:209], v[34:37]
	v_mfma_f32_16x16x32_bf16 v[22:25], v[164:167], v[214:217], v[22:25]
	v_mfma_f32_16x16x32_bf16 v[18:21], v[172:175], v[214:217], v[18:21]
	s_setprio 0
	s_barrier
	s_add_u32 s14, s18, 0x400000
	s_addc_u32 s15, s19, 0
	s_add_i32 s34, s35, s36
	v_lshl_add_u64 v[160:161], s[14:15], 0, v[0:1]
	s_mov_b32 m0, s34
	s_nop 0
	global_load_lds_dwordx4 v[160:161], off
	v_lshl_add_u64 v[160:161], s[14:15], 0, v[130:131]
	s_add_i32 m0, s34, 0x2000
	s_nop 0
	global_load_lds_dwordx4 v[160:161], off
	s_waitcnt vmcnt(10)
	s_barrier
	s_setprio 1
	v_mfma_f32_16x16x32_bf16 v[46:49], v[218:221], v[176:179], v[46:49]
	v_mfma_f32_16x16x32_bf16 v[42:45], v[196:199], v[176:179], v[42:45]
	v_mfma_f32_16x16x32_bf16 v[30:33], v[218:221], v[184:187], v[30:33]
	v_mfma_f32_16x16x32_bf16 v[26:29], v[196:199], v[184:187], v[26:29]
	v_mfma_f32_16x16x32_bf16 v[14:17], v[218:221], v[200:203], v[14:17]
	v_mfma_f32_16x16x32_bf16 v[10:13], v[196:199], v[200:203], v[10:13]
	v_mfma_f32_16x16x32_bf16 v[6:9], v[218:221], v[210:213], v[6:9]
	v_mfma_f32_16x16x32_bf16 v[2:5], v[196:199], v[210:213], v[2:5]
	v_mfma_f32_16x16x32_bf16 v[46:49], v[228:231], v[180:183], v[46:49]
	v_mfma_f32_16x16x32_bf16 v[42:45], v[222:225], v[180:183], v[42:45]
	v_mfma_f32_16x16x32_bf16 v[30:33], v[228:231], v[188:191], v[30:33]
	v_mfma_f32_16x16x32_bf16 v[26:29], v[222:225], v[188:191], v[26:29]
	v_mfma_f32_16x16x32_bf16 v[14:17], v[228:231], v[206:209], v[14:17]
	v_mfma_f32_16x16x32_bf16 v[10:13], v[222:225], v[206:209], v[10:13]
	v_mfma_f32_16x16x32_bf16 v[6:9], v[228:231], v[214:217], v[6:9]
	v_mfma_f32_16x16x32_bf16 v[2:5], v[222:225], v[214:217], v[2:5]
	s_setprio 0
	s_add_i32 s14, 0, 0x18000
	v_add_u32_e32 v159, s14, v156
	s_barrier
	ds_read_b128 v[160:163], v159
	ds_read_b128 v[164:167], v159 offset:1024
	ds_read_b128 v[168:171], v159 offset:2048
	ds_read_b128 v[172:175], v159 offset:3072
	s_add_u32 s2, s2, 0x20000
	s_addc_u32 s3, s3, 0
	s_mov_b32 m0, s39
	v_lshl_add_u64 v[214:215], s[2:3], 0, v[134:135]
	ds_read_b128 v[176:179], v158 offset:32768
	ds_read_b128 v[180:183], v158 offset:33792
	ds_read_b128 v[184:187], v158 offset:34816
	ds_read_b128 v[188:191], v158 offset:35840
	ds_read_b128 v[196:199], v158 offset:36864
	ds_read_b128 v[200:203], v158 offset:37888
	ds_read_b128 v[206:209], v158 offset:38912
	ds_read_b128 v[210:213], v158 offset:39936
	global_load_lds_dwordx4 v[214:215], off
	v_lshl_add_u64 v[214:215], s[2:3], 0, v[132:133]
	s_mov_b32 m0, s44
	s_nop 0
	global_load_lds_dwordx4 v[214:215], off
	s_waitcnt vmcnt(10)
	s_waitcnt lgkmcnt(8)
	s_barrier
	s_waitcnt lgkmcnt(0)
	s_setprio 1
	s_waitcnt lgkmcnt(0)
	v_mfma_f32_16x16x32_bf16 v[126:129], v[160:163], v[176:179], v[126:129]
	v_mfma_f32_16x16x32_bf16 v[122:125], v[168:171], v[176:179], v[122:125]
	v_mfma_f32_16x16x32_bf16 v[118:121], v[160:163], v[184:187], v[118:121]
	v_mfma_f32_16x16x32_bf16 v[114:117], v[168:171], v[184:187], v[114:117]
	v_mfma_f32_16x16x32_bf16 v[102:105], v[160:163], v[196:199], v[102:105]
	v_mfma_f32_16x16x32_bf16 v[98:101], v[168:171], v[196:199], v[98:101]
	v_mfma_f32_16x16x32_bf16 v[86:89], v[160:163], v[206:209], v[86:89]
	v_mfma_f32_16x16x32_bf16 v[82:85], v[168:171], v[206:209], v[82:85]
	v_mfma_f32_16x16x32_bf16 v[126:129], v[164:167], v[180:183], v[126:129]
	v_mfma_f32_16x16x32_bf16 v[122:125], v[172:175], v[180:183], v[122:125]
	v_mfma_f32_16x16x32_bf16 v[118:121], v[164:167], v[188:191], v[118:121]
	v_mfma_f32_16x16x32_bf16 v[114:117], v[172:175], v[188:191], v[114:117]
	v_mfma_f32_16x16x32_bf16 v[102:105], v[164:167], v[200:203], v[102:105]
	v_mfma_f32_16x16x32_bf16 v[98:101], v[172:175], v[200:203], v[98:101]
	v_mfma_f32_16x16x32_bf16 v[86:89], v[164:167], v[210:213], v[86:89]
	v_mfma_f32_16x16x32_bf16 v[82:85], v[172:175], v[210:213], v[82:85]
	s_setprio 0
	s_barrier
	s_add_i32 s15, 0, 0x1c000
	s_add_i32 s2, s14, s36
	v_add_u32_e32 v159, s15, v156
	v_lshl_add_u64 v[192:193], v[192:193], 0, s[74:75]
	s_mov_b32 m0, s2
	ds_read_b128 v[214:217], v159
	ds_read_b128 v[218:221], v159 offset:1024
	ds_read_b128 v[222:225], v159 offset:2048
	ds_read_b128 v[228:231], v159 offset:3072
	global_load_lds_dwordx4 v[192:193], off
	v_lshl_add_u64 v[192:193], v[242:243], 0, s[74:75]
	s_add_i32 m0, s2, 0x2000
	s_nop 0
	global_load_lds_dwordx4 v[192:193], off
	s_waitcnt vmcnt(10)
	s_barrier
	s_waitcnt lgkmcnt(0)
	s_setprio 1
	s_waitcnt lgkmcnt(0)
	v_mfma_f32_16x16x32_bf16 v[110:113], v[214:217], v[176:179], v[110:113]
	v_mfma_f32_16x16x32_bf16 v[106:109], v[222:225], v[176:179], v[106:109]
	v_mfma_f32_16x16x32_bf16 v[94:97], v[214:217], v[184:187], v[94:97]
	v_mfma_f32_16x16x32_bf16 v[90:93], v[222:225], v[184:187], v[90:93]
	v_mfma_f32_16x16x32_bf16 v[78:81], v[214:217], v[196:199], v[78:81]
	v_mfma_f32_16x16x32_bf16 v[74:77], v[222:225], v[196:199], v[74:77]
	v_mfma_f32_16x16x32_bf16 v[70:73], v[214:217], v[206:209], v[70:73]
	v_mfma_f32_16x16x32_bf16 v[66:69], v[222:225], v[206:209], v[66:69]
	v_mfma_f32_16x16x32_bf16 v[110:113], v[218:221], v[180:183], v[110:113]
	v_mfma_f32_16x16x32_bf16 v[106:109], v[228:231], v[180:183], v[106:109]
	v_mfma_f32_16x16x32_bf16 v[94:97], v[218:221], v[188:191], v[94:97]
	v_mfma_f32_16x16x32_bf16 v[90:93], v[228:231], v[188:191], v[90:93]
	v_mfma_f32_16x16x32_bf16 v[78:81], v[218:221], v[200:203], v[78:81]
	v_mfma_f32_16x16x32_bf16 v[74:77], v[228:231], v[200:203], v[74:77]
	v_mfma_f32_16x16x32_bf16 v[70:73], v[218:221], v[210:213], v[70:73]
	v_mfma_f32_16x16x32_bf16 v[66:69], v[228:231], v[210:213], v[66:69]
	s_setprio 0
	s_mov_b32 m0, s45
	v_lshl_add_u64 v[192:193], v[234:235], 0, s[74:75]
	s_barrier
	ds_read_b128 v[176:179], v158 offset:49152
	ds_read_b128 v[180:183], v158 offset:50176
	ds_read_b128 v[184:187], v158 offset:51200
	ds_read_b128 v[188:191], v158 offset:52224
	ds_read_b128 v[196:199], v158 offset:53248
	ds_read_b128 v[200:203], v158 offset:54272
	ds_read_b128 v[206:209], v158 offset:55296
	ds_read_b128 v[210:213], v158 offset:56320
	global_load_lds_dwordx4 v[192:193], off
	v_lshl_add_u64 v[192:193], v[236:237], 0, s[74:75]
	s_mov_b32 m0, s49
	s_nop 0
	global_load_lds_dwordx4 v[192:193], off
	s_barrier
	s_waitcnt lgkmcnt(0)
	s_setprio 1
	s_waitcnt lgkmcnt(0)
	v_mfma_f32_16x16x32_bf16 v[62:65], v[160:163], v[176:179], v[62:65]
	v_mfma_f32_16x16x32_bf16 v[58:61], v[168:171], v[176:179], v[58:61]
	v_mfma_f32_16x16x32_bf16 v[54:57], v[160:163], v[184:187], v[54:57]
	v_mfma_f32_16x16x32_bf16 v[50:53], v[168:171], v[184:187], v[50:53]
	v_mfma_f32_16x16x32_bf16 v[38:41], v[160:163], v[196:199], v[38:41]
	v_mfma_f32_16x16x32_bf16 v[34:37], v[168:171], v[196:199], v[34:37]
	v_mfma_f32_16x16x32_bf16 v[22:25], v[160:163], v[206:209], v[22:25]
	v_mfma_f32_16x16x32_bf16 v[18:21], v[168:171], v[206:209], v[18:21]
	v_mfma_f32_16x16x32_bf16 v[62:65], v[164:167], v[180:183], v[62:65]
	v_mfma_f32_16x16x32_bf16 v[58:61], v[172:175], v[180:183], v[58:61]
	v_mfma_f32_16x16x32_bf16 v[54:57], v[164:167], v[188:191], v[54:57]
	v_mfma_f32_16x16x32_bf16 v[50:53], v[172:175], v[188:191], v[50:53]
	v_mfma_f32_16x16x32_bf16 v[38:41], v[164:167], v[200:203], v[38:41]
	v_mfma_f32_16x16x32_bf16 v[34:37], v[172:175], v[200:203], v[34:37]
	v_mfma_f32_16x16x32_bf16 v[22:25], v[164:167], v[210:213], v[22:25]
	v_mfma_f32_16x16x32_bf16 v[18:21], v[172:175], v[210:213], v[18:21]
	s_setprio 0
	s_barrier
	s_add_u32 s2, s18, 0x400080
	s_addc_u32 s3, s19, 0
	s_add_i32 s14, s15, s36
	v_lshl_add_u64 v[160:161], s[2:3], 0, v[0:1]
	s_mov_b32 m0, s14
	s_nop 0
	global_load_lds_dwordx4 v[160:161], off
	v_lshl_add_u64 v[160:161], s[2:3], 0, v[130:131]
	s_add_i32 m0, s14, 0x2000
	s_nop 0
	global_load_lds_dwordx4 v[160:161], off
	s_waitcnt vmcnt(10)
	s_barrier
	s_setprio 1
	v_mfma_f32_16x16x32_bf16 v[46:49], v[214:217], v[176:179], v[46:49]
	v_mfma_f32_16x16x32_bf16 v[42:45], v[222:225], v[176:179], v[42:45]
	v_mfma_f32_16x16x32_bf16 v[30:33], v[214:217], v[184:187], v[30:33]
	v_mfma_f32_16x16x32_bf16 v[26:29], v[222:225], v[184:187], v[26:29]
	v_mfma_f32_16x16x32_bf16 v[14:17], v[214:217], v[196:199], v[14:17]
	v_mfma_f32_16x16x32_bf16 v[10:13], v[222:225], v[196:199], v[10:13]
	v_mfma_f32_16x16x32_bf16 v[6:9], v[214:217], v[206:209], v[6:9]
	v_mfma_f32_16x16x32_bf16 v[2:5], v[222:225], v[206:209], v[2:5]
	v_mfma_f32_16x16x32_bf16 v[46:49], v[218:221], v[180:183], v[46:49]
	v_mfma_f32_16x16x32_bf16 v[42:45], v[228:231], v[180:183], v[42:45]
	v_mfma_f32_16x16x32_bf16 v[30:33], v[218:221], v[188:191], v[30:33]
	v_mfma_f32_16x16x32_bf16 v[26:29], v[228:231], v[188:191], v[26:29]
	v_mfma_f32_16x16x32_bf16 v[14:17], v[218:221], v[200:203], v[14:17]
	v_mfma_f32_16x16x32_bf16 v[10:13], v[228:231], v[200:203], v[10:13]
	v_mfma_f32_16x16x32_bf16 v[6:9], v[218:221], v[210:213], v[6:9]
	v_mfma_f32_16x16x32_bf16 v[2:5], v[228:231], v[210:213], v[2:5]
	s_setprio 0
	s_add_i32 s53, s53, 2
	s_cmp_gt_u32 s53, 5
	s_mov_b64 s[14:15], s[16:17]
	s_barrier
	s_cbranch_scc0 .LBB0_495
	v_lshl_or_b32 v160, s13, 8, v157
	s_ashr_i32 s13, s12, 31
	s_lshl_b64 s[2:3], s[12:13], 18
	s_add_u32 s2, s40, s2
	s_addc_u32 s3, s54, s3
	v_ashrrev_i32_e32 v161, 31, v160
	v_lshl_add_u64 v[162:163], s[2:3], 0, v[136:137]
	v_lshlrev_b64 v[160:161], 1, v[160:161]
	v_cvt_pk_bf16_f32 v70, v70, v71
	v_cvt_pk_bf16_f32 v71, v72, v73
	v_cvt_pk_bf16_f32 v72, v66, v67
	v_lshl_add_u64 v[66:67], s[2:3], 0, v[144:145]
	v_lshl_add_u64 v[162:163], v[162:163], 0, v[160:161]
	v_cvt_pk_bf16_f32 v110, v110, v111
	v_cvt_pk_bf16_f32 v111, v112, v113
	v_cvt_pk_bf16_f32 v112, v106, v107
	v_cvt_pk_bf16_f32 v113, v108, v109
	v_lshl_add_u64 v[106:107], s[2:3], 0, v[138:139]
	v_lshl_add_u64 v[66:67], v[66:67], 0, v[160:161]
	v_cvt_pk_bf16_f32 v46, v46, v47
	v_cvt_pk_bf16_f32 v47, v48, v49
	v_cvt_pk_bf16_f32 v48, v42, v43
	v_cvt_pk_bf16_f32 v49, v44, v45
	v_lshl_add_u64 v[42:43], s[2:3], 0, v[146:147]
	global_store_dwordx4 v[162:163], v[110:113], off offset:256
	v_cvt_pk_bf16_f32 v94, v94, v95
	v_cvt_pk_bf16_f32 v95, v96, v97
	v_lshl_add_u64 v[110:111], v[106:107], 0, v[160:161]
	v_cvt_pk_bf16_f32 v96, v90, v91
	v_cvt_pk_bf16_f32 v97, v92, v93
	v_lshl_add_u64 v[90:91], s[2:3], 0, v[140:141]
	global_store_dwordx4 v[66:67], v[46:49], off offset:256
	v_cvt_pk_bf16_f32 v30, v30, v31
	v_cvt_pk_bf16_f32 v31, v32, v33
	v_lshl_add_u64 v[46:47], v[42:43], 0, v[160:161]
	v_cvt_pk_bf16_f32 v32, v26, v27
	v_cvt_pk_bf16_f32 v33, v28, v29
	v_lshl_add_u64 v[26:27], s[2:3], 0, v[148:149]
	global_store_dwordx4 v[110:111], v[94:97], off offset:256
	v_cvt_pk_bf16_f32 v78, v78, v79
	v_cvt_pk_bf16_f32 v79, v80, v81
	v_lshl_add_u64 v[94:95], v[90:91], 0, v[160:161]
	v_cvt_pk_bf16_f32 v80, v74, v75
	v_cvt_pk_bf16_f32 v81, v76, v77
	v_lshl_add_u64 v[74:75], s[2:3], 0, v[142:143]
	global_store_dwordx4 v[46:47], v[30:33], off offset:256
	v_cvt_pk_bf16_f32 v14, v14, v15
	v_cvt_pk_bf16_f32 v15, v16, v17
	v_lshl_add_u64 v[30:31], v[26:27], 0, v[160:161]
	v_cvt_pk_bf16_f32 v16, v10, v11
	v_cvt_pk_bf16_f32 v17, v12, v13
	v_lshl_add_u64 v[10:11], s[2:3], 0, v[150:151]
	v_cvt_pk_bf16_f32 v126, v126, v127
	v_cvt_pk_bf16_f32 v127, v128, v129
	v_cvt_pk_bf16_f32 v128, v122, v123
	v_cvt_pk_bf16_f32 v129, v124, v125
	v_cvt_pk_bf16_f32 v106, v118, v119
	v_cvt_pk_bf16_f32 v107, v120, v121
	v_cvt_pk_bf16_f32 v108, v114, v115
	v_cvt_pk_bf16_f32 v109, v116, v117
	v_cvt_pk_bf16_f32 v90, v102, v103
	v_cvt_pk_bf16_f32 v91, v104, v105
	v_cvt_pk_bf16_f32 v92, v98, v99
	v_cvt_pk_bf16_f32 v93, v100, v101
	global_store_dwordx4 v[94:95], v[78:81], off offset:256
	v_cvt_pk_bf16_f32 v76, v82, v83
	v_cvt_pk_bf16_f32 v77, v84, v85
	v_lshl_add_u64 v[78:79], v[74:75], 0, v[160:161]
	v_cvt_pk_bf16_f32 v74, v86, v87
	v_cvt_pk_bf16_f32 v75, v88, v89
	v_cvt_pk_bf16_f32 v73, v68, v69
	v_cvt_pk_bf16_f32 v62, v62, v63
	v_cvt_pk_bf16_f32 v63, v64, v65
	v_cvt_pk_bf16_f32 v64, v58, v59
	v_cvt_pk_bf16_f32 v65, v60, v61
	v_cvt_pk_bf16_f32 v42, v54, v55
	v_cvt_pk_bf16_f32 v43, v56, v57
	v_cvt_pk_bf16_f32 v44, v50, v51
	v_cvt_pk_bf16_f32 v45, v52, v53
	v_cvt_pk_bf16_f32 v26, v38, v39
	v_cvt_pk_bf16_f32 v27, v40, v41
	v_cvt_pk_bf16_f32 v28, v34, v35
	v_cvt_pk_bf16_f32 v29, v36, v37
	global_store_dwordx4 v[30:31], v[14:17], off offset:256
	v_cvt_pk_bf16_f32 v12, v18, v19
	v_cvt_pk_bf16_f32 v13, v20, v21
	v_lshl_add_u64 v[14:15], v[10:11], 0, v[160:161]
	v_cvt_pk_bf16_f32 v10, v22, v23
	v_cvt_pk_bf16_f32 v11, v24, v25
	v_cvt_pk_bf16_f32 v6, v6, v7
	v_cvt_pk_bf16_f32 v7, v8, v9
	v_cvt_pk_bf16_f32 v8, v2, v3
	v_cvt_pk_bf16_f32 v9, v4, v5
	s_and_b64 vcc, exec, s[8:9]
	s_mov_b32 s12, s0
	s_mov_b32 s13, s6
	s_mov_b64 s[2:3], s[10:11]
	global_store_dwordx4 v[162:163], v[126:129], off
	global_store_dwordx4 v[110:111], v[106:109], off
	global_store_dwordx4 v[94:95], v[90:93], off
	global_store_dwordx4 v[78:79], v[74:77], off
	global_store_dwordx4 v[78:79], v[70:73], off offset:256
	global_store_dwordx4 v[66:67], v[62:65], off
	global_store_dwordx4 v[46:47], v[42:45], off
	global_store_dwordx4 v[30:31], v[26:29], off
	global_store_dwordx4 v[14:15], v[10:13], off
	global_store_dwordx4 v[14:15], v[6:9], off offset:256
	s_cbranch_vccz .LBB0_492
	s_waitcnt vmcnt(0)
	s_cmpk_gt_u32 s5, 0xff
	s_cbranch_scc1 .LBB0_499
	s_barrier

.LBB0_553:
	s_add_u32 s2, s0, 0xfffe0080
	s_addc_u32 s3, s1, -1
	s_add_i32 s34, 0, 0x10000
	v_add_u32_e32 v0, s34, v156
	ds_read_b128 v[144:147], v0
	ds_read_b128 v[148:151], v0 offset:1024
	ds_read_b128 v[152:155], v0 offset:2048
	ds_read_b128 v[158:161], v0 offset:3072
	s_cmp_eq_u32 s50, 4
	s_cselect_b32 s3, s7, s3
	s_cselect_b32 s2, s13, s2
	s_cselect_b32 s15, s9, s17
	s_cselect_b32 s14, s8, s16
	v_lshl_add_u64 v[196:197], s[0:1], 0, v[140:141]
	s_add_i32 m0, s19, 0xc000
	ds_read_b128 v[162:165], v157
	ds_read_b128 v[166:169], v157 offset:1024
	ds_read_b128 v[170:173], v157 offset:2048
	ds_read_b128 v[174:177], v157 offset:3072
	ds_read_b128 v[178:181], v157 offset:4096
	ds_read_b128 v[182:185], v157 offset:5120
	ds_read_b128 v[186:189], v157 offset:6144
	ds_read_b128 v[190:193], v157 offset:7168
	global_load_lds_dwordx4 v[196:197], off
	v_lshl_add_u64 v[196:197], s[0:1], 0, v[142:143]
	s_add_i32 m0, s19, 0xe000
	s_nop 0
	global_load_lds_dwordx4 v[196:197], off
	s_waitcnt vmcnt(10)
	s_waitcnt lgkmcnt(8)
	s_barrier
	s_waitcnt lgkmcnt(0)
	s_setprio 1
	s_waitcnt lgkmcnt(0)
	v_mfma_f32_16x16x32_bf16 v[126:129], v[144:147], v[162:165], v[126:129]
	v_mfma_f32_16x16x32_bf16 v[122:125], v[152:155], v[162:165], v[122:125]
	v_mfma_f32_16x16x32_bf16 v[110:113], v[144:147], v[170:173], v[110:113]
	v_mfma_f32_16x16x32_bf16 v[106:109], v[152:155], v[170:173], v[106:109]
	v_mfma_f32_16x16x32_bf16 v[94:97], v[144:147], v[178:181], v[94:97]
	v_mfma_f32_16x16x32_bf16 v[90:93], v[152:155], v[178:181], v[90:93]
	v_mfma_f32_16x16x32_bf16 v[78:81], v[144:147], v[186:189], v[78:81]
	v_mfma_f32_16x16x32_bf16 v[74:77], v[152:155], v[186:189], v[74:77]
	v_mfma_f32_16x16x32_bf16 v[126:129], v[148:151], v[166:169], v[126:129]
	v_mfma_f32_16x16x32_bf16 v[122:125], v[158:161], v[166:169], v[122:125]
	v_mfma_f32_16x16x32_bf16 v[110:113], v[148:151], v[174:177], v[110:113]
	v_mfma_f32_16x16x32_bf16 v[106:109], v[158:161], v[174:177], v[106:109]
	v_mfma_f32_16x16x32_bf16 v[94:97], v[148:151], v[182:185], v[94:97]
	v_mfma_f32_16x16x32_bf16 v[90:93], v[158:161], v[182:185], v[90:93]
	v_mfma_f32_16x16x32_bf16 v[78:81], v[148:151], v[190:193], v[78:81]
	v_mfma_f32_16x16x32_bf16 v[74:77], v[158:161], v[190:193], v[74:77]
	s_setprio 0
	s_barrier
	s_add_i32 s40, 0, 0x14000
	s_add_i32 s34, s34, s18
	v_add_u32_e32 v0, s40, v156
	v_lshl_add_u64 v[196:197], s[14:15], 0, v[132:133]
	s_mov_b32 m0, s34
	ds_read_b128 v[200:203], v0
	ds_read_b128 v[206:209], v0 offset:1024
	ds_read_b128 v[210:213], v0 offset:2048
	ds_read_b128 v[214:217], v0 offset:3072
	global_load_lds_dwordx4 v[196:197], off
	v_lshl_add_u64 v[198:199], s[14:15], 0, v[136:137]
	s_add_i32 m0, s34, 0x2000
	s_nop 0
	global_load_lds_dwordx4 v[198:199], off
	s_waitcnt vmcnt(10)
	s_barrier
	s_waitcnt lgkmcnt(0)
	s_setprio 1
	s_waitcnt lgkmcnt(0)
	v_mfma_f32_16x16x32_bf16 v[118:121], v[200:203], v[162:165], v[118:121]
	v_mfma_f32_16x16x32_bf16 v[114:117], v[210:213], v[162:165], v[114:117]
	v_mfma_f32_16x16x32_bf16 v[102:105], v[200:203], v[170:173], v[102:105]
	v_mfma_f32_16x16x32_bf16 v[98:101], v[210:213], v[170:173], v[98:101]
	v_mfma_f32_16x16x32_bf16 v[86:89], v[200:203], v[178:181], v[86:89]
	v_mfma_f32_16x16x32_bf16 v[82:85], v[210:213], v[178:181], v[82:85]
	v_mfma_f32_16x16x32_bf16 v[70:73], v[200:203], v[186:189], v[70:73]
	v_mfma_f32_16x16x32_bf16 v[66:69], v[210:213], v[186:189], v[66:69]
	v_mfma_f32_16x16x32_bf16 v[118:121], v[206:209], v[166:169], v[118:121]
	v_mfma_f32_16x16x32_bf16 v[114:117], v[214:217], v[166:169], v[114:117]
	v_mfma_f32_16x16x32_bf16 v[102:105], v[206:209], v[174:177], v[102:105]
	v_mfma_f32_16x16x32_bf16 v[98:101], v[214:217], v[174:177], v[98:101]
	v_mfma_f32_16x16x32_bf16 v[86:89], v[206:209], v[182:185], v[86:89]
	v_mfma_f32_16x16x32_bf16 v[82:85], v[214:217], v[182:185], v[82:85]
	v_mfma_f32_16x16x32_bf16 v[70:73], v[206:209], v[190:193], v[70:73]
	v_mfma_f32_16x16x32_bf16 v[66:69], v[214:217], v[190:193], v[66:69]
	s_setprio 0
	s_mov_b32 m0, s19
	v_lshl_add_u64 v[218:219], s[2:3], 0, v[130:131]
	s_barrier
	ds_read_b128 v[162:165], v157 offset:16384
	ds_read_b128 v[166:169], v157 offset:17408
	ds_read_b128 v[170:173], v157 offset:18432
	ds_read_b128 v[174:177], v157 offset:19456
	ds_read_b128 v[178:181], v157 offset:20480
	ds_read_b128 v[182:185], v157 offset:21504
	ds_read_b128 v[186:189], v157 offset:22528
	ds_read_b128 v[190:193], v157 offset:23552
	global_load_lds_dwordx4 v[218:219], off
	v_lshl_add_u64 v[220:221], s[2:3], 0, v[134:135]
	s_mov_b32 m0, s38
	s_nop 0
	global_load_lds_dwordx4 v[220:221], off
	s_barrier
	s_waitcnt lgkmcnt(0)
	s_setprio 1
	s_waitcnt lgkmcnt(0)
	v_mfma_f32_16x16x32_bf16 v[62:65], v[144:147], v[162:165], v[62:65]
	v_mfma_f32_16x16x32_bf16 v[58:61], v[152:155], v[162:165], v[58:61]
	v_mfma_f32_16x16x32_bf16 v[46:49], v[144:147], v[170:173], v[46:49]
	v_mfma_f32_16x16x32_bf16 v[42:45], v[152:155], v[170:173], v[42:45]
	v_mfma_f32_16x16x32_bf16 v[30:33], v[144:147], v[178:181], v[30:33]
	v_mfma_f32_16x16x32_bf16 v[26:29], v[152:155], v[178:181], v[26:29]
	v_mfma_f32_16x16x32_bf16 v[14:17], v[144:147], v[186:189], v[14:17]
	v_mfma_f32_16x16x32_bf16 v[10:13], v[152:155], v[186:189], v[10:13]
	v_mfma_f32_16x16x32_bf16 v[62:65], v[148:151], v[166:169], v[62:65]
	v_mfma_f32_16x16x32_bf16 v[58:61], v[158:161], v[166:169], v[58:61]
	v_mfma_f32_16x16x32_bf16 v[46:49], v[148:151], v[174:177], v[46:49]
	v_mfma_f32_16x16x32_bf16 v[42:45], v[158:161], v[174:177], v[42:45]
	v_mfma_f32_16x16x32_bf16 v[30:33], v[148:151], v[182:185], v[30:33]
	v_mfma_f32_16x16x32_bf16 v[26:29], v[158:161], v[182:185], v[26:29]
	v_mfma_f32_16x16x32_bf16 v[14:17], v[148:151], v[190:193], v[14:17]
	v_mfma_f32_16x16x32_bf16 v[10:13], v[158:161], v[190:193], v[10:13]
	s_setprio 0
	s_barrier
	s_add_u32 s34, s14, 0xd0000
	s_addc_u32 s35, s15, 0
	s_add_i32 s40, s40, s18
	v_lshl_add_u64 v[144:145], s[34:35], 0, v[132:133]
	s_mov_b32 m0, s40
	s_nop 0
	global_load_lds_dwordx4 v[144:145], off
	v_lshl_add_u64 v[144:145], s[34:35], 0, v[136:137]
	s_add_i32 m0, s40, 0x2000
	s_nop 0
	global_load_lds_dwordx4 v[144:145], off
	s_waitcnt vmcnt(10)
	s_barrier
	s_setprio 1
	v_mfma_f32_16x16x32_bf16 v[54:57], v[200:203], v[162:165], v[54:57]
	v_mfma_f32_16x16x32_bf16 v[50:53], v[210:213], v[162:165], v[50:53]
	v_mfma_f32_16x16x32_bf16 v[38:41], v[200:203], v[170:173], v[38:41]
	v_mfma_f32_16x16x32_bf16 v[34:37], v[210:213], v[170:173], v[34:37]
	v_mfma_f32_16x16x32_bf16 v[22:25], v[200:203], v[178:181], v[22:25]
	v_mfma_f32_16x16x32_bf16 v[18:21], v[210:213], v[178:181], v[18:21]
	v_mfma_f32_16x16x32_bf16 v[6:9], v[200:203], v[186:189], v[6:9]
	v_mfma_f32_16x16x32_bf16 v[2:5], v[210:213], v[186:189], v[2:5]
	v_mfma_f32_16x16x32_bf16 v[54:57], v[206:209], v[166:169], v[54:57]
	v_mfma_f32_16x16x32_bf16 v[50:53], v[214:217], v[166:169], v[50:53]
	v_mfma_f32_16x16x32_bf16 v[38:41], v[206:209], v[174:177], v[38:41]
	v_mfma_f32_16x16x32_bf16 v[34:37], v[214:217], v[174:177], v[34:37]
	v_mfma_f32_16x16x32_bf16 v[22:25], v[206:209], v[182:185], v[22:25]
	v_mfma_f32_16x16x32_bf16 v[18:21], v[214:217], v[182:185], v[18:21]
	v_mfma_f32_16x16x32_bf16 v[6:9], v[206:209], v[190:193], v[6:9]
	v_mfma_f32_16x16x32_bf16 v[2:5], v[214:217], v[190:193], v[2:5]
	s_setprio 0
	s_add_i32 s34, 0, 0x18000
	v_add_u32_e32 v0, s34, v156
	s_barrier
	ds_read_b128 v[144:147], v0
	ds_read_b128 v[148:151], v0 offset:1024
	ds_read_b128 v[152:155], v0 offset:2048
	ds_read_b128 v[158:161], v0 offset:3072
	s_add_u32 s2, s2, 0x20000
	s_addc_u32 s3, s3, 0
	s_mov_b32 m0, s39
	v_lshl_add_u64 v[200:201], s[2:3], 0, v[130:131]
	ds_read_b128 v[162:165], v157 offset:32768
	ds_read_b128 v[166:169], v157 offset:33792
	ds_read_b128 v[170:173], v157 offset:34816
	ds_read_b128 v[174:177], v157 offset:35840
	ds_read_b128 v[178:181], v157 offset:36864
	ds_read_b128 v[182:185], v157 offset:37888
	ds_read_b128 v[186:189], v157 offset:38912
	ds_read_b128 v[190:193], v157 offset:39936
	global_load_lds_dwordx4 v[200:201], off
	v_lshl_add_u64 v[200:201], s[2:3], 0, v[134:135]
	s_mov_b32 m0, s44
	s_nop 0
	global_load_lds_dwordx4 v[200:201], off
	s_waitcnt vmcnt(10)
	s_waitcnt lgkmcnt(8)
	s_barrier
	s_waitcnt lgkmcnt(0)
	s_setprio 1
	s_waitcnt lgkmcnt(0)
	v_mfma_f32_16x16x32_bf16 v[126:129], v[144:147], v[162:165], v[126:129]
	v_mfma_f32_16x16x32_bf16 v[122:125], v[152:155], v[162:165], v[122:125]
	v_mfma_f32_16x16x32_bf16 v[110:113], v[144:147], v[170:173], v[110:113]
	v_mfma_f32_16x16x32_bf16 v[106:109], v[152:155], v[170:173], v[106:109]
	v_mfma_f32_16x16x32_bf16 v[94:97], v[144:147], v[178:181], v[94:97]
	v_mfma_f32_16x16x32_bf16 v[90:93], v[152:155], v[178:181], v[90:93]
	v_mfma_f32_16x16x32_bf16 v[78:81], v[144:147], v[186:189], v[78:81]
	v_mfma_f32_16x16x32_bf16 v[74:77], v[152:155], v[186:189], v[74:77]
	v_mfma_f32_16x16x32_bf16 v[126:129], v[148:151], v[166:169], v[126:129]
	v_mfma_f32_16x16x32_bf16 v[122:125], v[158:161], v[166:169], v[122:125]
	v_mfma_f32_16x16x32_bf16 v[110:113], v[148:151], v[174:177], v[110:113]
	v_mfma_f32_16x16x32_bf16 v[106:109], v[158:161], v[174:177], v[106:109]
	v_mfma_f32_16x16x32_bf16 v[94:97], v[148:151], v[182:185], v[94:97]
	v_mfma_f32_16x16x32_bf16 v[90:93], v[158:161], v[182:185], v[90:93]
	v_mfma_f32_16x16x32_bf16 v[78:81], v[148:151], v[190:193], v[78:81]
	v_mfma_f32_16x16x32_bf16 v[74:77], v[158:161], v[190:193], v[74:77]
	s_setprio 0
	s_barrier
	s_add_i32 s35, 0, 0x1c000
	s_add_i32 s2, s34, s18
	v_add_u32_e32 v0, s35, v156
	v_lshl_add_u64 v[196:197], v[196:197], 0, s[74:75]
	s_mov_b32 m0, s2
	ds_read_b128 v[200:203], v0
	ds_read_b128 v[206:209], v0 offset:1024
	ds_read_b128 v[210:213], v0 offset:2048
	ds_read_b128 v[214:217], v0 offset:3072
	global_load_lds_dwordx4 v[196:197], off
	v_lshl_add_u64 v[196:197], v[198:199], 0, s[74:75]
	s_add_i32 m0, s2, 0x2000
	s_nop 0
	global_load_lds_dwordx4 v[196:197], off
	s_waitcnt vmcnt(10)
	s_barrier
	s_waitcnt lgkmcnt(0)
	s_setprio 1
	s_waitcnt lgkmcnt(0)
	v_mfma_f32_16x16x32_bf16 v[118:121], v[200:203], v[162:165], v[118:121]
	v_mfma_f32_16x16x32_bf16 v[114:117], v[210:213], v[162:165], v[114:117]
	v_mfma_f32_16x16x32_bf16 v[102:105], v[200:203], v[170:173], v[102:105]
	v_mfma_f32_16x16x32_bf16 v[98:101], v[210:213], v[170:173], v[98:101]
	v_mfma_f32_16x16x32_bf16 v[86:89], v[200:203], v[178:181], v[86:89]
	v_mfma_f32_16x16x32_bf16 v[82:85], v[210:213], v[178:181], v[82:85]
	v_mfma_f32_16x16x32_bf16 v[70:73], v[200:203], v[186:189], v[70:73]
	v_mfma_f32_16x16x32_bf16 v[66:69], v[210:213], v[186:189], v[66:69]
	v_mfma_f32_16x16x32_bf16 v[118:121], v[206:209], v[166:169], v[118:121]
	v_mfma_f32_16x16x32_bf16 v[114:117], v[214:217], v[166:169], v[114:117]
	v_mfma_f32_16x16x32_bf16 v[102:105], v[206:209], v[174:177], v[102:105]
	v_mfma_f32_16x16x32_bf16 v[98:101], v[214:217], v[174:177], v[98:101]
	v_mfma_f32_16x16x32_bf16 v[86:89], v[206:209], v[182:185], v[86:89]
	v_mfma_f32_16x16x32_bf16 v[82:85], v[214:217], v[182:185], v[82:85]
	v_mfma_f32_16x16x32_bf16 v[70:73], v[206:209], v[190:193], v[70:73]
	v_mfma_f32_16x16x32_bf16 v[66:69], v[214:217], v[190:193], v[66:69]
	s_setprio 0
	s_mov_b32 m0, s51
	v_lshl_add_u64 v[196:197], v[218:219], 0, s[74:75]
	s_barrier
	ds_read_b128 v[162:165], v157 offset:49152
	ds_read_b128 v[166:169], v157 offset:50176
	ds_read_b128 v[170:173], v157 offset:51200
	ds_read_b128 v[174:177], v157 offset:52224
	ds_read_b128 v[178:181], v157 offset:53248
	ds_read_b128 v[182:185], v157 offset:54272
	ds_read_b128 v[186:189], v157 offset:55296
	ds_read_b128 v[190:193], v157 offset:56320
	global_load_lds_dwordx4 v[196:197], off
	v_lshl_add_u64 v[196:197], v[220:221], 0, s[74:75]
	s_mov_b32 m0, s52
	s_nop 0
	global_load_lds_dwordx4 v[196:197], off
	s_barrier
	s_waitcnt lgkmcnt(0)
	s_setprio 1
	s_waitcnt lgkmcnt(0)
	v_mfma_f32_16x16x32_bf16 v[62:65], v[144:147], v[162:165], v[62:65]
	v_mfma_f32_16x16x32_bf16 v[58:61], v[152:155], v[162:165], v[58:61]
	v_mfma_f32_16x16x32_bf16 v[46:49], v[144:147], v[170:173], v[46:49]
	v_mfma_f32_16x16x32_bf16 v[42:45], v[152:155], v[170:173], v[42:45]
	v_mfma_f32_16x16x32_bf16 v[30:33], v[144:147], v[178:181], v[30:33]
	v_mfma_f32_16x16x32_bf16 v[26:29], v[152:155], v[178:181], v[26:29]
	v_mfma_f32_16x16x32_bf16 v[14:17], v[144:147], v[186:189], v[14:17]
	v_mfma_f32_16x16x32_bf16 v[10:13], v[152:155], v[186:189], v[10:13]
	v_mfma_f32_16x16x32_bf16 v[62:65], v[148:151], v[166:169], v[62:65]
	v_mfma_f32_16x16x32_bf16 v[58:61], v[158:161], v[166:169], v[58:61]
	v_mfma_f32_16x16x32_bf16 v[46:49], v[148:151], v[174:177], v[46:49]
	v_mfma_f32_16x16x32_bf16 v[42:45], v[158:161], v[174:177], v[42:45]
	v_mfma_f32_16x16x32_bf16 v[30:33], v[148:151], v[182:185], v[30:33]
	v_mfma_f32_16x16x32_bf16 v[26:29], v[158:161], v[182:185], v[26:29]
	v_mfma_f32_16x16x32_bf16 v[14:17], v[148:151], v[190:193], v[14:17]
	v_mfma_f32_16x16x32_bf16 v[10:13], v[158:161], v[190:193], v[10:13]
	s_setprio 0
	s_barrier
	s_add_u32 s2, s14, 0xd0080
	s_addc_u32 s3, s15, 0
	s_add_i32 s14, s35, s18
	v_lshl_add_u64 v[144:145], s[2:3], 0, v[132:133]
	s_mov_b32 m0, s14
	s_nop 0
	global_load_lds_dwordx4 v[144:145], off
	v_lshl_add_u64 v[144:145], s[2:3], 0, v[136:137]
	s_add_i32 m0, s14, 0x2000
	s_nop 0
	global_load_lds_dwordx4 v[144:145], off
	s_waitcnt vmcnt(10)
	s_barrier
	s_setprio 1
	v_mfma_f32_16x16x32_bf16 v[54:57], v[200:203], v[162:165], v[54:57]
	v_mfma_f32_16x16x32_bf16 v[50:53], v[210:213], v[162:165], v[50:53]
	v_mfma_f32_16x16x32_bf16 v[38:41], v[200:203], v[170:173], v[38:41]
	v_mfma_f32_16x16x32_bf16 v[34:37], v[210:213], v[170:173], v[34:37]
	v_mfma_f32_16x16x32_bf16 v[22:25], v[200:203], v[178:181], v[22:25]
	v_mfma_f32_16x16x32_bf16 v[18:21], v[210:213], v[178:181], v[18:21]
	v_mfma_f32_16x16x32_bf16 v[6:9], v[200:203], v[186:189], v[6:9]
	v_mfma_f32_16x16x32_bf16 v[2:5], v[210:213], v[186:189], v[2:5]
	v_mfma_f32_16x16x32_bf16 v[54:57], v[206:209], v[166:169], v[54:57]
	v_mfma_f32_16x16x32_bf16 v[50:53], v[214:217], v[166:169], v[50:53]
	v_mfma_f32_16x16x32_bf16 v[38:41], v[206:209], v[174:177], v[38:41]
	v_mfma_f32_16x16x32_bf16 v[34:37], v[214:217], v[174:177], v[34:37]
	v_mfma_f32_16x16x32_bf16 v[22:25], v[206:209], v[182:185], v[22:25]
	v_mfma_f32_16x16x32_bf16 v[18:21], v[214:217], v[182:185], v[18:21]
	v_mfma_f32_16x16x32_bf16 v[6:9], v[206:209], v[190:193], v[6:9]
	v_mfma_f32_16x16x32_bf16 v[2:5], v[214:217], v[190:193], v[2:5]
	s_setprio 0
	s_add_i32 s50, s50, 2
	s_add_u32 s0, s0, 0x100
	s_addc_u32 s1, s1, 0
	s_add_u32 s16, s16, 0x100
	s_addc_u32 s17, s17, 0
	s_cmp_gt_u32 s50, 5
	s_barrier
	s_cbranch_scc0 .LBB0_553
	s_lshl_b32 s14, s12, 8
	s_lshl_b32 s12, s49, 9
	s_add_i32 s14, s14, s45
	s_add_i32 s0, s12, 0x7fffc000
	s_and_b32 s7, s0, 0x7ffff000
	s_ashr_i32 s0, s14, 1
	v_mov_b32_e32 v144, 0x4f
	s_and_b32 s0, s0, 0xffffff80
	v_bitop3_b32 v158, s14, v144, v139 bitop3:0xc8
	v_or_b32_e32 v148, s0, v158
	v_ashrrev_i32_e32 v149, 31, v148
	v_readlane_b32 s0, v250, 34
	v_lshl_or_b32 v0, s49, 8, v138
	v_lshlrev_b64 v[144:145], 14, v[148:149]
	v_readlane_b32 s1, v250, 35
	v_cmp_lt_i32_e32 vcc, s56, v0
	s_nop 0
	v_lshl_add_u64 v[150:151], s[0:1], 0, v[144:145]
	v_and_b32_e32 v144, 0x778, v0
	v_lshlrev_b32_e32 v144, 1, v144
	s_and_saveexec_b64 s[0:1], vcc
	s_xor_b64 s[0:1], exec, s[0:1]
	s_lshl_b32 s2, s7, 1
	s_mov_b32 s3, s4
	v_lshl_add_u64 v[146:147], v[150:151], 0, s[2:3]
	s_lshl_b32 s2, s53, 1
	v_lshl_add_u64 v[146:147], v[146:147], 0, s[2:3]
	v_mov_b32_e32 v145, v1
	v_lshl_add_u64 v[154:155], v[146:147], 0, v[144:145]
	s_or_saveexec_b64 s[0:1], s[0:1]
	v_readlane_b32 s2, v253, 61
	v_lshlrev_b64 v[146:147], 15, v[148:149]
	v_readlane_b32 s3, v253, 62
	s_ashr_i32 s13, s12, 31
	s_nop 0
	v_lshl_add_u64 v[146:147], s[2:3], 0, v[146:147]
	v_lshl_add_u64 v[152:153], s[12:13], 1, v[146:147]
	v_lshlrev_b32_e32 v146, 1, v138
	s_xor_b64 exec, exec, s[0:1]
	s_lshl_b32 s2, s59, 1
	s_mov_b32 s3, s4
	v_lshl_add_u64 v[154:155], v[152:153], 0, s[2:3]
	v_mov_b32_e32 v147, v1
	v_lshl_add_u64 v[154:155], v[154:155], 0, v[146:147]
	s_or_b64 exec, exec, s[0:1]
	v_cvt_pk_bf16_f32 v126, v126, v127
	v_cvt_pk_bf16_f32 v127, v128, v129
	v_cvt_pk_bf16_f32 v129, v124, v125
	v_or_b32_e32 v124, 0x80, v0
	v_cvt_pk_bf16_f32 v128, v122, v123
	v_cmp_lt_i32_e64 s[0:1], s56, v124
	global_store_dwordx4 v[154:155], v[126:129], off
	s_and_saveexec_b64 s[2:3], s[0:1]
	s_xor_b64 s[2:3], exec, s[2:3]
	s_lshl_b32 s16, s7, 1
	s_mov_b32 s17, s4
	v_lshl_add_u64 v[122:123], v[150:151], 0, s[16:17]
	s_lshl_b32 s16, s53, 1
	v_lshl_add_u64 v[122:123], v[122:123], 0, s[16:17]
	s_or_saveexec_b64 s[2:3], s[2:3]
	v_mov_b32_e32 v0, 0x7f8
	s_mov_b32 s35, 0x3fb8aa3b
	s_mov_b32 s34, 0xc2ce8ed0
	s_xor_b64 exec, exec, s[2:3]
	s_lshl_b32 s16, s59, 1
	s_mov_b32 s17, s4
	v_lshl_add_u64 v[122:123], v[152:153], 0, s[16:17]
	v_mov_b32_e32 v0, 0xf8
	s_or_b64 exec, exec, s[2:3]
	v_cvt_pk_bf16_f32 v118, v118, v119
	v_cvt_pk_bf16_f32 v119, v120, v121
	v_cvt_pk_bf16_f32 v121, v116, v117
	v_or_b32_e32 v116, 16, v148
	v_and_b32_e32 v0, v0, v124
	v_ashrrev_i32_e32 v117, 31, v116
	v_readlane_b32 s2, v250, 34
	v_lshlrev_b32_e32 v0, 1, v0
	v_cvt_pk_bf16_f32 v120, v114, v115
	v_lshlrev_b64 v[114:115], 14, v[116:117]
	v_readlane_b32 s3, v250, 35
	v_lshl_add_u64 v[122:123], v[122:123], 0, v[0:1]
	global_store_dwordx4 v[122:123], v[118:121], off
	v_lshl_add_u64 v[114:115], s[2:3], 0, v[114:115]
	s_and_saveexec_b64 s[2:3], vcc
	s_xor_b64 s[2:3], exec, s[2:3]
	s_lshl_b32 s16, s7, 1
	s_mov_b32 s17, s4
	v_lshl_add_u64 v[118:119], v[114:115], 0, s[16:17]
	s_lshl_b32 s16, s53, 1
	v_lshl_add_u64 v[118:119], v[118:119], 0, s[16:17]
	v_mov_b32_e32 v145, v1
	v_lshl_add_u64 v[118:119], v[118:119], 0, v[144:145]
	s_or_saveexec_b64 s[2:3], s[2:3]
	v_readlane_b32 s16, v253, 61
	v_lshlrev_b64 v[116:117], 15, v[116:117]
	v_readlane_b32 s17, v253, 62
	s_nop 1
	v_lshl_add_u64 v[116:117], s[16:17], 0, v[116:117]
	v_lshl_add_u64 v[116:117], s[12:13], 1, v[116:117]
	s_xor_b64 exec, exec, s[2:3]
	s_lshl_b32 s16, s59, 1
	s_mov_b32 s17, s4
	v_lshl_add_u64 v[118:119], v[116:117], 0, s[16:17]
	v_mov_b32_e32 v147, v1
	v_lshl_add_u64 v[118:119], v[118:119], 0, v[146:147]
	s_or_b64 exec, exec, s[2:3]
	v_cvt_pk_bf16_f32 v110, v110, v111
	v_cvt_pk_bf16_f32 v111, v112, v113
	v_cvt_pk_bf16_f32 v112, v106, v107
	v_cvt_pk_bf16_f32 v113, v108, v109
	global_store_dwordx4 v[118:119], v[110:113], off
	s_and_saveexec_b64 s[2:3], s[0:1]
	s_xor_b64 s[2:3], exec, s[2:3]
	s_lshl_b32 s16, s7, 1
	s_mov_b32 s17, s4
	v_lshl_add_u64 v[106:107], v[114:115], 0, s[16:17]
	s_lshl_b32 s16, s53, 1
	v_lshl_add_u64 v[106:107], v[106:107], 0, s[16:17]
	s_or_saveexec_b64 s[2:3], s[2:3]
	v_mov_b32_e32 v0, 0x7f8
	s_xor_b64 exec, exec, s[2:3]
	s_lshl_b32 s16, s59, 1
	s_mov_b32 s17, s4
	v_lshl_add_u64 v[106:107], v[116:117], 0, s[16:17]
	v_mov_b32_e32 v0, 0xf8
	s_or_b64 exec, exec, s[2:3]
	v_cvt_pk_bf16_f32 v102, v102, v103
	v_cvt_pk_bf16_f32 v103, v104, v105
	v_cvt_pk_bf16_f32 v105, v100, v101
	v_or_b32_e32 v100, 32, v148
	v_and_b32_e32 v0, v0, v124
	v_ashrrev_i32_e32 v101, 31, v100
	v_readlane_b32 s2, v250, 34
	v_lshlrev_b32_e32 v0, 1, v0
	v_cvt_pk_bf16_f32 v104, v98, v99
	v_lshlrev_b64 v[98:99], 14, v[100:101]
	v_readlane_b32 s3, v250, 35
	v_lshl_add_u64 v[106:107], v[106:107], 0, v[0:1]
	global_store_dwordx4 v[106:107], v[102:105], off
	v_lshl_add_u64 v[98:99], s[2:3], 0, v[98:99]
	s_and_saveexec_b64 s[2:3], vcc
	s_xor_b64 s[2:3], exec, s[2:3]
	s_lshl_b32 s16, s7, 1
	s_mov_b32 s17, s4
	v_lshl_add_u64 v[102:103], v[98:99], 0, s[16:17]
	s_lshl_b32 s16, s53, 1
	v_lshl_add_u64 v[102:103], v[102:103], 0, s[16:17]
	v_mov_b32_e32 v145, v1
	v_lshl_add_u64 v[102:103], v[102:103], 0, v[144:145]
	s_or_saveexec_b64 s[2:3], s[2:3]
	v_readlane_b32 s16, v253, 61
	v_lshlrev_b64 v[100:101], 15, v[100:101]
	v_readlane_b32 s17, v253, 62
	s_nop 1
	v_lshl_add_u64 v[100:101], s[16:17], 0, v[100:101]
	v_lshl_add_u64 v[100:101], s[12:13], 1, v[100:101]
	s_xor_b64 exec, exec, s[2:3]
	s_lshl_b32 s16, s59, 1
	s_mov_b32 s17, s4
	v_lshl_add_u64 v[102:103], v[100:101], 0, s[16:17]
	v_mov_b32_e32 v147, v1
	v_lshl_add_u64 v[102:103], v[102:103], 0, v[146:147]
	s_or_b64 exec, exec, s[2:3]
	v_cvt_pk_bf16_f32 v94, v94, v95
	v_cvt_pk_bf16_f32 v95, v96, v97
	v_cvt_pk_bf16_f32 v96, v90, v91
	v_cvt_pk_bf16_f32 v97, v92, v93
	global_store_dwordx4 v[102:103], v[94:97], off
	s_and_saveexec_b64 s[2:3], s[0:1]
	s_xor_b64 s[2:3], exec, s[2:3]
	s_lshl_b32 s16, s7, 1
	s_mov_b32 s17, s4
	v_lshl_add_u64 v[90:91], v[98:99], 0, s[16:17]
	s_lshl_b32 s16, s53, 1
	v_lshl_add_u64 v[90:91], v[90:91], 0, s[16:17]
	s_or_saveexec_b64 s[2:3], s[2:3]
	v_mov_b32_e32 v0, 0x7f8
	s_xor_b64 exec, exec, s[2:3]
	s_lshl_b32 s16, s59, 1
	s_mov_b32 s17, s4
	v_lshl_add_u64 v[90:91], v[100:101], 0, s[16:17]
	v_mov_b32_e32 v0, 0xf8
	s_or_b64 exec, exec, s[2:3]
	v_cvt_pk_bf16_f32 v86, v86, v87
	v_cvt_pk_bf16_f32 v87, v88, v89
	v_cvt_pk_bf16_f32 v89, v84, v85
	v_or_b32_e32 v84, 48, v148
	v_and_b32_e32 v0, v0, v124
	v_ashrrev_i32_e32 v85, 31, v84
	v_readlane_b32 s2, v250, 34
	v_lshlrev_b32_e32 v0, 1, v0
	v_cvt_pk_bf16_f32 v88, v82, v83
	v_lshlrev_b64 v[82:83], 14, v[84:85]
	v_readlane_b32 s3, v250, 35
	v_lshl_add_u64 v[90:91], v[90:91], 0, v[0:1]
	global_store_dwordx4 v[90:91], v[86:89], off
	v_lshl_add_u64 v[82:83], s[2:3], 0, v[82:83]
	s_and_saveexec_b64 s[2:3], vcc
	s_xor_b64 s[2:3], exec, s[2:3]
	s_lshl_b32 s16, s7, 1
	s_mov_b32 s17, s4
	v_lshl_add_u64 v[86:87], v[82:83], 0, s[16:17]
	s_lshl_b32 s16, s53, 1
	v_lshl_add_u64 v[86:87], v[86:87], 0, s[16:17]
	v_mov_b32_e32 v145, v1
	v_lshl_add_u64 v[86:87], v[86:87], 0, v[144:145]
	s_or_saveexec_b64 s[2:3], s[2:3]
	v_readlane_b32 s16, v253, 61
	v_lshlrev_b64 v[84:85], 15, v[84:85]
	v_readlane_b32 s17, v253, 62
	s_nop 1
	v_lshl_add_u64 v[84:85], s[16:17], 0, v[84:85]
	v_lshl_add_u64 v[84:85], s[12:13], 1, v[84:85]
	s_xor_b64 exec, exec, s[2:3]
	s_lshl_b32 s16, s59, 1
	s_mov_b32 s17, s4
	v_lshl_add_u64 v[86:87], v[84:85], 0, s[16:17]
	v_mov_b32_e32 v147, v1
	v_lshl_add_u64 v[86:87], v[86:87], 0, v[146:147]
	s_or_b64 exec, exec, s[2:3]
	v_cvt_pk_bf16_f32 v78, v78, v79
	v_cvt_pk_bf16_f32 v79, v80, v81
	v_cvt_pk_bf16_f32 v80, v74, v75
	v_cvt_pk_bf16_f32 v81, v76, v77
	global_store_dwordx4 v[86:87], v[78:81], off
	s_and_saveexec_b64 s[2:3], s[0:1]
	s_xor_b64 s[2:3], exec, s[2:3]
	s_lshl_b32 s16, s7, 1
	s_mov_b32 s17, s4
	v_lshl_add_u64 v[74:75], v[82:83], 0, s[16:17]
	s_lshl_b32 s16, s53, 1
	v_lshl_add_u64 v[74:75], v[74:75], 0, s[16:17]
	s_or_saveexec_b64 s[2:3], s[2:3]
	v_mov_b32_e32 v0, 0x7f8
	s_xor_b64 exec, exec, s[2:3]
	s_lshl_b32 s16, s59, 1
	s_mov_b32 s17, s4
	v_lshl_add_u64 v[74:75], v[84:85], 0, s[16:17]
	v_mov_b32_e32 v0, 0xf8
	s_or_b64 exec, exec, s[2:3]
	v_or_b32_e32 v76, s14, v139
	v_and_b32_e32 v0, v0, v124
	v_lshlrev_b32_e32 v0, 1, v0
	v_cvt_pk_bf16_f32 v70, v70, v71
	v_cvt_pk_bf16_f32 v71, v72, v73
	v_cvt_pk_bf16_f32 v72, v66, v67
	v_add_u32_e32 v66, 0x80, v76
	v_lshl_add_u64 v[74:75], v[74:75], 0, v[0:1]
	v_cvt_pk_bf16_f32 v73, v68, v69
	v_bfe_u32 v0, v66, 7, 1
	v_ashrrev_i32_e32 v66, 1, v66
	s_movk_i32 s2, 0xff80
	global_store_dwordx4 v[74:75], v[70:73], off
	v_lshlrev_b32_e32 v68, 11, v0
	s_nop 0
	v_and_or_b32 v70, v66, s2, v158
	v_ashrrev_i32_e32 v71, 31, v70
	v_readlane_b32 s2, v250, 34
	v_lshlrev_b64 v[66:67], 14, v[70:71]
	v_readlane_b32 s3, v250, 35
	s_nop 1
	v_lshl_add_u64 v[72:73], s[2:3], 0, v[66:67]
	v_lshlrev_b32_e32 v66, 1, v68
	s_and_saveexec_b64 s[2:3], vcc
	s_xor_b64 s[2:3], exec, s[2:3]
	s_lshl_b32 s14, s7, 1
	s_mov_b32 s15, s4
	v_lshl_add_u64 v[68:69], v[72:73], 0, s[14:15]
	v_mov_b32_e32 v67, v1
	v_lshl_add_u64 v[68:69], v[68:69], 0, v[66:67]
	v_mov_b32_e32 v145, v1
	v_lshl_add_u64 v[76:77], v[68:69], 0, v[144:145]
	s_or_saveexec_b64 s[2:3], s[2:3]
	v_readlane_b32 s14, v253, 61
	v_lshlrev_b64 v[68:69], 15, v[70:71]
	v_readlane_b32 s15, v253, 62
	v_lshlrev_b32_e32 v0, 8, v0
	s_nop 0
	v_lshl_add_u64 v[68:69], s[14:15], 0, v[68:69]
	v_lshl_add_u64 v[74:75], s[12:13], 1, v[68:69]
	v_lshlrev_b32_e32 v68, 1, v0
	s_xor_b64 exec, exec, s[2:3]
	v_mov_b32_e32 v69, v1
	v_lshl_add_u64 v[76:77], v[74:75], 0, v[68:69]
	v_mov_b32_e32 v147, v1
	v_lshl_add_u64 v[76:77], v[76:77], 0, v[146:147]
	s_or_b64 exec, exec, s[2:3]
	v_cvt_pk_bf16_f32 v62, v62, v63
	v_cvt_pk_bf16_f32 v63, v64, v65
	v_cvt_pk_bf16_f32 v64, v58, v59
	v_cvt_pk_bf16_f32 v65, v60, v61
	global_store_dwordx4 v[76:77], v[62:65], off
	s_and_saveexec_b64 s[2:3], s[0:1]
	s_xor_b64 s[2:3], exec, s[2:3]
	s_lshl_b32 s14, s7, 1
	s_mov_b32 s15, s4
	v_lshl_add_u64 v[58:59], v[72:73], 0, s[14:15]
	v_mov_b32_e32 v67, v1
	v_lshl_add_u64 v[58:59], v[58:59], 0, v[66:67]
	s_or_saveexec_b64 s[2:3], s[2:3]
	v_mov_b32_e32 v0, 0x7f8
	s_xor_b64 exec, exec, s[2:3]
	v_mov_b32_e32 v69, v1
	v_lshl_add_u64 v[58:59], v[74:75], 0, v[68:69]
	v_mov_b32_e32 v0, 0xf8
	s_or_b64 exec, exec, s[2:3]
	v_cvt_pk_bf16_f32 v54, v54, v55
	v_cvt_pk_bf16_f32 v55, v56, v57
	v_cvt_pk_bf16_f32 v57, v52, v53
	v_or_b32_e32 v52, 16, v70
	v_and_b32_e32 v0, v0, v124
	v_ashrrev_i32_e32 v53, 31, v52
	v_readlane_b32 s2, v250, 34
	v_lshlrev_b32_e32 v0, 1, v0
	v_cvt_pk_bf16_f32 v56, v50, v51
	v_lshlrev_b64 v[50:51], 14, v[52:53]
	v_readlane_b32 s3, v250, 35
	v_lshl_add_u64 v[58:59], v[58:59], 0, v[0:1]
	global_store_dwordx4 v[58:59], v[54:57], off
	v_lshl_add_u64 v[50:51], s[2:3], 0, v[50:51]
	s_and_saveexec_b64 s[2:3], vcc
	s_xor_b64 s[2:3], exec, s[2:3]
	s_lshl_b32 s14, s7, 1
	s_mov_b32 s15, s4
	v_lshl_add_u64 v[54:55], v[50:51], 0, s[14:15]
	v_mov_b32_e32 v67, v1
	v_lshl_add_u64 v[54:55], v[54:55], 0, v[66:67]
	v_mov_b32_e32 v145, v1
	v_lshl_add_u64 v[54:55], v[54:55], 0, v[144:145]
	s_or_saveexec_b64 s[2:3], s[2:3]
	v_readlane_b32 s14, v253, 61
	v_lshlrev_b64 v[52:53], 15, v[52:53]
	v_readlane_b32 s15, v253, 62
	s_nop 1
	v_lshl_add_u64 v[52:53], s[14:15], 0, v[52:53]
	v_lshl_add_u64 v[52:53], s[12:13], 1, v[52:53]
	s_xor_b64 exec, exec, s[2:3]
	v_mov_b32_e32 v69, v1
	v_lshl_add_u64 v[54:55], v[52:53], 0, v[68:69]
	v_mov_b32_e32 v147, v1
	v_lshl_add_u64 v[54:55], v[54:55], 0, v[146:147]
	s_or_b64 exec, exec, s[2:3]
	v_cvt_pk_bf16_f32 v46, v46, v47
	v_cvt_pk_bf16_f32 v47, v48, v49
	v_cvt_pk_bf16_f32 v48, v42, v43
	v_cvt_pk_bf16_f32 v49, v44, v45
	global_store_dwordx4 v[54:55], v[46:49], off
	s_and_saveexec_b64 s[2:3], s[0:1]
	s_xor_b64 s[2:3], exec, s[2:3]
	s_lshl_b32 s14, s7, 1
	s_mov_b32 s15, s4
	v_lshl_add_u64 v[42:43], v[50:51], 0, s[14:15]
	v_mov_b32_e32 v67, v1
	v_lshl_add_u64 v[42:43], v[42:43], 0, v[66:67]
	s_or_saveexec_b64 s[2:3], s[2:3]
	v_mov_b32_e32 v0, 0x7f8
	s_xor_b64 exec, exec, s[2:3]
	v_mov_b32_e32 v69, v1
	v_lshl_add_u64 v[42:43], v[52:53], 0, v[68:69]
	v_mov_b32_e32 v0, 0xf8
	s_or_b64 exec, exec, s[2:3]
	v_cvt_pk_bf16_f32 v38, v38, v39
	v_cvt_pk_bf16_f32 v39, v40, v41
	v_cvt_pk_bf16_f32 v41, v36, v37
	v_or_b32_e32 v36, 32, v70
	v_and_b32_e32 v0, v0, v124
	v_ashrrev_i32_e32 v37, 31, v36
	v_readlane_b32 s2, v250, 34
	v_lshlrev_b32_e32 v0, 1, v0
	v_cvt_pk_bf16_f32 v40, v34, v35
	v_lshlrev_b64 v[34:35], 14, v[36:37]
	v_readlane_b32 s3, v250, 35
	v_lshl_add_u64 v[42:43], v[42:43], 0, v[0:1]
	global_store_dwordx4 v[42:43], v[38:41], off
	v_lshl_add_u64 v[34:35], s[2:3], 0, v[34:35]
	s_and_saveexec_b64 s[2:3], vcc
	s_xor_b64 s[2:3], exec, s[2:3]
	s_lshl_b32 s14, s7, 1
	s_mov_b32 s15, s4
	v_lshl_add_u64 v[38:39], v[34:35], 0, s[14:15]
	v_mov_b32_e32 v67, v1
	v_lshl_add_u64 v[38:39], v[38:39], 0, v[66:67]
	v_mov_b32_e32 v145, v1
	v_lshl_add_u64 v[38:39], v[38:39], 0, v[144:145]
	s_or_saveexec_b64 s[2:3], s[2:3]
	v_readlane_b32 s14, v253, 61
	v_lshlrev_b64 v[36:37], 15, v[36:37]
	v_readlane_b32 s15, v253, 62
	s_nop 1
	v_lshl_add_u64 v[36:37], s[14:15], 0, v[36:37]
	v_lshl_add_u64 v[36:37], s[12:13], 1, v[36:37]
	s_xor_b64 exec, exec, s[2:3]
	v_mov_b32_e32 v69, v1
	v_lshl_add_u64 v[38:39], v[36:37], 0, v[68:69]
	v_mov_b32_e32 v147, v1
	v_lshl_add_u64 v[38:39], v[38:39], 0, v[146:147]
	s_or_b64 exec, exec, s[2:3]
	v_cvt_pk_bf16_f32 v30, v30, v31
	v_cvt_pk_bf16_f32 v31, v32, v33
	v_cvt_pk_bf16_f32 v32, v26, v27
	v_cvt_pk_bf16_f32 v33, v28, v29
	global_store_dwordx4 v[38:39], v[30:33], off
	s_and_saveexec_b64 s[2:3], s[0:1]
	s_xor_b64 s[2:3], exec, s[2:3]
	s_lshl_b32 s14, s7, 1
	s_mov_b32 s15, s4
	v_lshl_add_u64 v[26:27], v[34:35], 0, s[14:15]
	v_mov_b32_e32 v67, v1
	v_lshl_add_u64 v[26:27], v[26:27], 0, v[66:67]
	s_or_saveexec_b64 s[2:3], s[2:3]
	v_mov_b32_e32 v0, 0x7f8
	s_xor_b64 exec, exec, s[2:3]
	v_mov_b32_e32 v69, v1
	v_lshl_add_u64 v[26:27], v[36:37], 0, v[68:69]
	v_mov_b32_e32 v0, 0xf8
	s_or_b64 exec, exec, s[2:3]
	v_cvt_pk_bf16_f32 v22, v22, v23
	v_cvt_pk_bf16_f32 v23, v24, v25
	v_cvt_pk_bf16_f32 v25, v20, v21
	v_or_b32_e32 v20, 48, v70
	v_and_b32_e32 v0, v0, v124
	v_ashrrev_i32_e32 v21, 31, v20
	v_readlane_b32 s2, v250, 34
	v_lshlrev_b32_e32 v0, 1, v0
	v_cvt_pk_bf16_f32 v24, v18, v19
	v_lshlrev_b64 v[18:19], 14, v[20:21]
	v_readlane_b32 s3, v250, 35
	v_lshl_add_u64 v[26:27], v[26:27], 0, v[0:1]
	global_store_dwordx4 v[26:27], v[22:25], off
	v_lshl_add_u64 v[18:19], s[2:3], 0, v[18:19]
	s_and_saveexec_b64 s[2:3], vcc
	s_xor_b64 s[2:3], exec, s[2:3]
	s_lshl_b32 s14, s7, 1
	s_mov_b32 s15, s4
	v_lshl_add_u64 v[22:23], v[18:19], 0, s[14:15]
	v_mov_b32_e32 v67, v1
	v_lshl_add_u64 v[22:23], v[22:23], 0, v[66:67]
	v_mov_b32_e32 v145, v1
	v_lshl_add_u64 v[22:23], v[22:23], 0, v[144:145]
	s_or_saveexec_b64 s[2:3], s[2:3]
	v_readlane_b32 s14, v253, 61
	v_lshlrev_b64 v[20:21], 15, v[20:21]
	v_readlane_b32 s15, v253, 62
	s_nop 1
	v_lshl_add_u64 v[20:21], s[14:15], 0, v[20:21]
	v_lshl_add_u64 v[20:21], s[12:13], 1, v[20:21]
	s_xor_b64 exec, exec, s[2:3]
	v_mov_b32_e32 v69, v1
	v_lshl_add_u64 v[22:23], v[20:21], 0, v[68:69]
	v_mov_b32_e32 v147, v1
	v_lshl_add_u64 v[22:23], v[22:23], 0, v[146:147]
	s_or_b64 exec, exec, s[2:3]
	v_cvt_pk_bf16_f32 v14, v14, v15
	v_cvt_pk_bf16_f32 v15, v16, v17
	v_cvt_pk_bf16_f32 v16, v10, v11
	v_cvt_pk_bf16_f32 v17, v12, v13
	global_store_dwordx4 v[22:23], v[14:17], off
	s_and_saveexec_b64 s[2:3], s[0:1]
	s_xor_b64 s[0:1], exec, s[2:3]
	s_lshl_b32 s2, s7, 1
	s_mov_b32 s3, s4
	v_lshl_add_u64 v[10:11], v[18:19], 0, s[2:3]
	v_mov_b32_e32 v67, v1
	v_lshl_add_u64 v[10:11], v[10:11], 0, v[66:67]
	s_or_saveexec_b64 s[0:1], s[0:1]
	v_mov_b32_e32 v0, 0x7f8
	s_xor_b64 exec, exec, s[0:1]
	s_cbranch_execz .LBB0_547
	v_mov_b32_e32 v69, v1
	v_lshl_add_u64 v[10:11], v[20:21], 0, v[68:69]
	v_mov_b32_e32 v0, 0xf8
	s_branch .LBB0_547

.LBB0_644:
	s_add_u32 s2, s14, 0xfffc0080
	s_addc_u32 s3, s15, -1
	s_add_i32 s34, 0, 0x10000
	v_add_u32_e32 v0, s34, v161
	ds_read_b128 v[50:53], v0
	ds_read_b128 v[54:57], v0 offset:1024
	ds_read_b128 v[66:69], v0 offset:2048
	ds_read_b128 v[70:73], v0 offset:3072
	s_cmp_eq_u32 s50, 12
	s_cselect_b32 s3, s9, s3
	s_cselect_b32 s2, s52, s2
	s_cselect_b32 s17, s7, s55
	s_cselect_b32 s16, s53, s54
	v_lshl_add_u64 v[192:193], s[14:15], 0, v[156:157]
	s_add_i32 m0, s19, 0xc000
	ds_read_b128 v[164:167], v163
	ds_read_b128 v[168:171], v163 offset:1024
	ds_read_b128 v[172:175], v163 offset:2048
	ds_read_b128 v[176:179], v163 offset:3072
	ds_read_b128 v[180:183], v163 offset:4096
	ds_read_b128 v[184:187], v163 offset:5120
	ds_read_b128 v[188:191], v163 offset:6144
	ds_read_b128 v[206:209], v163 offset:7168
	global_load_lds_dwordx4 v[192:193], off
	v_lshl_add_u64 v[192:193], s[14:15], 0, v[158:159]
	s_add_i32 m0, s19, 0xe000
	s_nop 0
	global_load_lds_dwordx4 v[192:193], off
	s_waitcnt vmcnt(10)
	s_waitcnt lgkmcnt(8)
	s_barrier
	s_waitcnt lgkmcnt(0)
	s_setprio 1
	s_waitcnt lgkmcnt(0)
	v_mfma_f32_16x16x32_bf16 v[142:145], v[50:53], v[164:167], v[142:145]
	v_mfma_f32_16x16x32_bf16 v[138:141], v[66:69], v[164:167], v[138:141]
	v_mfma_f32_16x16x32_bf16 v[126:129], v[50:53], v[172:175], v[126:129]
	v_mfma_f32_16x16x32_bf16 v[122:125], v[66:69], v[172:175], v[122:125]
	v_mfma_f32_16x16x32_bf16 v[110:113], v[50:53], v[180:183], v[110:113]
	v_mfma_f32_16x16x32_bf16 v[106:109], v[66:69], v[180:183], v[106:109]
	v_mfma_f32_16x16x32_bf16 v[94:97], v[50:53], v[188:191], v[94:97]
	v_mfma_f32_16x16x32_bf16 v[90:93], v[66:69], v[188:191], v[90:93]
	v_mfma_f32_16x16x32_bf16 v[142:145], v[54:57], v[168:171], v[142:145]
	v_mfma_f32_16x16x32_bf16 v[138:141], v[70:73], v[168:171], v[138:141]
	v_mfma_f32_16x16x32_bf16 v[126:129], v[54:57], v[176:179], v[126:129]
	v_mfma_f32_16x16x32_bf16 v[122:125], v[70:73], v[176:179], v[122:125]
	v_mfma_f32_16x16x32_bf16 v[110:113], v[54:57], v[184:187], v[110:113]
	v_mfma_f32_16x16x32_bf16 v[106:109], v[70:73], v[184:187], v[106:109]
	v_mfma_f32_16x16x32_bf16 v[94:97], v[54:57], v[206:209], v[94:97]
	v_mfma_f32_16x16x32_bf16 v[90:93], v[70:73], v[206:209], v[90:93]
	s_setprio 0
	s_barrier
	s_add_i32 s40, 0, 0x14000
	s_add_i32 s34, s34, s18
	v_add_u32_e32 v0, s40, v161
	v_lshl_add_u64 v[192:193], s[16:17], 0, v[150:151]
	s_mov_b32 m0, s34
	ds_read_b128 v[210:213], v0
	ds_read_b128 v[214:217], v0 offset:1024
	ds_read_b128 v[218:221], v0 offset:2048
	ds_read_b128 v[200:203], v0 offset:3072
	global_load_lds_dwordx4 v[192:193], off
	v_lshl_add_u64 v[196:197], s[16:17], 0, v[146:147]
	s_add_i32 m0, s34, 0x2000
	s_nop 0
	global_load_lds_dwordx4 v[196:197], off
	s_waitcnt vmcnt(10)
	s_barrier
	s_waitcnt lgkmcnt(0)
	s_setprio 1
	s_waitcnt lgkmcnt(0)
	v_mfma_f32_16x16x32_bf16 v[134:137], v[210:213], v[164:167], v[134:137]
	v_mfma_f32_16x16x32_bf16 v[130:133], v[218:221], v[164:167], v[130:133]
	v_mfma_f32_16x16x32_bf16 v[118:121], v[210:213], v[172:175], v[118:121]
	v_mfma_f32_16x16x32_bf16 v[114:117], v[218:221], v[172:175], v[114:117]
	v_mfma_f32_16x16x32_bf16 v[102:105], v[210:213], v[180:183], v[102:105]
	v_mfma_f32_16x16x32_bf16 v[98:101], v[218:221], v[180:183], v[98:101]
	v_mfma_f32_16x16x32_bf16 v[86:89], v[210:213], v[188:191], v[86:89]
	v_mfma_f32_16x16x32_bf16 v[82:85], v[218:221], v[188:191], v[82:85]
	v_mfma_f32_16x16x32_bf16 v[134:137], v[214:217], v[168:171], v[134:137]
	v_mfma_f32_16x16x32_bf16 v[130:133], v[200:203], v[168:171], v[130:133]
	v_mfma_f32_16x16x32_bf16 v[118:121], v[214:217], v[176:179], v[118:121]
	v_mfma_f32_16x16x32_bf16 v[114:117], v[200:203], v[176:179], v[114:117]
	v_mfma_f32_16x16x32_bf16 v[102:105], v[214:217], v[184:187], v[102:105]
	v_mfma_f32_16x16x32_bf16 v[98:101], v[200:203], v[184:187], v[98:101]
	v_mfma_f32_16x16x32_bf16 v[86:89], v[214:217], v[206:209], v[86:89]
	v_mfma_f32_16x16x32_bf16 v[82:85], v[200:203], v[206:209], v[82:85]
	s_setprio 0
	s_mov_b32 m0, s19
	v_lshl_add_u64 v[198:199], s[2:3], 0, v[152:153]
	s_barrier
	ds_read_b128 v[164:167], v163 offset:16384
	ds_read_b128 v[168:171], v163 offset:17408
	ds_read_b128 v[172:175], v163 offset:18432
	ds_read_b128 v[176:179], v163 offset:19456
	ds_read_b128 v[180:183], v163 offset:20480
	ds_read_b128 v[184:187], v163 offset:21504
	ds_read_b128 v[188:191], v163 offset:22528
	ds_read_b128 v[206:209], v163 offset:23552
	global_load_lds_dwordx4 v[198:199], off
	v_lshl_add_u64 v[222:223], s[2:3], 0, v[148:149]
	s_mov_b32 m0, s38
	s_nop 0
	global_load_lds_dwordx4 v[222:223], off
	s_barrier
	s_waitcnt lgkmcnt(0)
	s_setprio 1
	s_waitcnt lgkmcnt(0)
	v_mfma_f32_16x16x32_bf16 v[78:81], v[50:53], v[164:167], v[78:81]
	v_mfma_f32_16x16x32_bf16 v[74:77], v[66:69], v[164:167], v[74:77]
	v_mfma_f32_16x16x32_bf16 v[46:49], v[50:53], v[172:175], v[46:49]
	v_mfma_f32_16x16x32_bf16 v[42:45], v[66:69], v[172:175], v[42:45]
	v_mfma_f32_16x16x32_bf16 v[30:33], v[50:53], v[180:183], v[30:33]
	v_mfma_f32_16x16x32_bf16 v[26:29], v[66:69], v[180:183], v[26:29]
	v_mfma_f32_16x16x32_bf16 v[14:17], v[50:53], v[188:191], v[14:17]
	v_mfma_f32_16x16x32_bf16 v[10:13], v[66:69], v[188:191], v[10:13]
	v_mfma_f32_16x16x32_bf16 v[78:81], v[54:57], v[168:171], v[78:81]
	v_mfma_f32_16x16x32_bf16 v[74:77], v[70:73], v[168:171], v[74:77]
	v_mfma_f32_16x16x32_bf16 v[46:49], v[54:57], v[176:179], v[46:49]
	v_mfma_f32_16x16x32_bf16 v[42:45], v[70:73], v[176:179], v[42:45]
	v_mfma_f32_16x16x32_bf16 v[30:33], v[54:57], v[184:187], v[30:33]
	v_mfma_f32_16x16x32_bf16 v[26:29], v[70:73], v[184:187], v[26:29]
	v_mfma_f32_16x16x32_bf16 v[14:17], v[54:57], v[206:209], v[14:17]
	v_mfma_f32_16x16x32_bf16 v[10:13], v[70:73], v[206:209], v[10:13]
	s_setprio 0
	s_barrier
	s_add_u32 s34, s16, 0x40000
	s_addc_u32 s35, s17, 0
	s_add_i32 s40, s40, s18
	v_lshl_add_u64 v[50:51], s[34:35], 0, v[150:151]
	s_mov_b32 m0, s40
	s_nop 0
	global_load_lds_dwordx4 v[50:51], off
	v_lshl_add_u64 v[50:51], s[34:35], 0, v[146:147]
	s_add_i32 m0, s40, 0x2000
	s_nop 0
	global_load_lds_dwordx4 v[50:51], off
	s_waitcnt vmcnt(10)
	s_barrier
	s_setprio 1
	v_mfma_f32_16x16x32_bf16 v[38:41], v[210:213], v[172:175], v[38:41]
	v_mfma_f32_16x16x32_bf16 v[34:37], v[218:221], v[172:175], v[34:37]
	v_mfma_f32_16x16x32_bf16 v[22:25], v[210:213], v[180:183], v[22:25]
	v_mfma_f32_16x16x32_bf16 v[18:21], v[218:221], v[180:183], v[18:21]
	v_mfma_f32_16x16x32_bf16 v[6:9], v[210:213], v[188:191], v[6:9]
	v_mfma_f32_16x16x32_bf16 v[2:5], v[218:221], v[188:191], v[2:5]
	v_mfma_f32_16x16x32_bf16 v[50:53], v[210:213], v[164:167], v[62:65]
	v_mfma_f32_16x16x32_bf16 v[54:57], v[218:221], v[164:167], v[58:61]
	v_mfma_f32_16x16x32_bf16 v[38:41], v[214:217], v[176:179], v[38:41]
	v_mfma_f32_16x16x32_bf16 v[34:37], v[200:203], v[176:179], v[34:37]
	v_mfma_f32_16x16x32_bf16 v[22:25], v[214:217], v[184:187], v[22:25]
	v_mfma_f32_16x16x32_bf16 v[18:21], v[200:203], v[184:187], v[18:21]
	v_mfma_f32_16x16x32_bf16 v[6:9], v[214:217], v[206:209], v[6:9]
	v_mfma_f32_16x16x32_bf16 v[2:5], v[200:203], v[206:209], v[2:5]
	v_mfma_f32_16x16x32_bf16 v[50:53], v[214:217], v[168:171], v[50:53]
	v_mfma_f32_16x16x32_bf16 v[54:57], v[200:203], v[168:171], v[54:57]
	s_setprio 0
	s_add_i32 s34, 0, 0x18000
	v_add_u32_e32 v0, s34, v161
	s_barrier
	ds_read_b128 v[58:61], v0
	ds_read_b128 v[62:65], v0 offset:1024
	ds_read_b128 v[66:69], v0 offset:2048
	ds_read_b128 v[70:73], v0 offset:3072
	s_add_u32 s2, s2, 0x40000
	s_addc_u32 s3, s3, 0
	s_mov_b32 m0, s39
	v_lshl_add_u64 v[206:207], s[2:3], 0, v[152:153]
	ds_read_b128 v[164:167], v163 offset:32768
	ds_read_b128 v[168:171], v163 offset:33792
	ds_read_b128 v[172:175], v163 offset:34816
	ds_read_b128 v[176:179], v163 offset:35840
	ds_read_b128 v[180:183], v163 offset:36864
	ds_read_b128 v[184:187], v163 offset:37888
	ds_read_b128 v[188:191], v163 offset:38912
	ds_read_b128 v[200:203], v163 offset:39936
	global_load_lds_dwordx4 v[206:207], off
	v_lshl_add_u64 v[206:207], s[2:3], 0, v[148:149]
	s_mov_b32 m0, s44
	s_nop 0
	global_load_lds_dwordx4 v[206:207], off
	s_waitcnt vmcnt(10)
	s_waitcnt lgkmcnt(8)
	s_barrier
	s_waitcnt lgkmcnt(0)
	s_setprio 1
	s_waitcnt lgkmcnt(0)
	v_mfma_f32_16x16x32_bf16 v[142:145], v[58:61], v[164:167], v[142:145]
	v_mfma_f32_16x16x32_bf16 v[138:141], v[66:69], v[164:167], v[138:141]
	v_mfma_f32_16x16x32_bf16 v[126:129], v[58:61], v[172:175], v[126:129]
	v_mfma_f32_16x16x32_bf16 v[122:125], v[66:69], v[172:175], v[122:125]
	v_mfma_f32_16x16x32_bf16 v[110:113], v[58:61], v[180:183], v[110:113]
	v_mfma_f32_16x16x32_bf16 v[106:109], v[66:69], v[180:183], v[106:109]
	v_mfma_f32_16x16x32_bf16 v[94:97], v[58:61], v[188:191], v[94:97]
	v_mfma_f32_16x16x32_bf16 v[90:93], v[66:69], v[188:191], v[90:93]
	v_mfma_f32_16x16x32_bf16 v[142:145], v[62:65], v[168:171], v[142:145]
	v_mfma_f32_16x16x32_bf16 v[138:141], v[70:73], v[168:171], v[138:141]
	v_mfma_f32_16x16x32_bf16 v[126:129], v[62:65], v[176:179], v[126:129]
	v_mfma_f32_16x16x32_bf16 v[122:125], v[70:73], v[176:179], v[122:125]
	v_mfma_f32_16x16x32_bf16 v[110:113], v[62:65], v[184:187], v[110:113]
	v_mfma_f32_16x16x32_bf16 v[106:109], v[70:73], v[184:187], v[106:109]
	v_mfma_f32_16x16x32_bf16 v[94:97], v[62:65], v[200:203], v[94:97]
	v_mfma_f32_16x16x32_bf16 v[90:93], v[70:73], v[200:203], v[90:93]
	s_setprio 0
	s_barrier
	s_add_i32 s35, 0, 0x1c000
	s_add_i32 s2, s34, s18
	v_add_u32_e32 v0, s35, v161
	v_lshl_add_u64 v[192:193], v[192:193], 0, s[74:75]
	s_mov_b32 m0, s2
	ds_read_b128 v[206:209], v0
	ds_read_b128 v[210:213], v0 offset:1024
	ds_read_b128 v[214:217], v0 offset:2048
	ds_read_b128 v[218:221], v0 offset:3072
	global_load_lds_dwordx4 v[192:193], off
	v_lshl_add_u64 v[192:193], v[196:197], 0, s[74:75]
	s_add_i32 m0, s2, 0x2000
	s_nop 0
	global_load_lds_dwordx4 v[192:193], off
	s_waitcnt vmcnt(10)
	s_barrier
	s_waitcnt lgkmcnt(0)
	s_setprio 1
	s_waitcnt lgkmcnt(0)
	v_mfma_f32_16x16x32_bf16 v[134:137], v[206:209], v[164:167], v[134:137]
	v_mfma_f32_16x16x32_bf16 v[130:133], v[214:217], v[164:167], v[130:133]
	v_mfma_f32_16x16x32_bf16 v[118:121], v[206:209], v[172:175], v[118:121]
	v_mfma_f32_16x16x32_bf16 v[114:117], v[214:217], v[172:175], v[114:117]
	v_mfma_f32_16x16x32_bf16 v[102:105], v[206:209], v[180:183], v[102:105]
	v_mfma_f32_16x16x32_bf16 v[98:101], v[214:217], v[180:183], v[98:101]
	v_mfma_f32_16x16x32_bf16 v[86:89], v[206:209], v[188:191], v[86:89]
	v_mfma_f32_16x16x32_bf16 v[82:85], v[214:217], v[188:191], v[82:85]
	v_mfma_f32_16x16x32_bf16 v[134:137], v[210:213], v[168:171], v[134:137]
	v_mfma_f32_16x16x32_bf16 v[130:133], v[218:221], v[168:171], v[130:133]
	v_mfma_f32_16x16x32_bf16 v[118:121], v[210:213], v[176:179], v[118:121]
	v_mfma_f32_16x16x32_bf16 v[114:117], v[218:221], v[176:179], v[114:117]
	v_mfma_f32_16x16x32_bf16 v[102:105], v[210:213], v[184:187], v[102:105]
	v_mfma_f32_16x16x32_bf16 v[98:101], v[218:221], v[184:187], v[98:101]
	v_mfma_f32_16x16x32_bf16 v[86:89], v[210:213], v[200:203], v[86:89]
	v_mfma_f32_16x16x32_bf16 v[82:85], v[218:221], v[200:203], v[82:85]
	s_setprio 0
	s_mov_b32 m0, s45
	v_lshl_add_u64 v[192:193], v[198:199], 0, s[74:75]
	s_barrier
	ds_read_b128 v[164:167], v163 offset:49152
	ds_read_b128 v[168:171], v163 offset:50176
	ds_read_b128 v[172:175], v163 offset:51200
	ds_read_b128 v[176:179], v163 offset:52224
	ds_read_b128 v[180:183], v163 offset:53248
	ds_read_b128 v[184:187], v163 offset:54272
	ds_read_b128 v[188:191], v163 offset:55296
	ds_read_b128 v[200:203], v163 offset:56320
	global_load_lds_dwordx4 v[192:193], off
	v_lshl_add_u64 v[192:193], v[222:223], 0, s[74:75]
	s_mov_b32 m0, s67
	s_nop 0
	global_load_lds_dwordx4 v[192:193], off
	s_barrier
	s_waitcnt lgkmcnt(0)
	s_setprio 1
	s_waitcnt lgkmcnt(0)
	v_mfma_f32_16x16x32_bf16 v[78:81], v[58:61], v[164:167], v[78:81]
	v_mfma_f32_16x16x32_bf16 v[74:77], v[66:69], v[164:167], v[74:77]
	v_mfma_f32_16x16x32_bf16 v[46:49], v[58:61], v[172:175], v[46:49]
	v_mfma_f32_16x16x32_bf16 v[42:45], v[66:69], v[172:175], v[42:45]
	v_mfma_f32_16x16x32_bf16 v[30:33], v[58:61], v[180:183], v[30:33]
	v_mfma_f32_16x16x32_bf16 v[26:29], v[66:69], v[180:183], v[26:29]
	v_mfma_f32_16x16x32_bf16 v[14:17], v[58:61], v[188:191], v[14:17]
	v_mfma_f32_16x16x32_bf16 v[10:13], v[66:69], v[188:191], v[10:13]
	v_mfma_f32_16x16x32_bf16 v[78:81], v[62:65], v[168:171], v[78:81]
	v_mfma_f32_16x16x32_bf16 v[74:77], v[70:73], v[168:171], v[74:77]
	v_mfma_f32_16x16x32_bf16 v[46:49], v[62:65], v[176:179], v[46:49]
	v_mfma_f32_16x16x32_bf16 v[42:45], v[70:73], v[176:179], v[42:45]
	v_mfma_f32_16x16x32_bf16 v[30:33], v[62:65], v[184:187], v[30:33]
	v_mfma_f32_16x16x32_bf16 v[26:29], v[70:73], v[184:187], v[26:29]
	v_mfma_f32_16x16x32_bf16 v[14:17], v[62:65], v[200:203], v[14:17]
	v_mfma_f32_16x16x32_bf16 v[10:13], v[70:73], v[200:203], v[10:13]
	s_setprio 0
	s_barrier
	s_add_u32 s2, s16, 0x40080
	s_addc_u32 s3, s17, 0
	s_add_i32 s16, s35, s18
	v_lshl_add_u64 v[58:59], s[2:3], 0, v[150:151]
	s_mov_b32 m0, s16
	s_nop 0
	global_load_lds_dwordx4 v[58:59], off
	v_lshl_add_u64 v[58:59], s[2:3], 0, v[146:147]
	s_add_i32 m0, s16, 0x2000
	s_nop 0
	global_load_lds_dwordx4 v[58:59], off
	s_waitcnt vmcnt(10)
	s_barrier
	s_setprio 1
	v_mfma_f32_16x16x32_bf16 v[50:53], v[206:209], v[164:167], v[50:53]
	v_mfma_f32_16x16x32_bf16 v[62:65], v[210:213], v[168:171], v[50:53]
	v_mfma_f32_16x16x32_bf16 v[50:53], v[214:217], v[164:167], v[54:57]
	v_mfma_f32_16x16x32_bf16 v[38:41], v[206:209], v[172:175], v[38:41]
	v_mfma_f32_16x16x32_bf16 v[34:37], v[214:217], v[172:175], v[34:37]
	v_mfma_f32_16x16x32_bf16 v[22:25], v[206:209], v[180:183], v[22:25]
	v_mfma_f32_16x16x32_bf16 v[18:21], v[214:217], v[180:183], v[18:21]
	v_mfma_f32_16x16x32_bf16 v[6:9], v[206:209], v[188:191], v[6:9]
	v_mfma_f32_16x16x32_bf16 v[2:5], v[214:217], v[188:191], v[2:5]
	v_mfma_f32_16x16x32_bf16 v[58:61], v[218:221], v[168:171], v[50:53]
	v_mfma_f32_16x16x32_bf16 v[38:41], v[210:213], v[176:179], v[38:41]
	v_mfma_f32_16x16x32_bf16 v[34:37], v[218:221], v[176:179], v[34:37]
	v_mfma_f32_16x16x32_bf16 v[22:25], v[210:213], v[184:187], v[22:25]
	v_mfma_f32_16x16x32_bf16 v[18:21], v[218:221], v[184:187], v[18:21]
	v_mfma_f32_16x16x32_bf16 v[6:9], v[210:213], v[200:203], v[6:9]
	v_mfma_f32_16x16x32_bf16 v[2:5], v[218:221], v[200:203], v[2:5]
	s_setprio 0
	s_add_i32 s50, s50, 2
	s_add_u32 s14, s14, 0x100
	s_addc_u32 s15, s15, 0
	s_add_u32 s54, s54, 0x100
	s_addc_u32 s55, s55, 0
	s_cmp_gt_u32 s50, 13
	s_barrier
	s_cbranch_scc0 .LBB0_644
	s_lshl_b32 s7, s49, 8
	s_mov_b64 s[2:3], -1
	s_cmp_lt_i32 s51, 13
	v_lshl_or_b32 v0, s51, 8, v162
	s_cbranch_scc0 .LBB0_647
	v_readlane_b32 s2, v249, 15
	v_readlane_b32 s3, v249, 16
	v_add_u32_e32 v68, s7, v160
	v_ashrrev_i32_e32 v53, 31, v0
	v_mov_b64_e32 v[54:55], s[2:3]
	v_mov_b32_e32 v52, v0
	v_mad_i64_i32 v[50:51], s[2:3], v68, s76, v[54:55]
	v_lshlrev_b64 v[56:57], 1, v[52:53]
	v_lshl_add_u64 v[66:67], v[50:51], 0, v[56:57]
	v_cvt_pk_bf16_f32 v50, v142, v143
	v_cvt_pk_bf16_f32 v51, v144, v145
	v_cvt_pk_bf16_f32 v52, v138, v139
	v_cvt_pk_bf16_f32 v53, v140, v141
	global_store_dwordx4 v[66:67], v[50:53], off
	s_nop 1
	v_cvt_pk_bf16_f32 v50, v134, v135
	v_cvt_pk_bf16_f32 v51, v136, v137
	v_cvt_pk_bf16_f32 v52, v130, v131
	v_cvt_pk_bf16_f32 v53, v132, v133
	global_store_dwordx4 v[66:67], v[50:53], off offset:256
	s_nop 1
	v_or_b32_e32 v50, 16, v68
	v_mad_i64_i32 v[50:51], s[2:3], v50, s76, v[54:55]
	v_lshl_add_u64 v[66:67], v[50:51], 0, v[56:57]
	v_cvt_pk_bf16_f32 v50, v126, v127
	v_cvt_pk_bf16_f32 v51, v128, v129
	v_cvt_pk_bf16_f32 v52, v122, v123
	v_cvt_pk_bf16_f32 v53, v124, v125
	global_store_dwordx4 v[66:67], v[50:53], off
	s_nop 1
	v_cvt_pk_bf16_f32 v50, v118, v119
	v_cvt_pk_bf16_f32 v51, v120, v121
	v_cvt_pk_bf16_f32 v52, v114, v115
	v_cvt_pk_bf16_f32 v53, v116, v117
	global_store_dwordx4 v[66:67], v[50:53], off offset:256
	s_nop 1
	v_or_b32_e32 v50, 32, v68
	v_mad_i64_i32 v[50:51], s[2:3], v50, s76, v[54:55]
	v_lshl_add_u64 v[66:67], v[50:51], 0, v[56:57]
	v_cvt_pk_bf16_f32 v50, v110, v111
	v_cvt_pk_bf16_f32 v51, v112, v113
	v_cvt_pk_bf16_f32 v52, v106, v107
	v_cvt_pk_bf16_f32 v53, v108, v109
	global_store_dwordx4 v[66:67], v[50:53], off
	s_nop 1
	v_cvt_pk_bf16_f32 v50, v102, v103
	v_cvt_pk_bf16_f32 v51, v104, v105
	v_cvt_pk_bf16_f32 v52, v98, v99
	v_cvt_pk_bf16_f32 v53, v100, v101
	global_store_dwordx4 v[66:67], v[50:53], off offset:256
	s_nop 1
	v_or_b32_e32 v50, 48, v68
	v_mad_i64_i32 v[50:51], s[2:3], v50, s76, v[54:55]
	v_lshl_add_u64 v[66:67], v[50:51], 0, v[56:57]
	v_cvt_pk_bf16_f32 v50, v94, v95
	v_cvt_pk_bf16_f32 v51, v96, v97
	v_cvt_pk_bf16_f32 v52, v90, v91
	v_cvt_pk_bf16_f32 v53, v92, v93
	global_store_dwordx4 v[66:67], v[50:53], off
	s_nop 1
	v_cvt_pk_bf16_f32 v50, v86, v87
	v_cvt_pk_bf16_f32 v51, v88, v89
	v_cvt_pk_bf16_f32 v52, v82, v83
	v_cvt_pk_bf16_f32 v53, v84, v85
	global_store_dwordx4 v[66:67], v[50:53], off offset:256
	s_nop 1
	v_add_u32_e32 v50, 0x80, v68
	v_mad_i64_i32 v[50:51], s[2:3], v50, s76, v[54:55]
	v_lshl_add_u64 v[66:67], v[50:51], 0, v[56:57]
	v_cvt_pk_bf16_f32 v50, v78, v79
	v_cvt_pk_bf16_f32 v51, v80, v81
	v_cvt_pk_bf16_f32 v52, v74, v75
	v_cvt_pk_bf16_f32 v53, v76, v77
	global_store_dwordx4 v[66:67], v[50:53], off
	s_nop 1
	v_cvt_pk_bf16_f32 v50, v62, v63
	v_cvt_pk_bf16_f32 v51, v64, v65
	v_cvt_pk_bf16_f32 v52, v58, v59
	v_cvt_pk_bf16_f32 v53, v60, v61
	global_store_dwordx4 v[66:67], v[50:53], off offset:256
	s_nop 1
	v_add_u32_e32 v50, 0x90, v68
	v_mad_i64_i32 v[50:51], s[2:3], v50, s76, v[54:55]
	v_lshl_add_u64 v[66:67], v[50:51], 0, v[56:57]
	v_cvt_pk_bf16_f32 v50, v46, v47
	v_cvt_pk_bf16_f32 v51, v48, v49
	v_cvt_pk_bf16_f32 v52, v42, v43
	v_cvt_pk_bf16_f32 v53, v44, v45
	global_store_dwordx4 v[66:67], v[50:53], off
	s_nop 1
	v_cvt_pk_bf16_f32 v50, v38, v39
	v_cvt_pk_bf16_f32 v51, v40, v41
	v_cvt_pk_bf16_f32 v52, v34, v35
	v_cvt_pk_bf16_f32 v53, v36, v37
	global_store_dwordx4 v[66:67], v[50:53], off offset:256
	s_nop 1
	v_add_u32_e32 v50, 0xa0, v68
	v_mad_i64_i32 v[50:51], s[2:3], v50, s76, v[54:55]
	v_lshl_add_u64 v[66:67], v[50:51], 0, v[56:57]
	v_cvt_pk_bf16_f32 v50, v30, v31
	v_cvt_pk_bf16_f32 v51, v32, v33
	v_cvt_pk_bf16_f32 v52, v26, v27
	v_cvt_pk_bf16_f32 v53, v28, v29
	global_store_dwordx4 v[66:67], v[50:53], off
	s_nop 1
	v_cvt_pk_bf16_f32 v50, v22, v23
	v_cvt_pk_bf16_f32 v51, v24, v25
	v_cvt_pk_bf16_f32 v52, v18, v19
	v_cvt_pk_bf16_f32 v53, v20, v21
	global_store_dwordx4 v[66:67], v[50:53], off offset:256
	s_nop 1
	v_add_u32_e32 v50, 0xb0, v68
	v_mad_i64_i32 v[50:51], s[2:3], v50, s76, v[54:55]
	v_lshl_add_u64 v[54:55], v[50:51], 0, v[56:57]
	v_cvt_pk_bf16_f32 v50, v14, v15
	v_cvt_pk_bf16_f32 v51, v16, v17
	v_cvt_pk_bf16_f32 v52, v10, v11
	v_cvt_pk_bf16_f32 v53, v12, v13
	global_store_dwordx4 v[54:55], v[50:53], off
	s_mov_b64 s[2:3], 0
	s_nop 0
	v_cvt_pk_bf16_f32 v50, v6, v7
	v_cvt_pk_bf16_f32 v51, v8, v9
	v_cvt_pk_bf16_f32 v52, v2, v3
	v_cvt_pk_bf16_f32 v53, v4, v5
	global_store_dwordx4 v[54:55], v[50:53], off offset:256
